# GEMM unit loops: accumulator clear moved from the loop preheader into the first iteration's first load segment (runs under that segment's loads; later iterations branch over it)
# speedup vs baseline: 1.0038x; 1.0038x over previous
.LBB0_288:
	s_ashr_i32 s13, s12, 31
	s_lshl_b64 s[16:17], s[12:13], 19
	s_add_u32 s16, s36, s16
	s_addc_u32 s17, s37, s17
	s_and_b64 s[18:19], s[0:1], exec
	s_cselect_b32 s13, s17, s27
	s_cselect_b32 s50, s16, s26
	s_ashr_i32 s15, s14, 31
	s_lshl_b64 s[18:19], s[14:15], 19
	s_add_u32 s18, s30, s18
	s_addc_u32 s19, s31, s19
	s_and_b64 s[28:29], s[0:1], exec
	s_cselect_b32 s15, s19, s25
	s_cselect_b32 s51, s18, s24
	s_add_u32 s52, s24, 0x10000
	s_addc_u32 s53, s25, 0
	s_add_u32 s24, s26, 0x40080
	s_addc_u32 s25, s27, 0
	s_mov_b32 s54, -2
.LBB0_289:
	ds_read_b128 v[170:173], v167
	ds_read_b128 v[174:177], v167 offset:1024
	ds_read_b128 v[178:181], v167 offset:2048
	ds_read_b128 v[182:185], v167 offset:3072
	ds_read_b128 v[186:189], v168
	ds_read_b128 v[190:193], v168 offset:1024
	ds_read_b128 v[194:197], v168 offset:2048
	ds_read_b128 v[198:201], v168 offset:3072
	s_add_u32 s26, s24, 0xfffc0080
	s_addc_u32 s27, s25, -1
	s_cmp_eq_u32 s54, 12
	s_cselect_b32 s29, s13, s27
	s_cselect_b32 s28, s50, s26
	s_cselect_b32 s27, s15, s53
	s_cselect_b32 s26, s51, s52
	v_lshl_add_u64 v[164:165], s[24:25], 0, v[158:159]
	s_add_i32 m0, s21, 0xc000
	ds_read_b128 v[210:213], v169
	ds_read_b128 v[214:217], v169 offset:1024
	ds_read_b128 v[218:221], v169 offset:2048
	ds_read_b128 v[222:225], v169 offset:3072
	ds_read_b128 v[226:229], v169 offset:4096
	ds_read_b128 v[230:233], v169 offset:5120
	ds_read_b128 v[234:237], v169 offset:6144
	ds_read_b128 v[238:241], v169 offset:7168
	global_load_lds_dwordx4 v[164:165], off
	v_lshl_add_u64 v[164:165], s[24:25], 0, v[156:157]
	s_add_i32 m0, s21, 0xe000
	s_nop 0
	global_load_lds_dwordx4 v[164:165], off
	s_cmp_lg_u32 s54, -2
	s_cbranch_scc1 .Lzm_15
	v_mov_b32_e32 v0, 0
	v_mov_b32_e32 v1, v0
	v_mov_b32_e32 v2, v0
	v_mov_b32_e32 v3, v0
	v_mov_b32_e32 v4, v0
	v_mov_b32_e32 v5, v0
	v_mov_b32_e32 v6, v0
	v_mov_b32_e32 v7, v0
	v_mov_b32_e32 v8, v0
	v_mov_b32_e32 v9, v0
	v_mov_b32_e32 v10, v0
	v_mov_b32_e32 v11, v0
	v_mov_b32_e32 v12, v0
	v_mov_b32_e32 v13, v0
	v_mov_b32_e32 v14, v0
	v_mov_b32_e32 v15, v0
	v_mov_b32_e32 v16, v0
	v_mov_b32_e32 v17, v0
	v_mov_b32_e32 v18, v0
	v_mov_b32_e32 v19, v0
	v_mov_b32_e32 v20, v0
	v_mov_b32_e32 v21, v0
	v_mov_b32_e32 v22, v0
	v_mov_b32_e32 v23, v0
	v_mov_b32_e32 v24, v0
	v_mov_b32_e32 v25, v0
	v_mov_b32_e32 v26, v0
	v_mov_b32_e32 v27, v0
	v_mov_b32_e32 v28, v0
	v_mov_b32_e32 v29, v0
	v_mov_b32_e32 v30, v0
	v_mov_b32_e32 v31, v0
	v_mov_b32_e32 v32, v0
	v_mov_b32_e32 v33, v0
	v_mov_b32_e32 v34, v0
	v_mov_b32_e32 v35, v0
	v_mov_b32_e32 v36, v0
	v_mov_b32_e32 v37, v0
	v_mov_b32_e32 v38, v0
	v_mov_b32_e32 v39, v0
	v_mov_b32_e32 v40, v0
	v_mov_b32_e32 v41, v0
	v_mov_b32_e32 v42, v0
	v_mov_b32_e32 v43, v0
	v_mov_b32_e32 v44, v0
	v_mov_b32_e32 v45, v0
	v_mov_b32_e32 v46, v0
	v_mov_b32_e32 v47, v0
	v_mov_b32_e32 v48, v0
	v_mov_b32_e32 v49, v0
	v_mov_b32_e32 v50, v0
	v_mov_b32_e32 v51, v0
	v_mov_b32_e32 v52, v0
	v_mov_b32_e32 v53, v0
	v_mov_b32_e32 v54, v0
	v_mov_b32_e32 v55, v0
	v_mov_b32_e32 v56, v0
	v_mov_b32_e32 v57, v0
	v_mov_b32_e32 v58, v0
	v_mov_b32_e32 v59, v0
	v_mov_b32_e32 v60, v0
	v_mov_b32_e32 v61, v0
	v_mov_b32_e32 v62, v0
	v_mov_b32_e32 v63, v0
	v_mov_b32_e32 v64, v0
	v_mov_b32_e32 v65, v0
	v_mov_b32_e32 v66, v0
	v_mov_b32_e32 v67, v0
	v_mov_b32_e32 v68, v0
	v_mov_b32_e32 v69, v0
	v_mov_b32_e32 v70, v0
	v_mov_b32_e32 v71, v0
	v_mov_b32_e32 v72, v0
	v_mov_b32_e32 v73, v0
	v_mov_b32_e32 v74, v0
	v_mov_b32_e32 v75, v0
	v_mov_b32_e32 v76, v0
	v_mov_b32_e32 v77, v0
	v_mov_b32_e32 v78, v0
	v_mov_b32_e32 v79, v0
	v_mov_b32_e32 v80, v0
	v_mov_b32_e32 v81, v0
	v_mov_b32_e32 v82, v0
	v_mov_b32_e32 v83, v0
	v_mov_b32_e32 v84, v0
	v_mov_b32_e32 v85, v0
	v_mov_b32_e32 v86, v0
	v_mov_b32_e32 v87, v0
	v_mov_b32_e32 v88, v0
	v_mov_b32_e32 v89, v0
	v_mov_b32_e32 v90, v0
	v_mov_b32_e32 v91, v0
	v_mov_b32_e32 v92, v0
	v_mov_b32_e32 v93, v0
	v_mov_b32_e32 v94, v0
	v_mov_b32_e32 v95, v0
	v_mov_b32_e32 v96, v0
	v_mov_b32_e32 v97, v0
	v_mov_b32_e32 v98, v0
	v_mov_b32_e32 v99, v0
	v_mov_b32_e32 v100, v0
	v_mov_b32_e32 v101, v0
	v_mov_b32_e32 v102, v0
	v_mov_b32_e32 v103, v0
	v_mov_b32_e32 v104, v0
	v_mov_b32_e32 v105, v0
	v_mov_b32_e32 v106, v0
	v_mov_b32_e32 v107, v0
	v_mov_b32_e32 v108, v0
	v_mov_b32_e32 v109, v0
	v_mov_b32_e32 v110, v0
	v_mov_b32_e32 v111, v0
	v_mov_b32_e32 v112, v0
	v_mov_b32_e32 v113, v0
	v_mov_b32_e32 v114, v0
	v_mov_b32_e32 v115, v0
	v_mov_b32_e32 v116, v0
	v_mov_b32_e32 v117, v0
	v_mov_b32_e32 v118, v0
	v_mov_b32_e32 v119, v0
	v_mov_b32_e32 v120, v0
	v_mov_b32_e32 v121, v0
	v_mov_b32_e32 v122, v0
	v_mov_b32_e32 v123, v0
	v_mov_b32_e32 v124, v0
	v_mov_b32_e32 v125, v0
	v_mov_b32_e32 v126, v0
	v_mov_b32_e32 v127, v0
.Lzm_15:
	s_waitcnt vmcnt(8)
	s_waitcnt lgkmcnt(0)
	s_barrier
	s_setprio 1
	s_waitcnt lgkmcnt(0)
	v_mfma_f32_16x16x32_bf16 v[124:127], v[170:173], v[210:213], v[124:127]
	v_mfma_f32_16x16x32_bf16 v[116:119], v[178:181], v[210:213], v[116:119]
	v_mfma_f32_16x16x32_bf16 v[108:111], v[170:173], v[218:221], v[108:111]
	v_mfma_f32_16x16x32_bf16 v[100:103], v[178:181], v[218:221], v[100:103]
	v_mfma_f32_16x16x32_bf16 v[92:95], v[170:173], v[226:229], v[92:95]
	v_mfma_f32_16x16x32_bf16 v[84:87], v[178:181], v[226:229], v[84:87]
	v_mfma_f32_16x16x32_bf16 v[76:79], v[170:173], v[234:237], v[76:79]
	v_mfma_f32_16x16x32_bf16 v[68:71], v[178:181], v[234:237], v[68:71]
	v_mfma_f32_16x16x32_bf16 v[124:127], v[174:177], v[214:217], v[124:127]
	v_mfma_f32_16x16x32_bf16 v[116:119], v[182:185], v[214:217], v[116:119]
	v_mfma_f32_16x16x32_bf16 v[108:111], v[174:177], v[222:225], v[108:111]
	v_mfma_f32_16x16x32_bf16 v[100:103], v[182:185], v[222:225], v[100:103]
	v_mfma_f32_16x16x32_bf16 v[92:95], v[174:177], v[230:233], v[92:95]
	v_mfma_f32_16x16x32_bf16 v[84:87], v[182:185], v[230:233], v[84:87]
	v_mfma_f32_16x16x32_bf16 v[76:79], v[174:177], v[238:241], v[76:79]
	v_mfma_f32_16x16x32_bf16 v[68:71], v[182:185], v[238:241], v[68:71]
	s_setprio 0
	s_setprio 1
	v_mfma_f32_16x16x32_bf16 v[120:123], v[186:189], v[210:213], v[120:123]
	v_mfma_f32_16x16x32_bf16 v[112:115], v[194:197], v[210:213], v[112:115]
	v_mfma_f32_16x16x32_bf16 v[104:107], v[186:189], v[218:221], v[104:107]
	v_mfma_f32_16x16x32_bf16 v[96:99], v[194:197], v[218:221], v[96:99]
	v_mfma_f32_16x16x32_bf16 v[88:91], v[186:189], v[226:229], v[88:91]
	v_mfma_f32_16x16x32_bf16 v[80:83], v[194:197], v[226:229], v[80:83]
	v_mfma_f32_16x16x32_bf16 v[72:75], v[186:189], v[234:237], v[72:75]
	v_mfma_f32_16x16x32_bf16 v[64:67], v[194:197], v[234:237], v[64:67]
	v_mfma_f32_16x16x32_bf16 v[120:123], v[190:193], v[214:217], v[120:123]
	v_mfma_f32_16x16x32_bf16 v[112:115], v[198:201], v[214:217], v[112:115]
	v_mfma_f32_16x16x32_bf16 v[104:107], v[190:193], v[222:225], v[104:107]
	v_mfma_f32_16x16x32_bf16 v[96:99], v[198:201], v[222:225], v[96:99]
	v_mfma_f32_16x16x32_bf16 v[88:91], v[190:193], v[230:233], v[88:91]
	v_mfma_f32_16x16x32_bf16 v[80:83], v[198:201], v[230:233], v[80:83]
	v_mfma_f32_16x16x32_bf16 v[72:75], v[190:193], v[238:241], v[72:75]
	v_mfma_f32_16x16x32_bf16 v[64:67], v[198:201], v[238:241], v[64:67]
	s_setprio 0
	s_barrier
	s_add_i32 s55, s48, s38
	v_lshl_add_u64 v[164:165], s[26:27], 0, v[134:135]
	s_mov_b32 m0, s55
	ds_read_b128 v[210:213], v169 offset:16384
	ds_read_b128 v[214:217], v169 offset:17408
	ds_read_b128 v[218:221], v169 offset:18432
	ds_read_b128 v[222:225], v169 offset:19456
	ds_read_b128 v[226:229], v169 offset:20480
	ds_read_b128 v[230:233], v169 offset:21504
	ds_read_b128 v[234:237], v169 offset:22528
	ds_read_b128 v[238:241], v169 offset:23552
	global_load_lds_dwordx4 v[164:165], off
	s_add_i32 m0, s55, 0x2000
	s_add_u32 s56, s26, 0x4000
	v_lshl_add_u64 v[164:165], s[26:27], 0, v[130:131]
	s_addc_u32 s57, s27, 0
	s_add_i32 s55, s49, s38
	global_load_lds_dwordx4 v[164:165], off
	v_lshl_add_u64 v[164:165], s[56:57], 0, v[134:135]
	s_mov_b32 m0, s55
	v_lshl_add_u64 v[242:243], s[28:29], 0, v[132:133]
	global_load_lds_dwordx4 v[164:165], off
	v_lshl_add_u64 v[164:165], s[56:57], 0, v[130:131]
	s_add_i32 m0, s55, 0x2000
	s_nop 0
	global_load_lds_dwordx4 v[164:165], off
	v_lshl_add_u64 v[164:165], s[28:29], 0, v[136:137]
	s_mov_b32 m0, s21
	s_nop 0
	global_load_lds_dwordx4 v[164:165], off
	s_mov_b32 m0, s23
	s_nop 0
	global_load_lds_dwordx4 v[242:243], off
	s_waitcnt vmcnt(8)
	s_waitcnt lgkmcnt(0)
	s_barrier
	s_setprio 1
	s_waitcnt lgkmcnt(0)
	v_mfma_f32_16x16x32_bf16 v[60:63], v[170:173], v[210:213], v[60:63]
	v_mfma_f32_16x16x32_bf16 v[52:55], v[178:181], v[210:213], v[52:55]
	v_mfma_f32_16x16x32_bf16 v[44:47], v[170:173], v[218:221], v[44:47]
	v_mfma_f32_16x16x32_bf16 v[36:39], v[178:181], v[218:221], v[36:39]
	v_mfma_f32_16x16x32_bf16 v[28:31], v[170:173], v[226:229], v[28:31]
	v_mfma_f32_16x16x32_bf16 v[20:23], v[178:181], v[226:229], v[20:23]
	v_mfma_f32_16x16x32_bf16 v[12:15], v[170:173], v[234:237], v[12:15]
	v_mfma_f32_16x16x32_bf16 v[4:7], v[178:181], v[234:237], v[4:7]
	v_mfma_f32_16x16x32_bf16 v[60:63], v[174:177], v[214:217], v[60:63]
	v_mfma_f32_16x16x32_bf16 v[52:55], v[182:185], v[214:217], v[52:55]
	v_mfma_f32_16x16x32_bf16 v[44:47], v[174:177], v[222:225], v[44:47]
	v_mfma_f32_16x16x32_bf16 v[36:39], v[182:185], v[222:225], v[36:39]
	v_mfma_f32_16x16x32_bf16 v[28:31], v[174:177], v[230:233], v[28:31]
	v_mfma_f32_16x16x32_bf16 v[20:23], v[182:185], v[230:233], v[20:23]
	v_mfma_f32_16x16x32_bf16 v[12:15], v[174:177], v[238:241], v[12:15]
	v_mfma_f32_16x16x32_bf16 v[4:7], v[182:185], v[238:241], v[4:7]
	s_setprio 0
	s_setprio 1
	v_mfma_f32_16x16x32_bf16 v[56:59], v[186:189], v[210:213], v[56:59]
	v_mfma_f32_16x16x32_bf16 v[48:51], v[194:197], v[210:213], v[48:51]
	v_mfma_f32_16x16x32_bf16 v[40:43], v[186:189], v[218:221], v[40:43]
	v_mfma_f32_16x16x32_bf16 v[32:35], v[194:197], v[218:221], v[32:35]
	v_mfma_f32_16x16x32_bf16 v[24:27], v[186:189], v[226:229], v[24:27]
	v_mfma_f32_16x16x32_bf16 v[16:19], v[194:197], v[226:229], v[16:19]
	v_mfma_f32_16x16x32_bf16 v[8:11], v[186:189], v[234:237], v[8:11]
	v_mfma_f32_16x16x32_bf16 v[0:3], v[194:197], v[234:237], v[0:3]
	v_mfma_f32_16x16x32_bf16 v[56:59], v[190:193], v[214:217], v[56:59]
	v_mfma_f32_16x16x32_bf16 v[48:51], v[198:201], v[214:217], v[48:51]
	v_mfma_f32_16x16x32_bf16 v[40:43], v[190:193], v[222:225], v[40:43]
	v_mfma_f32_16x16x32_bf16 v[32:35], v[198:201], v[222:225], v[32:35]
	v_mfma_f32_16x16x32_bf16 v[24:27], v[190:193], v[230:233], v[24:27]
	v_mfma_f32_16x16x32_bf16 v[16:19], v[198:201], v[230:233], v[16:19]
	v_mfma_f32_16x16x32_bf16 v[8:11], v[190:193], v[238:241], v[8:11]
	v_mfma_f32_16x16x32_bf16 v[0:3], v[198:201], v[238:241], v[0:3]
	s_setprio 0
	s_barrier
	s_add_i32 s55, 0, 0x18000
	s_add_i32 s56, 0, 0x1c000
	v_add_u32_e32 v182, s55, v129
	v_add_u32_e32 v198, s56, v129
	ds_read_b128 v[170:173], v182
	ds_read_b128 v[174:177], v182 offset:1024
	ds_read_b128 v[178:181], v182 offset:2048
	ds_read_b128 v[182:185], v182 offset:3072
	ds_read_b128 v[186:189], v198
	ds_read_b128 v[190:193], v198 offset:1024
	ds_read_b128 v[194:197], v198 offset:2048
	ds_read_b128 v[198:201], v198 offset:3072
	s_add_u32 s28, s28, 0x40000
	s_addc_u32 s29, s29, 0
	s_mov_b32 m0, s41
	v_lshl_add_u64 v[244:245], s[28:29], 0, v[136:137]
	ds_read_b128 v[210:213], v169 offset:32768
	ds_read_b128 v[214:217], v169 offset:33792
	ds_read_b128 v[218:221], v169 offset:34816
	ds_read_b128 v[222:225], v169 offset:35840
	ds_read_b128 v[226:229], v169 offset:36864
	ds_read_b128 v[230:233], v169 offset:37888
	ds_read_b128 v[234:237], v169 offset:38912
	ds_read_b128 v[238:241], v169 offset:39936
	global_load_lds_dwordx4 v[244:245], off
	v_lshl_add_u64 v[244:245], s[28:29], 0, v[132:133]
	s_mov_b32 m0, s42
	s_nop 0
	global_load_lds_dwordx4 v[244:245], off
	s_waitcnt vmcnt(8)
	s_waitcnt lgkmcnt(0)
	s_barrier
	s_setprio 1
	s_waitcnt lgkmcnt(0)
	v_mfma_f32_16x16x32_bf16 v[124:127], v[170:173], v[210:213], v[124:127]
	v_mfma_f32_16x16x32_bf16 v[116:119], v[178:181], v[210:213], v[116:119]
	v_mfma_f32_16x16x32_bf16 v[108:111], v[170:173], v[218:221], v[108:111]
	v_mfma_f32_16x16x32_bf16 v[100:103], v[178:181], v[218:221], v[100:103]
	v_mfma_f32_16x16x32_bf16 v[92:95], v[170:173], v[226:229], v[92:95]
	v_mfma_f32_16x16x32_bf16 v[84:87], v[178:181], v[226:229], v[84:87]
	v_mfma_f32_16x16x32_bf16 v[76:79], v[170:173], v[234:237], v[76:79]
	v_mfma_f32_16x16x32_bf16 v[68:71], v[178:181], v[234:237], v[68:71]
	v_mfma_f32_16x16x32_bf16 v[124:127], v[174:177], v[214:217], v[124:127]
	v_mfma_f32_16x16x32_bf16 v[116:119], v[182:185], v[214:217], v[116:119]
	v_mfma_f32_16x16x32_bf16 v[108:111], v[174:177], v[222:225], v[108:111]
	v_mfma_f32_16x16x32_bf16 v[100:103], v[182:185], v[222:225], v[100:103]
	v_mfma_f32_16x16x32_bf16 v[92:95], v[174:177], v[230:233], v[92:95]
	v_mfma_f32_16x16x32_bf16 v[84:87], v[182:185], v[230:233], v[84:87]
	v_mfma_f32_16x16x32_bf16 v[76:79], v[174:177], v[238:241], v[76:79]
	v_mfma_f32_16x16x32_bf16 v[68:71], v[182:185], v[238:241], v[68:71]
	s_setprio 0
	s_setprio 1
	v_mfma_f32_16x16x32_bf16 v[120:123], v[186:189], v[210:213], v[120:123]
	v_mfma_f32_16x16x32_bf16 v[112:115], v[194:197], v[210:213], v[112:115]
	v_mfma_f32_16x16x32_bf16 v[104:107], v[186:189], v[218:221], v[104:107]
	v_mfma_f32_16x16x32_bf16 v[96:99], v[194:197], v[218:221], v[96:99]
	v_mfma_f32_16x16x32_bf16 v[88:91], v[186:189], v[226:229], v[88:91]
	v_mfma_f32_16x16x32_bf16 v[80:83], v[194:197], v[226:229], v[80:83]
	v_mfma_f32_16x16x32_bf16 v[72:75], v[186:189], v[234:237], v[72:75]
	v_mfma_f32_16x16x32_bf16 v[64:67], v[194:197], v[234:237], v[64:67]
	v_mfma_f32_16x16x32_bf16 v[120:123], v[190:193], v[214:217], v[120:123]
	v_mfma_f32_16x16x32_bf16 v[112:115], v[198:201], v[214:217], v[112:115]
	v_mfma_f32_16x16x32_bf16 v[104:107], v[190:193], v[222:225], v[104:107]
	v_mfma_f32_16x16x32_bf16 v[96:99], v[198:201], v[222:225], v[96:99]
	v_mfma_f32_16x16x32_bf16 v[88:91], v[190:193], v[230:233], v[88:91]
	v_mfma_f32_16x16x32_bf16 v[80:83], v[198:201], v[230:233], v[80:83]
	v_mfma_f32_16x16x32_bf16 v[72:75], v[190:193], v[238:241], v[72:75]
	v_mfma_f32_16x16x32_bf16 v[64:67], v[198:201], v[238:241], v[64:67]
	s_setprio 0
	s_barrier
	s_add_u32 s28, s26, 0x8000
	s_addc_u32 s29, s27, 0
	s_add_i32 s55, s55, s38
	v_lshl_add_u64 v[244:245], s[28:29], 0, v[134:135]
	s_mov_b32 m0, s55
	ds_read_b128 v[210:213], v169 offset:49152
	ds_read_b128 v[214:217], v169 offset:50176
	ds_read_b128 v[218:221], v169 offset:51200
	ds_read_b128 v[222:225], v169 offset:52224
	ds_read_b128 v[226:229], v169 offset:53248
	ds_read_b128 v[230:233], v169 offset:54272
	ds_read_b128 v[234:237], v169 offset:55296
	ds_read_b128 v[238:241], v169 offset:56320
	global_load_lds_dwordx4 v[244:245], off
	s_add_i32 m0, s55, 0x2000
	s_add_u32 s26, s26, 0xc000
	v_lshl_add_u64 v[244:245], s[28:29], 0, v[130:131]
	s_addc_u32 s27, s27, 0
	s_add_i32 s28, s56, s38
	global_load_lds_dwordx4 v[244:245], off
	v_lshl_add_u64 v[244:245], s[26:27], 0, v[134:135]
	s_mov_b32 m0, s28
	v_lshl_add_u64 v[164:165], v[164:165], 0, s[8:9]
	global_load_lds_dwordx4 v[244:245], off
	v_lshl_add_u64 v[244:245], s[26:27], 0, v[130:131]
	s_add_i32 m0, s28, 0x2000
	s_nop 0
	global_load_lds_dwordx4 v[244:245], off
	s_mov_b32 m0, s45
	s_nop 0
	global_load_lds_dwordx4 v[164:165], off
	v_lshl_add_u64 v[164:165], v[242:243], 0, s[8:9]
	s_mov_b32 m0, s46
	s_nop 0
	global_load_lds_dwordx4 v[164:165], off
	s_waitcnt vmcnt(8)
	s_waitcnt lgkmcnt(0)
	s_barrier
	s_setprio 1
	s_waitcnt lgkmcnt(0)
	v_mfma_f32_16x16x32_bf16 v[60:63], v[170:173], v[210:213], v[60:63]
	v_mfma_f32_16x16x32_bf16 v[52:55], v[178:181], v[210:213], v[52:55]
	v_mfma_f32_16x16x32_bf16 v[44:47], v[170:173], v[218:221], v[44:47]
	v_mfma_f32_16x16x32_bf16 v[36:39], v[178:181], v[218:221], v[36:39]
	v_mfma_f32_16x16x32_bf16 v[28:31], v[170:173], v[226:229], v[28:31]
	v_mfma_f32_16x16x32_bf16 v[20:23], v[178:181], v[226:229], v[20:23]
	v_mfma_f32_16x16x32_bf16 v[12:15], v[170:173], v[234:237], v[12:15]
	v_mfma_f32_16x16x32_bf16 v[4:7], v[178:181], v[234:237], v[4:7]
	v_mfma_f32_16x16x32_bf16 v[60:63], v[174:177], v[214:217], v[60:63]
	v_mfma_f32_16x16x32_bf16 v[52:55], v[182:185], v[214:217], v[52:55]
	v_mfma_f32_16x16x32_bf16 v[44:47], v[174:177], v[222:225], v[44:47]
	v_mfma_f32_16x16x32_bf16 v[36:39], v[182:185], v[222:225], v[36:39]
	v_mfma_f32_16x16x32_bf16 v[28:31], v[174:177], v[230:233], v[28:31]
	v_mfma_f32_16x16x32_bf16 v[20:23], v[182:185], v[230:233], v[20:23]
	v_mfma_f32_16x16x32_bf16 v[12:15], v[174:177], v[238:241], v[12:15]
	v_mfma_f32_16x16x32_bf16 v[4:7], v[182:185], v[238:241], v[4:7]
	s_setprio 0
	s_setprio 1
	v_mfma_f32_16x16x32_bf16 v[56:59], v[186:189], v[210:213], v[56:59]
	v_mfma_f32_16x16x32_bf16 v[48:51], v[194:197], v[210:213], v[48:51]
	v_mfma_f32_16x16x32_bf16 v[40:43], v[186:189], v[218:221], v[40:43]
	v_mfma_f32_16x16x32_bf16 v[32:35], v[194:197], v[218:221], v[32:35]
	v_mfma_f32_16x16x32_bf16 v[24:27], v[186:189], v[226:229], v[24:27]
	v_mfma_f32_16x16x32_bf16 v[16:19], v[194:197], v[226:229], v[16:19]
	v_mfma_f32_16x16x32_bf16 v[8:11], v[186:189], v[234:237], v[8:11]
	v_mfma_f32_16x16x32_bf16 v[0:3], v[194:197], v[234:237], v[0:3]
	v_mfma_f32_16x16x32_bf16 v[56:59], v[190:193], v[214:217], v[56:59]
	v_mfma_f32_16x16x32_bf16 v[48:51], v[198:201], v[214:217], v[48:51]
	v_mfma_f32_16x16x32_bf16 v[40:43], v[190:193], v[222:225], v[40:43]
	v_mfma_f32_16x16x32_bf16 v[32:35], v[198:201], v[222:225], v[32:35]
	v_mfma_f32_16x16x32_bf16 v[24:27], v[190:193], v[230:233], v[24:27]
	v_mfma_f32_16x16x32_bf16 v[16:19], v[198:201], v[230:233], v[16:19]
	v_mfma_f32_16x16x32_bf16 v[8:11], v[190:193], v[238:241], v[8:11]
	v_mfma_f32_16x16x32_bf16 v[0:3], v[198:201], v[238:241], v[0:3]
	s_setprio 0
	s_barrier
	s_add_i32 s54, s54, 2
	s_add_u32 s52, s52, 0x10000
	s_addc_u32 s53, s53, 0
	s_add_u32 s24, s24, 0x100
	s_addc_u32 s25, s25, 0
	s_cmp_gt_u32 s54, 13
	s_cbranch_scc0 .LBB0_289
	s_and_b64 vcc, exec, s[10:11]
	s_cbranch_vccz .LBB0_292
	s_barrier

.LBB0_407:
	s_add_u32 s47, s38, 0x10000
	s_addc_u32 s48, s39, 0
	s_add_u32 s38, s40, 0xc000
	s_addc_u32 s39, s41, 0
	s_mov_b32 s49, -2
.LBB0_408:
	v_add_u32_e32 v168, s71, v182
	v_add_u32_e32 v204, s72, v182
	ds_read_b128 v[156:159], v168
	ds_read_b128 v[160:163], v168 offset:1024
	ds_read_b128 v[164:167], v168 offset:2048
	ds_read_b128 v[168:171], v168 offset:3072
	ds_read_b128 v[172:175], v204
	ds_read_b128 v[176:179], v204 offset:1024
	ds_read_b128 v[212:215], v204 offset:2048
	ds_read_b128 v[216:219], v204 offset:3072
	s_add_u32 s40, s38, 0x4000
	s_addc_u32 s41, s39, 0
	s_cmp_eq_u32 s49, 40
	s_cselect_b32 s44, s0, s40
	s_cselect_b32 s45, s1, s41
	s_cselect_b32 s42, s36, s47
	s_cselect_b32 s43, s37, s48
	s_add_u32 s40, s44, 0x8000
	s_addc_u32 s41, s45, 0
	v_lshl_add_u64 v[252:253], s[38:39], 0, v[150:151]
	s_add_i32 m0, s58, 0xc000
	ds_read_b128 v[220:223], v199
	ds_read_b128 v[224:227], v199 offset:1024
	ds_read_b128 v[228:231], v199 offset:2048
	ds_read_b128 v[232:235], v199 offset:3072
	ds_read_b128 v[236:239], v199 offset:4096
	ds_read_b128 v[240:243], v199 offset:5120
	ds_read_b128 v[244:247], v199 offset:6144
	ds_read_b128 v[248:251], v199 offset:7168
	global_load_lds_dwordx4 v[252:253], off
	v_lshl_add_u64 v[252:253], s[38:39], 0, v[148:149]
	s_add_i32 m0, s58, 0xe000
	s_nop 0
	global_load_lds_dwordx4 v[252:253], off
	s_cmp_lg_u32 s49, -2
	s_cbranch_scc1 .Lzm_14
	v_mov_b32_e32 v0, 0
	v_mov_b32_e32 v1, v0
	v_mov_b32_e32 v2, v0
	v_mov_b32_e32 v3, v0
	v_mov_b32_e32 v4, v0
	v_mov_b32_e32 v5, v0
	v_mov_b32_e32 v6, v0
	v_mov_b32_e32 v7, v0
	v_mov_b32_e32 v8, v0
	v_mov_b32_e32 v9, v0
	v_mov_b32_e32 v10, v0
	v_mov_b32_e32 v11, v0
	v_mov_b32_e32 v12, v0
	v_mov_b32_e32 v13, v0
	v_mov_b32_e32 v14, v0
	v_mov_b32_e32 v15, v0
	v_mov_b32_e32 v16, v0
	v_mov_b32_e32 v17, v0
	v_mov_b32_e32 v18, v0
	v_mov_b32_e32 v19, v0
	v_mov_b32_e32 v20, v0
	v_mov_b32_e32 v21, v0
	v_mov_b32_e32 v22, v0
	v_mov_b32_e32 v23, v0
	v_mov_b32_e32 v24, v0
	v_mov_b32_e32 v25, v0
	v_mov_b32_e32 v26, v0
	v_mov_b32_e32 v27, v0
	v_mov_b32_e32 v28, v0
	v_mov_b32_e32 v29, v0
	v_mov_b32_e32 v30, v0
	v_mov_b32_e32 v31, v0
	v_mov_b32_e32 v32, v0
	v_mov_b32_e32 v33, v0
	v_mov_b32_e32 v34, v0
	v_mov_b32_e32 v35, v0
	v_mov_b32_e32 v36, v0
	v_mov_b32_e32 v37, v0
	v_mov_b32_e32 v38, v0
	v_mov_b32_e32 v39, v0
	v_mov_b32_e32 v40, v0
	v_mov_b32_e32 v41, v0
	v_mov_b32_e32 v42, v0
	v_mov_b32_e32 v43, v0
	v_mov_b32_e32 v44, v0
	v_mov_b32_e32 v45, v0
	v_mov_b32_e32 v46, v0
	v_mov_b32_e32 v47, v0
	v_mov_b32_e32 v48, v0
	v_mov_b32_e32 v49, v0
	v_mov_b32_e32 v50, v0
	v_mov_b32_e32 v51, v0
	v_mov_b32_e32 v52, v0
	v_mov_b32_e32 v53, v0
	v_mov_b32_e32 v54, v0
	v_mov_b32_e32 v55, v0
	v_mov_b32_e32 v56, v0
	v_mov_b32_e32 v57, v0
	v_mov_b32_e32 v58, v0
	v_mov_b32_e32 v59, v0
	v_mov_b32_e32 v60, v0
	v_mov_b32_e32 v61, v0
	v_mov_b32_e32 v62, v0
	v_mov_b32_e32 v63, v0
	v_mov_b32_e32 v64, v0
	v_mov_b32_e32 v65, v0
	v_mov_b32_e32 v66, v0
	v_mov_b32_e32 v67, v0
	v_mov_b32_e32 v68, v0
	v_mov_b32_e32 v69, v0
	v_mov_b32_e32 v70, v0
	v_mov_b32_e32 v71, v0
	v_mov_b32_e32 v72, v0
	v_mov_b32_e32 v73, v0
	v_mov_b32_e32 v74, v0
	v_mov_b32_e32 v75, v0
	v_mov_b32_e32 v76, v0
	v_mov_b32_e32 v77, v0
	v_mov_b32_e32 v78, v0
	v_mov_b32_e32 v79, v0
	v_mov_b32_e32 v80, v0
	v_mov_b32_e32 v81, v0
	v_mov_b32_e32 v82, v0
	v_mov_b32_e32 v83, v0
	v_mov_b32_e32 v84, v0
	v_mov_b32_e32 v85, v0
	v_mov_b32_e32 v86, v0
	v_mov_b32_e32 v87, v0
	v_mov_b32_e32 v88, v0
	v_mov_b32_e32 v89, v0
	v_mov_b32_e32 v90, v0
	v_mov_b32_e32 v91, v0
	v_mov_b32_e32 v92, v0
	v_mov_b32_e32 v93, v0
	v_mov_b32_e32 v94, v0
	v_mov_b32_e32 v95, v0
	v_mov_b32_e32 v96, v0
	v_mov_b32_e32 v97, v0
	v_mov_b32_e32 v98, v0
	v_mov_b32_e32 v99, v0
	v_mov_b32_e32 v100, v0
	v_mov_b32_e32 v101, v0
	v_mov_b32_e32 v102, v0
	v_mov_b32_e32 v103, v0
	v_mov_b32_e32 v104, v0
	v_mov_b32_e32 v105, v0
	v_mov_b32_e32 v106, v0
	v_mov_b32_e32 v107, v0
	v_mov_b32_e32 v108, v0
	v_mov_b32_e32 v109, v0
	v_mov_b32_e32 v110, v0
	v_mov_b32_e32 v111, v0
	v_mov_b32_e32 v112, v0
	v_mov_b32_e32 v113, v0
	v_mov_b32_e32 v114, v0
	v_mov_b32_e32 v115, v0
	v_mov_b32_e32 v116, v0
	v_mov_b32_e32 v117, v0
	v_mov_b32_e32 v118, v0
	v_mov_b32_e32 v119, v0
	v_mov_b32_e32 v120, v0
	v_mov_b32_e32 v121, v0
	v_mov_b32_e32 v122, v0
	v_mov_b32_e32 v123, v0
	v_mov_b32_e32 v124, v0
	v_mov_b32_e32 v125, v0
	v_mov_b32_e32 v126, v0
	v_mov_b32_e32 v127, v0
.Lzm_14:
	s_waitcnt vmcnt(8)
	s_waitcnt lgkmcnt(0)
	s_barrier
	s_setprio 1
	s_waitcnt lgkmcnt(0)
	v_mfma_f32_16x16x32_bf16 v[124:127], v[156:159], v[220:223], v[124:127]
	v_mfma_f32_16x16x32_bf16 v[120:123], v[164:167], v[220:223], v[120:123]
	v_mfma_f32_16x16x32_bf16 v[116:119], v[156:159], v[228:231], v[116:119]
	v_mfma_f32_16x16x32_bf16 v[108:111], v[164:167], v[228:231], v[108:111]
	v_mfma_f32_16x16x32_bf16 v[92:95], v[156:159], v[236:239], v[92:95]
	v_mfma_f32_16x16x32_bf16 v[88:91], v[164:167], v[236:239], v[88:91]
	v_mfma_f32_16x16x32_bf16 v[84:87], v[156:159], v[244:247], v[84:87]
	v_mfma_f32_16x16x32_bf16 v[76:79], v[164:167], v[244:247], v[76:79]
	v_mfma_f32_16x16x32_bf16 v[124:127], v[160:163], v[224:227], v[124:127]
	v_mfma_f32_16x16x32_bf16 v[120:123], v[168:171], v[224:227], v[120:123]
	v_mfma_f32_16x16x32_bf16 v[116:119], v[160:163], v[232:235], v[116:119]
	v_mfma_f32_16x16x32_bf16 v[108:111], v[168:171], v[232:235], v[108:111]
	v_mfma_f32_16x16x32_bf16 v[92:95], v[160:163], v[240:243], v[92:95]
	v_mfma_f32_16x16x32_bf16 v[88:91], v[168:171], v[240:243], v[88:91]
	v_mfma_f32_16x16x32_bf16 v[84:87], v[160:163], v[248:251], v[84:87]
	v_mfma_f32_16x16x32_bf16 v[76:79], v[168:171], v[248:251], v[76:79]
	s_setprio 0
	s_setprio 1
	v_mfma_f32_16x16x32_bf16 v[112:115], v[172:175], v[220:223], v[112:115]
	v_mfma_f32_16x16x32_bf16 v[104:107], v[212:215], v[220:223], v[104:107]
	v_mfma_f32_16x16x32_bf16 v[100:103], v[172:175], v[228:231], v[100:103]
	v_mfma_f32_16x16x32_bf16 v[96:99], v[212:215], v[228:231], v[96:99]
	v_mfma_f32_16x16x32_bf16 v[80:83], v[172:175], v[236:239], v[80:83]
	v_mfma_f32_16x16x32_bf16 v[72:75], v[212:215], v[236:239], v[72:75]
	v_mfma_f32_16x16x32_bf16 v[68:71], v[172:175], v[244:247], v[68:71]
	v_mfma_f32_16x16x32_bf16 v[64:67], v[212:215], v[244:247], v[64:67]
	v_mfma_f32_16x16x32_bf16 v[112:115], v[176:179], v[224:227], v[112:115]
	v_mfma_f32_16x16x32_bf16 v[104:107], v[216:219], v[224:227], v[104:107]
	v_mfma_f32_16x16x32_bf16 v[100:103], v[176:179], v[232:235], v[100:103]
	v_mfma_f32_16x16x32_bf16 v[96:99], v[216:219], v[232:235], v[96:99]
	v_mfma_f32_16x16x32_bf16 v[80:83], v[176:179], v[240:243], v[80:83]
	v_mfma_f32_16x16x32_bf16 v[72:75], v[216:219], v[240:243], v[72:75]
	v_mfma_f32_16x16x32_bf16 v[68:71], v[176:179], v[248:251], v[68:71]
	v_mfma_f32_16x16x32_bf16 v[64:67], v[216:219], v[248:251], v[64:67]
	s_setprio 0
	s_barrier
	s_add_i32 s50, s71, s57
	v_lshl_add_u64 v[252:253], s[42:43], 0, v[128:129]
	s_mov_b32 m0, s50
	ds_read_b128 v[220:223], v199 offset:16384
	ds_read_b128 v[224:227], v199 offset:17408
	ds_read_b128 v[228:231], v199 offset:18432
	ds_read_b128 v[232:235], v199 offset:19456
	ds_read_b128 v[236:239], v199 offset:20480
	ds_read_b128 v[240:243], v199 offset:21504
	ds_read_b128 v[244:247], v199 offset:22528
	ds_read_b128 v[248:251], v199 offset:23552
	global_load_lds_dwordx4 v[252:253], off
	s_add_i32 m0, s50, 0x2000
	s_add_u32 s50, s42, 0x4000
	v_lshl_add_u64 v[252:253], s[42:43], 0, v[130:131]
	s_addc_u32 s51, s43, 0
	s_add_i32 s52, s72, s57
	global_load_lds_dwordx4 v[252:253], off
	v_lshl_add_u64 v[252:253], s[50:51], 0, v[128:129]
	s_mov_b32 m0, s52
	s_nop 0
	global_load_lds_dwordx4 v[252:253], off
	v_lshl_add_u64 v[252:253], s[50:51], 0, v[130:131]
	s_add_i32 m0, s52, 0x2000
	s_nop 0
	global_load_lds_dwordx4 v[252:253], off
	v_lshl_add_u64 v[252:253], s[44:45], 0, v[128:129]
	s_mov_b32 m0, s58
	s_nop 0
	global_load_lds_dwordx4 v[252:253], off
	v_lshl_add_u64 v[252:253], s[44:45], 0, v[130:131]
	s_mov_b32 m0, s59
	s_nop 0
	global_load_lds_dwordx4 v[252:253], off
	s_waitcnt vmcnt(8)
	s_waitcnt lgkmcnt(0)
	s_barrier
	s_setprio 1
	s_waitcnt lgkmcnt(0)
	v_mfma_f32_16x16x32_bf16 v[60:63], v[156:159], v[220:223], v[60:63]
	v_mfma_f32_16x16x32_bf16 v[56:59], v[164:167], v[220:223], v[56:59]
	v_mfma_f32_16x16x32_bf16 v[52:55], v[156:159], v[228:231], v[52:55]
	v_mfma_f32_16x16x32_bf16 v[44:47], v[164:167], v[228:231], v[44:47]
	v_mfma_f32_16x16x32_bf16 v[32:35], v[156:159], v[236:239], v[32:35]
	v_mfma_f32_16x16x32_bf16 v[24:27], v[164:167], v[236:239], v[24:27]
	v_mfma_f32_16x16x32_bf16 v[20:23], v[156:159], v[244:247], v[20:23]
	v_mfma_f32_16x16x32_bf16 v[12:15], v[164:167], v[244:247], v[12:15]
	v_mfma_f32_16x16x32_bf16 v[60:63], v[160:163], v[224:227], v[60:63]
	v_mfma_f32_16x16x32_bf16 v[56:59], v[168:171], v[224:227], v[56:59]
	v_mfma_f32_16x16x32_bf16 v[52:55], v[160:163], v[232:235], v[52:55]
	v_mfma_f32_16x16x32_bf16 v[44:47], v[168:171], v[232:235], v[44:47]
	v_mfma_f32_16x16x32_bf16 v[32:35], v[160:163], v[240:243], v[32:35]
	v_mfma_f32_16x16x32_bf16 v[24:27], v[168:171], v[240:243], v[24:27]
	v_mfma_f32_16x16x32_bf16 v[20:23], v[160:163], v[248:251], v[20:23]
	v_mfma_f32_16x16x32_bf16 v[12:15], v[168:171], v[248:251], v[12:15]
	s_setprio 0
	s_setprio 1
	v_mfma_f32_16x16x32_bf16 v[48:51], v[172:175], v[220:223], v[48:51]
	v_mfma_f32_16x16x32_bf16 v[40:43], v[212:215], v[220:223], v[40:43]
	v_mfma_f32_16x16x32_bf16 v[36:39], v[172:175], v[228:231], v[36:39]
	v_mfma_f32_16x16x32_bf16 v[28:31], v[212:215], v[228:231], v[28:31]
	v_mfma_f32_16x16x32_bf16 v[16:19], v[172:175], v[236:239], v[16:19]
	v_mfma_f32_16x16x32_bf16 v[8:11], v[212:215], v[236:239], v[8:11]
	v_mfma_f32_16x16x32_bf16 v[4:7], v[172:175], v[244:247], v[4:7]
	v_mfma_f32_16x16x32_bf16 v[0:3], v[212:215], v[244:247], v[0:3]
	v_mfma_f32_16x16x32_bf16 v[48:51], v[176:179], v[224:227], v[48:51]
	v_mfma_f32_16x16x32_bf16 v[40:43], v[216:219], v[224:227], v[40:43]
	v_mfma_f32_16x16x32_bf16 v[36:39], v[176:179], v[232:235], v[36:39]
	v_mfma_f32_16x16x32_bf16 v[28:31], v[216:219], v[232:235], v[28:31]
	v_mfma_f32_16x16x32_bf16 v[16:19], v[176:179], v[240:243], v[16:19]
	v_mfma_f32_16x16x32_bf16 v[8:11], v[216:219], v[240:243], v[8:11]
	v_mfma_f32_16x16x32_bf16 v[4:7], v[176:179], v[248:251], v[4:7]
	v_mfma_f32_16x16x32_bf16 v[0:3], v[216:219], v[248:251], v[0:3]
	s_setprio 0
	s_barrier
	s_add_i32 s50, 0, 0x18000
	s_add_i32 s51, 0, 0x1c000
	v_add_u32_e32 v168, s50, v182
	v_add_u32_e32 v204, s51, v182
	ds_read_b128 v[156:159], v168
	ds_read_b128 v[160:163], v168 offset:1024
	ds_read_b128 v[164:167], v168 offset:2048
	ds_read_b128 v[168:171], v168 offset:3072
	ds_read_b128 v[172:175], v204
	ds_read_b128 v[176:179], v204 offset:1024
	ds_read_b128 v[212:215], v204 offset:2048
	ds_read_b128 v[216:219], v204 offset:3072
	s_add_u32 s44, s44, 0x4000
	s_addc_u32 s45, s45, 0
	s_mov_b32 m0, s60
	v_lshl_add_u64 v[252:253], s[44:45], 0, v[128:129]
	ds_read_b128 v[220:223], v199 offset:32768
	ds_read_b128 v[224:227], v199 offset:33792
	ds_read_b128 v[228:231], v199 offset:34816
	ds_read_b128 v[232:235], v199 offset:35840
	ds_read_b128 v[236:239], v199 offset:36864
	ds_read_b128 v[240:243], v199 offset:37888
	ds_read_b128 v[244:247], v199 offset:38912
	ds_read_b128 v[248:251], v199 offset:39936
	global_load_lds_dwordx4 v[252:253], off
	v_lshl_add_u64 v[252:253], s[44:45], 0, v[130:131]
	s_mov_b32 m0, s61
	s_nop 0
	global_load_lds_dwordx4 v[252:253], off
	s_waitcnt vmcnt(8)
	s_waitcnt lgkmcnt(0)
	s_barrier
	s_setprio 1
	s_waitcnt lgkmcnt(0)
	v_mfma_f32_16x16x32_bf16 v[124:127], v[156:159], v[220:223], v[124:127]
	v_mfma_f32_16x16x32_bf16 v[120:123], v[164:167], v[220:223], v[120:123]
	v_mfma_f32_16x16x32_bf16 v[116:119], v[156:159], v[228:231], v[116:119]
	v_mfma_f32_16x16x32_bf16 v[108:111], v[164:167], v[228:231], v[108:111]
	v_mfma_f32_16x16x32_bf16 v[92:95], v[156:159], v[236:239], v[92:95]
	v_mfma_f32_16x16x32_bf16 v[88:91], v[164:167], v[236:239], v[88:91]
	v_mfma_f32_16x16x32_bf16 v[84:87], v[156:159], v[244:247], v[84:87]
	v_mfma_f32_16x16x32_bf16 v[76:79], v[164:167], v[244:247], v[76:79]
	v_mfma_f32_16x16x32_bf16 v[124:127], v[160:163], v[224:227], v[124:127]
	v_mfma_f32_16x16x32_bf16 v[120:123], v[168:171], v[224:227], v[120:123]
	v_mfma_f32_16x16x32_bf16 v[116:119], v[160:163], v[232:235], v[116:119]
	v_mfma_f32_16x16x32_bf16 v[108:111], v[168:171], v[232:235], v[108:111]
	v_mfma_f32_16x16x32_bf16 v[92:95], v[160:163], v[240:243], v[92:95]
	v_mfma_f32_16x16x32_bf16 v[88:91], v[168:171], v[240:243], v[88:91]
	v_mfma_f32_16x16x32_bf16 v[84:87], v[160:163], v[248:251], v[84:87]
	v_mfma_f32_16x16x32_bf16 v[76:79], v[168:171], v[248:251], v[76:79]
	s_setprio 0
	s_setprio 1
	v_mfma_f32_16x16x32_bf16 v[112:115], v[172:175], v[220:223], v[112:115]
	v_mfma_f32_16x16x32_bf16 v[104:107], v[212:215], v[220:223], v[104:107]
	v_mfma_f32_16x16x32_bf16 v[100:103], v[172:175], v[228:231], v[100:103]
	v_mfma_f32_16x16x32_bf16 v[96:99], v[212:215], v[228:231], v[96:99]
	v_mfma_f32_16x16x32_bf16 v[80:83], v[172:175], v[236:239], v[80:83]
	v_mfma_f32_16x16x32_bf16 v[72:75], v[212:215], v[236:239], v[72:75]
	v_mfma_f32_16x16x32_bf16 v[68:71], v[172:175], v[244:247], v[68:71]
	v_mfma_f32_16x16x32_bf16 v[64:67], v[212:215], v[244:247], v[64:67]
	v_mfma_f32_16x16x32_bf16 v[112:115], v[176:179], v[224:227], v[112:115]
	v_mfma_f32_16x16x32_bf16 v[104:107], v[216:219], v[224:227], v[104:107]
	v_mfma_f32_16x16x32_bf16 v[100:103], v[176:179], v[232:235], v[100:103]
	v_mfma_f32_16x16x32_bf16 v[96:99], v[216:219], v[232:235], v[96:99]
	v_mfma_f32_16x16x32_bf16 v[80:83], v[176:179], v[240:243], v[80:83]
	v_mfma_f32_16x16x32_bf16 v[72:75], v[216:219], v[240:243], v[72:75]
	v_mfma_f32_16x16x32_bf16 v[68:71], v[176:179], v[248:251], v[68:71]
	v_mfma_f32_16x16x32_bf16 v[64:67], v[216:219], v[248:251], v[64:67]
	s_setprio 0
	s_barrier
	s_add_u32 s44, s42, 0x8000
	s_addc_u32 s45, s43, 0
	s_add_i32 s50, s50, s57
	v_lshl_add_u64 v[252:253], s[44:45], 0, v[128:129]
	s_mov_b32 m0, s50
	ds_read_b128 v[220:223], v199 offset:49152
	ds_read_b128 v[224:227], v199 offset:50176
	ds_read_b128 v[228:231], v199 offset:51200
	ds_read_b128 v[232:235], v199 offset:52224
	ds_read_b128 v[236:239], v199 offset:53248
	ds_read_b128 v[240:243], v199 offset:54272
	ds_read_b128 v[244:247], v199 offset:55296
	ds_read_b128 v[248:251], v199 offset:56320
	global_load_lds_dwordx4 v[252:253], off
	s_add_i32 m0, s50, 0x2000
	s_add_u32 s42, s42, 0xc000
	v_lshl_add_u64 v[252:253], s[44:45], 0, v[130:131]
	s_addc_u32 s43, s43, 0
	s_add_i32 s44, s51, s57
	global_load_lds_dwordx4 v[252:253], off
	v_lshl_add_u64 v[252:253], s[42:43], 0, v[128:129]
	s_mov_b32 m0, s44
	s_nop 0
	global_load_lds_dwordx4 v[252:253], off
	v_lshl_add_u64 v[252:253], s[42:43], 0, v[130:131]
	s_add_i32 m0, s44, 0x2000
	s_nop 0
	global_load_lds_dwordx4 v[252:253], off
	v_lshl_add_u64 v[252:253], s[40:41], 0, v[128:129]
	s_mov_b32 m0, s67
	s_nop 0
	global_load_lds_dwordx4 v[252:253], off
	v_lshl_add_u64 v[252:253], s[40:41], 0, v[130:131]
	s_mov_b32 m0, s68
	s_nop 0
	global_load_lds_dwordx4 v[252:253], off
	s_waitcnt vmcnt(8)
	s_waitcnt lgkmcnt(0)
	s_barrier
	s_setprio 1
	s_waitcnt lgkmcnt(0)
	v_mfma_f32_16x16x32_bf16 v[60:63], v[156:159], v[220:223], v[60:63]
	v_mfma_f32_16x16x32_bf16 v[56:59], v[164:167], v[220:223], v[56:59]
	v_mfma_f32_16x16x32_bf16 v[52:55], v[156:159], v[228:231], v[52:55]
	v_mfma_f32_16x16x32_bf16 v[44:47], v[164:167], v[228:231], v[44:47]
	v_mfma_f32_16x16x32_bf16 v[32:35], v[156:159], v[236:239], v[32:35]
	v_mfma_f32_16x16x32_bf16 v[24:27], v[164:167], v[236:239], v[24:27]
	v_mfma_f32_16x16x32_bf16 v[20:23], v[156:159], v[244:247], v[20:23]
	v_mfma_f32_16x16x32_bf16 v[12:15], v[164:167], v[244:247], v[12:15]
	v_mfma_f32_16x16x32_bf16 v[60:63], v[160:163], v[224:227], v[60:63]
	v_mfma_f32_16x16x32_bf16 v[56:59], v[168:171], v[224:227], v[56:59]
	v_mfma_f32_16x16x32_bf16 v[52:55], v[160:163], v[232:235], v[52:55]
	v_mfma_f32_16x16x32_bf16 v[44:47], v[168:171], v[232:235], v[44:47]
	v_mfma_f32_16x16x32_bf16 v[32:35], v[160:163], v[240:243], v[32:35]
	v_mfma_f32_16x16x32_bf16 v[24:27], v[168:171], v[240:243], v[24:27]
	v_mfma_f32_16x16x32_bf16 v[20:23], v[160:163], v[248:251], v[20:23]
	v_mfma_f32_16x16x32_bf16 v[12:15], v[168:171], v[248:251], v[12:15]
	s_setprio 0
	s_setprio 1
	v_mfma_f32_16x16x32_bf16 v[48:51], v[172:175], v[220:223], v[48:51]
	v_mfma_f32_16x16x32_bf16 v[40:43], v[212:215], v[220:223], v[40:43]
	v_mfma_f32_16x16x32_bf16 v[36:39], v[172:175], v[228:231], v[36:39]
	v_mfma_f32_16x16x32_bf16 v[28:31], v[212:215], v[228:231], v[28:31]
	v_mfma_f32_16x16x32_bf16 v[16:19], v[172:175], v[236:239], v[16:19]
	v_mfma_f32_16x16x32_bf16 v[8:11], v[212:215], v[236:239], v[8:11]
	v_mfma_f32_16x16x32_bf16 v[4:7], v[172:175], v[244:247], v[4:7]
	v_mfma_f32_16x16x32_bf16 v[0:3], v[212:215], v[244:247], v[0:3]
	v_mfma_f32_16x16x32_bf16 v[48:51], v[176:179], v[224:227], v[48:51]
	v_mfma_f32_16x16x32_bf16 v[40:43], v[216:219], v[224:227], v[40:43]
	v_mfma_f32_16x16x32_bf16 v[36:39], v[176:179], v[232:235], v[36:39]
	v_mfma_f32_16x16x32_bf16 v[28:31], v[216:219], v[232:235], v[28:31]
	v_mfma_f32_16x16x32_bf16 v[16:19], v[176:179], v[240:243], v[16:19]
	v_mfma_f32_16x16x32_bf16 v[8:11], v[216:219], v[240:243], v[8:11]
	v_mfma_f32_16x16x32_bf16 v[4:7], v[176:179], v[248:251], v[4:7]
	v_mfma_f32_16x16x32_bf16 v[0:3], v[216:219], v[248:251], v[0:3]
	s_setprio 0
	s_barrier
	s_add_i32 s49, s49, 2
	s_add_u32 s47, s47, 0x10000
	s_addc_u32 s48, s48, 0
	s_add_u32 s38, s38, 0x10000
	s_addc_u32 s39, s39, 0
	s_cmp_gt_u32 s49, 41
	s_cbranch_scc0 .LBB0_408
	s_and_b64 vcc, exec, s[14:15]
	s_cbranch_vccz .LBB0_411
	s_barrier

.LBB0_491:
	s_ashr_i32 s23, s22, 31
	s_lshl_b64 s[26:27], s[22:23], 19
	s_add_u32 s26, s42, s26
	s_addc_u32 s27, s43, s27
	s_and_b64 s[28:29], s[4:5], exec
	s_cselect_b32 s1, s27, s35
	s_cselect_b32 s7, s26, s34
	s_ashr_i32 s25, s24, 31
	s_lshl_b64 s[28:29], s[24:25], 19
	s_add_u32 s28, s44, s28
	s_addc_u32 s29, s45, s29
	s_and_b64 s[36:37], s[4:5], exec
	s_cselect_b32 s10, s29, s31
	s_cselect_b32 s23, s28, s30
	s_add_u32 s25, s30, 0x10000
	s_addc_u32 s38, s31, 0
	s_add_u32 s30, s34, 0x40080
	s_addc_u32 s31, s35, 0
	s_mov_b32 s39, -2
.LBB0_492:
	ds_read_b128 v[128:131], v212
	ds_read_b128 v[132:135], v212 offset:1024
	ds_read_b128 v[136:139], v212 offset:2048
	ds_read_b128 v[140:143], v212 offset:3072
	ds_read_b128 v[144:147], v213
	ds_read_b128 v[148:151], v213 offset:1024
	ds_read_b128 v[152:155], v213 offset:2048
	ds_read_b128 v[156:159], v213 offset:3072
	s_add_u32 s34, s30, 0xfffc0080
	s_addc_u32 s35, s31, -1
	s_cmp_eq_u32 s39, 12
	s_cselect_b32 s37, s1, s35
	s_cselect_b32 s36, s7, s34
	s_cselect_b32 s35, s10, s38
	s_cselect_b32 s34, s23, s25
	v_lshl_add_u64 v[200:201], s[30:31], 0, v[190:191]
	s_add_i32 m0, s47, 0xc000
	ds_read_b128 v[160:163], v214
	ds_read_b128 v[164:167], v214 offset:1024
	ds_read_b128 v[196:199], v214 offset:2048
	ds_read_b128 v[216:219], v214 offset:3072
	ds_read_b128 v[220:223], v214 offset:4096
	ds_read_b128 v[224:227], v214 offset:5120
	ds_read_b128 v[228:231], v214 offset:6144
	ds_read_b128 v[232:235], v214 offset:7168
	global_load_lds_dwordx4 v[200:201], off
	v_lshl_add_u64 v[200:201], s[30:31], 0, v[188:189]
	s_add_i32 m0, s47, 0xe000
	s_nop 0
	global_load_lds_dwordx4 v[200:201], off
	s_cmp_lg_u32 s39, -2
	s_cbranch_scc1 .Lzm_13
	v_mov_b32_e32 v0, 0
	v_mov_b32_e32 v1, v0
	v_mov_b32_e32 v2, v0
	v_mov_b32_e32 v3, v0
	v_mov_b32_e32 v4, v0
	v_mov_b32_e32 v5, v0
	v_mov_b32_e32 v6, v0
	v_mov_b32_e32 v7, v0
	v_mov_b32_e32 v8, v0
	v_mov_b32_e32 v9, v0
	v_mov_b32_e32 v10, v0
	v_mov_b32_e32 v11, v0
	v_mov_b32_e32 v12, v0
	v_mov_b32_e32 v13, v0
	v_mov_b32_e32 v14, v0
	v_mov_b32_e32 v15, v0
	v_mov_b32_e32 v16, v0
	v_mov_b32_e32 v17, v0
	v_mov_b32_e32 v18, v0
	v_mov_b32_e32 v19, v0
	v_mov_b32_e32 v20, v0
	v_mov_b32_e32 v21, v0
	v_mov_b32_e32 v22, v0
	v_mov_b32_e32 v23, v0
	v_mov_b32_e32 v24, v0
	v_mov_b32_e32 v25, v0
	v_mov_b32_e32 v26, v0
	v_mov_b32_e32 v27, v0
	v_mov_b32_e32 v28, v0
	v_mov_b32_e32 v29, v0
	v_mov_b32_e32 v30, v0
	v_mov_b32_e32 v31, v0
	v_mov_b32_e32 v32, v0
	v_mov_b32_e32 v33, v0
	v_mov_b32_e32 v34, v0
	v_mov_b32_e32 v35, v0
	v_mov_b32_e32 v36, v0
	v_mov_b32_e32 v37, v0
	v_mov_b32_e32 v38, v0
	v_mov_b32_e32 v39, v0
	v_mov_b32_e32 v40, v0
	v_mov_b32_e32 v41, v0
	v_mov_b32_e32 v42, v0
	v_mov_b32_e32 v43, v0
	v_mov_b32_e32 v44, v0
	v_mov_b32_e32 v45, v0
	v_mov_b32_e32 v46, v0
	v_mov_b32_e32 v47, v0
	v_mov_b32_e32 v48, v0
	v_mov_b32_e32 v49, v0
	v_mov_b32_e32 v50, v0
	v_mov_b32_e32 v51, v0
	v_mov_b32_e32 v52, v0
	v_mov_b32_e32 v53, v0
	v_mov_b32_e32 v54, v0
	v_mov_b32_e32 v55, v0
	v_mov_b32_e32 v56, v0
	v_mov_b32_e32 v57, v0
	v_mov_b32_e32 v58, v0
	v_mov_b32_e32 v59, v0
	v_mov_b32_e32 v60, v0
	v_mov_b32_e32 v61, v0
	v_mov_b32_e32 v62, v0
	v_mov_b32_e32 v63, v0
	v_mov_b32_e32 v64, v0
	v_mov_b32_e32 v65, v0
	v_mov_b32_e32 v66, v0
	v_mov_b32_e32 v67, v0
	v_mov_b32_e32 v68, v0
	v_mov_b32_e32 v69, v0
	v_mov_b32_e32 v70, v0
	v_mov_b32_e32 v71, v0
	v_mov_b32_e32 v72, v0
	v_mov_b32_e32 v73, v0
	v_mov_b32_e32 v74, v0
	v_mov_b32_e32 v75, v0
	v_mov_b32_e32 v76, v0
	v_mov_b32_e32 v77, v0
	v_mov_b32_e32 v78, v0
	v_mov_b32_e32 v79, v0
	v_mov_b32_e32 v80, v0
	v_mov_b32_e32 v81, v0
	v_mov_b32_e32 v82, v0
	v_mov_b32_e32 v83, v0
	v_mov_b32_e32 v84, v0
	v_mov_b32_e32 v85, v0
	v_mov_b32_e32 v86, v0
	v_mov_b32_e32 v87, v0
	v_mov_b32_e32 v88, v0
	v_mov_b32_e32 v89, v0
	v_mov_b32_e32 v90, v0
	v_mov_b32_e32 v91, v0
	v_mov_b32_e32 v92, v0
	v_mov_b32_e32 v93, v0
	v_mov_b32_e32 v94, v0
	v_mov_b32_e32 v95, v0
	v_mov_b32_e32 v96, v0
	v_mov_b32_e32 v97, v0
	v_mov_b32_e32 v98, v0
	v_mov_b32_e32 v99, v0
	v_mov_b32_e32 v100, v0
	v_mov_b32_e32 v101, v0
	v_mov_b32_e32 v102, v0
	v_mov_b32_e32 v103, v0
	v_mov_b32_e32 v104, v0
	v_mov_b32_e32 v105, v0
	v_mov_b32_e32 v106, v0
	v_mov_b32_e32 v107, v0
	v_mov_b32_e32 v108, v0
	v_mov_b32_e32 v109, v0
	v_mov_b32_e32 v110, v0
	v_mov_b32_e32 v111, v0
	v_mov_b32_e32 v112, v0
	v_mov_b32_e32 v113, v0
	v_mov_b32_e32 v114, v0
	v_mov_b32_e32 v115, v0
	v_mov_b32_e32 v116, v0
	v_mov_b32_e32 v117, v0
	v_mov_b32_e32 v118, v0
	v_mov_b32_e32 v119, v0
	v_mov_b32_e32 v120, v0
	v_mov_b32_e32 v121, v0
	v_mov_b32_e32 v122, v0
	v_mov_b32_e32 v123, v0
	v_mov_b32_e32 v124, v0
	v_mov_b32_e32 v125, v0
	v_mov_b32_e32 v126, v0
	v_mov_b32_e32 v127, v0
.Lzm_13:
	s_waitcnt vmcnt(8)
	s_waitcnt lgkmcnt(0)
	s_barrier
	s_setprio 1
	s_waitcnt lgkmcnt(0)
	v_mfma_f32_16x16x32_bf16 v[124:127], v[128:131], v[160:163], v[124:127]
	v_mfma_f32_16x16x32_bf16 v[120:123], v[136:139], v[160:163], v[120:123]
	v_mfma_f32_16x16x32_bf16 v[116:119], v[128:131], v[196:199], v[116:119]
	v_mfma_f32_16x16x32_bf16 v[112:115], v[136:139], v[196:199], v[112:115]
	v_mfma_f32_16x16x32_bf16 v[108:111], v[128:131], v[220:223], v[108:111]
	v_mfma_f32_16x16x32_bf16 v[104:107], v[136:139], v[220:223], v[104:107]
	v_mfma_f32_16x16x32_bf16 v[100:103], v[128:131], v[228:231], v[100:103]
	v_mfma_f32_16x16x32_bf16 v[96:99], v[136:139], v[228:231], v[96:99]
	v_mfma_f32_16x16x32_bf16 v[124:127], v[132:135], v[164:167], v[124:127]
	v_mfma_f32_16x16x32_bf16 v[120:123], v[140:143], v[164:167], v[120:123]
	v_mfma_f32_16x16x32_bf16 v[116:119], v[132:135], v[216:219], v[116:119]
	v_mfma_f32_16x16x32_bf16 v[112:115], v[140:143], v[216:219], v[112:115]
	v_mfma_f32_16x16x32_bf16 v[108:111], v[132:135], v[224:227], v[108:111]
	v_mfma_f32_16x16x32_bf16 v[104:107], v[140:143], v[224:227], v[104:107]
	v_mfma_f32_16x16x32_bf16 v[100:103], v[132:135], v[232:235], v[100:103]
	v_mfma_f32_16x16x32_bf16 v[96:99], v[140:143], v[232:235], v[96:99]
	s_setprio 0
	s_setprio 1
	v_mfma_f32_16x16x32_bf16 v[60:63], v[144:147], v[160:163], v[60:63]
	v_mfma_f32_16x16x32_bf16 v[56:59], v[152:155], v[160:163], v[56:59]
	v_mfma_f32_16x16x32_bf16 v[52:55], v[144:147], v[196:199], v[52:55]
	v_mfma_f32_16x16x32_bf16 v[48:51], v[152:155], v[196:199], v[48:51]
	v_mfma_f32_16x16x32_bf16 v[44:47], v[144:147], v[220:223], v[44:47]
	v_mfma_f32_16x16x32_bf16 v[40:43], v[152:155], v[220:223], v[40:43]
	v_mfma_f32_16x16x32_bf16 v[36:39], v[144:147], v[228:231], v[36:39]
	v_mfma_f32_16x16x32_bf16 v[32:35], v[152:155], v[228:231], v[32:35]
	v_mfma_f32_16x16x32_bf16 v[60:63], v[148:151], v[164:167], v[60:63]
	v_mfma_f32_16x16x32_bf16 v[56:59], v[156:159], v[164:167], v[56:59]
	v_mfma_f32_16x16x32_bf16 v[52:55], v[148:151], v[216:219], v[52:55]
	v_mfma_f32_16x16x32_bf16 v[48:51], v[156:159], v[216:219], v[48:51]
	v_mfma_f32_16x16x32_bf16 v[44:47], v[148:151], v[224:227], v[44:47]
	v_mfma_f32_16x16x32_bf16 v[40:43], v[156:159], v[224:227], v[40:43]
	v_mfma_f32_16x16x32_bf16 v[36:39], v[148:151], v[232:235], v[36:39]
	v_mfma_f32_16x16x32_bf16 v[32:35], v[156:159], v[232:235], v[32:35]
	s_setprio 0
	s_barrier
	s_add_i32 s66, s61, s46
	v_lshl_add_u64 v[200:201], s[34:35], 0, v[172:173]
	s_mov_b32 m0, s66
	ds_read_b128 v[160:163], v214 offset:16384
	ds_read_b128 v[164:167], v214 offset:17408
	ds_read_b128 v[196:199], v214 offset:18432
	ds_read_b128 v[216:219], v214 offset:19456
	ds_read_b128 v[220:223], v214 offset:20480
	ds_read_b128 v[224:227], v214 offset:21504
	ds_read_b128 v[228:231], v214 offset:22528
	ds_read_b128 v[232:235], v214 offset:23552
	global_load_lds_dwordx4 v[200:201], off
	s_add_i32 m0, s66, 0x2000
	s_add_u32 s66, s34, 0x4000
	v_lshl_add_u64 v[200:201], s[34:35], 0, v[176:177]
	s_addc_u32 s67, s35, 0
	s_add_i32 s68, s62, s46
	global_load_lds_dwordx4 v[200:201], off
	v_lshl_add_u64 v[200:201], s[66:67], 0, v[172:173]
	s_mov_b32 m0, s68
	v_lshl_add_u64 v[236:237], s[36:37], 0, v[174:175]
	global_load_lds_dwordx4 v[200:201], off
	v_lshl_add_u64 v[200:201], s[66:67], 0, v[176:177]
	s_add_i32 m0, s68, 0x2000
	s_nop 0
	global_load_lds_dwordx4 v[200:201], off
	v_lshl_add_u64 v[200:201], s[36:37], 0, v[170:171]
	s_mov_b32 m0, s47
	s_nop 0
	global_load_lds_dwordx4 v[200:201], off
	s_mov_b32 m0, s48
	s_nop 0
	global_load_lds_dwordx4 v[236:237], off
	s_waitcnt vmcnt(8)
	s_waitcnt lgkmcnt(0)
	s_barrier
	s_setprio 1
	s_waitcnt lgkmcnt(0)
	v_mfma_f32_16x16x32_bf16 v[92:95], v[128:131], v[160:163], v[92:95]
	v_mfma_f32_16x16x32_bf16 v[88:91], v[136:139], v[160:163], v[88:91]
	v_mfma_f32_16x16x32_bf16 v[84:87], v[128:131], v[196:199], v[84:87]
	v_mfma_f32_16x16x32_bf16 v[80:83], v[136:139], v[196:199], v[80:83]
	v_mfma_f32_16x16x32_bf16 v[76:79], v[128:131], v[220:223], v[76:79]
	v_mfma_f32_16x16x32_bf16 v[72:75], v[136:139], v[220:223], v[72:75]
	v_mfma_f32_16x16x32_bf16 v[68:71], v[128:131], v[228:231], v[68:71]
	v_mfma_f32_16x16x32_bf16 v[64:67], v[136:139], v[228:231], v[64:67]
	v_mfma_f32_16x16x32_bf16 v[92:95], v[132:135], v[164:167], v[92:95]
	v_mfma_f32_16x16x32_bf16 v[88:91], v[140:143], v[164:167], v[88:91]
	v_mfma_f32_16x16x32_bf16 v[84:87], v[132:135], v[216:219], v[84:87]
	v_mfma_f32_16x16x32_bf16 v[80:83], v[140:143], v[216:219], v[80:83]
	v_mfma_f32_16x16x32_bf16 v[76:79], v[132:135], v[224:227], v[76:79]
	v_mfma_f32_16x16x32_bf16 v[72:75], v[140:143], v[224:227], v[72:75]
	v_mfma_f32_16x16x32_bf16 v[68:71], v[132:135], v[232:235], v[68:71]
	v_mfma_f32_16x16x32_bf16 v[64:67], v[140:143], v[232:235], v[64:67]
	s_setprio 0
	s_setprio 1
	v_mfma_f32_16x16x32_bf16 v[28:31], v[144:147], v[160:163], v[28:31]
	v_mfma_f32_16x16x32_bf16 v[24:27], v[152:155], v[160:163], v[24:27]
	v_mfma_f32_16x16x32_bf16 v[20:23], v[144:147], v[196:199], v[20:23]
	v_mfma_f32_16x16x32_bf16 v[16:19], v[152:155], v[196:199], v[16:19]
	v_mfma_f32_16x16x32_bf16 v[12:15], v[144:147], v[220:223], v[12:15]
	v_mfma_f32_16x16x32_bf16 v[8:11], v[152:155], v[220:223], v[8:11]
	v_mfma_f32_16x16x32_bf16 v[4:7], v[144:147], v[228:231], v[4:7]
	v_mfma_f32_16x16x32_bf16 v[0:3], v[152:155], v[228:231], v[0:3]
	v_mfma_f32_16x16x32_bf16 v[28:31], v[148:151], v[164:167], v[28:31]
	v_mfma_f32_16x16x32_bf16 v[24:27], v[156:159], v[164:167], v[24:27]
	v_mfma_f32_16x16x32_bf16 v[20:23], v[148:151], v[216:219], v[20:23]
	v_mfma_f32_16x16x32_bf16 v[16:19], v[156:159], v[216:219], v[16:19]
	v_mfma_f32_16x16x32_bf16 v[12:15], v[148:151], v[224:227], v[12:15]
	v_mfma_f32_16x16x32_bf16 v[8:11], v[156:159], v[224:227], v[8:11]
	v_mfma_f32_16x16x32_bf16 v[4:7], v[148:151], v[232:235], v[4:7]
	v_mfma_f32_16x16x32_bf16 v[0:3], v[156:159], v[232:235], v[0:3]
	s_setprio 0
	s_barrier
	s_add_i32 s66, 0, 0x18000
	s_add_i32 s67, 0, 0x1c000
	v_add_u32_e32 v140, s66, v210
	v_add_u32_e32 v156, s67, v210
	ds_read_b128 v[128:131], v140
	ds_read_b128 v[132:135], v140 offset:1024
	ds_read_b128 v[136:139], v140 offset:2048
	ds_read_b128 v[140:143], v140 offset:3072
	ds_read_b128 v[144:147], v156
	ds_read_b128 v[148:151], v156 offset:1024
	ds_read_b128 v[152:155], v156 offset:2048
	ds_read_b128 v[156:159], v156 offset:3072
	s_add_u32 s36, s36, 0x40000
	s_addc_u32 s37, s37, 0
	s_mov_b32 m0, s49
	v_lshl_add_u64 v[238:239], s[36:37], 0, v[170:171]
	ds_read_b128 v[160:163], v214 offset:32768
	ds_read_b128 v[164:167], v214 offset:33792
	ds_read_b128 v[196:199], v214 offset:34816
	ds_read_b128 v[216:219], v214 offset:35840
	ds_read_b128 v[220:223], v214 offset:36864
	ds_read_b128 v[224:227], v214 offset:37888
	ds_read_b128 v[228:231], v214 offset:38912
	ds_read_b128 v[232:235], v214 offset:39936
	global_load_lds_dwordx4 v[238:239], off
	v_lshl_add_u64 v[238:239], s[36:37], 0, v[174:175]
	s_mov_b32 m0, s50
	s_nop 0
	global_load_lds_dwordx4 v[238:239], off
	s_waitcnt vmcnt(8)
	s_waitcnt lgkmcnt(0)
	s_barrier
	s_setprio 1
	s_waitcnt lgkmcnt(0)
	v_mfma_f32_16x16x32_bf16 v[124:127], v[128:131], v[160:163], v[124:127]
	v_mfma_f32_16x16x32_bf16 v[120:123], v[136:139], v[160:163], v[120:123]
	v_mfma_f32_16x16x32_bf16 v[116:119], v[128:131], v[196:199], v[116:119]
	v_mfma_f32_16x16x32_bf16 v[112:115], v[136:139], v[196:199], v[112:115]
	v_mfma_f32_16x16x32_bf16 v[108:111], v[128:131], v[220:223], v[108:111]
	v_mfma_f32_16x16x32_bf16 v[104:107], v[136:139], v[220:223], v[104:107]
	v_mfma_f32_16x16x32_bf16 v[100:103], v[128:131], v[228:231], v[100:103]
	v_mfma_f32_16x16x32_bf16 v[96:99], v[136:139], v[228:231], v[96:99]
	v_mfma_f32_16x16x32_bf16 v[124:127], v[132:135], v[164:167], v[124:127]
	v_mfma_f32_16x16x32_bf16 v[120:123], v[140:143], v[164:167], v[120:123]
	v_mfma_f32_16x16x32_bf16 v[116:119], v[132:135], v[216:219], v[116:119]
	v_mfma_f32_16x16x32_bf16 v[112:115], v[140:143], v[216:219], v[112:115]
	v_mfma_f32_16x16x32_bf16 v[108:111], v[132:135], v[224:227], v[108:111]
	v_mfma_f32_16x16x32_bf16 v[104:107], v[140:143], v[224:227], v[104:107]
	v_mfma_f32_16x16x32_bf16 v[100:103], v[132:135], v[232:235], v[100:103]
	v_mfma_f32_16x16x32_bf16 v[96:99], v[140:143], v[232:235], v[96:99]
	s_setprio 0
	s_setprio 1
	v_mfma_f32_16x16x32_bf16 v[60:63], v[144:147], v[160:163], v[60:63]
	v_mfma_f32_16x16x32_bf16 v[56:59], v[152:155], v[160:163], v[56:59]
	v_mfma_f32_16x16x32_bf16 v[52:55], v[144:147], v[196:199], v[52:55]
	v_mfma_f32_16x16x32_bf16 v[48:51], v[152:155], v[196:199], v[48:51]
	v_mfma_f32_16x16x32_bf16 v[44:47], v[144:147], v[220:223], v[44:47]
	v_mfma_f32_16x16x32_bf16 v[40:43], v[152:155], v[220:223], v[40:43]
	v_mfma_f32_16x16x32_bf16 v[36:39], v[144:147], v[228:231], v[36:39]
	v_mfma_f32_16x16x32_bf16 v[32:35], v[152:155], v[228:231], v[32:35]
	v_mfma_f32_16x16x32_bf16 v[60:63], v[148:151], v[164:167], v[60:63]
	v_mfma_f32_16x16x32_bf16 v[56:59], v[156:159], v[164:167], v[56:59]
	v_mfma_f32_16x16x32_bf16 v[52:55], v[148:151], v[216:219], v[52:55]
	v_mfma_f32_16x16x32_bf16 v[48:51], v[156:159], v[216:219], v[48:51]
	v_mfma_f32_16x16x32_bf16 v[44:47], v[148:151], v[224:227], v[44:47]
	v_mfma_f32_16x16x32_bf16 v[40:43], v[156:159], v[224:227], v[40:43]
	v_mfma_f32_16x16x32_bf16 v[36:39], v[148:151], v[232:235], v[36:39]
	v_mfma_f32_16x16x32_bf16 v[32:35], v[156:159], v[232:235], v[32:35]
	s_setprio 0
	s_barrier
	s_add_u32 s36, s34, 0x8000
	s_addc_u32 s37, s35, 0
	s_add_i32 s66, s66, s46
	v_lshl_add_u64 v[238:239], s[36:37], 0, v[172:173]
	s_mov_b32 m0, s66
	ds_read_b128 v[160:163], v214 offset:49152
	ds_read_b128 v[164:167], v214 offset:50176
	ds_read_b128 v[196:199], v214 offset:51200
	ds_read_b128 v[216:219], v214 offset:52224
	ds_read_b128 v[220:223], v214 offset:53248
	ds_read_b128 v[224:227], v214 offset:54272
	ds_read_b128 v[228:231], v214 offset:55296
	ds_read_b128 v[232:235], v214 offset:56320
	global_load_lds_dwordx4 v[238:239], off
	s_add_i32 m0, s66, 0x2000
	s_add_u32 s34, s34, 0xc000
	v_lshl_add_u64 v[238:239], s[36:37], 0, v[176:177]
	s_addc_u32 s35, s35, 0
	s_add_i32 s36, s67, s46
	global_load_lds_dwordx4 v[238:239], off
	v_lshl_add_u64 v[238:239], s[34:35], 0, v[172:173]
	s_mov_b32 m0, s36
	v_lshl_add_u64 v[200:201], v[200:201], 0, s[16:17]
	global_load_lds_dwordx4 v[238:239], off
	v_lshl_add_u64 v[238:239], s[34:35], 0, v[176:177]
	s_add_i32 m0, s36, 0x2000
	s_nop 0
	global_load_lds_dwordx4 v[238:239], off
	s_mov_b32 m0, s55
	s_nop 0
	global_load_lds_dwordx4 v[200:201], off
	v_lshl_add_u64 v[200:201], v[236:237], 0, s[16:17]
	s_mov_b32 m0, s56
	s_nop 0
	global_load_lds_dwordx4 v[200:201], off
	s_waitcnt vmcnt(8)
	s_waitcnt lgkmcnt(0)
	s_barrier
	s_setprio 1
	s_waitcnt lgkmcnt(0)
	v_mfma_f32_16x16x32_bf16 v[92:95], v[128:131], v[160:163], v[92:95]
	v_mfma_f32_16x16x32_bf16 v[88:91], v[136:139], v[160:163], v[88:91]
	v_mfma_f32_16x16x32_bf16 v[84:87], v[128:131], v[196:199], v[84:87]
	v_mfma_f32_16x16x32_bf16 v[80:83], v[136:139], v[196:199], v[80:83]
	v_mfma_f32_16x16x32_bf16 v[76:79], v[128:131], v[220:223], v[76:79]
	v_mfma_f32_16x16x32_bf16 v[72:75], v[136:139], v[220:223], v[72:75]
	v_mfma_f32_16x16x32_bf16 v[68:71], v[128:131], v[228:231], v[68:71]
	v_mfma_f32_16x16x32_bf16 v[64:67], v[136:139], v[228:231], v[64:67]
	v_mfma_f32_16x16x32_bf16 v[92:95], v[132:135], v[164:167], v[92:95]
	v_mfma_f32_16x16x32_bf16 v[88:91], v[140:143], v[164:167], v[88:91]
	v_mfma_f32_16x16x32_bf16 v[84:87], v[132:135], v[216:219], v[84:87]
	v_mfma_f32_16x16x32_bf16 v[80:83], v[140:143], v[216:219], v[80:83]
	v_mfma_f32_16x16x32_bf16 v[76:79], v[132:135], v[224:227], v[76:79]
	v_mfma_f32_16x16x32_bf16 v[72:75], v[140:143], v[224:227], v[72:75]
	v_mfma_f32_16x16x32_bf16 v[68:71], v[132:135], v[232:235], v[68:71]
	v_mfma_f32_16x16x32_bf16 v[64:67], v[140:143], v[232:235], v[64:67]
	s_setprio 0
	s_setprio 1
	v_mfma_f32_16x16x32_bf16 v[28:31], v[144:147], v[160:163], v[28:31]
	v_mfma_f32_16x16x32_bf16 v[24:27], v[152:155], v[160:163], v[24:27]
	v_mfma_f32_16x16x32_bf16 v[20:23], v[144:147], v[196:199], v[20:23]
	v_mfma_f32_16x16x32_bf16 v[16:19], v[152:155], v[196:199], v[16:19]
	v_mfma_f32_16x16x32_bf16 v[12:15], v[144:147], v[220:223], v[12:15]
	v_mfma_f32_16x16x32_bf16 v[8:11], v[152:155], v[220:223], v[8:11]
	v_mfma_f32_16x16x32_bf16 v[4:7], v[144:147], v[228:231], v[4:7]
	v_mfma_f32_16x16x32_bf16 v[0:3], v[152:155], v[228:231], v[0:3]
	v_mfma_f32_16x16x32_bf16 v[28:31], v[148:151], v[164:167], v[28:31]
	v_mfma_f32_16x16x32_bf16 v[24:27], v[156:159], v[164:167], v[24:27]
	v_mfma_f32_16x16x32_bf16 v[20:23], v[148:151], v[216:219], v[20:23]
	v_mfma_f32_16x16x32_bf16 v[16:19], v[156:159], v[216:219], v[16:19]
	v_mfma_f32_16x16x32_bf16 v[12:15], v[148:151], v[224:227], v[12:15]
	v_mfma_f32_16x16x32_bf16 v[8:11], v[156:159], v[224:227], v[8:11]
	v_mfma_f32_16x16x32_bf16 v[4:7], v[148:151], v[232:235], v[4:7]
	v_mfma_f32_16x16x32_bf16 v[0:3], v[156:159], v[232:235], v[0:3]
	s_setprio 0
	s_barrier
	s_add_i32 s39, s39, 2
	s_add_u32 s25, s25, 0x10000
	s_addc_u32 s38, s38, 0
	s_add_u32 s30, s30, 0x100
	s_addc_u32 s31, s31, 0
	s_cmp_gt_u32 s39, 13
	s_cbranch_scc0 .LBB0_492
	s_and_b64 vcc, exec, s[18:19]
	s_cbranch_vccz .LBB0_503
	s_barrier
	v_lshl_add_u32 v216, s0, 8, v169
	s_cmp_gt_i32 s6, 4
	s_mov_b64 s[0:1], -1
	s_cbranch_scc1 .LBB0_504

.LBB0_1070:
	s_ashr_i32 s17, s16, 31
	s_lshl_b64 s[20:21], s[16:17], 18
	s_add_u32 s20, s38, s20
	s_addc_u32 s21, s39, s21
	s_and_b64 s[22:23], s[0:1], exec
	s_cselect_b32 s17, s21, s31
	s_cselect_b32 s52, s20, s30
	s_ashr_i32 s19, s18, 31
	s_lshl_b64 s[22:23], s[18:19], 18
	s_add_u32 s22, s40, s22
	s_addc_u32 s23, s41, s23
	s_and_b64 s[34:35], s[0:1], exec
	s_cselect_b32 s19, s23, s29
	s_cselect_b32 s53, s22, s28
	s_add_u32 s54, s28, 0x10000
	s_addc_u32 s55, s29, 0
	s_add_u32 s28, s30, 0x20080
	s_addc_u32 s29, s31, 0
	s_mov_b32 s56, -2
.LBB0_1071:
	ds_read_b128 v[128:131], v170
	ds_read_b128 v[148:151], v170 offset:1024
	ds_read_b128 v[152:155], v170 offset:2048
	ds_read_b128 v[174:177], v170 offset:3072
	ds_read_b128 v[178:181], v171
	ds_read_b128 v[182:185], v171 offset:1024
	ds_read_b128 v[186:189], v171 offset:2048
	ds_read_b128 v[190:193], v171 offset:3072
	s_add_u32 s30, s28, 0xfffe0080
	s_addc_u32 s31, s29, -1
	s_cmp_eq_u32 s56, 4
	s_cselect_b32 s35, s17, s31
	s_cselect_b32 s34, s52, s30
	s_cselect_b32 s31, s19, s55
	s_cselect_b32 s30, s53, s54
	v_lshl_add_u64 v[234:235], s[28:29], 0, v[142:143]
	s_add_i32 m0, s25, 0xc000
	ds_read_b128 v[194:197], v172
	ds_read_b128 v[198:201], v172 offset:1024
	ds_read_b128 v[210:213], v172 offset:2048
	ds_read_b128 v[214:217], v172 offset:3072
	ds_read_b128 v[218:221], v172 offset:4096
	ds_read_b128 v[222:225], v172 offset:5120
	ds_read_b128 v[226:229], v172 offset:6144
	ds_read_b128 v[230:233], v172 offset:7168
	global_load_lds_dwordx4 v[234:235], off
	v_lshl_add_u64 v[234:235], s[28:29], 0, v[140:141]
	s_add_i32 m0, s25, 0xe000
	s_nop 0
	global_load_lds_dwordx4 v[234:235], off
	s_cmp_lg_u32 s56, -2
	s_cbranch_scc1 .Lzm_12
	v_mov_b32_e32 v0, 0
	v_mov_b32_e32 v1, v0
	v_mov_b32_e32 v2, v0
	v_mov_b32_e32 v3, v0
	v_mov_b32_e32 v4, v0
	v_mov_b32_e32 v5, v0
	v_mov_b32_e32 v6, v0
	v_mov_b32_e32 v7, v0
	v_mov_b32_e32 v8, v0
	v_mov_b32_e32 v9, v0
	v_mov_b32_e32 v10, v0
	v_mov_b32_e32 v11, v0
	v_mov_b32_e32 v12, v0
	v_mov_b32_e32 v13, v0
	v_mov_b32_e32 v14, v0
	v_mov_b32_e32 v15, v0
	v_mov_b32_e32 v16, v0
	v_mov_b32_e32 v17, v0
	v_mov_b32_e32 v18, v0
	v_mov_b32_e32 v19, v0
	v_mov_b32_e32 v20, v0
	v_mov_b32_e32 v21, v0
	v_mov_b32_e32 v22, v0
	v_mov_b32_e32 v23, v0
	v_mov_b32_e32 v24, v0
	v_mov_b32_e32 v25, v0
	v_mov_b32_e32 v26, v0
	v_mov_b32_e32 v27, v0
	v_mov_b32_e32 v28, v0
	v_mov_b32_e32 v29, v0
	v_mov_b32_e32 v30, v0
	v_mov_b32_e32 v31, v0
	v_mov_b32_e32 v32, v0
	v_mov_b32_e32 v33, v0
	v_mov_b32_e32 v34, v0
	v_mov_b32_e32 v35, v0
	v_mov_b32_e32 v36, v0
	v_mov_b32_e32 v37, v0
	v_mov_b32_e32 v38, v0
	v_mov_b32_e32 v39, v0
	v_mov_b32_e32 v40, v0
	v_mov_b32_e32 v41, v0
	v_mov_b32_e32 v42, v0
	v_mov_b32_e32 v43, v0
	v_mov_b32_e32 v44, v0
	v_mov_b32_e32 v45, v0
	v_mov_b32_e32 v46, v0
	v_mov_b32_e32 v47, v0
	v_mov_b32_e32 v48, v0
	v_mov_b32_e32 v49, v0
	v_mov_b32_e32 v50, v0
	v_mov_b32_e32 v51, v0
	v_mov_b32_e32 v52, v0
	v_mov_b32_e32 v53, v0
	v_mov_b32_e32 v54, v0
	v_mov_b32_e32 v55, v0
	v_mov_b32_e32 v56, v0
	v_mov_b32_e32 v57, v0
	v_mov_b32_e32 v58, v0
	v_mov_b32_e32 v59, v0
	v_mov_b32_e32 v60, v0
	v_mov_b32_e32 v61, v0
	v_mov_b32_e32 v62, v0
	v_mov_b32_e32 v63, v0
	v_mov_b32_e32 v64, v0
	v_mov_b32_e32 v65, v0
	v_mov_b32_e32 v66, v0
	v_mov_b32_e32 v67, v0
	v_mov_b32_e32 v68, v0
	v_mov_b32_e32 v69, v0
	v_mov_b32_e32 v70, v0
	v_mov_b32_e32 v71, v0
	v_mov_b32_e32 v72, v0
	v_mov_b32_e32 v73, v0
	v_mov_b32_e32 v74, v0
	v_mov_b32_e32 v75, v0
	v_mov_b32_e32 v76, v0
	v_mov_b32_e32 v77, v0
	v_mov_b32_e32 v78, v0
	v_mov_b32_e32 v79, v0
	v_mov_b32_e32 v80, v0
	v_mov_b32_e32 v81, v0
	v_mov_b32_e32 v82, v0
	v_mov_b32_e32 v83, v0
	v_mov_b32_e32 v84, v0
	v_mov_b32_e32 v85, v0
	v_mov_b32_e32 v86, v0
	v_mov_b32_e32 v87, v0
	v_mov_b32_e32 v88, v0
	v_mov_b32_e32 v89, v0
	v_mov_b32_e32 v90, v0
	v_mov_b32_e32 v91, v0
	v_mov_b32_e32 v92, v0
	v_mov_b32_e32 v93, v0
	v_mov_b32_e32 v94, v0
	v_mov_b32_e32 v95, v0
	v_mov_b32_e32 v96, v0
	v_mov_b32_e32 v97, v0
	v_mov_b32_e32 v98, v0
	v_mov_b32_e32 v99, v0
	v_mov_b32_e32 v100, v0
	v_mov_b32_e32 v101, v0
	v_mov_b32_e32 v102, v0
	v_mov_b32_e32 v103, v0
	v_mov_b32_e32 v104, v0
	v_mov_b32_e32 v105, v0
	v_mov_b32_e32 v106, v0
	v_mov_b32_e32 v107, v0
	v_mov_b32_e32 v108, v0
	v_mov_b32_e32 v109, v0
	v_mov_b32_e32 v110, v0
	v_mov_b32_e32 v111, v0
	v_mov_b32_e32 v112, v0
	v_mov_b32_e32 v113, v0
	v_mov_b32_e32 v114, v0
	v_mov_b32_e32 v115, v0
	v_mov_b32_e32 v116, v0
	v_mov_b32_e32 v117, v0
	v_mov_b32_e32 v118, v0
	v_mov_b32_e32 v119, v0
	v_mov_b32_e32 v120, v0
	v_mov_b32_e32 v121, v0
	v_mov_b32_e32 v122, v0
	v_mov_b32_e32 v123, v0
	v_mov_b32_e32 v124, v0
	v_mov_b32_e32 v125, v0
	v_mov_b32_e32 v126, v0
	v_mov_b32_e32 v127, v0
.Lzm_12:
	s_waitcnt vmcnt(8)
	s_waitcnt lgkmcnt(0)
	s_barrier
	s_setprio 1
	s_waitcnt lgkmcnt(0)
	v_mfma_f32_16x16x32_bf16 v[124:127], v[128:131], v[194:197], v[124:127]
	v_mfma_f32_16x16x32_bf16 v[120:123], v[152:155], v[194:197], v[120:123]
	v_mfma_f32_16x16x32_bf16 v[116:119], v[128:131], v[210:213], v[116:119]
	v_mfma_f32_16x16x32_bf16 v[112:115], v[152:155], v[210:213], v[112:115]
	v_mfma_f32_16x16x32_bf16 v[92:95], v[128:131], v[218:221], v[92:95]
	v_mfma_f32_16x16x32_bf16 v[88:91], v[152:155], v[218:221], v[88:91]
	v_mfma_f32_16x16x32_bf16 v[84:87], v[128:131], v[226:229], v[84:87]
	v_mfma_f32_16x16x32_bf16 v[72:75], v[152:155], v[226:229], v[72:75]
	v_mfma_f32_16x16x32_bf16 v[124:127], v[148:151], v[198:201], v[124:127]
	v_mfma_f32_16x16x32_bf16 v[120:123], v[174:177], v[198:201], v[120:123]
	v_mfma_f32_16x16x32_bf16 v[116:119], v[148:151], v[214:217], v[116:119]
	v_mfma_f32_16x16x32_bf16 v[112:115], v[174:177], v[214:217], v[112:115]
	v_mfma_f32_16x16x32_bf16 v[92:95], v[148:151], v[222:225], v[92:95]
	v_mfma_f32_16x16x32_bf16 v[88:91], v[174:177], v[222:225], v[88:91]
	v_mfma_f32_16x16x32_bf16 v[84:87], v[148:151], v[230:233], v[84:87]
	v_mfma_f32_16x16x32_bf16 v[72:75], v[174:177], v[230:233], v[72:75]
	s_setprio 0
	s_setprio 1
	v_mfma_f32_16x16x32_bf16 v[108:111], v[178:181], v[194:197], v[108:111]
	v_mfma_f32_16x16x32_bf16 v[104:107], v[186:189], v[194:197], v[104:107]
	v_mfma_f32_16x16x32_bf16 v[100:103], v[178:181], v[210:213], v[100:103]
	v_mfma_f32_16x16x32_bf16 v[96:99], v[186:189], v[210:213], v[96:99]
	v_mfma_f32_16x16x32_bf16 v[80:83], v[178:181], v[218:221], v[80:83]
	v_mfma_f32_16x16x32_bf16 v[76:79], v[186:189], v[218:221], v[76:79]
	v_mfma_f32_16x16x32_bf16 v[68:71], v[178:181], v[226:229], v[68:71]
	v_mfma_f32_16x16x32_bf16 v[64:67], v[186:189], v[226:229], v[64:67]
	v_mfma_f32_16x16x32_bf16 v[108:111], v[182:185], v[198:201], v[108:111]
	v_mfma_f32_16x16x32_bf16 v[104:107], v[190:193], v[198:201], v[104:107]
	v_mfma_f32_16x16x32_bf16 v[100:103], v[182:185], v[214:217], v[100:103]
	v_mfma_f32_16x16x32_bf16 v[96:99], v[190:193], v[214:217], v[96:99]
	v_mfma_f32_16x16x32_bf16 v[80:83], v[182:185], v[222:225], v[80:83]
	v_mfma_f32_16x16x32_bf16 v[76:79], v[190:193], v[222:225], v[76:79]
	v_mfma_f32_16x16x32_bf16 v[68:71], v[182:185], v[230:233], v[68:71]
	v_mfma_f32_16x16x32_bf16 v[64:67], v[190:193], v[230:233], v[64:67]
	s_setprio 0
	s_barrier
	s_add_i32 s57, s49, s42
	v_lshl_add_u64 v[234:235], s[30:31], 0, v[134:135]
	s_mov_b32 m0, s57
	ds_read_b128 v[194:197], v172 offset:16384
	ds_read_b128 v[198:201], v172 offset:17408
	ds_read_b128 v[210:213], v172 offset:18432
	ds_read_b128 v[214:217], v172 offset:19456
	ds_read_b128 v[218:221], v172 offset:20480
	ds_read_b128 v[222:225], v172 offset:21504
	ds_read_b128 v[226:229], v172 offset:22528
	ds_read_b128 v[230:233], v172 offset:23552
	global_load_lds_dwordx4 v[234:235], off
	s_add_i32 m0, s57, 0x2000
	s_add_u32 s58, s30, 0x4000
	v_lshl_add_u64 v[234:235], s[30:31], 0, v[138:139]
	s_addc_u32 s59, s31, 0
	s_add_i32 s57, s50, s42
	global_load_lds_dwordx4 v[234:235], off
	v_lshl_add_u64 v[234:235], s[58:59], 0, v[134:135]
	s_mov_b32 m0, s57
	v_lshl_add_u64 v[236:237], s[34:35], 0, v[136:137]
	global_load_lds_dwordx4 v[234:235], off
	v_lshl_add_u64 v[234:235], s[58:59], 0, v[138:139]
	s_add_i32 m0, s57, 0x2000
	s_nop 0
	global_load_lds_dwordx4 v[234:235], off
	v_lshl_add_u64 v[234:235], s[34:35], 0, v[132:133]
	s_mov_b32 m0, s25
	s_nop 0
	global_load_lds_dwordx4 v[234:235], off
	s_mov_b32 m0, s27
	s_nop 0
	global_load_lds_dwordx4 v[236:237], off
	s_waitcnt vmcnt(8)
	s_waitcnt lgkmcnt(0)
	s_barrier
	s_setprio 1
	s_waitcnt lgkmcnt(0)
	v_mfma_f32_16x16x32_bf16 v[60:63], v[128:131], v[194:197], v[60:63]
	v_mfma_f32_16x16x32_bf16 v[56:59], v[152:155], v[194:197], v[56:59]
	v_mfma_f32_16x16x32_bf16 v[48:51], v[128:131], v[210:213], v[48:51]
	v_mfma_f32_16x16x32_bf16 v[40:43], v[152:155], v[210:213], v[40:43]
	v_mfma_f32_16x16x32_bf16 v[32:35], v[128:131], v[218:221], v[32:35]
	v_mfma_f32_16x16x32_bf16 v[24:27], v[152:155], v[218:221], v[24:27]
	v_mfma_f32_16x16x32_bf16 v[16:19], v[128:131], v[226:229], v[16:19]
	v_mfma_f32_16x16x32_bf16 v[8:11], v[152:155], v[226:229], v[8:11]
	v_mfma_f32_16x16x32_bf16 v[60:63], v[148:151], v[198:201], v[60:63]
	v_mfma_f32_16x16x32_bf16 v[56:59], v[174:177], v[198:201], v[56:59]
	v_mfma_f32_16x16x32_bf16 v[48:51], v[148:151], v[214:217], v[48:51]
	v_mfma_f32_16x16x32_bf16 v[40:43], v[174:177], v[214:217], v[40:43]
	v_mfma_f32_16x16x32_bf16 v[32:35], v[148:151], v[222:225], v[32:35]
	v_mfma_f32_16x16x32_bf16 v[24:27], v[174:177], v[222:225], v[24:27]
	v_mfma_f32_16x16x32_bf16 v[16:19], v[148:151], v[230:233], v[16:19]
	v_mfma_f32_16x16x32_bf16 v[8:11], v[174:177], v[230:233], v[8:11]
	s_setprio 0
	s_setprio 1
	v_mfma_f32_16x16x32_bf16 v[52:55], v[178:181], v[194:197], v[52:55]
	v_mfma_f32_16x16x32_bf16 v[44:47], v[186:189], v[194:197], v[44:47]
	v_mfma_f32_16x16x32_bf16 v[36:39], v[178:181], v[210:213], v[36:39]
	v_mfma_f32_16x16x32_bf16 v[28:31], v[186:189], v[210:213], v[28:31]
	v_mfma_f32_16x16x32_bf16 v[20:23], v[178:181], v[218:221], v[20:23]
	v_mfma_f32_16x16x32_bf16 v[12:15], v[186:189], v[218:221], v[12:15]
	v_mfma_f32_16x16x32_bf16 v[4:7], v[178:181], v[226:229], v[4:7]
	v_mfma_f32_16x16x32_bf16 v[0:3], v[186:189], v[226:229], v[0:3]
	v_mfma_f32_16x16x32_bf16 v[52:55], v[182:185], v[198:201], v[52:55]
	v_mfma_f32_16x16x32_bf16 v[44:47], v[190:193], v[198:201], v[44:47]
	v_mfma_f32_16x16x32_bf16 v[36:39], v[182:185], v[214:217], v[36:39]
	v_mfma_f32_16x16x32_bf16 v[28:31], v[190:193], v[214:217], v[28:31]
	v_mfma_f32_16x16x32_bf16 v[20:23], v[182:185], v[222:225], v[20:23]
	v_mfma_f32_16x16x32_bf16 v[12:15], v[190:193], v[222:225], v[12:15]
	v_mfma_f32_16x16x32_bf16 v[4:7], v[182:185], v[230:233], v[4:7]
	v_mfma_f32_16x16x32_bf16 v[0:3], v[190:193], v[230:233], v[0:3]
	s_setprio 0
	s_barrier
	s_add_i32 s57, 0, 0x18000
	v_add_u32_e32 v173, s57, v168
	s_add_i32 s58, 0, 0x1c000
	ds_read_b128 v[128:131], v173
	ds_read_b128 v[148:151], v173 offset:1024
	ds_read_b128 v[152:155], v173 offset:2048
	ds_read_b128 v[174:177], v173 offset:3072
	v_add_u32_e32 v173, s58, v168
	ds_read_b128 v[178:181], v173
	ds_read_b128 v[182:185], v173 offset:1024
	ds_read_b128 v[186:189], v173 offset:2048
	ds_read_b128 v[190:193], v173 offset:3072
	s_add_u32 s34, s34, 0x20000
	s_addc_u32 s35, s35, 0
	s_mov_b32 m0, s43
	v_lshl_add_u64 v[238:239], s[34:35], 0, v[132:133]
	ds_read_b128 v[194:197], v172 offset:32768
	ds_read_b128 v[198:201], v172 offset:33792
	ds_read_b128 v[210:213], v172 offset:34816
	ds_read_b128 v[214:217], v172 offset:35840
	ds_read_b128 v[218:221], v172 offset:36864
	ds_read_b128 v[222:225], v172 offset:37888
	ds_read_b128 v[226:229], v172 offset:38912
	ds_read_b128 v[230:233], v172 offset:39936
	global_load_lds_dwordx4 v[238:239], off
	v_lshl_add_u64 v[238:239], s[34:35], 0, v[136:137]
	s_mov_b32 m0, s44
	s_nop 0
	global_load_lds_dwordx4 v[238:239], off
	s_waitcnt vmcnt(8)
	s_waitcnt lgkmcnt(0)
	s_barrier
	s_setprio 1
	s_waitcnt lgkmcnt(0)
	v_mfma_f32_16x16x32_bf16 v[124:127], v[128:131], v[194:197], v[124:127]
	v_mfma_f32_16x16x32_bf16 v[120:123], v[152:155], v[194:197], v[120:123]
	v_mfma_f32_16x16x32_bf16 v[116:119], v[128:131], v[210:213], v[116:119]
	v_mfma_f32_16x16x32_bf16 v[112:115], v[152:155], v[210:213], v[112:115]
	v_mfma_f32_16x16x32_bf16 v[92:95], v[128:131], v[218:221], v[92:95]
	v_mfma_f32_16x16x32_bf16 v[88:91], v[152:155], v[218:221], v[88:91]
	v_mfma_f32_16x16x32_bf16 v[84:87], v[128:131], v[226:229], v[84:87]
	v_mfma_f32_16x16x32_bf16 v[72:75], v[152:155], v[226:229], v[72:75]
	v_mfma_f32_16x16x32_bf16 v[124:127], v[148:151], v[198:201], v[124:127]
	v_mfma_f32_16x16x32_bf16 v[120:123], v[174:177], v[198:201], v[120:123]
	v_mfma_f32_16x16x32_bf16 v[116:119], v[148:151], v[214:217], v[116:119]
	v_mfma_f32_16x16x32_bf16 v[112:115], v[174:177], v[214:217], v[112:115]
	v_mfma_f32_16x16x32_bf16 v[92:95], v[148:151], v[222:225], v[92:95]
	v_mfma_f32_16x16x32_bf16 v[88:91], v[174:177], v[222:225], v[88:91]
	v_mfma_f32_16x16x32_bf16 v[84:87], v[148:151], v[230:233], v[84:87]
	v_mfma_f32_16x16x32_bf16 v[72:75], v[174:177], v[230:233], v[72:75]
	s_setprio 0
	s_setprio 1
	v_mfma_f32_16x16x32_bf16 v[108:111], v[178:181], v[194:197], v[108:111]
	v_mfma_f32_16x16x32_bf16 v[104:107], v[186:189], v[194:197], v[104:107]
	v_mfma_f32_16x16x32_bf16 v[100:103], v[178:181], v[210:213], v[100:103]
	v_mfma_f32_16x16x32_bf16 v[96:99], v[186:189], v[210:213], v[96:99]
	v_mfma_f32_16x16x32_bf16 v[80:83], v[178:181], v[218:221], v[80:83]
	v_mfma_f32_16x16x32_bf16 v[76:79], v[186:189], v[218:221], v[76:79]
	v_mfma_f32_16x16x32_bf16 v[68:71], v[178:181], v[226:229], v[68:71]
	v_mfma_f32_16x16x32_bf16 v[64:67], v[186:189], v[226:229], v[64:67]
	v_mfma_f32_16x16x32_bf16 v[108:111], v[182:185], v[198:201], v[108:111]
	v_mfma_f32_16x16x32_bf16 v[104:107], v[190:193], v[198:201], v[104:107]
	v_mfma_f32_16x16x32_bf16 v[100:103], v[182:185], v[214:217], v[100:103]
	v_mfma_f32_16x16x32_bf16 v[96:99], v[190:193], v[214:217], v[96:99]
	v_mfma_f32_16x16x32_bf16 v[80:83], v[182:185], v[222:225], v[80:83]
	v_mfma_f32_16x16x32_bf16 v[76:79], v[190:193], v[222:225], v[76:79]
	v_mfma_f32_16x16x32_bf16 v[68:71], v[182:185], v[230:233], v[68:71]
	v_mfma_f32_16x16x32_bf16 v[64:67], v[190:193], v[230:233], v[64:67]
	s_setprio 0
	s_barrier
	s_add_u32 s34, s30, 0x8000
	s_addc_u32 s35, s31, 0
	s_add_i32 s57, s57, s42
	v_lshl_add_u64 v[238:239], s[34:35], 0, v[134:135]
	s_mov_b32 m0, s57
	ds_read_b128 v[194:197], v172 offset:49152
	ds_read_b128 v[198:201], v172 offset:50176
	ds_read_b128 v[210:213], v172 offset:51200
	ds_read_b128 v[214:217], v172 offset:52224
	ds_read_b128 v[218:221], v172 offset:53248
	ds_read_b128 v[222:225], v172 offset:54272
	ds_read_b128 v[226:229], v172 offset:55296
	ds_read_b128 v[230:233], v172 offset:56320
	global_load_lds_dwordx4 v[238:239], off
	s_add_i32 m0, s57, 0x2000
	s_add_u32 s30, s30, 0xc000
	v_lshl_add_u64 v[238:239], s[34:35], 0, v[138:139]
	s_addc_u32 s31, s31, 0
	s_add_i32 s34, s58, s42
	global_load_lds_dwordx4 v[238:239], off
	v_lshl_add_u64 v[238:239], s[30:31], 0, v[134:135]
	s_mov_b32 m0, s34
	v_lshl_add_u64 v[234:235], v[234:235], 0, s[12:13]
	global_load_lds_dwordx4 v[238:239], off
	v_lshl_add_u64 v[238:239], s[30:31], 0, v[138:139]
	s_add_i32 m0, s34, 0x2000
	s_nop 0
	global_load_lds_dwordx4 v[238:239], off
	s_mov_b32 m0, s46
	s_nop 0
	global_load_lds_dwordx4 v[234:235], off
	v_lshl_add_u64 v[234:235], v[236:237], 0, s[12:13]
	s_mov_b32 m0, s47
	s_nop 0
	global_load_lds_dwordx4 v[234:235], off
	s_waitcnt vmcnt(8)
	s_waitcnt lgkmcnt(0)
	s_barrier
	s_setprio 1
	s_waitcnt lgkmcnt(0)
	v_mfma_f32_16x16x32_bf16 v[60:63], v[128:131], v[194:197], v[60:63]
	v_mfma_f32_16x16x32_bf16 v[56:59], v[152:155], v[194:197], v[56:59]
	v_mfma_f32_16x16x32_bf16 v[48:51], v[128:131], v[210:213], v[48:51]
	v_mfma_f32_16x16x32_bf16 v[40:43], v[152:155], v[210:213], v[40:43]
	v_mfma_f32_16x16x32_bf16 v[32:35], v[128:131], v[218:221], v[32:35]
	v_mfma_f32_16x16x32_bf16 v[24:27], v[152:155], v[218:221], v[24:27]
	v_mfma_f32_16x16x32_bf16 v[16:19], v[128:131], v[226:229], v[16:19]
	v_mfma_f32_16x16x32_bf16 v[8:11], v[152:155], v[226:229], v[8:11]
	v_mfma_f32_16x16x32_bf16 v[60:63], v[148:151], v[198:201], v[60:63]
	v_mfma_f32_16x16x32_bf16 v[56:59], v[174:177], v[198:201], v[56:59]
	v_mfma_f32_16x16x32_bf16 v[48:51], v[148:151], v[214:217], v[48:51]
	v_mfma_f32_16x16x32_bf16 v[40:43], v[174:177], v[214:217], v[40:43]
	v_mfma_f32_16x16x32_bf16 v[32:35], v[148:151], v[222:225], v[32:35]
	v_mfma_f32_16x16x32_bf16 v[24:27], v[174:177], v[222:225], v[24:27]
	v_mfma_f32_16x16x32_bf16 v[16:19], v[148:151], v[230:233], v[16:19]
	v_mfma_f32_16x16x32_bf16 v[8:11], v[174:177], v[230:233], v[8:11]
	s_setprio 0
	s_setprio 1
	v_mfma_f32_16x16x32_bf16 v[52:55], v[178:181], v[194:197], v[52:55]
	v_mfma_f32_16x16x32_bf16 v[44:47], v[186:189], v[194:197], v[44:47]
	v_mfma_f32_16x16x32_bf16 v[36:39], v[178:181], v[210:213], v[36:39]
	v_mfma_f32_16x16x32_bf16 v[28:31], v[186:189], v[210:213], v[28:31]
	v_mfma_f32_16x16x32_bf16 v[20:23], v[178:181], v[218:221], v[20:23]
	v_mfma_f32_16x16x32_bf16 v[12:15], v[186:189], v[218:221], v[12:15]
	v_mfma_f32_16x16x32_bf16 v[4:7], v[178:181], v[226:229], v[4:7]
	v_mfma_f32_16x16x32_bf16 v[0:3], v[186:189], v[226:229], v[0:3]
	v_mfma_f32_16x16x32_bf16 v[52:55], v[182:185], v[198:201], v[52:55]
	v_mfma_f32_16x16x32_bf16 v[44:47], v[190:193], v[198:201], v[44:47]
	v_mfma_f32_16x16x32_bf16 v[36:39], v[182:185], v[214:217], v[36:39]
	v_mfma_f32_16x16x32_bf16 v[28:31], v[190:193], v[214:217], v[28:31]
	v_mfma_f32_16x16x32_bf16 v[20:23], v[182:185], v[222:225], v[20:23]
	v_mfma_f32_16x16x32_bf16 v[12:15], v[190:193], v[222:225], v[12:15]
	v_mfma_f32_16x16x32_bf16 v[4:7], v[182:185], v[230:233], v[4:7]
	v_mfma_f32_16x16x32_bf16 v[0:3], v[190:193], v[230:233], v[0:3]
	s_setprio 0
	s_barrier
	s_add_i32 s56, s56, 2
	s_add_u32 s54, s54, 0x10000
	s_addc_u32 s55, s55, 0
	s_add_u32 s28, s28, 0x100
	s_addc_u32 s29, s29, 0
	s_cmp_gt_u32 s56, 5
	s_cbranch_scc0 .LBB0_1071
	s_and_b64 vcc, exec, s[14:15]
	s_cbranch_vccz .LBB0_1074
	s_barrier

.LBB0_1094:
	s_ashr_i32 s15, s14, 31
	s_lshl_b64 s[18:19], s[14:15], 18
	s_add_u32 s18, s35, s18
	s_addc_u32 s19, s37, s19
	s_and_b64 s[20:21], s[0:1], exec
	s_cselect_b32 s15, s19, s29
	s_cselect_b32 s50, s18, s28
	s_ashr_i32 s17, s16, 31
	s_lshl_b64 s[20:21], s[16:17], 18
	s_add_u32 s20, s38, s20
	s_addc_u32 s21, s39, s21
	s_and_b64 s[30:31], s[0:1], exec
	s_cselect_b32 s17, s21, s27
	s_cselect_b32 s51, s20, s26
	s_add_u32 s52, s26, 0x10000
	s_addc_u32 s53, s27, 0
	s_add_u32 s26, s28, 0x20080
	s_addc_u32 s27, s29, 0
	s_mov_b32 s54, -2
.LBB0_1095:
	ds_read_b128 v[144:147], v155
	ds_read_b128 v[148:151], v155 offset:1024
	ds_read_b128 v[158:161], v155 offset:2048
	ds_read_b128 v[162:165], v155 offset:3072
	ds_read_b128 v[166:169], v156
	ds_read_b128 v[170:173], v156 offset:1024
	ds_read_b128 v[174:177], v156 offset:2048
	ds_read_b128 v[178:181], v156 offset:3072
	s_add_u32 s28, s26, 0xfffe0080
	s_addc_u32 s29, s27, -1
	s_cmp_eq_u32 s54, 4
	s_cselect_b32 s31, s15, s29
	s_cselect_b32 s30, s50, s28
	s_cselect_b32 s29, s17, s53
	s_cselect_b32 s28, s51, s52
	v_lshl_add_u64 v[222:223], s[26:27], 0, v[130:131]
	s_add_i32 m0, s23, 0xc000
	ds_read_b128 v[182:185], v157
	ds_read_b128 v[186:189], v157 offset:1024
	ds_read_b128 v[190:193], v157 offset:2048
	ds_read_b128 v[194:197], v157 offset:3072
	ds_read_b128 v[198:201], v157 offset:4096
	ds_read_b128 v[210:213], v157 offset:5120
	ds_read_b128 v[214:217], v157 offset:6144
	ds_read_b128 v[218:221], v157 offset:7168
	global_load_lds_dwordx4 v[222:223], off
	v_lshl_add_u64 v[222:223], s[26:27], 0, v[128:129]
	s_add_i32 m0, s23, 0xe000
	s_nop 0
	global_load_lds_dwordx4 v[222:223], off
	s_cmp_lg_u32 s54, -2
	s_cbranch_scc1 .Lzm_11
	v_mov_b32_e32 v0, 0
	v_mov_b32_e32 v1, v0
	v_mov_b32_e32 v2, v0
	v_mov_b32_e32 v3, v0
	v_mov_b32_e32 v4, v0
	v_mov_b32_e32 v5, v0
	v_mov_b32_e32 v6, v0
	v_mov_b32_e32 v7, v0
	v_mov_b32_e32 v8, v0
	v_mov_b32_e32 v9, v0
	v_mov_b32_e32 v10, v0
	v_mov_b32_e32 v11, v0
	v_mov_b32_e32 v12, v0
	v_mov_b32_e32 v13, v0
	v_mov_b32_e32 v14, v0
	v_mov_b32_e32 v15, v0
	v_mov_b32_e32 v16, v0
	v_mov_b32_e32 v17, v0
	v_mov_b32_e32 v18, v0
	v_mov_b32_e32 v19, v0
	v_mov_b32_e32 v20, v0
	v_mov_b32_e32 v21, v0
	v_mov_b32_e32 v22, v0
	v_mov_b32_e32 v23, v0
	v_mov_b32_e32 v24, v0
	v_mov_b32_e32 v25, v0
	v_mov_b32_e32 v26, v0
	v_mov_b32_e32 v27, v0
	v_mov_b32_e32 v28, v0
	v_mov_b32_e32 v29, v0
	v_mov_b32_e32 v30, v0
	v_mov_b32_e32 v31, v0
	v_mov_b32_e32 v32, v0
	v_mov_b32_e32 v33, v0
	v_mov_b32_e32 v34, v0
	v_mov_b32_e32 v35, v0
	v_mov_b32_e32 v36, v0
	v_mov_b32_e32 v37, v0
	v_mov_b32_e32 v38, v0
	v_mov_b32_e32 v39, v0
	v_mov_b32_e32 v40, v0
	v_mov_b32_e32 v41, v0
	v_mov_b32_e32 v42, v0
	v_mov_b32_e32 v43, v0
	v_mov_b32_e32 v44, v0
	v_mov_b32_e32 v45, v0
	v_mov_b32_e32 v46, v0
	v_mov_b32_e32 v47, v0
	v_mov_b32_e32 v48, v0
	v_mov_b32_e32 v49, v0
	v_mov_b32_e32 v50, v0
	v_mov_b32_e32 v51, v0
	v_mov_b32_e32 v52, v0
	v_mov_b32_e32 v53, v0
	v_mov_b32_e32 v54, v0
	v_mov_b32_e32 v55, v0
	v_mov_b32_e32 v56, v0
	v_mov_b32_e32 v57, v0
	v_mov_b32_e32 v58, v0
	v_mov_b32_e32 v59, v0
	v_mov_b32_e32 v60, v0
	v_mov_b32_e32 v61, v0
	v_mov_b32_e32 v62, v0
	v_mov_b32_e32 v63, v0
	v_mov_b32_e32 v64, v0
	v_mov_b32_e32 v65, v0
	v_mov_b32_e32 v66, v0
	v_mov_b32_e32 v67, v0
	v_mov_b32_e32 v68, v0
	v_mov_b32_e32 v69, v0
	v_mov_b32_e32 v70, v0
	v_mov_b32_e32 v71, v0
	v_mov_b32_e32 v72, v0
	v_mov_b32_e32 v73, v0
	v_mov_b32_e32 v74, v0
	v_mov_b32_e32 v75, v0
	v_mov_b32_e32 v76, v0
	v_mov_b32_e32 v77, v0
	v_mov_b32_e32 v78, v0
	v_mov_b32_e32 v79, v0
	v_mov_b32_e32 v80, v0
	v_mov_b32_e32 v81, v0
	v_mov_b32_e32 v82, v0
	v_mov_b32_e32 v83, v0
	v_mov_b32_e32 v84, v0
	v_mov_b32_e32 v85, v0
	v_mov_b32_e32 v86, v0
	v_mov_b32_e32 v87, v0
	v_mov_b32_e32 v88, v0
	v_mov_b32_e32 v89, v0
	v_mov_b32_e32 v90, v0
	v_mov_b32_e32 v91, v0
	v_mov_b32_e32 v92, v0
	v_mov_b32_e32 v93, v0
	v_mov_b32_e32 v94, v0
	v_mov_b32_e32 v95, v0
	v_mov_b32_e32 v96, v0
	v_mov_b32_e32 v97, v0
	v_mov_b32_e32 v98, v0
	v_mov_b32_e32 v99, v0
	v_mov_b32_e32 v100, v0
	v_mov_b32_e32 v101, v0
	v_mov_b32_e32 v102, v0
	v_mov_b32_e32 v103, v0
	v_mov_b32_e32 v104, v0
	v_mov_b32_e32 v105, v0
	v_mov_b32_e32 v106, v0
	v_mov_b32_e32 v107, v0
	v_mov_b32_e32 v108, v0
	v_mov_b32_e32 v109, v0
	v_mov_b32_e32 v110, v0
	v_mov_b32_e32 v111, v0
	v_mov_b32_e32 v112, v0
	v_mov_b32_e32 v113, v0
	v_mov_b32_e32 v114, v0
	v_mov_b32_e32 v115, v0
	v_mov_b32_e32 v116, v0
	v_mov_b32_e32 v117, v0
	v_mov_b32_e32 v118, v0
	v_mov_b32_e32 v119, v0
	v_mov_b32_e32 v120, v0
	v_mov_b32_e32 v121, v0
	v_mov_b32_e32 v122, v0
	v_mov_b32_e32 v123, v0
	v_mov_b32_e32 v124, v0
	v_mov_b32_e32 v125, v0
	v_mov_b32_e32 v126, v0
	v_mov_b32_e32 v127, v0
.Lzm_11:
	s_waitcnt vmcnt(8)
	s_waitcnt lgkmcnt(0)
	s_barrier
	s_setprio 1
	s_waitcnt lgkmcnt(0)
	v_mfma_f32_16x16x32_bf16 v[124:127], v[144:147], v[182:185], v[124:127]
	v_mfma_f32_16x16x32_bf16 v[120:123], v[158:161], v[182:185], v[120:123]
	v_mfma_f32_16x16x32_bf16 v[112:115], v[144:147], v[190:193], v[112:115]
	v_mfma_f32_16x16x32_bf16 v[104:107], v[158:161], v[190:193], v[104:107]
	v_mfma_f32_16x16x32_bf16 v[92:95], v[144:147], v[198:201], v[92:95]
	v_mfma_f32_16x16x32_bf16 v[88:91], v[158:161], v[198:201], v[88:91]
	v_mfma_f32_16x16x32_bf16 v[80:83], v[144:147], v[214:217], v[80:83]
	v_mfma_f32_16x16x32_bf16 v[72:75], v[158:161], v[214:217], v[72:75]
	v_mfma_f32_16x16x32_bf16 v[124:127], v[148:151], v[186:189], v[124:127]
	v_mfma_f32_16x16x32_bf16 v[120:123], v[162:165], v[186:189], v[120:123]
	v_mfma_f32_16x16x32_bf16 v[112:115], v[148:151], v[194:197], v[112:115]
	v_mfma_f32_16x16x32_bf16 v[104:107], v[162:165], v[194:197], v[104:107]
	v_mfma_f32_16x16x32_bf16 v[92:95], v[148:151], v[210:213], v[92:95]
	v_mfma_f32_16x16x32_bf16 v[88:91], v[162:165], v[210:213], v[88:91]
	v_mfma_f32_16x16x32_bf16 v[80:83], v[148:151], v[218:221], v[80:83]
	v_mfma_f32_16x16x32_bf16 v[72:75], v[162:165], v[218:221], v[72:75]
	s_setprio 0
	s_setprio 1
	v_mfma_f32_16x16x32_bf16 v[116:119], v[166:169], v[182:185], v[116:119]
	v_mfma_f32_16x16x32_bf16 v[108:111], v[174:177], v[182:185], v[108:111]
	v_mfma_f32_16x16x32_bf16 v[100:103], v[166:169], v[190:193], v[100:103]
	v_mfma_f32_16x16x32_bf16 v[96:99], v[174:177], v[190:193], v[96:99]
	v_mfma_f32_16x16x32_bf16 v[84:87], v[166:169], v[198:201], v[84:87]
	v_mfma_f32_16x16x32_bf16 v[76:79], v[174:177], v[198:201], v[76:79]
	v_mfma_f32_16x16x32_bf16 v[68:71], v[166:169], v[214:217], v[68:71]
	v_mfma_f32_16x16x32_bf16 v[64:67], v[174:177], v[214:217], v[64:67]
	v_mfma_f32_16x16x32_bf16 v[116:119], v[170:173], v[186:189], v[116:119]
	v_mfma_f32_16x16x32_bf16 v[108:111], v[178:181], v[186:189], v[108:111]
	v_mfma_f32_16x16x32_bf16 v[100:103], v[170:173], v[194:197], v[100:103]
	v_mfma_f32_16x16x32_bf16 v[96:99], v[178:181], v[194:197], v[96:99]
	v_mfma_f32_16x16x32_bf16 v[84:87], v[170:173], v[210:213], v[84:87]
	v_mfma_f32_16x16x32_bf16 v[76:79], v[178:181], v[210:213], v[76:79]
	v_mfma_f32_16x16x32_bf16 v[68:71], v[170:173], v[218:221], v[68:71]
	v_mfma_f32_16x16x32_bf16 v[64:67], v[178:181], v[218:221], v[64:67]
	s_setprio 0
	s_barrier
	s_add_i32 s55, s47, s40
	v_lshl_add_u64 v[222:223], s[28:29], 0, v[134:135]
	s_mov_b32 m0, s55
	ds_read_b128 v[182:185], v157 offset:16384
	ds_read_b128 v[186:189], v157 offset:17408
	ds_read_b128 v[190:193], v157 offset:18432
	ds_read_b128 v[194:197], v157 offset:19456
	ds_read_b128 v[198:201], v157 offset:20480
	ds_read_b128 v[210:213], v157 offset:21504
	ds_read_b128 v[214:217], v157 offset:22528
	ds_read_b128 v[218:221], v157 offset:23552
	global_load_lds_dwordx4 v[222:223], off
	s_add_i32 m0, s55, 0x2000
	s_add_u32 s56, s28, 0x4000
	v_lshl_add_u64 v[222:223], s[28:29], 0, v[138:139]
	s_addc_u32 s57, s29, 0
	s_add_i32 s55, s48, s40
	global_load_lds_dwordx4 v[222:223], off
	v_lshl_add_u64 v[222:223], s[56:57], 0, v[134:135]
	s_mov_b32 m0, s55
	v_lshl_add_u64 v[224:225], s[30:31], 0, v[136:137]
	global_load_lds_dwordx4 v[222:223], off
	v_lshl_add_u64 v[222:223], s[56:57], 0, v[138:139]
	s_add_i32 m0, s55, 0x2000
	s_nop 0
	global_load_lds_dwordx4 v[222:223], off
	v_lshl_add_u64 v[222:223], s[30:31], 0, v[132:133]
	s_mov_b32 m0, s23
	s_nop 0
	global_load_lds_dwordx4 v[222:223], off
	s_mov_b32 m0, s25
	s_nop 0
	global_load_lds_dwordx4 v[224:225], off
	s_waitcnt vmcnt(8)
	s_waitcnt lgkmcnt(0)
	s_barrier
	s_setprio 1
	s_waitcnt lgkmcnt(0)
	v_mfma_f32_16x16x32_bf16 v[60:63], v[144:147], v[182:185], v[60:63]
	v_mfma_f32_16x16x32_bf16 v[56:59], v[158:161], v[182:185], v[56:59]
	v_mfma_f32_16x16x32_bf16 v[48:51], v[144:147], v[190:193], v[48:51]
	v_mfma_f32_16x16x32_bf16 v[40:43], v[158:161], v[190:193], v[40:43]
	v_mfma_f32_16x16x32_bf16 v[28:31], v[144:147], v[198:201], v[28:31]
	v_mfma_f32_16x16x32_bf16 v[24:27], v[158:161], v[198:201], v[24:27]
	v_mfma_f32_16x16x32_bf16 v[16:19], v[144:147], v[214:217], v[16:19]
	v_mfma_f32_16x16x32_bf16 v[8:11], v[158:161], v[214:217], v[8:11]
	v_mfma_f32_16x16x32_bf16 v[60:63], v[148:151], v[186:189], v[60:63]
	v_mfma_f32_16x16x32_bf16 v[56:59], v[162:165], v[186:189], v[56:59]
	v_mfma_f32_16x16x32_bf16 v[48:51], v[148:151], v[194:197], v[48:51]
	v_mfma_f32_16x16x32_bf16 v[40:43], v[162:165], v[194:197], v[40:43]
	v_mfma_f32_16x16x32_bf16 v[28:31], v[148:151], v[210:213], v[28:31]
	v_mfma_f32_16x16x32_bf16 v[24:27], v[162:165], v[210:213], v[24:27]
	v_mfma_f32_16x16x32_bf16 v[16:19], v[148:151], v[218:221], v[16:19]
	v_mfma_f32_16x16x32_bf16 v[8:11], v[162:165], v[218:221], v[8:11]
	s_setprio 0
	s_setprio 1
	v_mfma_f32_16x16x32_bf16 v[52:55], v[166:169], v[182:185], v[52:55]
	v_mfma_f32_16x16x32_bf16 v[44:47], v[174:177], v[182:185], v[44:47]
	v_mfma_f32_16x16x32_bf16 v[36:39], v[166:169], v[190:193], v[36:39]
	v_mfma_f32_16x16x32_bf16 v[32:35], v[174:177], v[190:193], v[32:35]
	v_mfma_f32_16x16x32_bf16 v[20:23], v[166:169], v[198:201], v[20:23]
	v_mfma_f32_16x16x32_bf16 v[12:15], v[174:177], v[198:201], v[12:15]
	v_mfma_f32_16x16x32_bf16 v[4:7], v[166:169], v[214:217], v[4:7]
	v_mfma_f32_16x16x32_bf16 v[0:3], v[174:177], v[214:217], v[0:3]
	v_mfma_f32_16x16x32_bf16 v[52:55], v[170:173], v[186:189], v[52:55]
	v_mfma_f32_16x16x32_bf16 v[44:47], v[178:181], v[186:189], v[44:47]
	v_mfma_f32_16x16x32_bf16 v[36:39], v[170:173], v[194:197], v[36:39]
	v_mfma_f32_16x16x32_bf16 v[32:35], v[178:181], v[194:197], v[32:35]
	v_mfma_f32_16x16x32_bf16 v[20:23], v[170:173], v[210:213], v[20:23]
	v_mfma_f32_16x16x32_bf16 v[12:15], v[178:181], v[210:213], v[12:15]
	v_mfma_f32_16x16x32_bf16 v[4:7], v[170:173], v[218:221], v[4:7]
	v_mfma_f32_16x16x32_bf16 v[0:3], v[178:181], v[218:221], v[0:3]
	s_setprio 0
	s_barrier
	s_add_i32 s55, 0, 0x18000
	s_add_i32 s56, 0, 0x1c000
	v_add_u32_e32 v162, s55, v153
	v_add_u32_e32 v178, s56, v153
	ds_read_b128 v[144:147], v162
	ds_read_b128 v[148:151], v162 offset:1024
	ds_read_b128 v[158:161], v162 offset:2048
	ds_read_b128 v[162:165], v162 offset:3072
	ds_read_b128 v[166:169], v178
	ds_read_b128 v[170:173], v178 offset:1024
	ds_read_b128 v[174:177], v178 offset:2048
	ds_read_b128 v[178:181], v178 offset:3072
	s_add_u32 s30, s30, 0x20000
	s_addc_u32 s31, s31, 0
	s_mov_b32 m0, s41
	v_lshl_add_u64 v[226:227], s[30:31], 0, v[132:133]
	ds_read_b128 v[182:185], v157 offset:32768
	ds_read_b128 v[186:189], v157 offset:33792
	ds_read_b128 v[190:193], v157 offset:34816
	ds_read_b128 v[194:197], v157 offset:35840
	ds_read_b128 v[198:201], v157 offset:36864
	ds_read_b128 v[210:213], v157 offset:37888
	ds_read_b128 v[214:217], v157 offset:38912
	ds_read_b128 v[218:221], v157 offset:39936
	global_load_lds_dwordx4 v[226:227], off
	v_lshl_add_u64 v[226:227], s[30:31], 0, v[136:137]
	s_mov_b32 m0, s42
	s_nop 0
	global_load_lds_dwordx4 v[226:227], off
	s_waitcnt vmcnt(8)
	s_waitcnt lgkmcnt(0)
	s_barrier
	s_setprio 1
	s_waitcnt lgkmcnt(0)
	v_mfma_f32_16x16x32_bf16 v[124:127], v[144:147], v[182:185], v[124:127]
	v_mfma_f32_16x16x32_bf16 v[120:123], v[158:161], v[182:185], v[120:123]
	v_mfma_f32_16x16x32_bf16 v[112:115], v[144:147], v[190:193], v[112:115]
	v_mfma_f32_16x16x32_bf16 v[104:107], v[158:161], v[190:193], v[104:107]
	v_mfma_f32_16x16x32_bf16 v[92:95], v[144:147], v[198:201], v[92:95]
	v_mfma_f32_16x16x32_bf16 v[88:91], v[158:161], v[198:201], v[88:91]
	v_mfma_f32_16x16x32_bf16 v[80:83], v[144:147], v[214:217], v[80:83]
	v_mfma_f32_16x16x32_bf16 v[72:75], v[158:161], v[214:217], v[72:75]
	v_mfma_f32_16x16x32_bf16 v[124:127], v[148:151], v[186:189], v[124:127]
	v_mfma_f32_16x16x32_bf16 v[120:123], v[162:165], v[186:189], v[120:123]
	v_mfma_f32_16x16x32_bf16 v[112:115], v[148:151], v[194:197], v[112:115]
	v_mfma_f32_16x16x32_bf16 v[104:107], v[162:165], v[194:197], v[104:107]
	v_mfma_f32_16x16x32_bf16 v[92:95], v[148:151], v[210:213], v[92:95]
	v_mfma_f32_16x16x32_bf16 v[88:91], v[162:165], v[210:213], v[88:91]
	v_mfma_f32_16x16x32_bf16 v[80:83], v[148:151], v[218:221], v[80:83]
	v_mfma_f32_16x16x32_bf16 v[72:75], v[162:165], v[218:221], v[72:75]
	s_setprio 0
	s_setprio 1
	v_mfma_f32_16x16x32_bf16 v[116:119], v[166:169], v[182:185], v[116:119]
	v_mfma_f32_16x16x32_bf16 v[108:111], v[174:177], v[182:185], v[108:111]
	v_mfma_f32_16x16x32_bf16 v[100:103], v[166:169], v[190:193], v[100:103]
	v_mfma_f32_16x16x32_bf16 v[96:99], v[174:177], v[190:193], v[96:99]
	v_mfma_f32_16x16x32_bf16 v[84:87], v[166:169], v[198:201], v[84:87]
	v_mfma_f32_16x16x32_bf16 v[76:79], v[174:177], v[198:201], v[76:79]
	v_mfma_f32_16x16x32_bf16 v[68:71], v[166:169], v[214:217], v[68:71]
	v_mfma_f32_16x16x32_bf16 v[64:67], v[174:177], v[214:217], v[64:67]
	v_mfma_f32_16x16x32_bf16 v[116:119], v[170:173], v[186:189], v[116:119]
	v_mfma_f32_16x16x32_bf16 v[108:111], v[178:181], v[186:189], v[108:111]
	v_mfma_f32_16x16x32_bf16 v[100:103], v[170:173], v[194:197], v[100:103]
	v_mfma_f32_16x16x32_bf16 v[96:99], v[178:181], v[194:197], v[96:99]
	v_mfma_f32_16x16x32_bf16 v[84:87], v[170:173], v[210:213], v[84:87]
	v_mfma_f32_16x16x32_bf16 v[76:79], v[178:181], v[210:213], v[76:79]
	v_mfma_f32_16x16x32_bf16 v[68:71], v[170:173], v[218:221], v[68:71]
	v_mfma_f32_16x16x32_bf16 v[64:67], v[178:181], v[218:221], v[64:67]
	s_setprio 0
	s_barrier
	s_add_u32 s30, s28, 0x8000
	s_addc_u32 s31, s29, 0
	s_add_i32 s55, s55, s40
	v_lshl_add_u64 v[226:227], s[30:31], 0, v[134:135]
	s_mov_b32 m0, s55
	ds_read_b128 v[182:185], v157 offset:49152
	ds_read_b128 v[186:189], v157 offset:50176
	ds_read_b128 v[190:193], v157 offset:51200
	ds_read_b128 v[194:197], v157 offset:52224
	ds_read_b128 v[198:201], v157 offset:53248
	ds_read_b128 v[210:213], v157 offset:54272
	ds_read_b128 v[214:217], v157 offset:55296
	ds_read_b128 v[218:221], v157 offset:56320
	global_load_lds_dwordx4 v[226:227], off
	s_add_i32 m0, s55, 0x2000
	s_add_u32 s28, s28, 0xc000
	v_lshl_add_u64 v[226:227], s[30:31], 0, v[138:139]
	s_addc_u32 s29, s29, 0
	s_add_i32 s30, s56, s40
	global_load_lds_dwordx4 v[226:227], off
	v_lshl_add_u64 v[226:227], s[28:29], 0, v[134:135]
	s_mov_b32 m0, s30
	v_lshl_add_u64 v[222:223], v[222:223], 0, s[8:9]
	global_load_lds_dwordx4 v[226:227], off
	v_lshl_add_u64 v[226:227], s[28:29], 0, v[138:139]
	s_add_i32 m0, s30, 0x2000
	s_nop 0
	global_load_lds_dwordx4 v[226:227], off
	s_mov_b32 m0, s44
	s_nop 0
	global_load_lds_dwordx4 v[222:223], off
	v_lshl_add_u64 v[222:223], v[224:225], 0, s[8:9]
	s_mov_b32 m0, s45
	s_nop 0
	global_load_lds_dwordx4 v[222:223], off
	s_waitcnt vmcnt(8)
	s_waitcnt lgkmcnt(0)
	s_barrier
	s_setprio 1
	s_waitcnt lgkmcnt(0)
	v_mfma_f32_16x16x32_bf16 v[60:63], v[144:147], v[182:185], v[60:63]
	v_mfma_f32_16x16x32_bf16 v[56:59], v[158:161], v[182:185], v[56:59]
	v_mfma_f32_16x16x32_bf16 v[48:51], v[144:147], v[190:193], v[48:51]
	v_mfma_f32_16x16x32_bf16 v[40:43], v[158:161], v[190:193], v[40:43]
	v_mfma_f32_16x16x32_bf16 v[28:31], v[144:147], v[198:201], v[28:31]
	v_mfma_f32_16x16x32_bf16 v[24:27], v[158:161], v[198:201], v[24:27]
	v_mfma_f32_16x16x32_bf16 v[16:19], v[144:147], v[214:217], v[16:19]
	v_mfma_f32_16x16x32_bf16 v[8:11], v[158:161], v[214:217], v[8:11]
	v_mfma_f32_16x16x32_bf16 v[60:63], v[148:151], v[186:189], v[60:63]
	v_mfma_f32_16x16x32_bf16 v[56:59], v[162:165], v[186:189], v[56:59]
	v_mfma_f32_16x16x32_bf16 v[48:51], v[148:151], v[194:197], v[48:51]
	v_mfma_f32_16x16x32_bf16 v[40:43], v[162:165], v[194:197], v[40:43]
	v_mfma_f32_16x16x32_bf16 v[28:31], v[148:151], v[210:213], v[28:31]
	v_mfma_f32_16x16x32_bf16 v[24:27], v[162:165], v[210:213], v[24:27]
	v_mfma_f32_16x16x32_bf16 v[16:19], v[148:151], v[218:221], v[16:19]
	v_mfma_f32_16x16x32_bf16 v[8:11], v[162:165], v[218:221], v[8:11]
	s_setprio 0
	s_setprio 1
	v_mfma_f32_16x16x32_bf16 v[52:55], v[166:169], v[182:185], v[52:55]
	v_mfma_f32_16x16x32_bf16 v[44:47], v[174:177], v[182:185], v[44:47]
	v_mfma_f32_16x16x32_bf16 v[36:39], v[166:169], v[190:193], v[36:39]
	v_mfma_f32_16x16x32_bf16 v[32:35], v[174:177], v[190:193], v[32:35]
	v_mfma_f32_16x16x32_bf16 v[20:23], v[166:169], v[198:201], v[20:23]
	v_mfma_f32_16x16x32_bf16 v[12:15], v[174:177], v[198:201], v[12:15]
	v_mfma_f32_16x16x32_bf16 v[4:7], v[166:169], v[214:217], v[4:7]
	v_mfma_f32_16x16x32_bf16 v[0:3], v[174:177], v[214:217], v[0:3]
	v_mfma_f32_16x16x32_bf16 v[52:55], v[170:173], v[186:189], v[52:55]
	v_mfma_f32_16x16x32_bf16 v[44:47], v[178:181], v[186:189], v[44:47]
	v_mfma_f32_16x16x32_bf16 v[36:39], v[170:173], v[194:197], v[36:39]
	v_mfma_f32_16x16x32_bf16 v[32:35], v[178:181], v[194:197], v[32:35]
	v_mfma_f32_16x16x32_bf16 v[20:23], v[170:173], v[210:213], v[20:23]
	v_mfma_f32_16x16x32_bf16 v[12:15], v[178:181], v[210:213], v[12:15]
	v_mfma_f32_16x16x32_bf16 v[4:7], v[170:173], v[218:221], v[4:7]
	v_mfma_f32_16x16x32_bf16 v[0:3], v[178:181], v[218:221], v[0:3]
	s_setprio 0
	s_barrier
	s_add_i32 s54, s54, 2
	s_add_u32 s52, s52, 0x10000
	s_addc_u32 s53, s53, 0
	s_add_u32 s26, s26, 0x100
	s_addc_u32 s27, s27, 0
	s_cmp_gt_u32 s54, 5
	s_cbranch_scc0 .LBB0_1095
	s_and_b64 vcc, exec, s[10:11]
	s_cbranch_vccz .LBB0_1098
	s_barrier

.LBB0_1170:
	s_ashr_i32 s35, s34, 31
	s_lshl_b64 s[38:39], s[34:35], 19
	s_add_u32 s38, s60, s38
	s_addc_u32 s39, s61, s39
	s_and_b64 s[40:41], s[8:9], exec
	s_cselect_b32 s35, s39, s49
	s_cselect_b32 s43, s38, s48
	s_ashr_i32 s37, s36, 31
	s_lshl_b64 s[40:41], s[36:37], 19
	s_add_u32 s40, s62, s40
	s_addc_u32 s41, s63, s41
	s_and_b64 s[50:51], s[8:9], exec
	s_cselect_b32 s37, s41, s47
	s_cselect_b32 s45, s40, s46
	s_add_u32 s52, s46, 0x10000
	s_addc_u32 s53, s47, 0
	s_add_u32 s46, s48, 0x40080
	s_addc_u32 s47, s49, 0
	s_mov_b32 s54, -2
.LBB0_1171:
	v_add_u32_e32 v168, s77, v182
	v_add_u32_e32 v204, s78, v182
	ds_read_b128 v[156:159], v168
	ds_read_b128 v[160:163], v168 offset:1024
	ds_read_b128 v[164:167], v168 offset:2048
	ds_read_b128 v[168:171], v168 offset:3072
	ds_read_b128 v[172:175], v204
	ds_read_b128 v[176:179], v204 offset:1024
	ds_read_b128 v[212:215], v204 offset:2048
	ds_read_b128 v[216:219], v204 offset:3072
	s_add_u32 s48, s46, 0xfffc0080
	s_addc_u32 s49, s47, -1
	s_cmp_eq_u32 s54, 12
	s_cselect_b32 s51, s35, s49
	s_cselect_b32 s50, s43, s48
	s_cselect_b32 s49, s37, s53
	s_cselect_b32 s48, s45, s52
	v_lshl_add_u64 v[252:253], s[46:47], 0, v[154:155]
	s_add_i32 m0, s65, 0xc000
	ds_read_b128 v[220:223], v199
	ds_read_b128 v[224:227], v199 offset:1024
	ds_read_b128 v[228:231], v199 offset:2048
	ds_read_b128 v[232:235], v199 offset:3072
	ds_read_b128 v[236:239], v199 offset:4096
	ds_read_b128 v[240:243], v199 offset:5120
	ds_read_b128 v[244:247], v199 offset:6144
	ds_read_b128 v[248:251], v199 offset:7168
	global_load_lds_dwordx4 v[252:253], off
	v_lshl_add_u64 v[252:253], s[46:47], 0, v[152:153]
	s_add_i32 m0, s65, 0xe000
	s_nop 0
	global_load_lds_dwordx4 v[252:253], off
	s_cmp_lg_u32 s54, -2
	s_cbranch_scc1 .Lzm_10
	v_mov_b32_e32 v0, 0
	v_mov_b32_e32 v1, v0
	v_mov_b32_e32 v2, v0
	v_mov_b32_e32 v3, v0
	v_mov_b32_e32 v4, v0
	v_mov_b32_e32 v5, v0
	v_mov_b32_e32 v6, v0
	v_mov_b32_e32 v7, v0
	v_mov_b32_e32 v8, v0
	v_mov_b32_e32 v9, v0
	v_mov_b32_e32 v10, v0
	v_mov_b32_e32 v11, v0
	v_mov_b32_e32 v12, v0
	v_mov_b32_e32 v13, v0
	v_mov_b32_e32 v14, v0
	v_mov_b32_e32 v15, v0
	v_mov_b32_e32 v16, v0
	v_mov_b32_e32 v17, v0
	v_mov_b32_e32 v18, v0
	v_mov_b32_e32 v19, v0
	v_mov_b32_e32 v20, v0
	v_mov_b32_e32 v21, v0
	v_mov_b32_e32 v22, v0
	v_mov_b32_e32 v23, v0
	v_mov_b32_e32 v24, v0
	v_mov_b32_e32 v25, v0
	v_mov_b32_e32 v26, v0
	v_mov_b32_e32 v27, v0
	v_mov_b32_e32 v28, v0
	v_mov_b32_e32 v29, v0
	v_mov_b32_e32 v30, v0
	v_mov_b32_e32 v31, v0
	v_mov_b32_e32 v32, v0
	v_mov_b32_e32 v33, v0
	v_mov_b32_e32 v34, v0
	v_mov_b32_e32 v35, v0
	v_mov_b32_e32 v36, v0
	v_mov_b32_e32 v37, v0
	v_mov_b32_e32 v38, v0
	v_mov_b32_e32 v39, v0
	v_mov_b32_e32 v40, v0
	v_mov_b32_e32 v41, v0
	v_mov_b32_e32 v42, v0
	v_mov_b32_e32 v43, v0
	v_mov_b32_e32 v44, v0
	v_mov_b32_e32 v45, v0
	v_mov_b32_e32 v46, v0
	v_mov_b32_e32 v47, v0
	v_mov_b32_e32 v48, v0
	v_mov_b32_e32 v49, v0
	v_mov_b32_e32 v50, v0
	v_mov_b32_e32 v51, v0
	v_mov_b32_e32 v52, v0
	v_mov_b32_e32 v53, v0
	v_mov_b32_e32 v54, v0
	v_mov_b32_e32 v55, v0
	v_mov_b32_e32 v56, v0
	v_mov_b32_e32 v57, v0
	v_mov_b32_e32 v58, v0
	v_mov_b32_e32 v59, v0
	v_mov_b32_e32 v60, v0
	v_mov_b32_e32 v61, v0
	v_mov_b32_e32 v62, v0
	v_mov_b32_e32 v63, v0
	v_mov_b32_e32 v64, v0
	v_mov_b32_e32 v65, v0
	v_mov_b32_e32 v66, v0
	v_mov_b32_e32 v67, v0
	v_mov_b32_e32 v68, v0
	v_mov_b32_e32 v69, v0
	v_mov_b32_e32 v70, v0
	v_mov_b32_e32 v71, v0
	v_mov_b32_e32 v72, v0
	v_mov_b32_e32 v73, v0
	v_mov_b32_e32 v74, v0
	v_mov_b32_e32 v75, v0
	v_mov_b32_e32 v76, v0
	v_mov_b32_e32 v77, v0
	v_mov_b32_e32 v78, v0
	v_mov_b32_e32 v79, v0
	v_mov_b32_e32 v80, v0
	v_mov_b32_e32 v81, v0
	v_mov_b32_e32 v82, v0
	v_mov_b32_e32 v83, v0
	v_mov_b32_e32 v84, v0
	v_mov_b32_e32 v85, v0
	v_mov_b32_e32 v86, v0
	v_mov_b32_e32 v87, v0
	v_mov_b32_e32 v88, v0
	v_mov_b32_e32 v89, v0
	v_mov_b32_e32 v90, v0
	v_mov_b32_e32 v91, v0
	v_mov_b32_e32 v92, v0
	v_mov_b32_e32 v93, v0
	v_mov_b32_e32 v94, v0
	v_mov_b32_e32 v95, v0
	v_mov_b32_e32 v96, v0
	v_mov_b32_e32 v97, v0
	v_mov_b32_e32 v98, v0
	v_mov_b32_e32 v99, v0
	v_mov_b32_e32 v100, v0
	v_mov_b32_e32 v101, v0
	v_mov_b32_e32 v102, v0
	v_mov_b32_e32 v103, v0
	v_mov_b32_e32 v104, v0
	v_mov_b32_e32 v105, v0
	v_mov_b32_e32 v106, v0
	v_mov_b32_e32 v107, v0
	v_mov_b32_e32 v108, v0
	v_mov_b32_e32 v109, v0
	v_mov_b32_e32 v110, v0
	v_mov_b32_e32 v111, v0
	v_mov_b32_e32 v112, v0
	v_mov_b32_e32 v113, v0
	v_mov_b32_e32 v114, v0
	v_mov_b32_e32 v115, v0
	v_mov_b32_e32 v116, v0
	v_mov_b32_e32 v117, v0
	v_mov_b32_e32 v118, v0
	v_mov_b32_e32 v119, v0
	v_mov_b32_e32 v120, v0
	v_mov_b32_e32 v121, v0
	v_mov_b32_e32 v122, v0
	v_mov_b32_e32 v123, v0
	v_mov_b32_e32 v124, v0
	v_mov_b32_e32 v125, v0
	v_mov_b32_e32 v126, v0
	v_mov_b32_e32 v127, v0
.Lzm_10:
	s_waitcnt vmcnt(8)
	s_waitcnt lgkmcnt(0)
	s_barrier
	s_setprio 1
	s_waitcnt lgkmcnt(0)
	v_mfma_f32_16x16x32_bf16 v[124:127], v[156:159], v[220:223], v[124:127]
	v_mfma_f32_16x16x32_bf16 v[120:123], v[164:167], v[220:223], v[120:123]
	v_mfma_f32_16x16x32_bf16 v[116:119], v[156:159], v[228:231], v[116:119]
	v_mfma_f32_16x16x32_bf16 v[112:115], v[164:167], v[228:231], v[112:115]
	v_mfma_f32_16x16x32_bf16 v[92:95], v[156:159], v[236:239], v[92:95]
	v_mfma_f32_16x16x32_bf16 v[88:91], v[164:167], v[236:239], v[88:91]
	v_mfma_f32_16x16x32_bf16 v[84:87], v[156:159], v[244:247], v[84:87]
	v_mfma_f32_16x16x32_bf16 v[80:83], v[164:167], v[244:247], v[80:83]
	v_mfma_f32_16x16x32_bf16 v[124:127], v[160:163], v[224:227], v[124:127]
	v_mfma_f32_16x16x32_bf16 v[120:123], v[168:171], v[224:227], v[120:123]
	v_mfma_f32_16x16x32_bf16 v[116:119], v[160:163], v[232:235], v[116:119]
	v_mfma_f32_16x16x32_bf16 v[112:115], v[168:171], v[232:235], v[112:115]
	v_mfma_f32_16x16x32_bf16 v[92:95], v[160:163], v[240:243], v[92:95]
	v_mfma_f32_16x16x32_bf16 v[88:91], v[168:171], v[240:243], v[88:91]
	v_mfma_f32_16x16x32_bf16 v[84:87], v[160:163], v[248:251], v[84:87]
	v_mfma_f32_16x16x32_bf16 v[80:83], v[168:171], v[248:251], v[80:83]
	s_setprio 0
	s_setprio 1
	v_mfma_f32_16x16x32_bf16 v[108:111], v[172:175], v[220:223], v[108:111]
	v_mfma_f32_16x16x32_bf16 v[104:107], v[212:215], v[220:223], v[104:107]
	v_mfma_f32_16x16x32_bf16 v[100:103], v[172:175], v[228:231], v[100:103]
	v_mfma_f32_16x16x32_bf16 v[96:99], v[212:215], v[228:231], v[96:99]
	v_mfma_f32_16x16x32_bf16 v[76:79], v[172:175], v[236:239], v[76:79]
	v_mfma_f32_16x16x32_bf16 v[72:75], v[212:215], v[236:239], v[72:75]
	v_mfma_f32_16x16x32_bf16 v[68:71], v[172:175], v[244:247], v[68:71]
	v_mfma_f32_16x16x32_bf16 v[64:67], v[212:215], v[244:247], v[64:67]
	v_mfma_f32_16x16x32_bf16 v[108:111], v[176:179], v[224:227], v[108:111]
	v_mfma_f32_16x16x32_bf16 v[104:107], v[216:219], v[224:227], v[104:107]
	v_mfma_f32_16x16x32_bf16 v[100:103], v[176:179], v[232:235], v[100:103]
	v_mfma_f32_16x16x32_bf16 v[96:99], v[216:219], v[232:235], v[96:99]
	v_mfma_f32_16x16x32_bf16 v[76:79], v[176:179], v[240:243], v[76:79]
	v_mfma_f32_16x16x32_bf16 v[72:75], v[216:219], v[240:243], v[72:75]
	v_mfma_f32_16x16x32_bf16 v[68:71], v[176:179], v[248:251], v[68:71]
	v_mfma_f32_16x16x32_bf16 v[64:67], v[216:219], v[248:251], v[64:67]
	s_setprio 0
	s_barrier
	s_add_i32 s55, s77, s64
	v_lshl_add_u64 v[252:253], s[48:49], 0, v[130:131]
	s_mov_b32 m0, s55
	ds_read_b128 v[220:223], v199 offset:16384
	ds_read_b128 v[224:227], v199 offset:17408
	ds_read_b128 v[228:231], v199 offset:18432
	ds_read_b128 v[232:235], v199 offset:19456
	ds_read_b128 v[236:239], v199 offset:20480
	ds_read_b128 v[240:243], v199 offset:21504
	ds_read_b128 v[244:247], v199 offset:22528
	ds_read_b128 v[248:251], v199 offset:23552
	global_load_lds_dwordx4 v[252:253], off
	s_add_i32 m0, s55, 0x2000
	s_add_u32 s56, s48, 0x4000
	v_lshl_add_u64 v[252:253], s[48:49], 0, v[134:135]
	s_addc_u32 s57, s49, 0
	s_add_i32 s55, s78, s64
	global_load_lds_dwordx4 v[252:253], off
	v_lshl_add_u64 v[252:253], s[56:57], 0, v[130:131]
	s_mov_b32 m0, s55
	v_lshl_add_u64 v[204:205], s[50:51], 0, v[132:133]
	global_load_lds_dwordx4 v[252:253], off
	v_lshl_add_u64 v[252:253], s[56:57], 0, v[134:135]
	s_add_i32 m0, s55, 0x2000
	s_nop 0
	global_load_lds_dwordx4 v[252:253], off
	v_lshl_add_u64 v[252:253], s[50:51], 0, v[128:129]
	s_mov_b32 m0, s65
	s_nop 0
	global_load_lds_dwordx4 v[252:253], off
	s_mov_b32 m0, s66
	s_nop 0
	global_load_lds_dwordx4 v[204:205], off
	s_waitcnt vmcnt(8)
	s_waitcnt lgkmcnt(0)
	s_barrier
	s_setprio 1
	s_waitcnt lgkmcnt(0)
	v_mfma_f32_16x16x32_bf16 v[60:63], v[156:159], v[220:223], v[60:63]
	v_mfma_f32_16x16x32_bf16 v[56:59], v[164:167], v[220:223], v[56:59]
	v_mfma_f32_16x16x32_bf16 v[52:55], v[156:159], v[228:231], v[52:55]
	v_mfma_f32_16x16x32_bf16 v[48:51], v[164:167], v[228:231], v[48:51]
	v_mfma_f32_16x16x32_bf16 v[28:31], v[156:159], v[236:239], v[28:31]
	v_mfma_f32_16x16x32_bf16 v[24:27], v[164:167], v[236:239], v[24:27]
	v_mfma_f32_16x16x32_bf16 v[20:23], v[156:159], v[244:247], v[20:23]
	v_mfma_f32_16x16x32_bf16 v[12:15], v[164:167], v[244:247], v[12:15]
	v_mfma_f32_16x16x32_bf16 v[60:63], v[160:163], v[224:227], v[60:63]
	v_mfma_f32_16x16x32_bf16 v[56:59], v[168:171], v[224:227], v[56:59]
	v_mfma_f32_16x16x32_bf16 v[52:55], v[160:163], v[232:235], v[52:55]
	v_mfma_f32_16x16x32_bf16 v[48:51], v[168:171], v[232:235], v[48:51]
	v_mfma_f32_16x16x32_bf16 v[28:31], v[160:163], v[240:243], v[28:31]
	v_mfma_f32_16x16x32_bf16 v[24:27], v[168:171], v[240:243], v[24:27]
	v_mfma_f32_16x16x32_bf16 v[20:23], v[160:163], v[248:251], v[20:23]
	v_mfma_f32_16x16x32_bf16 v[12:15], v[168:171], v[248:251], v[12:15]
	s_setprio 0
	s_setprio 1
	v_mfma_f32_16x16x32_bf16 v[44:47], v[172:175], v[220:223], v[44:47]
	v_mfma_f32_16x16x32_bf16 v[40:43], v[212:215], v[220:223], v[40:43]
	v_mfma_f32_16x16x32_bf16 v[36:39], v[172:175], v[228:231], v[36:39]
	v_mfma_f32_16x16x32_bf16 v[32:35], v[212:215], v[228:231], v[32:35]
	v_mfma_f32_16x16x32_bf16 v[16:19], v[172:175], v[236:239], v[16:19]
	v_mfma_f32_16x16x32_bf16 v[8:11], v[212:215], v[236:239], v[8:11]
	v_mfma_f32_16x16x32_bf16 v[4:7], v[172:175], v[244:247], v[4:7]
	v_mfma_f32_16x16x32_bf16 v[0:3], v[212:215], v[244:247], v[0:3]
	v_mfma_f32_16x16x32_bf16 v[44:47], v[176:179], v[224:227], v[44:47]
	v_mfma_f32_16x16x32_bf16 v[40:43], v[216:219], v[224:227], v[40:43]
	v_mfma_f32_16x16x32_bf16 v[36:39], v[176:179], v[232:235], v[36:39]
	v_mfma_f32_16x16x32_bf16 v[32:35], v[216:219], v[232:235], v[32:35]
	v_mfma_f32_16x16x32_bf16 v[16:19], v[176:179], v[240:243], v[16:19]
	v_mfma_f32_16x16x32_bf16 v[8:11], v[216:219], v[240:243], v[8:11]
	v_mfma_f32_16x16x32_bf16 v[4:7], v[176:179], v[248:251], v[4:7]
	v_mfma_f32_16x16x32_bf16 v[0:3], v[216:219], v[248:251], v[0:3]
	s_setprio 0
	s_barrier
	s_add_i32 s55, 0, 0x18000
	s_add_i32 s56, 0, 0x1c000
	v_add_u32_e32 v168, s55, v182
	v_add_u32_e32 v206, s56, v182
	ds_read_b128 v[156:159], v168
	ds_read_b128 v[160:163], v168 offset:1024
	ds_read_b128 v[164:167], v168 offset:2048
	ds_read_b128 v[168:171], v168 offset:3072
	ds_read_b128 v[172:175], v206
	ds_read_b128 v[176:179], v206 offset:1024
	ds_read_b128 v[212:215], v206 offset:2048
	ds_read_b128 v[216:219], v206 offset:3072
	s_add_u32 s50, s50, 0x40000
	s_addc_u32 s51, s51, 0
	s_mov_b32 m0, s67
	v_lshl_add_u64 v[206:207], s[50:51], 0, v[128:129]
	ds_read_b128 v[220:223], v199 offset:32768
	ds_read_b128 v[224:227], v199 offset:33792
	ds_read_b128 v[228:231], v199 offset:34816
	ds_read_b128 v[232:235], v199 offset:35840
	ds_read_b128 v[236:239], v199 offset:36864
	ds_read_b128 v[240:243], v199 offset:37888
	ds_read_b128 v[244:247], v199 offset:38912
	ds_read_b128 v[248:251], v199 offset:39936
	global_load_lds_dwordx4 v[206:207], off
	v_lshl_add_u64 v[206:207], s[50:51], 0, v[132:133]
	s_mov_b32 m0, s68
	s_nop 0
	global_load_lds_dwordx4 v[206:207], off
	s_waitcnt vmcnt(8)
	s_waitcnt lgkmcnt(0)
	s_barrier
	s_setprio 1
	s_waitcnt lgkmcnt(0)
	v_mfma_f32_16x16x32_bf16 v[124:127], v[156:159], v[220:223], v[124:127]
	v_mfma_f32_16x16x32_bf16 v[120:123], v[164:167], v[220:223], v[120:123]
	v_mfma_f32_16x16x32_bf16 v[116:119], v[156:159], v[228:231], v[116:119]
	v_mfma_f32_16x16x32_bf16 v[112:115], v[164:167], v[228:231], v[112:115]
	v_mfma_f32_16x16x32_bf16 v[92:95], v[156:159], v[236:239], v[92:95]
	v_mfma_f32_16x16x32_bf16 v[88:91], v[164:167], v[236:239], v[88:91]
	v_mfma_f32_16x16x32_bf16 v[84:87], v[156:159], v[244:247], v[84:87]
	v_mfma_f32_16x16x32_bf16 v[80:83], v[164:167], v[244:247], v[80:83]
	v_mfma_f32_16x16x32_bf16 v[124:127], v[160:163], v[224:227], v[124:127]
	v_mfma_f32_16x16x32_bf16 v[120:123], v[168:171], v[224:227], v[120:123]
	v_mfma_f32_16x16x32_bf16 v[116:119], v[160:163], v[232:235], v[116:119]
	v_mfma_f32_16x16x32_bf16 v[112:115], v[168:171], v[232:235], v[112:115]
	v_mfma_f32_16x16x32_bf16 v[92:95], v[160:163], v[240:243], v[92:95]
	v_mfma_f32_16x16x32_bf16 v[88:91], v[168:171], v[240:243], v[88:91]
	v_mfma_f32_16x16x32_bf16 v[84:87], v[160:163], v[248:251], v[84:87]
	v_mfma_f32_16x16x32_bf16 v[80:83], v[168:171], v[248:251], v[80:83]
	s_setprio 0
	s_setprio 1
	v_mfma_f32_16x16x32_bf16 v[108:111], v[172:175], v[220:223], v[108:111]
	v_mfma_f32_16x16x32_bf16 v[104:107], v[212:215], v[220:223], v[104:107]
	v_mfma_f32_16x16x32_bf16 v[100:103], v[172:175], v[228:231], v[100:103]
	v_mfma_f32_16x16x32_bf16 v[96:99], v[212:215], v[228:231], v[96:99]
	v_mfma_f32_16x16x32_bf16 v[76:79], v[172:175], v[236:239], v[76:79]
	v_mfma_f32_16x16x32_bf16 v[72:75], v[212:215], v[236:239], v[72:75]
	v_mfma_f32_16x16x32_bf16 v[68:71], v[172:175], v[244:247], v[68:71]
	v_mfma_f32_16x16x32_bf16 v[64:67], v[212:215], v[244:247], v[64:67]
	v_mfma_f32_16x16x32_bf16 v[108:111], v[176:179], v[224:227], v[108:111]
	v_mfma_f32_16x16x32_bf16 v[104:107], v[216:219], v[224:227], v[104:107]
	v_mfma_f32_16x16x32_bf16 v[100:103], v[176:179], v[232:235], v[100:103]
	v_mfma_f32_16x16x32_bf16 v[96:99], v[216:219], v[232:235], v[96:99]
	v_mfma_f32_16x16x32_bf16 v[76:79], v[176:179], v[240:243], v[76:79]
	v_mfma_f32_16x16x32_bf16 v[72:75], v[216:219], v[240:243], v[72:75]
	v_mfma_f32_16x16x32_bf16 v[68:71], v[176:179], v[248:251], v[68:71]
	v_mfma_f32_16x16x32_bf16 v[64:67], v[216:219], v[248:251], v[64:67]
	s_setprio 0
	s_barrier
	s_add_u32 s50, s48, 0x8000
	s_addc_u32 s51, s49, 0
	s_add_i32 s55, s55, s64
	v_lshl_add_u64 v[206:207], s[50:51], 0, v[130:131]
	s_mov_b32 m0, s55
	ds_read_b128 v[220:223], v199 offset:49152
	ds_read_b128 v[224:227], v199 offset:50176
	ds_read_b128 v[228:231], v199 offset:51200
	ds_read_b128 v[232:235], v199 offset:52224
	ds_read_b128 v[236:239], v199 offset:53248
	ds_read_b128 v[240:243], v199 offset:54272
	ds_read_b128 v[244:247], v199 offset:55296
	ds_read_b128 v[248:251], v199 offset:56320
	global_load_lds_dwordx4 v[206:207], off
	s_add_i32 m0, s55, 0x2000
	s_add_u32 s48, s48, 0xc000
	v_lshl_add_u64 v[206:207], s[50:51], 0, v[134:135]
	s_addc_u32 s49, s49, 0
	s_add_i32 s50, s56, s64
	global_load_lds_dwordx4 v[206:207], off
	v_lshl_add_u64 v[206:207], s[48:49], 0, v[130:131]
	s_mov_b32 m0, s50
	v_lshl_add_u64 v[204:205], v[204:205], 0, s[14:15]
	global_load_lds_dwordx4 v[206:207], off
	v_lshl_add_u64 v[206:207], s[48:49], 0, v[134:135]
	s_add_i32 m0, s50, 0x2000
	s_nop 0
	global_load_lds_dwordx4 v[206:207], off
	v_lshl_add_u64 v[206:207], v[252:253], 0, s[14:15]
	s_mov_b32 m0, s74
	s_nop 0
	global_load_lds_dwordx4 v[206:207], off
	s_mov_b32 m0, s75
	s_nop 0
	global_load_lds_dwordx4 v[204:205], off
	s_waitcnt vmcnt(8)
	s_waitcnt lgkmcnt(0)
	s_barrier
	s_setprio 1
	s_waitcnt lgkmcnt(0)
	v_mfma_f32_16x16x32_bf16 v[60:63], v[156:159], v[220:223], v[60:63]
	v_mfma_f32_16x16x32_bf16 v[56:59], v[164:167], v[220:223], v[56:59]
	v_mfma_f32_16x16x32_bf16 v[52:55], v[156:159], v[228:231], v[52:55]
	v_mfma_f32_16x16x32_bf16 v[48:51], v[164:167], v[228:231], v[48:51]
	v_mfma_f32_16x16x32_bf16 v[28:31], v[156:159], v[236:239], v[28:31]
	v_mfma_f32_16x16x32_bf16 v[24:27], v[164:167], v[236:239], v[24:27]
	v_mfma_f32_16x16x32_bf16 v[20:23], v[156:159], v[244:247], v[20:23]
	v_mfma_f32_16x16x32_bf16 v[12:15], v[164:167], v[244:247], v[12:15]
	v_mfma_f32_16x16x32_bf16 v[60:63], v[160:163], v[224:227], v[60:63]
	v_mfma_f32_16x16x32_bf16 v[56:59], v[168:171], v[224:227], v[56:59]
	v_mfma_f32_16x16x32_bf16 v[52:55], v[160:163], v[232:235], v[52:55]
	v_mfma_f32_16x16x32_bf16 v[48:51], v[168:171], v[232:235], v[48:51]
	v_mfma_f32_16x16x32_bf16 v[28:31], v[160:163], v[240:243], v[28:31]
	v_mfma_f32_16x16x32_bf16 v[24:27], v[168:171], v[240:243], v[24:27]
	v_mfma_f32_16x16x32_bf16 v[20:23], v[160:163], v[248:251], v[20:23]
	v_mfma_f32_16x16x32_bf16 v[12:15], v[168:171], v[248:251], v[12:15]
	s_setprio 0
	s_setprio 1
	v_mfma_f32_16x16x32_bf16 v[44:47], v[172:175], v[220:223], v[44:47]
	v_mfma_f32_16x16x32_bf16 v[40:43], v[212:215], v[220:223], v[40:43]
	v_mfma_f32_16x16x32_bf16 v[36:39], v[172:175], v[228:231], v[36:39]
	v_mfma_f32_16x16x32_bf16 v[32:35], v[212:215], v[228:231], v[32:35]
	v_mfma_f32_16x16x32_bf16 v[16:19], v[172:175], v[236:239], v[16:19]
	v_mfma_f32_16x16x32_bf16 v[8:11], v[212:215], v[236:239], v[8:11]
	v_mfma_f32_16x16x32_bf16 v[4:7], v[172:175], v[244:247], v[4:7]
	v_mfma_f32_16x16x32_bf16 v[0:3], v[212:215], v[244:247], v[0:3]
	v_mfma_f32_16x16x32_bf16 v[44:47], v[176:179], v[224:227], v[44:47]
	v_mfma_f32_16x16x32_bf16 v[40:43], v[216:219], v[224:227], v[40:43]
	v_mfma_f32_16x16x32_bf16 v[36:39], v[176:179], v[232:235], v[36:39]
	v_mfma_f32_16x16x32_bf16 v[32:35], v[216:219], v[232:235], v[32:35]
	v_mfma_f32_16x16x32_bf16 v[16:19], v[176:179], v[240:243], v[16:19]
	v_mfma_f32_16x16x32_bf16 v[8:11], v[216:219], v[240:243], v[8:11]
	v_mfma_f32_16x16x32_bf16 v[4:7], v[176:179], v[248:251], v[4:7]
	v_mfma_f32_16x16x32_bf16 v[0:3], v[216:219], v[248:251], v[0:3]
	s_setprio 0
	s_barrier
	s_add_i32 s54, s54, 2
	s_add_u32 s52, s52, 0x10000
	s_addc_u32 s53, s53, 0
	s_add_u32 s46, s46, 0x100
	s_addc_u32 s47, s47, 0
	s_cmp_gt_u32 s54, 13
	s_cbranch_scc0 .LBB0_1171
	s_and_b64 vcc, exec, s[18:19]
	s_cbranch_vccz .LBB0_1174
	s_barrier

.LBB0_1252:
	s_ashr_i32 s11, s10, 31
	s_lshl_b64 s[16:17], s[10:11], 19
	s_add_u32 s16, s30, s16
	s_addc_u32 s17, s31, s17
	s_and_b64 s[18:19], s[0:1], exec
	s_cselect_b32 s11, s17, s27
	s_cselect_b32 s50, s16, s26
	s_ashr_i32 s13, s12, 31
	s_lshl_b64 s[18:19], s[12:13], 19
	s_add_u32 s18, s33, s18
	s_addc_u32 s19, s34, s19
	s_and_b64 s[28:29], s[0:1], exec
	s_cselect_b32 s13, s19, s25
	s_cselect_b32 s51, s18, s24
	s_add_u32 s52, s24, 0x10000
	s_addc_u32 s53, s25, 0
	s_add_u32 s24, s26, 0x40080
	s_addc_u32 s25, s27, 0
	s_mov_b32 s54, -2
.LBB0_1253:
	ds_read_b128 v[170:173], v167
	ds_read_b128 v[174:177], v167 offset:1024
	ds_read_b128 v[178:181], v167 offset:2048
	ds_read_b128 v[182:185], v167 offset:3072
	ds_read_b128 v[186:189], v168
	ds_read_b128 v[190:193], v168 offset:1024
	ds_read_b128 v[194:197], v168 offset:2048
	ds_read_b128 v[198:201], v168 offset:3072
	s_add_u32 s26, s24, 0xfffc0080
	s_addc_u32 s27, s25, -1
	s_cmp_eq_u32 s54, 12
	s_cselect_b32 s29, s11, s27
	s_cselect_b32 s28, s50, s26
	s_cselect_b32 s27, s13, s53
	s_cselect_b32 s26, s51, s52
	v_lshl_add_u64 v[164:165], s[24:25], 0, v[158:159]
	s_add_i32 m0, s21, 0xc000
	ds_read_b128 v[210:213], v169
	ds_read_b128 v[214:217], v169 offset:1024
	ds_read_b128 v[218:221], v169 offset:2048
	ds_read_b128 v[222:225], v169 offset:3072
	ds_read_b128 v[226:229], v169 offset:4096
	ds_read_b128 v[230:233], v169 offset:5120
	ds_read_b128 v[234:237], v169 offset:6144
	ds_read_b128 v[238:241], v169 offset:7168
	global_load_lds_dwordx4 v[164:165], off
	v_lshl_add_u64 v[164:165], s[24:25], 0, v[156:157]
	s_add_i32 m0, s21, 0xe000
	s_nop 0
	global_load_lds_dwordx4 v[164:165], off
	s_cmp_lg_u32 s54, -2
	s_cbranch_scc1 .Lzm_9
	v_mov_b32_e32 v0, 0
	v_mov_b32_e32 v1, v0
	v_mov_b32_e32 v2, v0
	v_mov_b32_e32 v3, v0
	v_mov_b32_e32 v4, v0
	v_mov_b32_e32 v5, v0
	v_mov_b32_e32 v6, v0
	v_mov_b32_e32 v7, v0
	v_mov_b32_e32 v8, v0
	v_mov_b32_e32 v9, v0
	v_mov_b32_e32 v10, v0
	v_mov_b32_e32 v11, v0
	v_mov_b32_e32 v12, v0
	v_mov_b32_e32 v13, v0
	v_mov_b32_e32 v14, v0
	v_mov_b32_e32 v15, v0
	v_mov_b32_e32 v16, v0
	v_mov_b32_e32 v17, v0
	v_mov_b32_e32 v18, v0
	v_mov_b32_e32 v19, v0
	v_mov_b32_e32 v20, v0
	v_mov_b32_e32 v21, v0
	v_mov_b32_e32 v22, v0
	v_mov_b32_e32 v23, v0
	v_mov_b32_e32 v24, v0
	v_mov_b32_e32 v25, v0
	v_mov_b32_e32 v26, v0
	v_mov_b32_e32 v27, v0
	v_mov_b32_e32 v28, v0
	v_mov_b32_e32 v29, v0
	v_mov_b32_e32 v30, v0
	v_mov_b32_e32 v31, v0
	v_mov_b32_e32 v32, v0
	v_mov_b32_e32 v33, v0
	v_mov_b32_e32 v34, v0
	v_mov_b32_e32 v35, v0
	v_mov_b32_e32 v36, v0
	v_mov_b32_e32 v37, v0
	v_mov_b32_e32 v38, v0
	v_mov_b32_e32 v39, v0
	v_mov_b32_e32 v40, v0
	v_mov_b32_e32 v41, v0
	v_mov_b32_e32 v42, v0
	v_mov_b32_e32 v43, v0
	v_mov_b32_e32 v44, v0
	v_mov_b32_e32 v45, v0
	v_mov_b32_e32 v46, v0
	v_mov_b32_e32 v47, v0
	v_mov_b32_e32 v48, v0
	v_mov_b32_e32 v49, v0
	v_mov_b32_e32 v50, v0
	v_mov_b32_e32 v51, v0
	v_mov_b32_e32 v52, v0
	v_mov_b32_e32 v53, v0
	v_mov_b32_e32 v54, v0
	v_mov_b32_e32 v55, v0
	v_mov_b32_e32 v56, v0
	v_mov_b32_e32 v57, v0
	v_mov_b32_e32 v58, v0
	v_mov_b32_e32 v59, v0
	v_mov_b32_e32 v60, v0
	v_mov_b32_e32 v61, v0
	v_mov_b32_e32 v62, v0
	v_mov_b32_e32 v63, v0
	v_mov_b32_e32 v64, v0
	v_mov_b32_e32 v65, v0
	v_mov_b32_e32 v66, v0
	v_mov_b32_e32 v67, v0
	v_mov_b32_e32 v68, v0
	v_mov_b32_e32 v69, v0
	v_mov_b32_e32 v70, v0
	v_mov_b32_e32 v71, v0
	v_mov_b32_e32 v72, v0
	v_mov_b32_e32 v73, v0
	v_mov_b32_e32 v74, v0
	v_mov_b32_e32 v75, v0
	v_mov_b32_e32 v76, v0
	v_mov_b32_e32 v77, v0
	v_mov_b32_e32 v78, v0
	v_mov_b32_e32 v79, v0
	v_mov_b32_e32 v80, v0
	v_mov_b32_e32 v81, v0
	v_mov_b32_e32 v82, v0
	v_mov_b32_e32 v83, v0
	v_mov_b32_e32 v84, v0
	v_mov_b32_e32 v85, v0
	v_mov_b32_e32 v86, v0
	v_mov_b32_e32 v87, v0
	v_mov_b32_e32 v88, v0
	v_mov_b32_e32 v89, v0
	v_mov_b32_e32 v90, v0
	v_mov_b32_e32 v91, v0
	v_mov_b32_e32 v92, v0
	v_mov_b32_e32 v93, v0
	v_mov_b32_e32 v94, v0
	v_mov_b32_e32 v95, v0
	v_mov_b32_e32 v96, v0
	v_mov_b32_e32 v97, v0
	v_mov_b32_e32 v98, v0
	v_mov_b32_e32 v99, v0
	v_mov_b32_e32 v100, v0
	v_mov_b32_e32 v101, v0
	v_mov_b32_e32 v102, v0
	v_mov_b32_e32 v103, v0
	v_mov_b32_e32 v104, v0
	v_mov_b32_e32 v105, v0
	v_mov_b32_e32 v106, v0
	v_mov_b32_e32 v107, v0
	v_mov_b32_e32 v108, v0
	v_mov_b32_e32 v109, v0
	v_mov_b32_e32 v110, v0
	v_mov_b32_e32 v111, v0
	v_mov_b32_e32 v112, v0
	v_mov_b32_e32 v113, v0
	v_mov_b32_e32 v114, v0
	v_mov_b32_e32 v115, v0
	v_mov_b32_e32 v116, v0
	v_mov_b32_e32 v117, v0
	v_mov_b32_e32 v118, v0
	v_mov_b32_e32 v119, v0
	v_mov_b32_e32 v120, v0
	v_mov_b32_e32 v121, v0
	v_mov_b32_e32 v122, v0
	v_mov_b32_e32 v123, v0
	v_mov_b32_e32 v124, v0
	v_mov_b32_e32 v125, v0
	v_mov_b32_e32 v126, v0
	v_mov_b32_e32 v127, v0
.Lzm_9:
	s_waitcnt vmcnt(8)
	s_waitcnt lgkmcnt(0)
	s_barrier
	s_setprio 1
	s_waitcnt lgkmcnt(0)
	v_mfma_f32_16x16x32_bf16 v[124:127], v[170:173], v[210:213], v[124:127]
	v_mfma_f32_16x16x32_bf16 v[116:119], v[178:181], v[210:213], v[116:119]
	v_mfma_f32_16x16x32_bf16 v[108:111], v[170:173], v[218:221], v[108:111]
	v_mfma_f32_16x16x32_bf16 v[100:103], v[178:181], v[218:221], v[100:103]
	v_mfma_f32_16x16x32_bf16 v[92:95], v[170:173], v[226:229], v[92:95]
	v_mfma_f32_16x16x32_bf16 v[84:87], v[178:181], v[226:229], v[84:87]
	v_mfma_f32_16x16x32_bf16 v[76:79], v[170:173], v[234:237], v[76:79]
	v_mfma_f32_16x16x32_bf16 v[68:71], v[178:181], v[234:237], v[68:71]
	v_mfma_f32_16x16x32_bf16 v[124:127], v[174:177], v[214:217], v[124:127]
	v_mfma_f32_16x16x32_bf16 v[116:119], v[182:185], v[214:217], v[116:119]
	v_mfma_f32_16x16x32_bf16 v[108:111], v[174:177], v[222:225], v[108:111]
	v_mfma_f32_16x16x32_bf16 v[100:103], v[182:185], v[222:225], v[100:103]
	v_mfma_f32_16x16x32_bf16 v[92:95], v[174:177], v[230:233], v[92:95]
	v_mfma_f32_16x16x32_bf16 v[84:87], v[182:185], v[230:233], v[84:87]
	v_mfma_f32_16x16x32_bf16 v[76:79], v[174:177], v[238:241], v[76:79]
	v_mfma_f32_16x16x32_bf16 v[68:71], v[182:185], v[238:241], v[68:71]
	s_setprio 0
	s_setprio 1
	v_mfma_f32_16x16x32_bf16 v[120:123], v[186:189], v[210:213], v[120:123]
	v_mfma_f32_16x16x32_bf16 v[112:115], v[194:197], v[210:213], v[112:115]
	v_mfma_f32_16x16x32_bf16 v[104:107], v[186:189], v[218:221], v[104:107]
	v_mfma_f32_16x16x32_bf16 v[96:99], v[194:197], v[218:221], v[96:99]
	v_mfma_f32_16x16x32_bf16 v[88:91], v[186:189], v[226:229], v[88:91]
	v_mfma_f32_16x16x32_bf16 v[80:83], v[194:197], v[226:229], v[80:83]
	v_mfma_f32_16x16x32_bf16 v[72:75], v[186:189], v[234:237], v[72:75]
	v_mfma_f32_16x16x32_bf16 v[64:67], v[194:197], v[234:237], v[64:67]
	v_mfma_f32_16x16x32_bf16 v[120:123], v[190:193], v[214:217], v[120:123]
	v_mfma_f32_16x16x32_bf16 v[112:115], v[198:201], v[214:217], v[112:115]
	v_mfma_f32_16x16x32_bf16 v[104:107], v[190:193], v[222:225], v[104:107]
	v_mfma_f32_16x16x32_bf16 v[96:99], v[198:201], v[222:225], v[96:99]
	v_mfma_f32_16x16x32_bf16 v[88:91], v[190:193], v[230:233], v[88:91]
	v_mfma_f32_16x16x32_bf16 v[80:83], v[198:201], v[230:233], v[80:83]
	v_mfma_f32_16x16x32_bf16 v[72:75], v[190:193], v[238:241], v[72:75]
	v_mfma_f32_16x16x32_bf16 v[64:67], v[198:201], v[238:241], v[64:67]
	s_setprio 0
	s_barrier
	s_add_i32 s55, s48, s35
	v_lshl_add_u64 v[164:165], s[26:27], 0, v[134:135]
	s_mov_b32 m0, s55
	ds_read_b128 v[210:213], v169 offset:16384
	ds_read_b128 v[214:217], v169 offset:17408
	ds_read_b128 v[218:221], v169 offset:18432
	ds_read_b128 v[222:225], v169 offset:19456
	ds_read_b128 v[226:229], v169 offset:20480
	ds_read_b128 v[230:233], v169 offset:21504
	ds_read_b128 v[234:237], v169 offset:22528
	ds_read_b128 v[238:241], v169 offset:23552
	global_load_lds_dwordx4 v[164:165], off
	s_add_i32 m0, s55, 0x2000
	s_add_u32 s56, s26, 0x4000
	v_lshl_add_u64 v[164:165], s[26:27], 0, v[130:131]
	s_addc_u32 s57, s27, 0
	s_add_i32 s55, s49, s35
	global_load_lds_dwordx4 v[164:165], off
	v_lshl_add_u64 v[164:165], s[56:57], 0, v[134:135]
	s_mov_b32 m0, s55
	v_lshl_add_u64 v[204:205], s[28:29], 0, v[132:133]
	global_load_lds_dwordx4 v[164:165], off
	v_lshl_add_u64 v[164:165], s[56:57], 0, v[130:131]
	s_add_i32 m0, s55, 0x2000
	s_nop 0
	global_load_lds_dwordx4 v[164:165], off
	v_lshl_add_u64 v[164:165], s[28:29], 0, v[136:137]
	s_mov_b32 m0, s21
	s_nop 0
	global_load_lds_dwordx4 v[164:165], off
	s_mov_b32 m0, s23
	s_nop 0
	global_load_lds_dwordx4 v[204:205], off
	s_waitcnt vmcnt(8)
	s_waitcnt lgkmcnt(0)
	s_barrier
	s_setprio 1
	s_waitcnt lgkmcnt(0)
	v_mfma_f32_16x16x32_bf16 v[60:63], v[170:173], v[210:213], v[60:63]
	v_mfma_f32_16x16x32_bf16 v[52:55], v[178:181], v[210:213], v[52:55]
	v_mfma_f32_16x16x32_bf16 v[44:47], v[170:173], v[218:221], v[44:47]
	v_mfma_f32_16x16x32_bf16 v[36:39], v[178:181], v[218:221], v[36:39]
	v_mfma_f32_16x16x32_bf16 v[28:31], v[170:173], v[226:229], v[28:31]
	v_mfma_f32_16x16x32_bf16 v[20:23], v[178:181], v[226:229], v[20:23]
	v_mfma_f32_16x16x32_bf16 v[12:15], v[170:173], v[234:237], v[12:15]
	v_mfma_f32_16x16x32_bf16 v[4:7], v[178:181], v[234:237], v[4:7]
	v_mfma_f32_16x16x32_bf16 v[60:63], v[174:177], v[214:217], v[60:63]
	v_mfma_f32_16x16x32_bf16 v[52:55], v[182:185], v[214:217], v[52:55]
	v_mfma_f32_16x16x32_bf16 v[44:47], v[174:177], v[222:225], v[44:47]
	v_mfma_f32_16x16x32_bf16 v[36:39], v[182:185], v[222:225], v[36:39]
	v_mfma_f32_16x16x32_bf16 v[28:31], v[174:177], v[230:233], v[28:31]
	v_mfma_f32_16x16x32_bf16 v[20:23], v[182:185], v[230:233], v[20:23]
	v_mfma_f32_16x16x32_bf16 v[12:15], v[174:177], v[238:241], v[12:15]
	v_mfma_f32_16x16x32_bf16 v[4:7], v[182:185], v[238:241], v[4:7]
	s_setprio 0
	s_setprio 1
	v_mfma_f32_16x16x32_bf16 v[56:59], v[186:189], v[210:213], v[56:59]
	v_mfma_f32_16x16x32_bf16 v[48:51], v[194:197], v[210:213], v[48:51]
	v_mfma_f32_16x16x32_bf16 v[40:43], v[186:189], v[218:221], v[40:43]
	v_mfma_f32_16x16x32_bf16 v[32:35], v[194:197], v[218:221], v[32:35]
	v_mfma_f32_16x16x32_bf16 v[24:27], v[186:189], v[226:229], v[24:27]
	v_mfma_f32_16x16x32_bf16 v[16:19], v[194:197], v[226:229], v[16:19]
	v_mfma_f32_16x16x32_bf16 v[8:11], v[186:189], v[234:237], v[8:11]
	v_mfma_f32_16x16x32_bf16 v[0:3], v[194:197], v[234:237], v[0:3]
	v_mfma_f32_16x16x32_bf16 v[56:59], v[190:193], v[214:217], v[56:59]
	v_mfma_f32_16x16x32_bf16 v[48:51], v[198:201], v[214:217], v[48:51]
	v_mfma_f32_16x16x32_bf16 v[40:43], v[190:193], v[222:225], v[40:43]
	v_mfma_f32_16x16x32_bf16 v[32:35], v[198:201], v[222:225], v[32:35]
	v_mfma_f32_16x16x32_bf16 v[24:27], v[190:193], v[230:233], v[24:27]
	v_mfma_f32_16x16x32_bf16 v[16:19], v[198:201], v[230:233], v[16:19]
	v_mfma_f32_16x16x32_bf16 v[8:11], v[190:193], v[238:241], v[8:11]
	v_mfma_f32_16x16x32_bf16 v[0:3], v[198:201], v[238:241], v[0:3]
	s_setprio 0
	s_barrier
	s_add_i32 s55, 0, 0x18000
	s_add_i32 s56, 0, 0x1c000
	v_add_u32_e32 v182, s55, v129
	v_add_u32_e32 v198, s56, v129
	ds_read_b128 v[170:173], v182
	ds_read_b128 v[174:177], v182 offset:1024
	ds_read_b128 v[178:181], v182 offset:2048
	ds_read_b128 v[182:185], v182 offset:3072
	ds_read_b128 v[186:189], v198
	ds_read_b128 v[190:193], v198 offset:1024
	ds_read_b128 v[194:197], v198 offset:2048
	ds_read_b128 v[198:201], v198 offset:3072
	s_add_u32 s28, s28, 0x40000
	s_addc_u32 s29, s29, 0
	s_mov_b32 m0, s39
	v_lshl_add_u64 v[206:207], s[28:29], 0, v[136:137]
	ds_read_b128 v[210:213], v169 offset:32768
	ds_read_b128 v[214:217], v169 offset:33792
	ds_read_b128 v[218:221], v169 offset:34816
	ds_read_b128 v[222:225], v169 offset:35840
	ds_read_b128 v[226:229], v169 offset:36864
	ds_read_b128 v[230:233], v169 offset:37888
	ds_read_b128 v[234:237], v169 offset:38912
	ds_read_b128 v[238:241], v169 offset:39936
	global_load_lds_dwordx4 v[206:207], off
	v_lshl_add_u64 v[206:207], s[28:29], 0, v[132:133]
	s_mov_b32 m0, s40
	s_nop 0
	global_load_lds_dwordx4 v[206:207], off
	s_waitcnt vmcnt(8)
	s_waitcnt lgkmcnt(0)
	s_barrier
	s_setprio 1
	s_waitcnt lgkmcnt(0)
	v_mfma_f32_16x16x32_bf16 v[124:127], v[170:173], v[210:213], v[124:127]
	v_mfma_f32_16x16x32_bf16 v[116:119], v[178:181], v[210:213], v[116:119]
	v_mfma_f32_16x16x32_bf16 v[108:111], v[170:173], v[218:221], v[108:111]
	v_mfma_f32_16x16x32_bf16 v[100:103], v[178:181], v[218:221], v[100:103]
	v_mfma_f32_16x16x32_bf16 v[92:95], v[170:173], v[226:229], v[92:95]
	v_mfma_f32_16x16x32_bf16 v[84:87], v[178:181], v[226:229], v[84:87]
	v_mfma_f32_16x16x32_bf16 v[76:79], v[170:173], v[234:237], v[76:79]
	v_mfma_f32_16x16x32_bf16 v[68:71], v[178:181], v[234:237], v[68:71]
	v_mfma_f32_16x16x32_bf16 v[124:127], v[174:177], v[214:217], v[124:127]
	v_mfma_f32_16x16x32_bf16 v[116:119], v[182:185], v[214:217], v[116:119]
	v_mfma_f32_16x16x32_bf16 v[108:111], v[174:177], v[222:225], v[108:111]
	v_mfma_f32_16x16x32_bf16 v[100:103], v[182:185], v[222:225], v[100:103]
	v_mfma_f32_16x16x32_bf16 v[92:95], v[174:177], v[230:233], v[92:95]
	v_mfma_f32_16x16x32_bf16 v[84:87], v[182:185], v[230:233], v[84:87]
	v_mfma_f32_16x16x32_bf16 v[76:79], v[174:177], v[238:241], v[76:79]
	v_mfma_f32_16x16x32_bf16 v[68:71], v[182:185], v[238:241], v[68:71]
	s_setprio 0
	s_setprio 1
	v_mfma_f32_16x16x32_bf16 v[120:123], v[186:189], v[210:213], v[120:123]
	v_mfma_f32_16x16x32_bf16 v[112:115], v[194:197], v[210:213], v[112:115]
	v_mfma_f32_16x16x32_bf16 v[104:107], v[186:189], v[218:221], v[104:107]
	v_mfma_f32_16x16x32_bf16 v[96:99], v[194:197], v[218:221], v[96:99]
	v_mfma_f32_16x16x32_bf16 v[88:91], v[186:189], v[226:229], v[88:91]
	v_mfma_f32_16x16x32_bf16 v[80:83], v[194:197], v[226:229], v[80:83]
	v_mfma_f32_16x16x32_bf16 v[72:75], v[186:189], v[234:237], v[72:75]
	v_mfma_f32_16x16x32_bf16 v[64:67], v[194:197], v[234:237], v[64:67]
	v_mfma_f32_16x16x32_bf16 v[120:123], v[190:193], v[214:217], v[120:123]
	v_mfma_f32_16x16x32_bf16 v[112:115], v[198:201], v[214:217], v[112:115]
	v_mfma_f32_16x16x32_bf16 v[104:107], v[190:193], v[222:225], v[104:107]
	v_mfma_f32_16x16x32_bf16 v[96:99], v[198:201], v[222:225], v[96:99]
	v_mfma_f32_16x16x32_bf16 v[88:91], v[190:193], v[230:233], v[88:91]
	v_mfma_f32_16x16x32_bf16 v[80:83], v[198:201], v[230:233], v[80:83]
	v_mfma_f32_16x16x32_bf16 v[72:75], v[190:193], v[238:241], v[72:75]
	v_mfma_f32_16x16x32_bf16 v[64:67], v[198:201], v[238:241], v[64:67]
	s_setprio 0
	s_barrier
	s_add_u32 s28, s26, 0x8000
	s_addc_u32 s29, s27, 0
	s_add_i32 s55, s55, s35
	v_lshl_add_u64 v[206:207], s[28:29], 0, v[134:135]
	s_mov_b32 m0, s55
	ds_read_b128 v[210:213], v169 offset:49152
	ds_read_b128 v[214:217], v169 offset:50176
	ds_read_b128 v[218:221], v169 offset:51200
	ds_read_b128 v[222:225], v169 offset:52224
	ds_read_b128 v[226:229], v169 offset:53248
	ds_read_b128 v[230:233], v169 offset:54272
	ds_read_b128 v[234:237], v169 offset:55296
	ds_read_b128 v[238:241], v169 offset:56320
	global_load_lds_dwordx4 v[206:207], off
	s_add_i32 m0, s55, 0x2000
	s_add_u32 s26, s26, 0xc000
	v_lshl_add_u64 v[206:207], s[28:29], 0, v[130:131]
	s_addc_u32 s27, s27, 0
	s_add_i32 s28, s56, s35
	global_load_lds_dwordx4 v[206:207], off
	v_lshl_add_u64 v[206:207], s[26:27], 0, v[134:135]
	s_mov_b32 m0, s28
	v_lshl_add_u64 v[164:165], v[164:165], 0, s[6:7]
	global_load_lds_dwordx4 v[206:207], off
	v_lshl_add_u64 v[206:207], s[26:27], 0, v[130:131]
	s_add_i32 m0, s28, 0x2000
	s_nop 0
	global_load_lds_dwordx4 v[206:207], off
	s_mov_b32 m0, s45
	s_nop 0
	global_load_lds_dwordx4 v[164:165], off
	v_lshl_add_u64 v[164:165], v[204:205], 0, s[6:7]
	s_mov_b32 m0, s46
	s_nop 0
	global_load_lds_dwordx4 v[164:165], off
	s_waitcnt vmcnt(8)
	s_waitcnt lgkmcnt(0)
	s_barrier
	s_setprio 1
	s_waitcnt lgkmcnt(0)
	v_mfma_f32_16x16x32_bf16 v[60:63], v[170:173], v[210:213], v[60:63]
	v_mfma_f32_16x16x32_bf16 v[52:55], v[178:181], v[210:213], v[52:55]
	v_mfma_f32_16x16x32_bf16 v[44:47], v[170:173], v[218:221], v[44:47]
	v_mfma_f32_16x16x32_bf16 v[36:39], v[178:181], v[218:221], v[36:39]
	v_mfma_f32_16x16x32_bf16 v[28:31], v[170:173], v[226:229], v[28:31]
	v_mfma_f32_16x16x32_bf16 v[20:23], v[178:181], v[226:229], v[20:23]
	v_mfma_f32_16x16x32_bf16 v[12:15], v[170:173], v[234:237], v[12:15]
	v_mfma_f32_16x16x32_bf16 v[4:7], v[178:181], v[234:237], v[4:7]
	v_mfma_f32_16x16x32_bf16 v[60:63], v[174:177], v[214:217], v[60:63]
	v_mfma_f32_16x16x32_bf16 v[52:55], v[182:185], v[214:217], v[52:55]
	v_mfma_f32_16x16x32_bf16 v[44:47], v[174:177], v[222:225], v[44:47]
	v_mfma_f32_16x16x32_bf16 v[36:39], v[182:185], v[222:225], v[36:39]
	v_mfma_f32_16x16x32_bf16 v[28:31], v[174:177], v[230:233], v[28:31]
	v_mfma_f32_16x16x32_bf16 v[20:23], v[182:185], v[230:233], v[20:23]
	v_mfma_f32_16x16x32_bf16 v[12:15], v[174:177], v[238:241], v[12:15]
	v_mfma_f32_16x16x32_bf16 v[4:7], v[182:185], v[238:241], v[4:7]
	s_setprio 0
	s_setprio 1
	v_mfma_f32_16x16x32_bf16 v[56:59], v[186:189], v[210:213], v[56:59]
	v_mfma_f32_16x16x32_bf16 v[48:51], v[194:197], v[210:213], v[48:51]
	v_mfma_f32_16x16x32_bf16 v[40:43], v[186:189], v[218:221], v[40:43]
	v_mfma_f32_16x16x32_bf16 v[32:35], v[194:197], v[218:221], v[32:35]
	v_mfma_f32_16x16x32_bf16 v[24:27], v[186:189], v[226:229], v[24:27]
	v_mfma_f32_16x16x32_bf16 v[16:19], v[194:197], v[226:229], v[16:19]
	v_mfma_f32_16x16x32_bf16 v[8:11], v[186:189], v[234:237], v[8:11]
	v_mfma_f32_16x16x32_bf16 v[0:3], v[194:197], v[234:237], v[0:3]
	v_mfma_f32_16x16x32_bf16 v[56:59], v[190:193], v[214:217], v[56:59]
	v_mfma_f32_16x16x32_bf16 v[48:51], v[198:201], v[214:217], v[48:51]
	v_mfma_f32_16x16x32_bf16 v[40:43], v[190:193], v[222:225], v[40:43]
	v_mfma_f32_16x16x32_bf16 v[32:35], v[198:201], v[222:225], v[32:35]
	v_mfma_f32_16x16x32_bf16 v[24:27], v[190:193], v[230:233], v[24:27]
	v_mfma_f32_16x16x32_bf16 v[16:19], v[198:201], v[230:233], v[16:19]
	v_mfma_f32_16x16x32_bf16 v[8:11], v[190:193], v[238:241], v[8:11]
	v_mfma_f32_16x16x32_bf16 v[0:3], v[198:201], v[238:241], v[0:3]
	s_setprio 0
	s_barrier
	s_add_i32 s54, s54, 2
	s_add_u32 s52, s52, 0x10000
	s_addc_u32 s53, s53, 0
	s_add_u32 s24, s24, 0x100
	s_addc_u32 s25, s25, 0
	s_cmp_gt_u32 s54, 13
	s_cbranch_scc0 .LBB0_1253
	s_and_b64 vcc, exec, s[8:9]
	s_cbranch_vccz .LBB0_1256
	s_barrier

.LBB0_1480:
	s_add_u32 s68, s36, 0x10000
	s_addc_u32 s69, s37, 0
	s_add_u32 s36, s38, 0xc000
	s_addc_u32 s37, s39, 0
	s_mov_b32 s70, -2
.LBB0_1481:
	v_add_u32_e32 v168, s61, v182
	v_add_u32_e32 v204, s62, v182
	ds_read_b128 v[156:159], v168
	ds_read_b128 v[160:163], v168 offset:1024
	ds_read_b128 v[164:167], v168 offset:2048
	ds_read_b128 v[168:171], v168 offset:3072
	ds_read_b128 v[172:175], v204
	ds_read_b128 v[176:179], v204 offset:1024
	ds_read_b128 v[212:215], v204 offset:2048
	ds_read_b128 v[216:219], v204 offset:3072
	s_add_u32 s38, s36, 0x4000
	s_addc_u32 s39, s37, 0
	s_cmp_eq_u32 s70, 40
	s_cselect_b32 s42, s0, s38
	s_cselect_b32 s43, s1, s39
	s_cselect_b32 s40, s34, s68
	s_cselect_b32 s41, s35, s69
	s_add_u32 s38, s42, 0x8000
	s_addc_u32 s39, s43, 0
	v_lshl_add_u64 v[204:205], s[36:37], 0, v[150:151]
	s_add_i32 m0, s48, 0xc000
	ds_read_b128 v[220:223], v199
	ds_read_b128 v[224:227], v199 offset:1024
	ds_read_b128 v[228:231], v199 offset:2048
	ds_read_b128 v[232:235], v199 offset:3072
	ds_read_b128 v[236:239], v199 offset:4096
	ds_read_b128 v[240:243], v199 offset:5120
	ds_read_b128 v[244:247], v199 offset:6144
	ds_read_b128 v[248:251], v199 offset:7168
	global_load_lds_dwordx4 v[204:205], off
	v_lshl_add_u64 v[204:205], s[36:37], 0, v[148:149]
	s_add_i32 m0, s48, 0xe000
	s_nop 0
	global_load_lds_dwordx4 v[204:205], off
	s_cmp_lg_u32 s70, -2
	s_cbranch_scc1 .Lzm_8
	v_mov_b32_e32 v0, 0
	v_mov_b32_e32 v1, v0
	v_mov_b32_e32 v2, v0
	v_mov_b32_e32 v3, v0
	v_mov_b32_e32 v4, v0
	v_mov_b32_e32 v5, v0
	v_mov_b32_e32 v6, v0
	v_mov_b32_e32 v7, v0
	v_mov_b32_e32 v8, v0
	v_mov_b32_e32 v9, v0
	v_mov_b32_e32 v10, v0
	v_mov_b32_e32 v11, v0
	v_mov_b32_e32 v12, v0
	v_mov_b32_e32 v13, v0
	v_mov_b32_e32 v14, v0
	v_mov_b32_e32 v15, v0
	v_mov_b32_e32 v16, v0
	v_mov_b32_e32 v17, v0
	v_mov_b32_e32 v18, v0
	v_mov_b32_e32 v19, v0
	v_mov_b32_e32 v20, v0
	v_mov_b32_e32 v21, v0
	v_mov_b32_e32 v22, v0
	v_mov_b32_e32 v23, v0
	v_mov_b32_e32 v24, v0
	v_mov_b32_e32 v25, v0
	v_mov_b32_e32 v26, v0
	v_mov_b32_e32 v27, v0
	v_mov_b32_e32 v28, v0
	v_mov_b32_e32 v29, v0
	v_mov_b32_e32 v30, v0
	v_mov_b32_e32 v31, v0
	v_mov_b32_e32 v32, v0
	v_mov_b32_e32 v33, v0
	v_mov_b32_e32 v34, v0
	v_mov_b32_e32 v35, v0
	v_mov_b32_e32 v36, v0
	v_mov_b32_e32 v37, v0
	v_mov_b32_e32 v38, v0
	v_mov_b32_e32 v39, v0
	v_mov_b32_e32 v40, v0
	v_mov_b32_e32 v41, v0
	v_mov_b32_e32 v42, v0
	v_mov_b32_e32 v43, v0
	v_mov_b32_e32 v44, v0
	v_mov_b32_e32 v45, v0
	v_mov_b32_e32 v46, v0
	v_mov_b32_e32 v47, v0
	v_mov_b32_e32 v48, v0
	v_mov_b32_e32 v49, v0
	v_mov_b32_e32 v50, v0
	v_mov_b32_e32 v51, v0
	v_mov_b32_e32 v52, v0
	v_mov_b32_e32 v53, v0
	v_mov_b32_e32 v54, v0
	v_mov_b32_e32 v55, v0
	v_mov_b32_e32 v56, v0
	v_mov_b32_e32 v57, v0
	v_mov_b32_e32 v58, v0
	v_mov_b32_e32 v59, v0
	v_mov_b32_e32 v60, v0
	v_mov_b32_e32 v61, v0
	v_mov_b32_e32 v62, v0
	v_mov_b32_e32 v63, v0
	v_mov_b32_e32 v64, v0
	v_mov_b32_e32 v65, v0
	v_mov_b32_e32 v66, v0
	v_mov_b32_e32 v67, v0
	v_mov_b32_e32 v68, v0
	v_mov_b32_e32 v69, v0
	v_mov_b32_e32 v70, v0
	v_mov_b32_e32 v71, v0
	v_mov_b32_e32 v72, v0
	v_mov_b32_e32 v73, v0
	v_mov_b32_e32 v74, v0
	v_mov_b32_e32 v75, v0
	v_mov_b32_e32 v76, v0
	v_mov_b32_e32 v77, v0
	v_mov_b32_e32 v78, v0
	v_mov_b32_e32 v79, v0
	v_mov_b32_e32 v80, v0
	v_mov_b32_e32 v81, v0
	v_mov_b32_e32 v82, v0
	v_mov_b32_e32 v83, v0
	v_mov_b32_e32 v84, v0
	v_mov_b32_e32 v85, v0
	v_mov_b32_e32 v86, v0
	v_mov_b32_e32 v87, v0
	v_mov_b32_e32 v88, v0
	v_mov_b32_e32 v89, v0
	v_mov_b32_e32 v90, v0
	v_mov_b32_e32 v91, v0
	v_mov_b32_e32 v92, v0
	v_mov_b32_e32 v93, v0
	v_mov_b32_e32 v94, v0
	v_mov_b32_e32 v95, v0
	v_mov_b32_e32 v96, v0
	v_mov_b32_e32 v97, v0
	v_mov_b32_e32 v98, v0
	v_mov_b32_e32 v99, v0
	v_mov_b32_e32 v100, v0
	v_mov_b32_e32 v101, v0
	v_mov_b32_e32 v102, v0
	v_mov_b32_e32 v103, v0
	v_mov_b32_e32 v104, v0
	v_mov_b32_e32 v105, v0
	v_mov_b32_e32 v106, v0
	v_mov_b32_e32 v107, v0
	v_mov_b32_e32 v108, v0
	v_mov_b32_e32 v109, v0
	v_mov_b32_e32 v110, v0
	v_mov_b32_e32 v111, v0
	v_mov_b32_e32 v112, v0
	v_mov_b32_e32 v113, v0
	v_mov_b32_e32 v114, v0
	v_mov_b32_e32 v115, v0
	v_mov_b32_e32 v116, v0
	v_mov_b32_e32 v117, v0
	v_mov_b32_e32 v118, v0
	v_mov_b32_e32 v119, v0
	v_mov_b32_e32 v120, v0
	v_mov_b32_e32 v121, v0
	v_mov_b32_e32 v122, v0
	v_mov_b32_e32 v123, v0
	v_mov_b32_e32 v124, v0
	v_mov_b32_e32 v125, v0
	v_mov_b32_e32 v126, v0
	v_mov_b32_e32 v127, v0
.Lzm_8:
	s_waitcnt vmcnt(8)
	s_waitcnt lgkmcnt(0)
	s_barrier
	s_setprio 1
	s_waitcnt lgkmcnt(0)
	v_mfma_f32_16x16x32_bf16 v[124:127], v[156:159], v[220:223], v[124:127]
	v_mfma_f32_16x16x32_bf16 v[120:123], v[164:167], v[220:223], v[120:123]
	v_mfma_f32_16x16x32_bf16 v[116:119], v[156:159], v[228:231], v[116:119]
	v_mfma_f32_16x16x32_bf16 v[112:115], v[164:167], v[228:231], v[112:115]
	v_mfma_f32_16x16x32_bf16 v[92:95], v[156:159], v[236:239], v[92:95]
	v_mfma_f32_16x16x32_bf16 v[88:91], v[164:167], v[236:239], v[88:91]
	v_mfma_f32_16x16x32_bf16 v[84:87], v[156:159], v[244:247], v[84:87]
	v_mfma_f32_16x16x32_bf16 v[80:83], v[164:167], v[244:247], v[80:83]
	v_mfma_f32_16x16x32_bf16 v[124:127], v[160:163], v[224:227], v[124:127]
	v_mfma_f32_16x16x32_bf16 v[120:123], v[168:171], v[224:227], v[120:123]
	v_mfma_f32_16x16x32_bf16 v[116:119], v[160:163], v[232:235], v[116:119]
	v_mfma_f32_16x16x32_bf16 v[112:115], v[168:171], v[232:235], v[112:115]
	v_mfma_f32_16x16x32_bf16 v[92:95], v[160:163], v[240:243], v[92:95]
	v_mfma_f32_16x16x32_bf16 v[88:91], v[168:171], v[240:243], v[88:91]
	v_mfma_f32_16x16x32_bf16 v[84:87], v[160:163], v[248:251], v[84:87]
	v_mfma_f32_16x16x32_bf16 v[80:83], v[168:171], v[248:251], v[80:83]
	s_setprio 0
	s_setprio 1
	v_mfma_f32_16x16x32_bf16 v[108:111], v[172:175], v[220:223], v[108:111]
	v_mfma_f32_16x16x32_bf16 v[104:107], v[212:215], v[220:223], v[104:107]
	v_mfma_f32_16x16x32_bf16 v[100:103], v[172:175], v[228:231], v[100:103]
	v_mfma_f32_16x16x32_bf16 v[96:99], v[212:215], v[228:231], v[96:99]
	v_mfma_f32_16x16x32_bf16 v[76:79], v[172:175], v[236:239], v[76:79]
	v_mfma_f32_16x16x32_bf16 v[72:75], v[212:215], v[236:239], v[72:75]
	v_mfma_f32_16x16x32_bf16 v[68:71], v[172:175], v[244:247], v[68:71]
	v_mfma_f32_16x16x32_bf16 v[64:67], v[212:215], v[244:247], v[64:67]
	v_mfma_f32_16x16x32_bf16 v[108:111], v[176:179], v[224:227], v[108:111]
	v_mfma_f32_16x16x32_bf16 v[104:107], v[216:219], v[224:227], v[104:107]
	v_mfma_f32_16x16x32_bf16 v[100:103], v[176:179], v[232:235], v[100:103]
	v_mfma_f32_16x16x32_bf16 v[96:99], v[216:219], v[232:235], v[96:99]
	v_mfma_f32_16x16x32_bf16 v[76:79], v[176:179], v[240:243], v[76:79]
	v_mfma_f32_16x16x32_bf16 v[72:75], v[216:219], v[240:243], v[72:75]
	v_mfma_f32_16x16x32_bf16 v[68:71], v[176:179], v[248:251], v[68:71]
	v_mfma_f32_16x16x32_bf16 v[64:67], v[216:219], v[248:251], v[64:67]
	s_setprio 0
	s_barrier
	s_add_i32 s71, s61, s47
	v_lshl_add_u64 v[204:205], s[40:41], 0, v[128:129]
	s_mov_b32 m0, s71
	ds_read_b128 v[220:223], v199 offset:16384
	ds_read_b128 v[224:227], v199 offset:17408
	ds_read_b128 v[228:231], v199 offset:18432
	ds_read_b128 v[232:235], v199 offset:19456
	ds_read_b128 v[236:239], v199 offset:20480
	ds_read_b128 v[240:243], v199 offset:21504
	ds_read_b128 v[244:247], v199 offset:22528
	ds_read_b128 v[248:251], v199 offset:23552
	global_load_lds_dwordx4 v[204:205], off
	s_add_i32 m0, s71, 0x2000
	s_add_u32 s72, s40, 0x4000
	v_lshl_add_u64 v[204:205], s[40:41], 0, v[130:131]
	s_addc_u32 s73, s41, 0
	s_add_i32 s71, s62, s47
	global_load_lds_dwordx4 v[204:205], off
	v_lshl_add_u64 v[204:205], s[72:73], 0, v[128:129]
	s_mov_b32 m0, s71
	s_nop 0
	global_load_lds_dwordx4 v[204:205], off
	v_lshl_add_u64 v[204:205], s[72:73], 0, v[130:131]
	s_add_i32 m0, s71, 0x2000
	s_nop 0
	global_load_lds_dwordx4 v[204:205], off
	v_lshl_add_u64 v[204:205], s[42:43], 0, v[128:129]
	s_mov_b32 m0, s48
	s_nop 0
	global_load_lds_dwordx4 v[204:205], off
	v_lshl_add_u64 v[204:205], s[42:43], 0, v[130:131]
	s_mov_b32 m0, s49
	s_nop 0
	global_load_lds_dwordx4 v[204:205], off
	s_waitcnt vmcnt(8)
	s_waitcnt lgkmcnt(0)
	s_barrier
	s_setprio 1
	s_waitcnt lgkmcnt(0)
	v_mfma_f32_16x16x32_bf16 v[60:63], v[156:159], v[220:223], v[60:63]
	v_mfma_f32_16x16x32_bf16 v[56:59], v[164:167], v[220:223], v[56:59]
	v_mfma_f32_16x16x32_bf16 v[52:55], v[156:159], v[228:231], v[52:55]
	v_mfma_f32_16x16x32_bf16 v[48:51], v[164:167], v[228:231], v[48:51]
	v_mfma_f32_16x16x32_bf16 v[28:31], v[156:159], v[236:239], v[28:31]
	v_mfma_f32_16x16x32_bf16 v[24:27], v[164:167], v[236:239], v[24:27]
	v_mfma_f32_16x16x32_bf16 v[20:23], v[156:159], v[244:247], v[20:23]
	v_mfma_f32_16x16x32_bf16 v[12:15], v[164:167], v[244:247], v[12:15]
	v_mfma_f32_16x16x32_bf16 v[60:63], v[160:163], v[224:227], v[60:63]
	v_mfma_f32_16x16x32_bf16 v[56:59], v[168:171], v[224:227], v[56:59]
	v_mfma_f32_16x16x32_bf16 v[52:55], v[160:163], v[232:235], v[52:55]
	v_mfma_f32_16x16x32_bf16 v[48:51], v[168:171], v[232:235], v[48:51]
	v_mfma_f32_16x16x32_bf16 v[28:31], v[160:163], v[240:243], v[28:31]
	v_mfma_f32_16x16x32_bf16 v[24:27], v[168:171], v[240:243], v[24:27]
	v_mfma_f32_16x16x32_bf16 v[20:23], v[160:163], v[248:251], v[20:23]
	v_mfma_f32_16x16x32_bf16 v[12:15], v[168:171], v[248:251], v[12:15]
	s_setprio 0
	s_setprio 1
	v_mfma_f32_16x16x32_bf16 v[44:47], v[172:175], v[220:223], v[44:47]
	v_mfma_f32_16x16x32_bf16 v[40:43], v[212:215], v[220:223], v[40:43]
	v_mfma_f32_16x16x32_bf16 v[36:39], v[172:175], v[228:231], v[36:39]
	v_mfma_f32_16x16x32_bf16 v[32:35], v[212:215], v[228:231], v[32:35]
	v_mfma_f32_16x16x32_bf16 v[16:19], v[172:175], v[236:239], v[16:19]
	v_mfma_f32_16x16x32_bf16 v[8:11], v[212:215], v[236:239], v[8:11]
	v_mfma_f32_16x16x32_bf16 v[4:7], v[172:175], v[244:247], v[4:7]
	v_mfma_f32_16x16x32_bf16 v[0:3], v[212:215], v[244:247], v[0:3]
	v_mfma_f32_16x16x32_bf16 v[44:47], v[176:179], v[224:227], v[44:47]
	v_mfma_f32_16x16x32_bf16 v[40:43], v[216:219], v[224:227], v[40:43]
	v_mfma_f32_16x16x32_bf16 v[36:39], v[176:179], v[232:235], v[36:39]
	v_mfma_f32_16x16x32_bf16 v[32:35], v[216:219], v[232:235], v[32:35]
	v_mfma_f32_16x16x32_bf16 v[16:19], v[176:179], v[240:243], v[16:19]
	v_mfma_f32_16x16x32_bf16 v[8:11], v[216:219], v[240:243], v[8:11]
	v_mfma_f32_16x16x32_bf16 v[4:7], v[176:179], v[248:251], v[4:7]
	v_mfma_f32_16x16x32_bf16 v[0:3], v[216:219], v[248:251], v[0:3]
	s_setprio 0
	s_barrier
	s_add_i32 s71, 0, 0x18000
	s_add_i32 s72, 0, 0x1c000
	v_add_u32_e32 v168, s71, v182
	v_add_u32_e32 v204, s72, v182
	ds_read_b128 v[156:159], v168
	ds_read_b128 v[160:163], v168 offset:1024
	ds_read_b128 v[164:167], v168 offset:2048
	ds_read_b128 v[168:171], v168 offset:3072
	ds_read_b128 v[172:175], v204
	ds_read_b128 v[176:179], v204 offset:1024
	ds_read_b128 v[212:215], v204 offset:2048
	ds_read_b128 v[216:219], v204 offset:3072
	s_add_u32 s42, s42, 0x4000
	s_addc_u32 s43, s43, 0
	s_mov_b32 m0, s50
	v_lshl_add_u64 v[204:205], s[42:43], 0, v[128:129]
	ds_read_b128 v[220:223], v199 offset:32768
	ds_read_b128 v[224:227], v199 offset:33792
	ds_read_b128 v[228:231], v199 offset:34816
	ds_read_b128 v[232:235], v199 offset:35840
	ds_read_b128 v[236:239], v199 offset:36864
	ds_read_b128 v[240:243], v199 offset:37888
	ds_read_b128 v[244:247], v199 offset:38912
	ds_read_b128 v[248:251], v199 offset:39936
	global_load_lds_dwordx4 v[204:205], off
	v_lshl_add_u64 v[204:205], s[42:43], 0, v[130:131]
	s_mov_b32 m0, s51
	s_nop 0
	global_load_lds_dwordx4 v[204:205], off
	s_waitcnt vmcnt(8)
	s_waitcnt lgkmcnt(0)
	s_barrier
	s_setprio 1
	s_waitcnt lgkmcnt(0)
	v_mfma_f32_16x16x32_bf16 v[124:127], v[156:159], v[220:223], v[124:127]
	v_mfma_f32_16x16x32_bf16 v[120:123], v[164:167], v[220:223], v[120:123]
	v_mfma_f32_16x16x32_bf16 v[116:119], v[156:159], v[228:231], v[116:119]
	v_mfma_f32_16x16x32_bf16 v[112:115], v[164:167], v[228:231], v[112:115]
	v_mfma_f32_16x16x32_bf16 v[92:95], v[156:159], v[236:239], v[92:95]
	v_mfma_f32_16x16x32_bf16 v[88:91], v[164:167], v[236:239], v[88:91]
	v_mfma_f32_16x16x32_bf16 v[84:87], v[156:159], v[244:247], v[84:87]
	v_mfma_f32_16x16x32_bf16 v[80:83], v[164:167], v[244:247], v[80:83]
	v_mfma_f32_16x16x32_bf16 v[124:127], v[160:163], v[224:227], v[124:127]
	v_mfma_f32_16x16x32_bf16 v[120:123], v[168:171], v[224:227], v[120:123]
	v_mfma_f32_16x16x32_bf16 v[116:119], v[160:163], v[232:235], v[116:119]
	v_mfma_f32_16x16x32_bf16 v[112:115], v[168:171], v[232:235], v[112:115]
	v_mfma_f32_16x16x32_bf16 v[92:95], v[160:163], v[240:243], v[92:95]
	v_mfma_f32_16x16x32_bf16 v[88:91], v[168:171], v[240:243], v[88:91]
	v_mfma_f32_16x16x32_bf16 v[84:87], v[160:163], v[248:251], v[84:87]
	v_mfma_f32_16x16x32_bf16 v[80:83], v[168:171], v[248:251], v[80:83]
	s_setprio 0
	s_setprio 1
	v_mfma_f32_16x16x32_bf16 v[108:111], v[172:175], v[220:223], v[108:111]
	v_mfma_f32_16x16x32_bf16 v[104:107], v[212:215], v[220:223], v[104:107]
	v_mfma_f32_16x16x32_bf16 v[100:103], v[172:175], v[228:231], v[100:103]
	v_mfma_f32_16x16x32_bf16 v[96:99], v[212:215], v[228:231], v[96:99]
	v_mfma_f32_16x16x32_bf16 v[76:79], v[172:175], v[236:239], v[76:79]
	v_mfma_f32_16x16x32_bf16 v[72:75], v[212:215], v[236:239], v[72:75]
	v_mfma_f32_16x16x32_bf16 v[68:71], v[172:175], v[244:247], v[68:71]
	v_mfma_f32_16x16x32_bf16 v[64:67], v[212:215], v[244:247], v[64:67]
	v_mfma_f32_16x16x32_bf16 v[108:111], v[176:179], v[224:227], v[108:111]
	v_mfma_f32_16x16x32_bf16 v[104:107], v[216:219], v[224:227], v[104:107]
	v_mfma_f32_16x16x32_bf16 v[100:103], v[176:179], v[232:235], v[100:103]
	v_mfma_f32_16x16x32_bf16 v[96:99], v[216:219], v[232:235], v[96:99]
	v_mfma_f32_16x16x32_bf16 v[76:79], v[176:179], v[240:243], v[76:79]
	v_mfma_f32_16x16x32_bf16 v[72:75], v[216:219], v[240:243], v[72:75]
	v_mfma_f32_16x16x32_bf16 v[68:71], v[176:179], v[248:251], v[68:71]
	v_mfma_f32_16x16x32_bf16 v[64:67], v[216:219], v[248:251], v[64:67]
	s_setprio 0
	s_barrier
	s_add_u32 s42, s40, 0x8000
	s_addc_u32 s43, s41, 0
	s_add_i32 s71, s71, s47
	v_lshl_add_u64 v[204:205], s[42:43], 0, v[128:129]
	s_mov_b32 m0, s71
	ds_read_b128 v[220:223], v199 offset:49152
	ds_read_b128 v[224:227], v199 offset:50176
	ds_read_b128 v[228:231], v199 offset:51200
	ds_read_b128 v[232:235], v199 offset:52224
	ds_read_b128 v[236:239], v199 offset:53248
	ds_read_b128 v[240:243], v199 offset:54272
	ds_read_b128 v[244:247], v199 offset:55296
	ds_read_b128 v[248:251], v199 offset:56320
	global_load_lds_dwordx4 v[204:205], off
	s_add_i32 m0, s71, 0x2000
	s_add_u32 s40, s40, 0xc000
	v_lshl_add_u64 v[204:205], s[42:43], 0, v[130:131]
	s_addc_u32 s41, s41, 0
	s_add_i32 s42, s72, s47
	global_load_lds_dwordx4 v[204:205], off
	v_lshl_add_u64 v[204:205], s[40:41], 0, v[128:129]
	s_mov_b32 m0, s42
	s_nop 0
	global_load_lds_dwordx4 v[204:205], off
	v_lshl_add_u64 v[204:205], s[40:41], 0, v[130:131]
	s_add_i32 m0, s42, 0x2000
	s_nop 0
	global_load_lds_dwordx4 v[204:205], off
	v_lshl_add_u64 v[204:205], s[38:39], 0, v[128:129]
	s_mov_b32 m0, s57
	s_nop 0
	global_load_lds_dwordx4 v[204:205], off
	v_lshl_add_u64 v[204:205], s[38:39], 0, v[130:131]
	s_mov_b32 m0, s58
	s_nop 0
	global_load_lds_dwordx4 v[204:205], off
	s_waitcnt vmcnt(8)
	s_waitcnt lgkmcnt(0)
	s_barrier
	s_setprio 1
	s_waitcnt lgkmcnt(0)
	v_mfma_f32_16x16x32_bf16 v[60:63], v[156:159], v[220:223], v[60:63]
	v_mfma_f32_16x16x32_bf16 v[56:59], v[164:167], v[220:223], v[56:59]
	v_mfma_f32_16x16x32_bf16 v[52:55], v[156:159], v[228:231], v[52:55]
	v_mfma_f32_16x16x32_bf16 v[48:51], v[164:167], v[228:231], v[48:51]
	v_mfma_f32_16x16x32_bf16 v[28:31], v[156:159], v[236:239], v[28:31]
	v_mfma_f32_16x16x32_bf16 v[24:27], v[164:167], v[236:239], v[24:27]
	v_mfma_f32_16x16x32_bf16 v[20:23], v[156:159], v[244:247], v[20:23]
	v_mfma_f32_16x16x32_bf16 v[12:15], v[164:167], v[244:247], v[12:15]
	v_mfma_f32_16x16x32_bf16 v[60:63], v[160:163], v[224:227], v[60:63]
	v_mfma_f32_16x16x32_bf16 v[56:59], v[168:171], v[224:227], v[56:59]
	v_mfma_f32_16x16x32_bf16 v[52:55], v[160:163], v[232:235], v[52:55]
	v_mfma_f32_16x16x32_bf16 v[48:51], v[168:171], v[232:235], v[48:51]
	v_mfma_f32_16x16x32_bf16 v[28:31], v[160:163], v[240:243], v[28:31]
	v_mfma_f32_16x16x32_bf16 v[24:27], v[168:171], v[240:243], v[24:27]
	v_mfma_f32_16x16x32_bf16 v[20:23], v[160:163], v[248:251], v[20:23]
	v_mfma_f32_16x16x32_bf16 v[12:15], v[168:171], v[248:251], v[12:15]
	s_setprio 0
	s_setprio 1
	v_mfma_f32_16x16x32_bf16 v[44:47], v[172:175], v[220:223], v[44:47]
	v_mfma_f32_16x16x32_bf16 v[40:43], v[212:215], v[220:223], v[40:43]
	v_mfma_f32_16x16x32_bf16 v[36:39], v[172:175], v[228:231], v[36:39]
	v_mfma_f32_16x16x32_bf16 v[32:35], v[212:215], v[228:231], v[32:35]
	v_mfma_f32_16x16x32_bf16 v[16:19], v[172:175], v[236:239], v[16:19]
	v_mfma_f32_16x16x32_bf16 v[8:11], v[212:215], v[236:239], v[8:11]
	v_mfma_f32_16x16x32_bf16 v[4:7], v[172:175], v[244:247], v[4:7]
	v_mfma_f32_16x16x32_bf16 v[0:3], v[212:215], v[244:247], v[0:3]
	v_mfma_f32_16x16x32_bf16 v[44:47], v[176:179], v[224:227], v[44:47]
	v_mfma_f32_16x16x32_bf16 v[40:43], v[216:219], v[224:227], v[40:43]
	v_mfma_f32_16x16x32_bf16 v[36:39], v[176:179], v[232:235], v[36:39]
	v_mfma_f32_16x16x32_bf16 v[32:35], v[216:219], v[232:235], v[32:35]
	v_mfma_f32_16x16x32_bf16 v[16:19], v[176:179], v[240:243], v[16:19]
	v_mfma_f32_16x16x32_bf16 v[8:11], v[216:219], v[240:243], v[8:11]
	v_mfma_f32_16x16x32_bf16 v[4:7], v[176:179], v[248:251], v[4:7]
	v_mfma_f32_16x16x32_bf16 v[0:3], v[216:219], v[248:251], v[0:3]
	s_setprio 0
	s_barrier
	s_add_i32 s70, s70, 2
	s_add_u32 s68, s68, 0x10000
	s_addc_u32 s69, s69, 0
	s_add_u32 s36, s36, 0x10000
	s_addc_u32 s37, s37, 0
	s_cmp_gt_u32 s70, 41
	s_cbranch_scc0 .LBB0_1481
	s_and_b64 vcc, exec, s[18:19]
	s_cbranch_vccz .LBB0_1484
	s_barrier

.LBB0_1562:
	s_ashr_i32 s9, s8, 31
	s_lshl_b64 s[12:13], s[8:9], 19
	s_add_u32 s12, s28, s12
	s_addc_u32 s13, s29, s13
	s_cmp_eq_u32 s53, 2
	s_cselect_b32 s55, 0x40000, 0
	s_add_u32 s12, s12, s55
	s_addc_u32 s13, s13, 0
	s_and_b64 s[14:15], s[0:1], exec
	s_cselect_b32 s9, s13, s23
	s_cselect_b32 s45, s12, s22
	s_ashr_i32 s11, s10, 31
	s_lshl_b64 s[14:15], s[10:11], 19
	s_add_u32 s14, s30, s14
	s_addc_u32 s15, s31, s15
	s_and_b64 s[24:25], s[0:1], exec
	s_cselect_b32 s11, s15, s21
	s_cselect_b32 s46, s14, s20
	s_add_u32 s47, s20, 0x10000
	s_addc_u32 s48, s21, 0
	s_add_u32 s20, s22, 0x40080
	s_addc_u32 s21, s23, 0
	s_mov_b32 s49, -2
.LBB0_1563:
	ds_read_b128 v[168:171], v165
	ds_read_b128 v[172:175], v165 offset:1024
	ds_read_b128 v[176:179], v165 offset:2048
	ds_read_b128 v[180:183], v165 offset:3072
	ds_read_b128 v[184:187], v166
	ds_read_b128 v[188:191], v166 offset:1024
	ds_read_b128 v[192:195], v166 offset:2048
	ds_read_b128 v[196:199], v166 offset:3072
	s_add_u32 s22, s20, 0xfffc0080
	s_addc_u32 s23, s21, -1
	s_cmp_eq_u32 s49, 12
	s_cselect_b32 s25, s9, s23
	s_cselect_b32 s24, s45, s22
	s_cselect_b32 s23, s11, s48
	s_cselect_b32 s22, s46, s47
	v_lshl_add_u64 v[162:163], s[20:21], 0, v[156:157]
	s_add_i32 m0, s17, 0xc000
	ds_read_b128 v[210:213], v167
	ds_read_b128 v[214:217], v167 offset:1024
	ds_read_b128 v[218:221], v167 offset:2048
	ds_read_b128 v[222:225], v167 offset:3072
	ds_read_b128 v[226:229], v167 offset:4096
	ds_read_b128 v[230:233], v167 offset:5120
	ds_read_b128 v[234:237], v167 offset:6144
	ds_read_b128 v[238:241], v167 offset:7168
	global_load_lds_dwordx4 v[162:163], off
	v_lshl_add_u64 v[162:163], s[20:21], 0, v[154:155]
	s_add_i32 m0, s17, 0xe000
	s_nop 0
	global_load_lds_dwordx4 v[162:163], off
	s_cmp_lg_u32 s49, -2
	s_cbranch_scc1 .Lzm_7
	v_mov_b32_e32 v0, 0
	v_mov_b32_e32 v1, v0
	v_mov_b32_e32 v2, v0
	v_mov_b32_e32 v3, v0
	v_mov_b32_e32 v4, v0
	v_mov_b32_e32 v5, v0
	v_mov_b32_e32 v6, v0
	v_mov_b32_e32 v7, v0
	v_mov_b32_e32 v8, v0
	v_mov_b32_e32 v9, v0
	v_mov_b32_e32 v10, v0
	v_mov_b32_e32 v11, v0
	v_mov_b32_e32 v12, v0
	v_mov_b32_e32 v13, v0
	v_mov_b32_e32 v14, v0
	v_mov_b32_e32 v15, v0
	v_mov_b32_e32 v16, v0
	v_mov_b32_e32 v17, v0
	v_mov_b32_e32 v18, v0
	v_mov_b32_e32 v19, v0
	v_mov_b32_e32 v20, v0
	v_mov_b32_e32 v21, v0
	v_mov_b32_e32 v22, v0
	v_mov_b32_e32 v23, v0
	v_mov_b32_e32 v24, v0
	v_mov_b32_e32 v25, v0
	v_mov_b32_e32 v26, v0
	v_mov_b32_e32 v27, v0
	v_mov_b32_e32 v28, v0
	v_mov_b32_e32 v29, v0
	v_mov_b32_e32 v30, v0
	v_mov_b32_e32 v31, v0
	v_mov_b32_e32 v32, v0
	v_mov_b32_e32 v33, v0
	v_mov_b32_e32 v34, v0
	v_mov_b32_e32 v35, v0
	v_mov_b32_e32 v36, v0
	v_mov_b32_e32 v37, v0
	v_mov_b32_e32 v38, v0
	v_mov_b32_e32 v39, v0
	v_mov_b32_e32 v40, v0
	v_mov_b32_e32 v41, v0
	v_mov_b32_e32 v42, v0
	v_mov_b32_e32 v43, v0
	v_mov_b32_e32 v44, v0
	v_mov_b32_e32 v45, v0
	v_mov_b32_e32 v46, v0
	v_mov_b32_e32 v47, v0
	v_mov_b32_e32 v48, v0
	v_mov_b32_e32 v49, v0
	v_mov_b32_e32 v50, v0
	v_mov_b32_e32 v51, v0
	v_mov_b32_e32 v52, v0
	v_mov_b32_e32 v53, v0
	v_mov_b32_e32 v54, v0
	v_mov_b32_e32 v55, v0
	v_mov_b32_e32 v56, v0
	v_mov_b32_e32 v57, v0
	v_mov_b32_e32 v58, v0
	v_mov_b32_e32 v59, v0
	v_mov_b32_e32 v60, v0
	v_mov_b32_e32 v61, v0
	v_mov_b32_e32 v62, v0
	v_mov_b32_e32 v63, v0
	v_mov_b32_e32 v64, v0
	v_mov_b32_e32 v65, v0
	v_mov_b32_e32 v66, v0
	v_mov_b32_e32 v67, v0
	v_mov_b32_e32 v68, v0
	v_mov_b32_e32 v69, v0
	v_mov_b32_e32 v70, v0
	v_mov_b32_e32 v71, v0
	v_mov_b32_e32 v72, v0
	v_mov_b32_e32 v73, v0
	v_mov_b32_e32 v74, v0
	v_mov_b32_e32 v75, v0
	v_mov_b32_e32 v76, v0
	v_mov_b32_e32 v77, v0
	v_mov_b32_e32 v78, v0
	v_mov_b32_e32 v79, v0
	v_mov_b32_e32 v80, v0
	v_mov_b32_e32 v81, v0
	v_mov_b32_e32 v82, v0
	v_mov_b32_e32 v83, v0
	v_mov_b32_e32 v84, v0
	v_mov_b32_e32 v85, v0
	v_mov_b32_e32 v86, v0
	v_mov_b32_e32 v87, v0
	v_mov_b32_e32 v88, v0
	v_mov_b32_e32 v89, v0
	v_mov_b32_e32 v90, v0
	v_mov_b32_e32 v91, v0
	v_mov_b32_e32 v92, v0
	v_mov_b32_e32 v93, v0
	v_mov_b32_e32 v94, v0
	v_mov_b32_e32 v95, v0
	v_mov_b32_e32 v96, v0
	v_mov_b32_e32 v97, v0
	v_mov_b32_e32 v98, v0
	v_mov_b32_e32 v99, v0
	v_mov_b32_e32 v100, v0
	v_mov_b32_e32 v101, v0
	v_mov_b32_e32 v102, v0
	v_mov_b32_e32 v103, v0
	v_mov_b32_e32 v104, v0
	v_mov_b32_e32 v105, v0
	v_mov_b32_e32 v106, v0
	v_mov_b32_e32 v107, v0
	v_mov_b32_e32 v108, v0
	v_mov_b32_e32 v109, v0
	v_mov_b32_e32 v110, v0
	v_mov_b32_e32 v111, v0
	v_mov_b32_e32 v112, v0
	v_mov_b32_e32 v113, v0
	v_mov_b32_e32 v114, v0
	v_mov_b32_e32 v115, v0
	v_mov_b32_e32 v116, v0
	v_mov_b32_e32 v117, v0
	v_mov_b32_e32 v118, v0
	v_mov_b32_e32 v119, v0
	v_mov_b32_e32 v120, v0
	v_mov_b32_e32 v121, v0
	v_mov_b32_e32 v122, v0
	v_mov_b32_e32 v123, v0
	v_mov_b32_e32 v124, v0
	v_mov_b32_e32 v125, v0
	v_mov_b32_e32 v126, v0
	v_mov_b32_e32 v127, v0
.Lzm_7:
	s_waitcnt vmcnt(8)
	s_waitcnt lgkmcnt(0)
	s_barrier
	s_setprio 1
	s_waitcnt lgkmcnt(0)
	v_mfma_f32_16x16x32_bf16 v[124:127], v[168:171], v[210:213], v[124:127]
	v_mfma_f32_16x16x32_bf16 v[116:119], v[176:179], v[210:213], v[116:119]
	v_mfma_f32_16x16x32_bf16 v[108:111], v[168:171], v[218:221], v[108:111]
	v_mfma_f32_16x16x32_bf16 v[100:103], v[176:179], v[218:221], v[100:103]
	v_mfma_f32_16x16x32_bf16 v[92:95], v[168:171], v[226:229], v[92:95]
	v_mfma_f32_16x16x32_bf16 v[84:87], v[176:179], v[226:229], v[84:87]
	v_mfma_f32_16x16x32_bf16 v[76:79], v[168:171], v[234:237], v[76:79]
	v_mfma_f32_16x16x32_bf16 v[68:71], v[176:179], v[234:237], v[68:71]
	v_mfma_f32_16x16x32_bf16 v[124:127], v[172:175], v[214:217], v[124:127]
	v_mfma_f32_16x16x32_bf16 v[116:119], v[180:183], v[214:217], v[116:119]
	v_mfma_f32_16x16x32_bf16 v[108:111], v[172:175], v[222:225], v[108:111]
	v_mfma_f32_16x16x32_bf16 v[100:103], v[180:183], v[222:225], v[100:103]
	v_mfma_f32_16x16x32_bf16 v[92:95], v[172:175], v[230:233], v[92:95]
	v_mfma_f32_16x16x32_bf16 v[84:87], v[180:183], v[230:233], v[84:87]
	v_mfma_f32_16x16x32_bf16 v[76:79], v[172:175], v[238:241], v[76:79]
	v_mfma_f32_16x16x32_bf16 v[68:71], v[180:183], v[238:241], v[68:71]
	s_setprio 0
	s_setprio 1
	v_mfma_f32_16x16x32_bf16 v[120:123], v[184:187], v[210:213], v[120:123]
	v_mfma_f32_16x16x32_bf16 v[112:115], v[192:195], v[210:213], v[112:115]
	v_mfma_f32_16x16x32_bf16 v[104:107], v[184:187], v[218:221], v[104:107]
	v_mfma_f32_16x16x32_bf16 v[96:99], v[192:195], v[218:221], v[96:99]
	v_mfma_f32_16x16x32_bf16 v[88:91], v[184:187], v[226:229], v[88:91]
	v_mfma_f32_16x16x32_bf16 v[80:83], v[192:195], v[226:229], v[80:83]
	v_mfma_f32_16x16x32_bf16 v[72:75], v[184:187], v[234:237], v[72:75]
	v_mfma_f32_16x16x32_bf16 v[64:67], v[192:195], v[234:237], v[64:67]
	v_mfma_f32_16x16x32_bf16 v[120:123], v[188:191], v[214:217], v[120:123]
	v_mfma_f32_16x16x32_bf16 v[112:115], v[196:199], v[214:217], v[112:115]
	v_mfma_f32_16x16x32_bf16 v[104:107], v[188:191], v[222:225], v[104:107]
	v_mfma_f32_16x16x32_bf16 v[96:99], v[196:199], v[222:225], v[96:99]
	v_mfma_f32_16x16x32_bf16 v[88:91], v[188:191], v[230:233], v[88:91]
	v_mfma_f32_16x16x32_bf16 v[80:83], v[196:199], v[230:233], v[80:83]
	v_mfma_f32_16x16x32_bf16 v[72:75], v[188:191], v[238:241], v[72:75]
	v_mfma_f32_16x16x32_bf16 v[64:67], v[196:199], v[238:241], v[64:67]
	s_setprio 0
	s_barrier
	s_add_i32 s50, s43, s33
	v_lshl_add_u64 v[162:163], s[22:23], 0, v[132:133]
	s_mov_b32 m0, s50
	s_cmp_lg_u32 s54, 0
	s_cbranch_scc1 .Lts0_skip1
	ds_read_b128 v[210:213], v167 offset:16384
	ds_read_b128 v[214:217], v167 offset:17408
	ds_read_b128 v[218:221], v167 offset:18432
	ds_read_b128 v[222:225], v167 offset:19456
	ds_read_b128 v[226:229], v167 offset:20480
	ds_read_b128 v[230:233], v167 offset:21504
	ds_read_b128 v[234:237], v167 offset:22528
	ds_read_b128 v[238:241], v167 offset:23552

.LBB0_1644:
	s_add_u32 s45, s36, 0x10000
	s_addc_u32 s46, s37, 0
	s_add_u32 s36, s38, 0xc000
	s_addc_u32 s37, s39, 0
	s_mov_b32 s47, -2
.LBB0_1645:
	v_add_u32_e32 v168, s69, v182
	v_add_u32_e32 v204, s70, v182
	ds_read_b128 v[156:159], v168
	ds_read_b128 v[160:163], v168 offset:1024
	ds_read_b128 v[164:167], v168 offset:2048
	ds_read_b128 v[168:171], v168 offset:3072
	ds_read_b128 v[172:175], v204
	ds_read_b128 v[176:179], v204 offset:1024
	ds_read_b128 v[212:215], v204 offset:2048
	ds_read_b128 v[216:219], v204 offset:3072
	s_add_u32 s38, s36, 0x4000
	s_addc_u32 s39, s37, 0
	s_cmp_eq_u32 s47, 40
	s_cselect_b32 s42, s0, s38
	s_cselect_b32 s43, s1, s39
	s_cselect_b32 s40, s34, s45
	s_cselect_b32 s41, s35, s46
	s_add_u32 s38, s42, 0x8000
	s_addc_u32 s39, s43, 0
	v_lshl_add_u64 v[204:205], s[36:37], 0, v[150:151]
	s_add_i32 m0, s56, 0xc000
	ds_read_b128 v[220:223], v199
	ds_read_b128 v[224:227], v199 offset:1024
	ds_read_b128 v[228:231], v199 offset:2048
	ds_read_b128 v[232:235], v199 offset:3072
	ds_read_b128 v[236:239], v199 offset:4096
	ds_read_b128 v[240:243], v199 offset:5120
	ds_read_b128 v[244:247], v199 offset:6144
	ds_read_b128 v[248:251], v199 offset:7168
	global_load_lds_dwordx4 v[204:205], off
	v_lshl_add_u64 v[204:205], s[36:37], 0, v[148:149]
	s_add_i32 m0, s56, 0xe000
	s_nop 0
	global_load_lds_dwordx4 v[204:205], off
	s_cmp_lg_u32 s47, -2
	s_cbranch_scc1 .Lzm_6
	v_mov_b32_e32 v0, 0
	v_mov_b32_e32 v1, v0
	v_mov_b32_e32 v2, v0
	v_mov_b32_e32 v3, v0
	v_mov_b32_e32 v4, v0
	v_mov_b32_e32 v5, v0
	v_mov_b32_e32 v6, v0
	v_mov_b32_e32 v7, v0
	v_mov_b32_e32 v8, v0
	v_mov_b32_e32 v9, v0
	v_mov_b32_e32 v10, v0
	v_mov_b32_e32 v11, v0
	v_mov_b32_e32 v12, v0
	v_mov_b32_e32 v13, v0
	v_mov_b32_e32 v14, v0
	v_mov_b32_e32 v15, v0
	v_mov_b32_e32 v16, v0
	v_mov_b32_e32 v17, v0
	v_mov_b32_e32 v18, v0
	v_mov_b32_e32 v19, v0
	v_mov_b32_e32 v20, v0
	v_mov_b32_e32 v21, v0
	v_mov_b32_e32 v22, v0
	v_mov_b32_e32 v23, v0
	v_mov_b32_e32 v24, v0
	v_mov_b32_e32 v25, v0
	v_mov_b32_e32 v26, v0
	v_mov_b32_e32 v27, v0
	v_mov_b32_e32 v28, v0
	v_mov_b32_e32 v29, v0
	v_mov_b32_e32 v30, v0
	v_mov_b32_e32 v31, v0
	v_mov_b32_e32 v32, v0
	v_mov_b32_e32 v33, v0
	v_mov_b32_e32 v34, v0
	v_mov_b32_e32 v35, v0
	v_mov_b32_e32 v36, v0
	v_mov_b32_e32 v37, v0
	v_mov_b32_e32 v38, v0
	v_mov_b32_e32 v39, v0
	v_mov_b32_e32 v40, v0
	v_mov_b32_e32 v41, v0
	v_mov_b32_e32 v42, v0
	v_mov_b32_e32 v43, v0
	v_mov_b32_e32 v44, v0
	v_mov_b32_e32 v45, v0
	v_mov_b32_e32 v46, v0
	v_mov_b32_e32 v47, v0
	v_mov_b32_e32 v48, v0
	v_mov_b32_e32 v49, v0
	v_mov_b32_e32 v50, v0
	v_mov_b32_e32 v51, v0
	v_mov_b32_e32 v52, v0
	v_mov_b32_e32 v53, v0
	v_mov_b32_e32 v54, v0
	v_mov_b32_e32 v55, v0
	v_mov_b32_e32 v56, v0
	v_mov_b32_e32 v57, v0
	v_mov_b32_e32 v58, v0
	v_mov_b32_e32 v59, v0
	v_mov_b32_e32 v60, v0
	v_mov_b32_e32 v61, v0
	v_mov_b32_e32 v62, v0
	v_mov_b32_e32 v63, v0
	v_mov_b32_e32 v64, v0
	v_mov_b32_e32 v65, v0
	v_mov_b32_e32 v66, v0
	v_mov_b32_e32 v67, v0
	v_mov_b32_e32 v68, v0
	v_mov_b32_e32 v69, v0
	v_mov_b32_e32 v70, v0
	v_mov_b32_e32 v71, v0
	v_mov_b32_e32 v72, v0
	v_mov_b32_e32 v73, v0
	v_mov_b32_e32 v74, v0
	v_mov_b32_e32 v75, v0
	v_mov_b32_e32 v76, v0
	v_mov_b32_e32 v77, v0
	v_mov_b32_e32 v78, v0
	v_mov_b32_e32 v79, v0
	v_mov_b32_e32 v80, v0
	v_mov_b32_e32 v81, v0
	v_mov_b32_e32 v82, v0
	v_mov_b32_e32 v83, v0
	v_mov_b32_e32 v84, v0
	v_mov_b32_e32 v85, v0
	v_mov_b32_e32 v86, v0
	v_mov_b32_e32 v87, v0
	v_mov_b32_e32 v88, v0
	v_mov_b32_e32 v89, v0
	v_mov_b32_e32 v90, v0
	v_mov_b32_e32 v91, v0
	v_mov_b32_e32 v92, v0
	v_mov_b32_e32 v93, v0
	v_mov_b32_e32 v94, v0
	v_mov_b32_e32 v95, v0
	v_mov_b32_e32 v96, v0
	v_mov_b32_e32 v97, v0
	v_mov_b32_e32 v98, v0
	v_mov_b32_e32 v99, v0
	v_mov_b32_e32 v100, v0
	v_mov_b32_e32 v101, v0
	v_mov_b32_e32 v102, v0
	v_mov_b32_e32 v103, v0
	v_mov_b32_e32 v104, v0
	v_mov_b32_e32 v105, v0
	v_mov_b32_e32 v106, v0
	v_mov_b32_e32 v107, v0
	v_mov_b32_e32 v108, v0
	v_mov_b32_e32 v109, v0
	v_mov_b32_e32 v110, v0
	v_mov_b32_e32 v111, v0
	v_mov_b32_e32 v112, v0
	v_mov_b32_e32 v113, v0
	v_mov_b32_e32 v114, v0
	v_mov_b32_e32 v115, v0
	v_mov_b32_e32 v116, v0
	v_mov_b32_e32 v117, v0
	v_mov_b32_e32 v118, v0
	v_mov_b32_e32 v119, v0
	v_mov_b32_e32 v120, v0
	v_mov_b32_e32 v121, v0
	v_mov_b32_e32 v122, v0
	v_mov_b32_e32 v123, v0
	v_mov_b32_e32 v124, v0
	v_mov_b32_e32 v125, v0
	v_mov_b32_e32 v126, v0
	v_mov_b32_e32 v127, v0
.Lzm_6:
	s_waitcnt vmcnt(8)
	s_waitcnt lgkmcnt(0)
	s_barrier
	s_setprio 1
	s_waitcnt lgkmcnt(0)
	v_mfma_f32_16x16x32_bf16 v[124:127], v[156:159], v[220:223], v[124:127]
	v_mfma_f32_16x16x32_bf16 v[120:123], v[164:167], v[220:223], v[120:123]
	v_mfma_f32_16x16x32_bf16 v[116:119], v[156:159], v[228:231], v[116:119]
	v_mfma_f32_16x16x32_bf16 v[112:115], v[164:167], v[228:231], v[112:115]
	v_mfma_f32_16x16x32_bf16 v[92:95], v[156:159], v[236:239], v[92:95]
	v_mfma_f32_16x16x32_bf16 v[88:91], v[164:167], v[236:239], v[88:91]
	v_mfma_f32_16x16x32_bf16 v[84:87], v[156:159], v[244:247], v[84:87]
	v_mfma_f32_16x16x32_bf16 v[80:83], v[164:167], v[244:247], v[80:83]
	v_mfma_f32_16x16x32_bf16 v[124:127], v[160:163], v[224:227], v[124:127]
	v_mfma_f32_16x16x32_bf16 v[120:123], v[168:171], v[224:227], v[120:123]
	v_mfma_f32_16x16x32_bf16 v[116:119], v[160:163], v[232:235], v[116:119]
	v_mfma_f32_16x16x32_bf16 v[112:115], v[168:171], v[232:235], v[112:115]
	v_mfma_f32_16x16x32_bf16 v[92:95], v[160:163], v[240:243], v[92:95]
	v_mfma_f32_16x16x32_bf16 v[88:91], v[168:171], v[240:243], v[88:91]
	v_mfma_f32_16x16x32_bf16 v[84:87], v[160:163], v[248:251], v[84:87]
	v_mfma_f32_16x16x32_bf16 v[80:83], v[168:171], v[248:251], v[80:83]
	s_setprio 0
	s_setprio 1
	v_mfma_f32_16x16x32_bf16 v[108:111], v[172:175], v[220:223], v[108:111]
	v_mfma_f32_16x16x32_bf16 v[104:107], v[212:215], v[220:223], v[104:107]
	v_mfma_f32_16x16x32_bf16 v[100:103], v[172:175], v[228:231], v[100:103]
	v_mfma_f32_16x16x32_bf16 v[96:99], v[212:215], v[228:231], v[96:99]
	v_mfma_f32_16x16x32_bf16 v[76:79], v[172:175], v[236:239], v[76:79]
	v_mfma_f32_16x16x32_bf16 v[72:75], v[212:215], v[236:239], v[72:75]
	v_mfma_f32_16x16x32_bf16 v[68:71], v[172:175], v[244:247], v[68:71]
	v_mfma_f32_16x16x32_bf16 v[64:67], v[212:215], v[244:247], v[64:67]
	v_mfma_f32_16x16x32_bf16 v[108:111], v[176:179], v[224:227], v[108:111]
	v_mfma_f32_16x16x32_bf16 v[104:107], v[216:219], v[224:227], v[104:107]
	v_mfma_f32_16x16x32_bf16 v[100:103], v[176:179], v[232:235], v[100:103]
	v_mfma_f32_16x16x32_bf16 v[96:99], v[216:219], v[232:235], v[96:99]
	v_mfma_f32_16x16x32_bf16 v[76:79], v[176:179], v[240:243], v[76:79]
	v_mfma_f32_16x16x32_bf16 v[72:75], v[216:219], v[240:243], v[72:75]
	v_mfma_f32_16x16x32_bf16 v[68:71], v[176:179], v[248:251], v[68:71]
	v_mfma_f32_16x16x32_bf16 v[64:67], v[216:219], v[248:251], v[64:67]
	s_setprio 0
	s_barrier
	s_add_i32 s48, s69, s55
	v_lshl_add_u64 v[204:205], s[40:41], 0, v[128:129]
	s_mov_b32 m0, s48
	ds_read_b128 v[220:223], v199 offset:16384
	ds_read_b128 v[224:227], v199 offset:17408
	ds_read_b128 v[228:231], v199 offset:18432
	ds_read_b128 v[232:235], v199 offset:19456
	ds_read_b128 v[236:239], v199 offset:20480
	ds_read_b128 v[240:243], v199 offset:21504
	ds_read_b128 v[244:247], v199 offset:22528
	ds_read_b128 v[248:251], v199 offset:23552
	global_load_lds_dwordx4 v[204:205], off
	s_add_i32 m0, s48, 0x2000
	s_add_u32 s48, s40, 0x4000
	v_lshl_add_u64 v[204:205], s[40:41], 0, v[130:131]
	s_addc_u32 s49, s41, 0
	s_add_i32 s50, s70, s55
	global_load_lds_dwordx4 v[204:205], off
	v_lshl_add_u64 v[204:205], s[48:49], 0, v[128:129]
	s_mov_b32 m0, s50
	s_nop 0
	global_load_lds_dwordx4 v[204:205], off
	v_lshl_add_u64 v[204:205], s[48:49], 0, v[130:131]
	s_add_i32 m0, s50, 0x2000
	s_nop 0
	global_load_lds_dwordx4 v[204:205], off
	v_lshl_add_u64 v[204:205], s[42:43], 0, v[128:129]
	s_mov_b32 m0, s56
	s_nop 0
	global_load_lds_dwordx4 v[204:205], off
	v_lshl_add_u64 v[204:205], s[42:43], 0, v[130:131]
	s_mov_b32 m0, s57
	s_nop 0
	global_load_lds_dwordx4 v[204:205], off
	s_waitcnt vmcnt(8)
	s_waitcnt lgkmcnt(0)
	s_barrier
	s_setprio 1
	s_waitcnt lgkmcnt(0)
	v_mfma_f32_16x16x32_bf16 v[60:63], v[156:159], v[220:223], v[60:63]
	v_mfma_f32_16x16x32_bf16 v[56:59], v[164:167], v[220:223], v[56:59]
	v_mfma_f32_16x16x32_bf16 v[52:55], v[156:159], v[228:231], v[52:55]
	v_mfma_f32_16x16x32_bf16 v[48:51], v[164:167], v[228:231], v[48:51]
	v_mfma_f32_16x16x32_bf16 v[28:31], v[156:159], v[236:239], v[28:31]
	v_mfma_f32_16x16x32_bf16 v[24:27], v[164:167], v[236:239], v[24:27]
	v_mfma_f32_16x16x32_bf16 v[20:23], v[156:159], v[244:247], v[20:23]
	v_mfma_f32_16x16x32_bf16 v[12:15], v[164:167], v[244:247], v[12:15]
	v_mfma_f32_16x16x32_bf16 v[60:63], v[160:163], v[224:227], v[60:63]
	v_mfma_f32_16x16x32_bf16 v[56:59], v[168:171], v[224:227], v[56:59]
	v_mfma_f32_16x16x32_bf16 v[52:55], v[160:163], v[232:235], v[52:55]
	v_mfma_f32_16x16x32_bf16 v[48:51], v[168:171], v[232:235], v[48:51]
	v_mfma_f32_16x16x32_bf16 v[28:31], v[160:163], v[240:243], v[28:31]
	v_mfma_f32_16x16x32_bf16 v[24:27], v[168:171], v[240:243], v[24:27]
	v_mfma_f32_16x16x32_bf16 v[20:23], v[160:163], v[248:251], v[20:23]
	v_mfma_f32_16x16x32_bf16 v[12:15], v[168:171], v[248:251], v[12:15]
	s_setprio 0
	s_setprio 1
	v_mfma_f32_16x16x32_bf16 v[44:47], v[172:175], v[220:223], v[44:47]
	v_mfma_f32_16x16x32_bf16 v[40:43], v[212:215], v[220:223], v[40:43]
	v_mfma_f32_16x16x32_bf16 v[36:39], v[172:175], v[228:231], v[36:39]
	v_mfma_f32_16x16x32_bf16 v[32:35], v[212:215], v[228:231], v[32:35]
	v_mfma_f32_16x16x32_bf16 v[16:19], v[172:175], v[236:239], v[16:19]
	v_mfma_f32_16x16x32_bf16 v[8:11], v[212:215], v[236:239], v[8:11]
	v_mfma_f32_16x16x32_bf16 v[4:7], v[172:175], v[244:247], v[4:7]
	v_mfma_f32_16x16x32_bf16 v[0:3], v[212:215], v[244:247], v[0:3]
	v_mfma_f32_16x16x32_bf16 v[44:47], v[176:179], v[224:227], v[44:47]
	v_mfma_f32_16x16x32_bf16 v[40:43], v[216:219], v[224:227], v[40:43]
	v_mfma_f32_16x16x32_bf16 v[36:39], v[176:179], v[232:235], v[36:39]
	v_mfma_f32_16x16x32_bf16 v[32:35], v[216:219], v[232:235], v[32:35]
	v_mfma_f32_16x16x32_bf16 v[16:19], v[176:179], v[240:243], v[16:19]
	v_mfma_f32_16x16x32_bf16 v[8:11], v[216:219], v[240:243], v[8:11]
	v_mfma_f32_16x16x32_bf16 v[4:7], v[176:179], v[248:251], v[4:7]
	v_mfma_f32_16x16x32_bf16 v[0:3], v[216:219], v[248:251], v[0:3]
	s_setprio 0
	s_barrier
	s_add_i32 s48, 0, 0x18000
	s_add_i32 s49, 0, 0x1c000
	v_add_u32_e32 v168, s48, v182
	v_add_u32_e32 v204, s49, v182
	ds_read_b128 v[156:159], v168
	ds_read_b128 v[160:163], v168 offset:1024
	ds_read_b128 v[164:167], v168 offset:2048
	ds_read_b128 v[168:171], v168 offset:3072
	ds_read_b128 v[172:175], v204
	ds_read_b128 v[176:179], v204 offset:1024
	ds_read_b128 v[212:215], v204 offset:2048
	ds_read_b128 v[216:219], v204 offset:3072
	s_add_u32 s42, s42, 0x4000
	s_addc_u32 s43, s43, 0
	s_mov_b32 m0, s58
	v_lshl_add_u64 v[204:205], s[42:43], 0, v[128:129]
	ds_read_b128 v[220:223], v199 offset:32768
	ds_read_b128 v[224:227], v199 offset:33792
	ds_read_b128 v[228:231], v199 offset:34816
	ds_read_b128 v[232:235], v199 offset:35840
	ds_read_b128 v[236:239], v199 offset:36864
	ds_read_b128 v[240:243], v199 offset:37888
	ds_read_b128 v[244:247], v199 offset:38912
	ds_read_b128 v[248:251], v199 offset:39936
	global_load_lds_dwordx4 v[204:205], off
	v_lshl_add_u64 v[204:205], s[42:43], 0, v[130:131]
	s_mov_b32 m0, s59
	s_nop 0
	global_load_lds_dwordx4 v[204:205], off
	s_waitcnt vmcnt(8)
	s_waitcnt lgkmcnt(0)
	s_barrier
	s_setprio 1
	s_waitcnt lgkmcnt(0)
	v_mfma_f32_16x16x32_bf16 v[124:127], v[156:159], v[220:223], v[124:127]
	v_mfma_f32_16x16x32_bf16 v[120:123], v[164:167], v[220:223], v[120:123]
	v_mfma_f32_16x16x32_bf16 v[116:119], v[156:159], v[228:231], v[116:119]
	v_mfma_f32_16x16x32_bf16 v[112:115], v[164:167], v[228:231], v[112:115]
	v_mfma_f32_16x16x32_bf16 v[92:95], v[156:159], v[236:239], v[92:95]
	v_mfma_f32_16x16x32_bf16 v[88:91], v[164:167], v[236:239], v[88:91]
	v_mfma_f32_16x16x32_bf16 v[84:87], v[156:159], v[244:247], v[84:87]
	v_mfma_f32_16x16x32_bf16 v[80:83], v[164:167], v[244:247], v[80:83]
	v_mfma_f32_16x16x32_bf16 v[124:127], v[160:163], v[224:227], v[124:127]
	v_mfma_f32_16x16x32_bf16 v[120:123], v[168:171], v[224:227], v[120:123]
	v_mfma_f32_16x16x32_bf16 v[116:119], v[160:163], v[232:235], v[116:119]
	v_mfma_f32_16x16x32_bf16 v[112:115], v[168:171], v[232:235], v[112:115]
	v_mfma_f32_16x16x32_bf16 v[92:95], v[160:163], v[240:243], v[92:95]
	v_mfma_f32_16x16x32_bf16 v[88:91], v[168:171], v[240:243], v[88:91]
	v_mfma_f32_16x16x32_bf16 v[84:87], v[160:163], v[248:251], v[84:87]
	v_mfma_f32_16x16x32_bf16 v[80:83], v[168:171], v[248:251], v[80:83]
	s_setprio 0
	s_setprio 1
	v_mfma_f32_16x16x32_bf16 v[108:111], v[172:175], v[220:223], v[108:111]
	v_mfma_f32_16x16x32_bf16 v[104:107], v[212:215], v[220:223], v[104:107]
	v_mfma_f32_16x16x32_bf16 v[100:103], v[172:175], v[228:231], v[100:103]
	v_mfma_f32_16x16x32_bf16 v[96:99], v[212:215], v[228:231], v[96:99]
	v_mfma_f32_16x16x32_bf16 v[76:79], v[172:175], v[236:239], v[76:79]
	v_mfma_f32_16x16x32_bf16 v[72:75], v[212:215], v[236:239], v[72:75]
	v_mfma_f32_16x16x32_bf16 v[68:71], v[172:175], v[244:247], v[68:71]
	v_mfma_f32_16x16x32_bf16 v[64:67], v[212:215], v[244:247], v[64:67]
	v_mfma_f32_16x16x32_bf16 v[108:111], v[176:179], v[224:227], v[108:111]
	v_mfma_f32_16x16x32_bf16 v[104:107], v[216:219], v[224:227], v[104:107]
	v_mfma_f32_16x16x32_bf16 v[100:103], v[176:179], v[232:235], v[100:103]
	v_mfma_f32_16x16x32_bf16 v[96:99], v[216:219], v[232:235], v[96:99]
	v_mfma_f32_16x16x32_bf16 v[76:79], v[176:179], v[240:243], v[76:79]
	v_mfma_f32_16x16x32_bf16 v[72:75], v[216:219], v[240:243], v[72:75]
	v_mfma_f32_16x16x32_bf16 v[68:71], v[176:179], v[248:251], v[68:71]
	v_mfma_f32_16x16x32_bf16 v[64:67], v[216:219], v[248:251], v[64:67]
	s_setprio 0
	s_barrier
	s_add_u32 s42, s40, 0x8000
	s_addc_u32 s43, s41, 0
	s_add_i32 s48, s48, s55
	v_lshl_add_u64 v[204:205], s[42:43], 0, v[128:129]
	s_mov_b32 m0, s48
	ds_read_b128 v[220:223], v199 offset:49152
	ds_read_b128 v[224:227], v199 offset:50176
	ds_read_b128 v[228:231], v199 offset:51200
	ds_read_b128 v[232:235], v199 offset:52224
	ds_read_b128 v[236:239], v199 offset:53248
	ds_read_b128 v[240:243], v199 offset:54272
	ds_read_b128 v[244:247], v199 offset:55296
	ds_read_b128 v[248:251], v199 offset:56320
	global_load_lds_dwordx4 v[204:205], off
	s_add_i32 m0, s48, 0x2000
	s_add_u32 s40, s40, 0xc000
	v_lshl_add_u64 v[204:205], s[42:43], 0, v[130:131]
	s_addc_u32 s41, s41, 0
	s_add_i32 s42, s49, s55
	global_load_lds_dwordx4 v[204:205], off
	v_lshl_add_u64 v[204:205], s[40:41], 0, v[128:129]
	s_mov_b32 m0, s42
	s_nop 0
	global_load_lds_dwordx4 v[204:205], off
	v_lshl_add_u64 v[204:205], s[40:41], 0, v[130:131]
	s_add_i32 m0, s42, 0x2000
	s_nop 0
	global_load_lds_dwordx4 v[204:205], off
	v_lshl_add_u64 v[204:205], s[38:39], 0, v[128:129]
	s_mov_b32 m0, s65
	s_nop 0
	global_load_lds_dwordx4 v[204:205], off
	v_lshl_add_u64 v[204:205], s[38:39], 0, v[130:131]
	s_mov_b32 m0, s66
	s_nop 0
	global_load_lds_dwordx4 v[204:205], off
	s_waitcnt vmcnt(8)
	s_waitcnt lgkmcnt(0)
	s_barrier
	s_setprio 1
	s_waitcnt lgkmcnt(0)
	v_mfma_f32_16x16x32_bf16 v[60:63], v[156:159], v[220:223], v[60:63]
	v_mfma_f32_16x16x32_bf16 v[56:59], v[164:167], v[220:223], v[56:59]
	v_mfma_f32_16x16x32_bf16 v[52:55], v[156:159], v[228:231], v[52:55]
	v_mfma_f32_16x16x32_bf16 v[48:51], v[164:167], v[228:231], v[48:51]
	v_mfma_f32_16x16x32_bf16 v[28:31], v[156:159], v[236:239], v[28:31]
	v_mfma_f32_16x16x32_bf16 v[24:27], v[164:167], v[236:239], v[24:27]
	v_mfma_f32_16x16x32_bf16 v[20:23], v[156:159], v[244:247], v[20:23]
	v_mfma_f32_16x16x32_bf16 v[12:15], v[164:167], v[244:247], v[12:15]
	v_mfma_f32_16x16x32_bf16 v[60:63], v[160:163], v[224:227], v[60:63]
	v_mfma_f32_16x16x32_bf16 v[56:59], v[168:171], v[224:227], v[56:59]
	v_mfma_f32_16x16x32_bf16 v[52:55], v[160:163], v[232:235], v[52:55]
	v_mfma_f32_16x16x32_bf16 v[48:51], v[168:171], v[232:235], v[48:51]
	v_mfma_f32_16x16x32_bf16 v[28:31], v[160:163], v[240:243], v[28:31]
	v_mfma_f32_16x16x32_bf16 v[24:27], v[168:171], v[240:243], v[24:27]
	v_mfma_f32_16x16x32_bf16 v[20:23], v[160:163], v[248:251], v[20:23]
	v_mfma_f32_16x16x32_bf16 v[12:15], v[168:171], v[248:251], v[12:15]
	s_setprio 0
	s_setprio 1
	v_mfma_f32_16x16x32_bf16 v[44:47], v[172:175], v[220:223], v[44:47]
	v_mfma_f32_16x16x32_bf16 v[40:43], v[212:215], v[220:223], v[40:43]
	v_mfma_f32_16x16x32_bf16 v[36:39], v[172:175], v[228:231], v[36:39]
	v_mfma_f32_16x16x32_bf16 v[32:35], v[212:215], v[228:231], v[32:35]
	v_mfma_f32_16x16x32_bf16 v[16:19], v[172:175], v[236:239], v[16:19]
	v_mfma_f32_16x16x32_bf16 v[8:11], v[212:215], v[236:239], v[8:11]
	v_mfma_f32_16x16x32_bf16 v[4:7], v[172:175], v[244:247], v[4:7]
	v_mfma_f32_16x16x32_bf16 v[0:3], v[212:215], v[244:247], v[0:3]
	v_mfma_f32_16x16x32_bf16 v[44:47], v[176:179], v[224:227], v[44:47]
	v_mfma_f32_16x16x32_bf16 v[40:43], v[216:219], v[224:227], v[40:43]
	v_mfma_f32_16x16x32_bf16 v[36:39], v[176:179], v[232:235], v[36:39]
	v_mfma_f32_16x16x32_bf16 v[32:35], v[216:219], v[232:235], v[32:35]
	v_mfma_f32_16x16x32_bf16 v[16:19], v[176:179], v[240:243], v[16:19]
	v_mfma_f32_16x16x32_bf16 v[8:11], v[216:219], v[240:243], v[8:11]
	v_mfma_f32_16x16x32_bf16 v[4:7], v[176:179], v[248:251], v[4:7]
	v_mfma_f32_16x16x32_bf16 v[0:3], v[216:219], v[248:251], v[0:3]
	s_setprio 0
	s_barrier
	s_add_i32 s47, s47, 2
	s_add_u32 s45, s45, 0x10000
	s_addc_u32 s46, s46, 0
	s_add_u32 s36, s36, 0x10000
	s_addc_u32 s37, s37, 0
	s_cmp_gt_u32 s47, 41
	s_cbranch_scc0 .LBB0_1645
	s_and_b64 vcc, exec, s[2:3]
	s_cbranch_vccz .LBB0_1648
	s_barrier

.LBB0_1728:
	s_ashr_i32 s19, s18, 31
	s_lshl_b64 s[22:23], s[18:19], 19
	s_add_u32 s22, s37, s22
	s_addc_u32 s23, s38, s23
	s_and_b64 s[24:25], s[4:5], exec
	s_cselect_b32 s1, s23, s27
	s_cselect_b32 s19, s22, s26
	s_ashr_i32 s21, s20, 31
	s_lshl_b64 s[24:25], s[20:21], 19
	s_add_u32 s24, s39, s24
	s_addc_u32 s25, s40, s25
	s_and_b64 s[28:29], s[4:5], exec
	s_cselect_b32 s21, s25, s7
	s_cselect_b32 s30, s24, s6
	s_add_u32 s31, s6, 0x10000
	s_addc_u32 s34, s7, 0
	s_add_u32 s6, s26, 0x40080
	s_addc_u32 s7, s27, 0
	s_mov_b32 s35, -2
.LBB0_1729:
	ds_read_b128 v[128:131], v210
	ds_read_b128 v[132:135], v210 offset:1024
	ds_read_b128 v[136:139], v210 offset:2048
	ds_read_b128 v[140:143], v210 offset:3072
	ds_read_b128 v[144:147], v211
	ds_read_b128 v[148:151], v211 offset:1024
	ds_read_b128 v[152:155], v211 offset:2048
	ds_read_b128 v[156:159], v211 offset:3072
	s_add_u32 s26, s6, 0xfffc0080
	s_addc_u32 s27, s7, -1
	s_cmp_eq_u32 s35, 12
	s_cselect_b32 s29, s1, s27
	s_cselect_b32 s28, s19, s26
	s_cselect_b32 s27, s21, s34
	s_cselect_b32 s26, s30, s31
	v_lshl_add_u64 v[198:199], s[6:7], 0, v[188:189]
	s_add_i32 m0, s42, 0xc000
	ds_read_b128 v[160:163], v212
	ds_read_b128 v[164:167], v212 offset:1024
	ds_read_b128 v[194:197], v212 offset:2048
	ds_read_b128 v[214:217], v212 offset:3072
	ds_read_b128 v[218:221], v212 offset:4096
	ds_read_b128 v[222:225], v212 offset:5120
	ds_read_b128 v[226:229], v212 offset:6144
	ds_read_b128 v[230:233], v212 offset:7168
	global_load_lds_dwordx4 v[198:199], off
	v_lshl_add_u64 v[198:199], s[6:7], 0, v[186:187]
	s_add_i32 m0, s42, 0xe000
	s_nop 0
	global_load_lds_dwordx4 v[198:199], off
	s_cmp_lg_u32 s35, -2
	s_cbranch_scc1 .Lzm_5
	v_mov_b32_e32 v0, 0
	v_mov_b32_e32 v1, v0
	v_mov_b32_e32 v2, v0
	v_mov_b32_e32 v3, v0
	v_mov_b32_e32 v4, v0
	v_mov_b32_e32 v5, v0
	v_mov_b32_e32 v6, v0
	v_mov_b32_e32 v7, v0
	v_mov_b32_e32 v8, v0
	v_mov_b32_e32 v9, v0
	v_mov_b32_e32 v10, v0
	v_mov_b32_e32 v11, v0
	v_mov_b32_e32 v12, v0
	v_mov_b32_e32 v13, v0
	v_mov_b32_e32 v14, v0
	v_mov_b32_e32 v15, v0
	v_mov_b32_e32 v16, v0
	v_mov_b32_e32 v17, v0
	v_mov_b32_e32 v18, v0
	v_mov_b32_e32 v19, v0
	v_mov_b32_e32 v20, v0
	v_mov_b32_e32 v21, v0
	v_mov_b32_e32 v22, v0
	v_mov_b32_e32 v23, v0
	v_mov_b32_e32 v24, v0
	v_mov_b32_e32 v25, v0
	v_mov_b32_e32 v26, v0
	v_mov_b32_e32 v27, v0
	v_mov_b32_e32 v28, v0
	v_mov_b32_e32 v29, v0
	v_mov_b32_e32 v30, v0
	v_mov_b32_e32 v31, v0
	v_mov_b32_e32 v32, v0
	v_mov_b32_e32 v33, v0
	v_mov_b32_e32 v34, v0
	v_mov_b32_e32 v35, v0
	v_mov_b32_e32 v36, v0
	v_mov_b32_e32 v37, v0
	v_mov_b32_e32 v38, v0
	v_mov_b32_e32 v39, v0
	v_mov_b32_e32 v40, v0
	v_mov_b32_e32 v41, v0
	v_mov_b32_e32 v42, v0
	v_mov_b32_e32 v43, v0
	v_mov_b32_e32 v44, v0
	v_mov_b32_e32 v45, v0
	v_mov_b32_e32 v46, v0
	v_mov_b32_e32 v47, v0
	v_mov_b32_e32 v48, v0
	v_mov_b32_e32 v49, v0
	v_mov_b32_e32 v50, v0
	v_mov_b32_e32 v51, v0
	v_mov_b32_e32 v52, v0
	v_mov_b32_e32 v53, v0
	v_mov_b32_e32 v54, v0
	v_mov_b32_e32 v55, v0
	v_mov_b32_e32 v56, v0
	v_mov_b32_e32 v57, v0
	v_mov_b32_e32 v58, v0
	v_mov_b32_e32 v59, v0
	v_mov_b32_e32 v60, v0
	v_mov_b32_e32 v61, v0
	v_mov_b32_e32 v62, v0
	v_mov_b32_e32 v63, v0
	v_mov_b32_e32 v64, v0
	v_mov_b32_e32 v65, v0
	v_mov_b32_e32 v66, v0
	v_mov_b32_e32 v67, v0
	v_mov_b32_e32 v68, v0
	v_mov_b32_e32 v69, v0
	v_mov_b32_e32 v70, v0
	v_mov_b32_e32 v71, v0
	v_mov_b32_e32 v72, v0
	v_mov_b32_e32 v73, v0
	v_mov_b32_e32 v74, v0
	v_mov_b32_e32 v75, v0
	v_mov_b32_e32 v76, v0
	v_mov_b32_e32 v77, v0
	v_mov_b32_e32 v78, v0
	v_mov_b32_e32 v79, v0
	v_mov_b32_e32 v80, v0
	v_mov_b32_e32 v81, v0
	v_mov_b32_e32 v82, v0
	v_mov_b32_e32 v83, v0
	v_mov_b32_e32 v84, v0
	v_mov_b32_e32 v85, v0
	v_mov_b32_e32 v86, v0
	v_mov_b32_e32 v87, v0
	v_mov_b32_e32 v88, v0
	v_mov_b32_e32 v89, v0
	v_mov_b32_e32 v90, v0
	v_mov_b32_e32 v91, v0
	v_mov_b32_e32 v92, v0
	v_mov_b32_e32 v93, v0
	v_mov_b32_e32 v94, v0
	v_mov_b32_e32 v95, v0
	v_mov_b32_e32 v96, v0
	v_mov_b32_e32 v97, v0
	v_mov_b32_e32 v98, v0
	v_mov_b32_e32 v99, v0
	v_mov_b32_e32 v100, v0
	v_mov_b32_e32 v101, v0
	v_mov_b32_e32 v102, v0
	v_mov_b32_e32 v103, v0
	v_mov_b32_e32 v104, v0
	v_mov_b32_e32 v105, v0
	v_mov_b32_e32 v106, v0
	v_mov_b32_e32 v107, v0
	v_mov_b32_e32 v108, v0
	v_mov_b32_e32 v109, v0
	v_mov_b32_e32 v110, v0
	v_mov_b32_e32 v111, v0
	v_mov_b32_e32 v112, v0
	v_mov_b32_e32 v113, v0
	v_mov_b32_e32 v114, v0
	v_mov_b32_e32 v115, v0
	v_mov_b32_e32 v116, v0
	v_mov_b32_e32 v117, v0
	v_mov_b32_e32 v118, v0
	v_mov_b32_e32 v119, v0
	v_mov_b32_e32 v120, v0
	v_mov_b32_e32 v121, v0
	v_mov_b32_e32 v122, v0
	v_mov_b32_e32 v123, v0
	v_mov_b32_e32 v124, v0
	v_mov_b32_e32 v125, v0
	v_mov_b32_e32 v126, v0
	v_mov_b32_e32 v127, v0
.Lzm_5:
	s_waitcnt vmcnt(8)
	s_waitcnt lgkmcnt(0)
	s_barrier
	s_setprio 1
	s_waitcnt lgkmcnt(0)
	v_mfma_f32_16x16x32_bf16 v[124:127], v[128:131], v[160:163], v[124:127]
	v_mfma_f32_16x16x32_bf16 v[120:123], v[136:139], v[160:163], v[120:123]
	v_mfma_f32_16x16x32_bf16 v[116:119], v[128:131], v[194:197], v[116:119]
	v_mfma_f32_16x16x32_bf16 v[112:115], v[136:139], v[194:197], v[112:115]
	v_mfma_f32_16x16x32_bf16 v[108:111], v[128:131], v[218:221], v[108:111]
	v_mfma_f32_16x16x32_bf16 v[104:107], v[136:139], v[218:221], v[104:107]
	v_mfma_f32_16x16x32_bf16 v[100:103], v[128:131], v[226:229], v[100:103]
	v_mfma_f32_16x16x32_bf16 v[96:99], v[136:139], v[226:229], v[96:99]
	v_mfma_f32_16x16x32_bf16 v[124:127], v[132:135], v[164:167], v[124:127]
	v_mfma_f32_16x16x32_bf16 v[120:123], v[140:143], v[164:167], v[120:123]
	v_mfma_f32_16x16x32_bf16 v[116:119], v[132:135], v[214:217], v[116:119]
	v_mfma_f32_16x16x32_bf16 v[112:115], v[140:143], v[214:217], v[112:115]
	v_mfma_f32_16x16x32_bf16 v[108:111], v[132:135], v[222:225], v[108:111]
	v_mfma_f32_16x16x32_bf16 v[104:107], v[140:143], v[222:225], v[104:107]
	v_mfma_f32_16x16x32_bf16 v[100:103], v[132:135], v[230:233], v[100:103]
	v_mfma_f32_16x16x32_bf16 v[96:99], v[140:143], v[230:233], v[96:99]
	s_setprio 0
	s_setprio 1
	v_mfma_f32_16x16x32_bf16 v[60:63], v[144:147], v[160:163], v[60:63]
	v_mfma_f32_16x16x32_bf16 v[56:59], v[152:155], v[160:163], v[56:59]
	v_mfma_f32_16x16x32_bf16 v[52:55], v[144:147], v[194:197], v[52:55]
	v_mfma_f32_16x16x32_bf16 v[48:51], v[152:155], v[194:197], v[48:51]
	v_mfma_f32_16x16x32_bf16 v[44:47], v[144:147], v[218:221], v[44:47]
	v_mfma_f32_16x16x32_bf16 v[40:43], v[152:155], v[218:221], v[40:43]
	v_mfma_f32_16x16x32_bf16 v[36:39], v[144:147], v[226:229], v[36:39]
	v_mfma_f32_16x16x32_bf16 v[32:35], v[152:155], v[226:229], v[32:35]
	v_mfma_f32_16x16x32_bf16 v[60:63], v[148:151], v[164:167], v[60:63]
	v_mfma_f32_16x16x32_bf16 v[56:59], v[156:159], v[164:167], v[56:59]
	v_mfma_f32_16x16x32_bf16 v[52:55], v[148:151], v[214:217], v[52:55]
	v_mfma_f32_16x16x32_bf16 v[48:51], v[156:159], v[214:217], v[48:51]
	v_mfma_f32_16x16x32_bf16 v[44:47], v[148:151], v[222:225], v[44:47]
	v_mfma_f32_16x16x32_bf16 v[40:43], v[156:159], v[222:225], v[40:43]
	v_mfma_f32_16x16x32_bf16 v[36:39], v[148:151], v[230:233], v[36:39]
	v_mfma_f32_16x16x32_bf16 v[32:35], v[156:159], v[230:233], v[32:35]
	s_setprio 0
	s_barrier
	s_add_i32 s61, s56, s41
	v_lshl_add_u64 v[198:199], s[26:27], 0, v[170:171]
	s_mov_b32 m0, s61
	ds_read_b128 v[160:163], v212 offset:16384
	ds_read_b128 v[164:167], v212 offset:17408
	ds_read_b128 v[194:197], v212 offset:18432
	ds_read_b128 v[214:217], v212 offset:19456
	ds_read_b128 v[218:221], v212 offset:20480
	ds_read_b128 v[222:225], v212 offset:21504
	ds_read_b128 v[226:229], v212 offset:22528
	ds_read_b128 v[230:233], v212 offset:23552
	global_load_lds_dwordx4 v[198:199], off
	s_add_i32 m0, s61, 0x2000
	s_add_u32 s62, s26, 0x4000
	v_lshl_add_u64 v[198:199], s[26:27], 0, v[174:175]
	s_addc_u32 s63, s27, 0
	s_add_i32 s61, s57, s41
	global_load_lds_dwordx4 v[198:199], off
	v_lshl_add_u64 v[198:199], s[62:63], 0, v[170:171]
	s_mov_b32 m0, s61
	v_lshl_add_u64 v[204:205], s[28:29], 0, v[172:173]
	global_load_lds_dwordx4 v[198:199], off
	v_lshl_add_u64 v[198:199], s[62:63], 0, v[174:175]
	s_add_i32 m0, s61, 0x2000
	s_nop 0
	global_load_lds_dwordx4 v[198:199], off
	v_lshl_add_u64 v[198:199], s[28:29], 0, v[168:169]
	s_mov_b32 m0, s42
	s_nop 0
	global_load_lds_dwordx4 v[198:199], off
	s_mov_b32 m0, s43
	s_nop 0
	global_load_lds_dwordx4 v[204:205], off
	s_waitcnt vmcnt(8)
	s_waitcnt lgkmcnt(0)
	s_barrier
	s_setprio 1
	s_waitcnt lgkmcnt(0)
	v_mfma_f32_16x16x32_bf16 v[92:95], v[128:131], v[160:163], v[92:95]
	v_mfma_f32_16x16x32_bf16 v[88:91], v[136:139], v[160:163], v[88:91]
	v_mfma_f32_16x16x32_bf16 v[84:87], v[128:131], v[194:197], v[84:87]
	v_mfma_f32_16x16x32_bf16 v[80:83], v[136:139], v[194:197], v[80:83]
	v_mfma_f32_16x16x32_bf16 v[76:79], v[128:131], v[218:221], v[76:79]
	v_mfma_f32_16x16x32_bf16 v[72:75], v[136:139], v[218:221], v[72:75]
	v_mfma_f32_16x16x32_bf16 v[68:71], v[128:131], v[226:229], v[68:71]
	v_mfma_f32_16x16x32_bf16 v[64:67], v[136:139], v[226:229], v[64:67]
	v_mfma_f32_16x16x32_bf16 v[92:95], v[132:135], v[164:167], v[92:95]
	v_mfma_f32_16x16x32_bf16 v[88:91], v[140:143], v[164:167], v[88:91]
	v_mfma_f32_16x16x32_bf16 v[84:87], v[132:135], v[214:217], v[84:87]
	v_mfma_f32_16x16x32_bf16 v[80:83], v[140:143], v[214:217], v[80:83]
	v_mfma_f32_16x16x32_bf16 v[76:79], v[132:135], v[222:225], v[76:79]
	v_mfma_f32_16x16x32_bf16 v[72:75], v[140:143], v[222:225], v[72:75]
	v_mfma_f32_16x16x32_bf16 v[68:71], v[132:135], v[230:233], v[68:71]
	v_mfma_f32_16x16x32_bf16 v[64:67], v[140:143], v[230:233], v[64:67]
	s_setprio 0
	s_setprio 1
	v_mfma_f32_16x16x32_bf16 v[28:31], v[144:147], v[160:163], v[28:31]
	v_mfma_f32_16x16x32_bf16 v[24:27], v[152:155], v[160:163], v[24:27]
	v_mfma_f32_16x16x32_bf16 v[20:23], v[144:147], v[194:197], v[20:23]
	v_mfma_f32_16x16x32_bf16 v[16:19], v[152:155], v[194:197], v[16:19]
	v_mfma_f32_16x16x32_bf16 v[12:15], v[144:147], v[218:221], v[12:15]
	v_mfma_f32_16x16x32_bf16 v[8:11], v[152:155], v[218:221], v[8:11]
	v_mfma_f32_16x16x32_bf16 v[4:7], v[144:147], v[226:229], v[4:7]
	v_mfma_f32_16x16x32_bf16 v[0:3], v[152:155], v[226:229], v[0:3]
	v_mfma_f32_16x16x32_bf16 v[28:31], v[148:151], v[164:167], v[28:31]
	v_mfma_f32_16x16x32_bf16 v[24:27], v[156:159], v[164:167], v[24:27]
	v_mfma_f32_16x16x32_bf16 v[20:23], v[148:151], v[214:217], v[20:23]
	v_mfma_f32_16x16x32_bf16 v[16:19], v[156:159], v[214:217], v[16:19]
	v_mfma_f32_16x16x32_bf16 v[12:15], v[148:151], v[222:225], v[12:15]
	v_mfma_f32_16x16x32_bf16 v[8:11], v[156:159], v[222:225], v[8:11]
	v_mfma_f32_16x16x32_bf16 v[4:7], v[148:151], v[230:233], v[4:7]
	v_mfma_f32_16x16x32_bf16 v[0:3], v[156:159], v[230:233], v[0:3]
	s_setprio 0
	s_barrier
	s_add_i32 s61, 0, 0x18000
	s_add_i32 s62, 0, 0x1c000
	v_add_u32_e32 v140, s61, v200
	v_add_u32_e32 v156, s62, v200
	ds_read_b128 v[128:131], v140
	ds_read_b128 v[132:135], v140 offset:1024
	ds_read_b128 v[136:139], v140 offset:2048
	ds_read_b128 v[140:143], v140 offset:3072
	ds_read_b128 v[144:147], v156
	ds_read_b128 v[148:151], v156 offset:1024
	ds_read_b128 v[152:155], v156 offset:2048
	ds_read_b128 v[156:159], v156 offset:3072
	s_add_u32 s28, s28, 0x40000
	s_addc_u32 s29, s29, 0
	s_mov_b32 m0, s44
	v_lshl_add_u64 v[206:207], s[28:29], 0, v[168:169]
	ds_read_b128 v[160:163], v212 offset:32768
	ds_read_b128 v[164:167], v212 offset:33792
	ds_read_b128 v[194:197], v212 offset:34816
	ds_read_b128 v[214:217], v212 offset:35840
	ds_read_b128 v[218:221], v212 offset:36864
	ds_read_b128 v[222:225], v212 offset:37888
	ds_read_b128 v[226:229], v212 offset:38912
	ds_read_b128 v[230:233], v212 offset:39936
	global_load_lds_dwordx4 v[206:207], off
	v_lshl_add_u64 v[206:207], s[28:29], 0, v[172:173]
	s_mov_b32 m0, s45
	s_nop 0
	global_load_lds_dwordx4 v[206:207], off
	s_waitcnt vmcnt(8)
	s_waitcnt lgkmcnt(0)
	s_barrier
	s_setprio 1
	s_waitcnt lgkmcnt(0)
	v_mfma_f32_16x16x32_bf16 v[124:127], v[128:131], v[160:163], v[124:127]
	v_mfma_f32_16x16x32_bf16 v[120:123], v[136:139], v[160:163], v[120:123]
	v_mfma_f32_16x16x32_bf16 v[116:119], v[128:131], v[194:197], v[116:119]
	v_mfma_f32_16x16x32_bf16 v[112:115], v[136:139], v[194:197], v[112:115]
	v_mfma_f32_16x16x32_bf16 v[108:111], v[128:131], v[218:221], v[108:111]
	v_mfma_f32_16x16x32_bf16 v[104:107], v[136:139], v[218:221], v[104:107]
	v_mfma_f32_16x16x32_bf16 v[100:103], v[128:131], v[226:229], v[100:103]
	v_mfma_f32_16x16x32_bf16 v[96:99], v[136:139], v[226:229], v[96:99]
	v_mfma_f32_16x16x32_bf16 v[124:127], v[132:135], v[164:167], v[124:127]
	v_mfma_f32_16x16x32_bf16 v[120:123], v[140:143], v[164:167], v[120:123]
	v_mfma_f32_16x16x32_bf16 v[116:119], v[132:135], v[214:217], v[116:119]
	v_mfma_f32_16x16x32_bf16 v[112:115], v[140:143], v[214:217], v[112:115]
	v_mfma_f32_16x16x32_bf16 v[108:111], v[132:135], v[222:225], v[108:111]
	v_mfma_f32_16x16x32_bf16 v[104:107], v[140:143], v[222:225], v[104:107]
	v_mfma_f32_16x16x32_bf16 v[100:103], v[132:135], v[230:233], v[100:103]
	v_mfma_f32_16x16x32_bf16 v[96:99], v[140:143], v[230:233], v[96:99]
	s_setprio 0
	s_setprio 1
	v_mfma_f32_16x16x32_bf16 v[60:63], v[144:147], v[160:163], v[60:63]
	v_mfma_f32_16x16x32_bf16 v[56:59], v[152:155], v[160:163], v[56:59]
	v_mfma_f32_16x16x32_bf16 v[52:55], v[144:147], v[194:197], v[52:55]
	v_mfma_f32_16x16x32_bf16 v[48:51], v[152:155], v[194:197], v[48:51]
	v_mfma_f32_16x16x32_bf16 v[44:47], v[144:147], v[218:221], v[44:47]
	v_mfma_f32_16x16x32_bf16 v[40:43], v[152:155], v[218:221], v[40:43]
	v_mfma_f32_16x16x32_bf16 v[36:39], v[144:147], v[226:229], v[36:39]
	v_mfma_f32_16x16x32_bf16 v[32:35], v[152:155], v[226:229], v[32:35]
	v_mfma_f32_16x16x32_bf16 v[60:63], v[148:151], v[164:167], v[60:63]
	v_mfma_f32_16x16x32_bf16 v[56:59], v[156:159], v[164:167], v[56:59]
	v_mfma_f32_16x16x32_bf16 v[52:55], v[148:151], v[214:217], v[52:55]
	v_mfma_f32_16x16x32_bf16 v[48:51], v[156:159], v[214:217], v[48:51]
	v_mfma_f32_16x16x32_bf16 v[44:47], v[148:151], v[222:225], v[44:47]
	v_mfma_f32_16x16x32_bf16 v[40:43], v[156:159], v[222:225], v[40:43]
	v_mfma_f32_16x16x32_bf16 v[36:39], v[148:151], v[230:233], v[36:39]
	v_mfma_f32_16x16x32_bf16 v[32:35], v[156:159], v[230:233], v[32:35]
	s_setprio 0
	s_barrier
	s_add_u32 s28, s26, 0x8000
	s_addc_u32 s29, s27, 0
	s_add_i32 s61, s61, s41
	v_lshl_add_u64 v[206:207], s[28:29], 0, v[170:171]
	s_mov_b32 m0, s61
	ds_read_b128 v[160:163], v212 offset:49152
	ds_read_b128 v[164:167], v212 offset:50176
	ds_read_b128 v[194:197], v212 offset:51200
	ds_read_b128 v[214:217], v212 offset:52224
	ds_read_b128 v[218:221], v212 offset:53248
	ds_read_b128 v[222:225], v212 offset:54272
	ds_read_b128 v[226:229], v212 offset:55296
	ds_read_b128 v[230:233], v212 offset:56320
	global_load_lds_dwordx4 v[206:207], off
	s_add_i32 m0, s61, 0x2000
	s_add_u32 s26, s26, 0xc000
	v_lshl_add_u64 v[206:207], s[28:29], 0, v[174:175]
	s_addc_u32 s27, s27, 0
	s_add_i32 s28, s62, s41
	global_load_lds_dwordx4 v[206:207], off
	v_lshl_add_u64 v[206:207], s[26:27], 0, v[170:171]
	s_mov_b32 m0, s28
	v_lshl_add_u64 v[198:199], v[198:199], 0, s[12:13]
	global_load_lds_dwordx4 v[206:207], off
	v_lshl_add_u64 v[206:207], s[26:27], 0, v[174:175]
	s_add_i32 m0, s28, 0x2000
	s_nop 0
	global_load_lds_dwordx4 v[206:207], off
	s_mov_b32 m0, s50
	s_nop 0
	global_load_lds_dwordx4 v[198:199], off
	v_lshl_add_u64 v[198:199], v[204:205], 0, s[12:13]
	s_mov_b32 m0, s51
	s_nop 0
	global_load_lds_dwordx4 v[198:199], off
	s_waitcnt vmcnt(8)
	s_waitcnt lgkmcnt(0)
	s_barrier
	s_setprio 1
	s_waitcnt lgkmcnt(0)
	v_mfma_f32_16x16x32_bf16 v[92:95], v[128:131], v[160:163], v[92:95]
	v_mfma_f32_16x16x32_bf16 v[88:91], v[136:139], v[160:163], v[88:91]
	v_mfma_f32_16x16x32_bf16 v[84:87], v[128:131], v[194:197], v[84:87]
	v_mfma_f32_16x16x32_bf16 v[80:83], v[136:139], v[194:197], v[80:83]
	v_mfma_f32_16x16x32_bf16 v[76:79], v[128:131], v[218:221], v[76:79]
	v_mfma_f32_16x16x32_bf16 v[72:75], v[136:139], v[218:221], v[72:75]
	v_mfma_f32_16x16x32_bf16 v[68:71], v[128:131], v[226:229], v[68:71]
	v_mfma_f32_16x16x32_bf16 v[64:67], v[136:139], v[226:229], v[64:67]
	v_mfma_f32_16x16x32_bf16 v[92:95], v[132:135], v[164:167], v[92:95]
	v_mfma_f32_16x16x32_bf16 v[88:91], v[140:143], v[164:167], v[88:91]
	v_mfma_f32_16x16x32_bf16 v[84:87], v[132:135], v[214:217], v[84:87]
	v_mfma_f32_16x16x32_bf16 v[80:83], v[140:143], v[214:217], v[80:83]
	v_mfma_f32_16x16x32_bf16 v[76:79], v[132:135], v[222:225], v[76:79]
	v_mfma_f32_16x16x32_bf16 v[72:75], v[140:143], v[222:225], v[72:75]
	v_mfma_f32_16x16x32_bf16 v[68:71], v[132:135], v[230:233], v[68:71]
	v_mfma_f32_16x16x32_bf16 v[64:67], v[140:143], v[230:233], v[64:67]
	s_setprio 0
	s_setprio 1
	v_mfma_f32_16x16x32_bf16 v[28:31], v[144:147], v[160:163], v[28:31]
	v_mfma_f32_16x16x32_bf16 v[24:27], v[152:155], v[160:163], v[24:27]
	v_mfma_f32_16x16x32_bf16 v[20:23], v[144:147], v[194:197], v[20:23]
	v_mfma_f32_16x16x32_bf16 v[16:19], v[152:155], v[194:197], v[16:19]
	v_mfma_f32_16x16x32_bf16 v[12:15], v[144:147], v[218:221], v[12:15]
	v_mfma_f32_16x16x32_bf16 v[8:11], v[152:155], v[218:221], v[8:11]
	v_mfma_f32_16x16x32_bf16 v[4:7], v[144:147], v[226:229], v[4:7]
	v_mfma_f32_16x16x32_bf16 v[0:3], v[152:155], v[226:229], v[0:3]
	v_mfma_f32_16x16x32_bf16 v[28:31], v[148:151], v[164:167], v[28:31]
	v_mfma_f32_16x16x32_bf16 v[24:27], v[156:159], v[164:167], v[24:27]
	v_mfma_f32_16x16x32_bf16 v[20:23], v[148:151], v[214:217], v[20:23]
	v_mfma_f32_16x16x32_bf16 v[16:19], v[156:159], v[214:217], v[16:19]
	v_mfma_f32_16x16x32_bf16 v[12:15], v[148:151], v[222:225], v[12:15]
	v_mfma_f32_16x16x32_bf16 v[8:11], v[156:159], v[222:225], v[8:11]
	v_mfma_f32_16x16x32_bf16 v[4:7], v[148:151], v[230:233], v[4:7]
	v_mfma_f32_16x16x32_bf16 v[0:3], v[156:159], v[230:233], v[0:3]
	s_setprio 0
	s_barrier
	s_add_i32 s35, s35, 2
	s_add_u32 s31, s31, 0x10000
	s_addc_u32 s34, s34, 0
	s_add_u32 s6, s6, 0x100
	s_addc_u32 s7, s7, 0
	s_cmp_gt_u32 s35, 13
	s_cbranch_scc0 .LBB0_1729
	s_and_b64 vcc, exec, s[14:15]
	s_cbranch_vccz .LBB0_1740
	s_barrier
	v_lshl_add_u32 v214, s0, 8, v179
	s_cmp_gt_i32 s2, 4
	s_mov_b64 s[0:1], -1
	s_cbranch_scc1 .LBB0_1741

.LBB0_2258:
	ds_read_b128 v[128:131], v170
	ds_read_b128 v[148:151], v170 offset:1024
	ds_read_b128 v[152:155], v170 offset:2048
	ds_read_b128 v[174:177], v170 offset:3072
	ds_read_b128 v[178:181], v171
	ds_read_b128 v[182:185], v171 offset:1024
	ds_read_b128 v[186:189], v171 offset:2048
	ds_read_b128 v[190:193], v171 offset:3072
	s_add_u32 s30, s28, 0xfffe0080
	s_addc_u32 s31, s29, -1
	s_cmp_eq_u32 s56, 4
	s_cselect_b32 s35, s17, s31
	s_cselect_b32 s34, s52, s30
	s_cselect_b32 s31, s19, s55
	s_cselect_b32 s30, s53, s54
	v_lshl_add_u64 v[204:205], s[28:29], 0, v[142:143]
	s_add_i32 m0, s25, 0xc000
	ds_read_b128 v[194:197], v172
	ds_read_b128 v[198:201], v172 offset:1024
	ds_read_b128 v[210:213], v172 offset:2048
	ds_read_b128 v[214:217], v172 offset:3072
	ds_read_b128 v[218:221], v172 offset:4096
	ds_read_b128 v[222:225], v172 offset:5120
	ds_read_b128 v[226:229], v172 offset:6144
	ds_read_b128 v[230:233], v172 offset:7168
	global_load_lds_dwordx4 v[204:205], off
	v_lshl_add_u64 v[204:205], s[28:29], 0, v[140:141]
	s_add_i32 m0, s25, 0xe000
	s_nop 0
	global_load_lds_dwordx4 v[204:205], off
	s_cmp_lg_u32 s56, -2
	s_cbranch_scc1 .Lzm_4
	v_mov_b32_e32 v0, 0
	v_mov_b32_e32 v1, v0
	v_mov_b32_e32 v2, v0
	v_mov_b32_e32 v3, v0
	v_mov_b32_e32 v4, v0
	v_mov_b32_e32 v5, v0
	v_mov_b32_e32 v6, v0
	v_mov_b32_e32 v7, v0
	v_mov_b32_e32 v8, v0
	v_mov_b32_e32 v9, v0
	v_mov_b32_e32 v10, v0
	v_mov_b32_e32 v11, v0
	v_mov_b32_e32 v12, v0
	v_mov_b32_e32 v13, v0
	v_mov_b32_e32 v14, v0
	v_mov_b32_e32 v15, v0
	v_mov_b32_e32 v16, v0
	v_mov_b32_e32 v17, v0
	v_mov_b32_e32 v18, v0
	v_mov_b32_e32 v19, v0
	v_mov_b32_e32 v20, v0
	v_mov_b32_e32 v21, v0
	v_mov_b32_e32 v22, v0
	v_mov_b32_e32 v23, v0
	v_mov_b32_e32 v24, v0
	v_mov_b32_e32 v25, v0
	v_mov_b32_e32 v26, v0
	v_mov_b32_e32 v27, v0
	v_mov_b32_e32 v28, v0
	v_mov_b32_e32 v29, v0
	v_mov_b32_e32 v30, v0
	v_mov_b32_e32 v31, v0
	v_mov_b32_e32 v32, v0
	v_mov_b32_e32 v33, v0
	v_mov_b32_e32 v34, v0
	v_mov_b32_e32 v35, v0
	v_mov_b32_e32 v36, v0
	v_mov_b32_e32 v37, v0
	v_mov_b32_e32 v38, v0
	v_mov_b32_e32 v39, v0
	v_mov_b32_e32 v40, v0
	v_mov_b32_e32 v41, v0
	v_mov_b32_e32 v42, v0
	v_mov_b32_e32 v43, v0
	v_mov_b32_e32 v44, v0
	v_mov_b32_e32 v45, v0
	v_mov_b32_e32 v46, v0
	v_mov_b32_e32 v47, v0
	v_mov_b32_e32 v48, v0
	v_mov_b32_e32 v49, v0
	v_mov_b32_e32 v50, v0
	v_mov_b32_e32 v51, v0
	v_mov_b32_e32 v52, v0
	v_mov_b32_e32 v53, v0
	v_mov_b32_e32 v54, v0
	v_mov_b32_e32 v55, v0
	v_mov_b32_e32 v56, v0
	v_mov_b32_e32 v57, v0
	v_mov_b32_e32 v58, v0
	v_mov_b32_e32 v59, v0
	v_mov_b32_e32 v60, v0
	v_mov_b32_e32 v61, v0
	v_mov_b32_e32 v62, v0
	v_mov_b32_e32 v63, v0
	v_mov_b32_e32 v64, v0
	v_mov_b32_e32 v65, v0
	v_mov_b32_e32 v66, v0
	v_mov_b32_e32 v67, v0
	v_mov_b32_e32 v68, v0
	v_mov_b32_e32 v69, v0
	v_mov_b32_e32 v70, v0
	v_mov_b32_e32 v71, v0
	v_mov_b32_e32 v72, v0
	v_mov_b32_e32 v73, v0
	v_mov_b32_e32 v74, v0
	v_mov_b32_e32 v75, v0
	v_mov_b32_e32 v76, v0
	v_mov_b32_e32 v77, v0
	v_mov_b32_e32 v78, v0
	v_mov_b32_e32 v79, v0
	v_mov_b32_e32 v80, v0
	v_mov_b32_e32 v81, v0
	v_mov_b32_e32 v82, v0
	v_mov_b32_e32 v83, v0
	v_mov_b32_e32 v84, v0
	v_mov_b32_e32 v85, v0
	v_mov_b32_e32 v86, v0
	v_mov_b32_e32 v87, v0
	v_mov_b32_e32 v88, v0
	v_mov_b32_e32 v89, v0
	v_mov_b32_e32 v90, v0
	v_mov_b32_e32 v91, v0
	v_mov_b32_e32 v92, v0
	v_mov_b32_e32 v93, v0
	v_mov_b32_e32 v94, v0
	v_mov_b32_e32 v95, v0
	v_mov_b32_e32 v96, v0
	v_mov_b32_e32 v97, v0
	v_mov_b32_e32 v98, v0
	v_mov_b32_e32 v99, v0
	v_mov_b32_e32 v100, v0
	v_mov_b32_e32 v101, v0
	v_mov_b32_e32 v102, v0
	v_mov_b32_e32 v103, v0
	v_mov_b32_e32 v104, v0
	v_mov_b32_e32 v105, v0
	v_mov_b32_e32 v106, v0
	v_mov_b32_e32 v107, v0
	v_mov_b32_e32 v108, v0
	v_mov_b32_e32 v109, v0
	v_mov_b32_e32 v110, v0
	v_mov_b32_e32 v111, v0
	v_mov_b32_e32 v112, v0
	v_mov_b32_e32 v113, v0
	v_mov_b32_e32 v114, v0
	v_mov_b32_e32 v115, v0
	v_mov_b32_e32 v116, v0
	v_mov_b32_e32 v117, v0
	v_mov_b32_e32 v118, v0
	v_mov_b32_e32 v119, v0
	v_mov_b32_e32 v120, v0
	v_mov_b32_e32 v121, v0
	v_mov_b32_e32 v122, v0
	v_mov_b32_e32 v123, v0
	v_mov_b32_e32 v124, v0
	v_mov_b32_e32 v125, v0
	v_mov_b32_e32 v126, v0
	v_mov_b32_e32 v127, v0
.Lzm_4:
	s_waitcnt vmcnt(8)
	s_waitcnt lgkmcnt(0)
	s_barrier
	s_setprio 1
	s_waitcnt lgkmcnt(0)
	v_mfma_f32_16x16x32_bf16 v[124:127], v[128:131], v[194:197], v[124:127]
	v_mfma_f32_16x16x32_bf16 v[120:123], v[152:155], v[194:197], v[120:123]
	v_mfma_f32_16x16x32_bf16 v[116:119], v[128:131], v[210:213], v[116:119]
	v_mfma_f32_16x16x32_bf16 v[112:115], v[152:155], v[210:213], v[112:115]
	v_mfma_f32_16x16x32_bf16 v[92:95], v[128:131], v[218:221], v[92:95]
	v_mfma_f32_16x16x32_bf16 v[88:91], v[152:155], v[218:221], v[88:91]
	v_mfma_f32_16x16x32_bf16 v[84:87], v[128:131], v[226:229], v[84:87]
	v_mfma_f32_16x16x32_bf16 v[72:75], v[152:155], v[226:229], v[72:75]
	v_mfma_f32_16x16x32_bf16 v[124:127], v[148:151], v[198:201], v[124:127]
	v_mfma_f32_16x16x32_bf16 v[120:123], v[174:177], v[198:201], v[120:123]
	v_mfma_f32_16x16x32_bf16 v[116:119], v[148:151], v[214:217], v[116:119]
	v_mfma_f32_16x16x32_bf16 v[112:115], v[174:177], v[214:217], v[112:115]
	v_mfma_f32_16x16x32_bf16 v[92:95], v[148:151], v[222:225], v[92:95]
	v_mfma_f32_16x16x32_bf16 v[88:91], v[174:177], v[222:225], v[88:91]
	v_mfma_f32_16x16x32_bf16 v[84:87], v[148:151], v[230:233], v[84:87]
	v_mfma_f32_16x16x32_bf16 v[72:75], v[174:177], v[230:233], v[72:75]
	s_setprio 0
	s_setprio 1
	v_mfma_f32_16x16x32_bf16 v[108:111], v[178:181], v[194:197], v[108:111]
	v_mfma_f32_16x16x32_bf16 v[104:107], v[186:189], v[194:197], v[104:107]
	v_mfma_f32_16x16x32_bf16 v[100:103], v[178:181], v[210:213], v[100:103]
	v_mfma_f32_16x16x32_bf16 v[96:99], v[186:189], v[210:213], v[96:99]
	v_mfma_f32_16x16x32_bf16 v[80:83], v[178:181], v[218:221], v[80:83]
	v_mfma_f32_16x16x32_bf16 v[76:79], v[186:189], v[218:221], v[76:79]
	v_mfma_f32_16x16x32_bf16 v[68:71], v[178:181], v[226:229], v[68:71]
	v_mfma_f32_16x16x32_bf16 v[64:67], v[186:189], v[226:229], v[64:67]
	v_mfma_f32_16x16x32_bf16 v[108:111], v[182:185], v[198:201], v[108:111]
	v_mfma_f32_16x16x32_bf16 v[104:107], v[190:193], v[198:201], v[104:107]
	v_mfma_f32_16x16x32_bf16 v[100:103], v[182:185], v[214:217], v[100:103]
	v_mfma_f32_16x16x32_bf16 v[96:99], v[190:193], v[214:217], v[96:99]
	v_mfma_f32_16x16x32_bf16 v[80:83], v[182:185], v[222:225], v[80:83]
	v_mfma_f32_16x16x32_bf16 v[76:79], v[190:193], v[222:225], v[76:79]
	v_mfma_f32_16x16x32_bf16 v[68:71], v[182:185], v[230:233], v[68:71]
	v_mfma_f32_16x16x32_bf16 v[64:67], v[190:193], v[230:233], v[64:67]
	s_setprio 0
	s_barrier
	s_add_i32 s57, s49, s42
	v_lshl_add_u64 v[204:205], s[30:31], 0, v[134:135]
	s_mov_b32 m0, s57
	ds_read_b128 v[194:197], v172 offset:16384
	ds_read_b128 v[198:201], v172 offset:17408
	ds_read_b128 v[210:213], v172 offset:18432
	ds_read_b128 v[214:217], v172 offset:19456
	ds_read_b128 v[218:221], v172 offset:20480
	ds_read_b128 v[222:225], v172 offset:21504
	ds_read_b128 v[226:229], v172 offset:22528
	ds_read_b128 v[230:233], v172 offset:23552
	global_load_lds_dwordx4 v[204:205], off
	s_add_i32 m0, s57, 0x2000
	s_add_u32 s58, s30, 0x4000
	v_lshl_add_u64 v[204:205], s[30:31], 0, v[138:139]
	s_addc_u32 s59, s31, 0
	s_add_i32 s57, s50, s42
	global_load_lds_dwordx4 v[204:205], off
	v_lshl_add_u64 v[204:205], s[58:59], 0, v[134:135]
	s_mov_b32 m0, s57
	v_lshl_add_u64 v[206:207], s[34:35], 0, v[136:137]
	global_load_lds_dwordx4 v[204:205], off
	v_lshl_add_u64 v[204:205], s[58:59], 0, v[138:139]
	s_add_i32 m0, s57, 0x2000
	s_nop 0
	global_load_lds_dwordx4 v[204:205], off
	v_lshl_add_u64 v[204:205], s[34:35], 0, v[132:133]
	s_mov_b32 m0, s25
	s_nop 0
	global_load_lds_dwordx4 v[204:205], off
	s_mov_b32 m0, s27
	s_nop 0
	global_load_lds_dwordx4 v[206:207], off
	s_waitcnt vmcnt(8)
	s_waitcnt lgkmcnt(0)
	s_barrier
	s_setprio 1
	s_waitcnt lgkmcnt(0)
	v_mfma_f32_16x16x32_bf16 v[60:63], v[128:131], v[194:197], v[60:63]
	v_mfma_f32_16x16x32_bf16 v[56:59], v[152:155], v[194:197], v[56:59]
	v_mfma_f32_16x16x32_bf16 v[48:51], v[128:131], v[210:213], v[48:51]
	v_mfma_f32_16x16x32_bf16 v[40:43], v[152:155], v[210:213], v[40:43]
	v_mfma_f32_16x16x32_bf16 v[32:35], v[128:131], v[218:221], v[32:35]
	v_mfma_f32_16x16x32_bf16 v[24:27], v[152:155], v[218:221], v[24:27]
	v_mfma_f32_16x16x32_bf16 v[16:19], v[128:131], v[226:229], v[16:19]
	v_mfma_f32_16x16x32_bf16 v[8:11], v[152:155], v[226:229], v[8:11]
	v_mfma_f32_16x16x32_bf16 v[60:63], v[148:151], v[198:201], v[60:63]
	v_mfma_f32_16x16x32_bf16 v[56:59], v[174:177], v[198:201], v[56:59]
	v_mfma_f32_16x16x32_bf16 v[48:51], v[148:151], v[214:217], v[48:51]
	v_mfma_f32_16x16x32_bf16 v[40:43], v[174:177], v[214:217], v[40:43]
	v_mfma_f32_16x16x32_bf16 v[32:35], v[148:151], v[222:225], v[32:35]
	v_mfma_f32_16x16x32_bf16 v[24:27], v[174:177], v[222:225], v[24:27]
	v_mfma_f32_16x16x32_bf16 v[16:19], v[148:151], v[230:233], v[16:19]
	v_mfma_f32_16x16x32_bf16 v[8:11], v[174:177], v[230:233], v[8:11]
	s_setprio 0
	s_setprio 1
	v_mfma_f32_16x16x32_bf16 v[52:55], v[178:181], v[194:197], v[52:55]
	v_mfma_f32_16x16x32_bf16 v[44:47], v[186:189], v[194:197], v[44:47]
	v_mfma_f32_16x16x32_bf16 v[36:39], v[178:181], v[210:213], v[36:39]
	v_mfma_f32_16x16x32_bf16 v[28:31], v[186:189], v[210:213], v[28:31]
	v_mfma_f32_16x16x32_bf16 v[20:23], v[178:181], v[218:221], v[20:23]
	v_mfma_f32_16x16x32_bf16 v[12:15], v[186:189], v[218:221], v[12:15]
	v_mfma_f32_16x16x32_bf16 v[4:7], v[178:181], v[226:229], v[4:7]
	v_mfma_f32_16x16x32_bf16 v[0:3], v[186:189], v[226:229], v[0:3]
	v_mfma_f32_16x16x32_bf16 v[52:55], v[182:185], v[198:201], v[52:55]
	v_mfma_f32_16x16x32_bf16 v[44:47], v[190:193], v[198:201], v[44:47]
	v_mfma_f32_16x16x32_bf16 v[36:39], v[182:185], v[214:217], v[36:39]
	v_mfma_f32_16x16x32_bf16 v[28:31], v[190:193], v[214:217], v[28:31]
	v_mfma_f32_16x16x32_bf16 v[20:23], v[182:185], v[222:225], v[20:23]
	v_mfma_f32_16x16x32_bf16 v[12:15], v[190:193], v[222:225], v[12:15]
	v_mfma_f32_16x16x32_bf16 v[4:7], v[182:185], v[230:233], v[4:7]
	v_mfma_f32_16x16x32_bf16 v[0:3], v[190:193], v[230:233], v[0:3]
	s_setprio 0
	s_barrier
	s_add_i32 s57, 0, 0x18000
	v_add_u32_e32 v173, s57, v168
	s_add_i32 s58, 0, 0x1c000
	ds_read_b128 v[128:131], v173
	ds_read_b128 v[148:151], v173 offset:1024
	ds_read_b128 v[152:155], v173 offset:2048
	ds_read_b128 v[174:177], v173 offset:3072
	v_add_u32_e32 v173, s58, v168
	ds_read_b128 v[178:181], v173
	ds_read_b128 v[182:185], v173 offset:1024
	ds_read_b128 v[186:189], v173 offset:2048
	ds_read_b128 v[190:193], v173 offset:3072
	s_add_u32 s34, s34, 0x20000
	s_addc_u32 s35, s35, 0
	s_mov_b32 m0, s43
	v_lshl_add_u64 v[234:235], s[34:35], 0, v[132:133]
	ds_read_b128 v[194:197], v172 offset:32768
	ds_read_b128 v[198:201], v172 offset:33792
	ds_read_b128 v[210:213], v172 offset:34816
	ds_read_b128 v[214:217], v172 offset:35840
	ds_read_b128 v[218:221], v172 offset:36864
	ds_read_b128 v[222:225], v172 offset:37888
	ds_read_b128 v[226:229], v172 offset:38912
	ds_read_b128 v[230:233], v172 offset:39936
	global_load_lds_dwordx4 v[234:235], off
	v_lshl_add_u64 v[234:235], s[34:35], 0, v[136:137]
	s_mov_b32 m0, s44
	s_nop 0
	global_load_lds_dwordx4 v[234:235], off
	s_waitcnt vmcnt(8)
	s_waitcnt lgkmcnt(0)
	s_barrier
	s_setprio 1
	s_waitcnt lgkmcnt(0)
	v_mfma_f32_16x16x32_bf16 v[124:127], v[128:131], v[194:197], v[124:127]
	v_mfma_f32_16x16x32_bf16 v[120:123], v[152:155], v[194:197], v[120:123]
	v_mfma_f32_16x16x32_bf16 v[116:119], v[128:131], v[210:213], v[116:119]
	v_mfma_f32_16x16x32_bf16 v[112:115], v[152:155], v[210:213], v[112:115]
	v_mfma_f32_16x16x32_bf16 v[92:95], v[128:131], v[218:221], v[92:95]
	v_mfma_f32_16x16x32_bf16 v[88:91], v[152:155], v[218:221], v[88:91]
	v_mfma_f32_16x16x32_bf16 v[84:87], v[128:131], v[226:229], v[84:87]
	v_mfma_f32_16x16x32_bf16 v[72:75], v[152:155], v[226:229], v[72:75]
	v_mfma_f32_16x16x32_bf16 v[124:127], v[148:151], v[198:201], v[124:127]
	v_mfma_f32_16x16x32_bf16 v[120:123], v[174:177], v[198:201], v[120:123]
	v_mfma_f32_16x16x32_bf16 v[116:119], v[148:151], v[214:217], v[116:119]
	v_mfma_f32_16x16x32_bf16 v[112:115], v[174:177], v[214:217], v[112:115]
	v_mfma_f32_16x16x32_bf16 v[92:95], v[148:151], v[222:225], v[92:95]
	v_mfma_f32_16x16x32_bf16 v[88:91], v[174:177], v[222:225], v[88:91]
	v_mfma_f32_16x16x32_bf16 v[84:87], v[148:151], v[230:233], v[84:87]
	v_mfma_f32_16x16x32_bf16 v[72:75], v[174:177], v[230:233], v[72:75]
	s_setprio 0
	s_setprio 1
	v_mfma_f32_16x16x32_bf16 v[108:111], v[178:181], v[194:197], v[108:111]
	v_mfma_f32_16x16x32_bf16 v[104:107], v[186:189], v[194:197], v[104:107]
	v_mfma_f32_16x16x32_bf16 v[100:103], v[178:181], v[210:213], v[100:103]
	v_mfma_f32_16x16x32_bf16 v[96:99], v[186:189], v[210:213], v[96:99]
	v_mfma_f32_16x16x32_bf16 v[80:83], v[178:181], v[218:221], v[80:83]
	v_mfma_f32_16x16x32_bf16 v[76:79], v[186:189], v[218:221], v[76:79]
	v_mfma_f32_16x16x32_bf16 v[68:71], v[178:181], v[226:229], v[68:71]
	v_mfma_f32_16x16x32_bf16 v[64:67], v[186:189], v[226:229], v[64:67]
	v_mfma_f32_16x16x32_bf16 v[108:111], v[182:185], v[198:201], v[108:111]
	v_mfma_f32_16x16x32_bf16 v[104:107], v[190:193], v[198:201], v[104:107]
	v_mfma_f32_16x16x32_bf16 v[100:103], v[182:185], v[214:217], v[100:103]
	v_mfma_f32_16x16x32_bf16 v[96:99], v[190:193], v[214:217], v[96:99]
	v_mfma_f32_16x16x32_bf16 v[80:83], v[182:185], v[222:225], v[80:83]
	v_mfma_f32_16x16x32_bf16 v[76:79], v[190:193], v[222:225], v[76:79]
	v_mfma_f32_16x16x32_bf16 v[68:71], v[182:185], v[230:233], v[68:71]
	v_mfma_f32_16x16x32_bf16 v[64:67], v[190:193], v[230:233], v[64:67]
	s_setprio 0
	s_barrier
	s_add_u32 s34, s30, 0x8000
	s_addc_u32 s35, s31, 0
	s_add_i32 s57, s57, s42
	v_lshl_add_u64 v[234:235], s[34:35], 0, v[134:135]
	s_mov_b32 m0, s57
	ds_read_b128 v[194:197], v172 offset:49152
	ds_read_b128 v[198:201], v172 offset:50176
	ds_read_b128 v[210:213], v172 offset:51200
	ds_read_b128 v[214:217], v172 offset:52224
	ds_read_b128 v[218:221], v172 offset:53248
	ds_read_b128 v[222:225], v172 offset:54272
	ds_read_b128 v[226:229], v172 offset:55296
	ds_read_b128 v[230:233], v172 offset:56320
	global_load_lds_dwordx4 v[234:235], off
	s_add_i32 m0, s57, 0x2000
	s_add_u32 s30, s30, 0xc000
	v_lshl_add_u64 v[234:235], s[34:35], 0, v[138:139]
	s_addc_u32 s31, s31, 0
	s_add_i32 s34, s58, s42
	global_load_lds_dwordx4 v[234:235], off
	v_lshl_add_u64 v[234:235], s[30:31], 0, v[134:135]
	s_mov_b32 m0, s34
	v_lshl_add_u64 v[204:205], v[204:205], 0, s[12:13]
	global_load_lds_dwordx4 v[234:235], off
	v_lshl_add_u64 v[234:235], s[30:31], 0, v[138:139]
	s_add_i32 m0, s34, 0x2000
	s_nop 0
	global_load_lds_dwordx4 v[234:235], off
	s_mov_b32 m0, s46
	s_nop 0
	global_load_lds_dwordx4 v[204:205], off
	v_lshl_add_u64 v[204:205], v[206:207], 0, s[12:13]
	s_mov_b32 m0, s47
	s_nop 0
	global_load_lds_dwordx4 v[204:205], off
	s_waitcnt vmcnt(8)
	s_waitcnt lgkmcnt(0)
	s_barrier
	s_setprio 1
	s_waitcnt lgkmcnt(0)
	v_mfma_f32_16x16x32_bf16 v[60:63], v[128:131], v[194:197], v[60:63]
	v_mfma_f32_16x16x32_bf16 v[56:59], v[152:155], v[194:197], v[56:59]
	v_mfma_f32_16x16x32_bf16 v[48:51], v[128:131], v[210:213], v[48:51]
	v_mfma_f32_16x16x32_bf16 v[40:43], v[152:155], v[210:213], v[40:43]
	v_mfma_f32_16x16x32_bf16 v[32:35], v[128:131], v[218:221], v[32:35]
	v_mfma_f32_16x16x32_bf16 v[24:27], v[152:155], v[218:221], v[24:27]
	v_mfma_f32_16x16x32_bf16 v[16:19], v[128:131], v[226:229], v[16:19]
	v_mfma_f32_16x16x32_bf16 v[8:11], v[152:155], v[226:229], v[8:11]
	v_mfma_f32_16x16x32_bf16 v[60:63], v[148:151], v[198:201], v[60:63]
	v_mfma_f32_16x16x32_bf16 v[56:59], v[174:177], v[198:201], v[56:59]
	v_mfma_f32_16x16x32_bf16 v[48:51], v[148:151], v[214:217], v[48:51]
	v_mfma_f32_16x16x32_bf16 v[40:43], v[174:177], v[214:217], v[40:43]
	v_mfma_f32_16x16x32_bf16 v[32:35], v[148:151], v[222:225], v[32:35]
	v_mfma_f32_16x16x32_bf16 v[24:27], v[174:177], v[222:225], v[24:27]
	v_mfma_f32_16x16x32_bf16 v[16:19], v[148:151], v[230:233], v[16:19]
	v_mfma_f32_16x16x32_bf16 v[8:11], v[174:177], v[230:233], v[8:11]
	s_setprio 0
	s_setprio 1
	v_mfma_f32_16x16x32_bf16 v[52:55], v[178:181], v[194:197], v[52:55]
	v_mfma_f32_16x16x32_bf16 v[44:47], v[186:189], v[194:197], v[44:47]
	v_mfma_f32_16x16x32_bf16 v[36:39], v[178:181], v[210:213], v[36:39]
	v_mfma_f32_16x16x32_bf16 v[28:31], v[186:189], v[210:213], v[28:31]
	v_mfma_f32_16x16x32_bf16 v[20:23], v[178:181], v[218:221], v[20:23]
	v_mfma_f32_16x16x32_bf16 v[12:15], v[186:189], v[218:221], v[12:15]
	v_mfma_f32_16x16x32_bf16 v[4:7], v[178:181], v[226:229], v[4:7]
	v_mfma_f32_16x16x32_bf16 v[0:3], v[186:189], v[226:229], v[0:3]
	v_mfma_f32_16x16x32_bf16 v[52:55], v[182:185], v[198:201], v[52:55]
	v_mfma_f32_16x16x32_bf16 v[44:47], v[190:193], v[198:201], v[44:47]
	v_mfma_f32_16x16x32_bf16 v[36:39], v[182:185], v[214:217], v[36:39]
	v_mfma_f32_16x16x32_bf16 v[28:31], v[190:193], v[214:217], v[28:31]
	v_mfma_f32_16x16x32_bf16 v[20:23], v[182:185], v[222:225], v[20:23]
	v_mfma_f32_16x16x32_bf16 v[12:15], v[190:193], v[222:225], v[12:15]
	v_mfma_f32_16x16x32_bf16 v[4:7], v[182:185], v[230:233], v[4:7]
	v_mfma_f32_16x16x32_bf16 v[0:3], v[190:193], v[230:233], v[0:3]
	s_setprio 0
	s_barrier
	s_add_i32 s56, s56, 2
	s_add_u32 s54, s54, 0x10000
	s_addc_u32 s55, s55, 0
	s_add_u32 s28, s28, 0x100
	s_addc_u32 s29, s29, 0
	s_cmp_gt_u32 s56, 5
	s_cbranch_scc0 .LBB0_2258
	s_and_b64 vcc, exec, s[14:15]
	s_cbranch_vccz .LBB0_2261
	s_barrier

.LBB0_2282:
	ds_read_b128 v[144:147], v155
	ds_read_b128 v[148:151], v155 offset:1024
	ds_read_b128 v[158:161], v155 offset:2048
	ds_read_b128 v[162:165], v155 offset:3072
	ds_read_b128 v[166:169], v156
	ds_read_b128 v[170:173], v156 offset:1024
	ds_read_b128 v[174:177], v156 offset:2048
	ds_read_b128 v[178:181], v156 offset:3072
	s_add_u32 s28, s26, 0xfffe0080
	s_addc_u32 s29, s27, -1
	s_cmp_eq_u32 s54, 4
	s_cselect_b32 s31, s15, s29
	s_cselect_b32 s30, s50, s28
	s_cselect_b32 s29, s17, s53
	s_cselect_b32 s28, s51, s52
	v_lshl_add_u64 v[204:205], s[26:27], 0, v[130:131]
	s_add_i32 m0, s23, 0xc000
	ds_read_b128 v[182:185], v157
	ds_read_b128 v[186:189], v157 offset:1024
	ds_read_b128 v[190:193], v157 offset:2048
	ds_read_b128 v[194:197], v157 offset:3072
	ds_read_b128 v[198:201], v157 offset:4096
	ds_read_b128 v[210:213], v157 offset:5120
	ds_read_b128 v[214:217], v157 offset:6144
	ds_read_b128 v[218:221], v157 offset:7168
	global_load_lds_dwordx4 v[204:205], off
	v_lshl_add_u64 v[204:205], s[26:27], 0, v[128:129]
	s_add_i32 m0, s23, 0xe000
	s_nop 0
	global_load_lds_dwordx4 v[204:205], off
	s_cmp_lg_u32 s54, -2
	s_cbranch_scc1 .Lzm_3
	v_mov_b32_e32 v0, 0
	v_mov_b32_e32 v1, v0
	v_mov_b32_e32 v2, v0
	v_mov_b32_e32 v3, v0
	v_mov_b32_e32 v4, v0
	v_mov_b32_e32 v5, v0
	v_mov_b32_e32 v6, v0
	v_mov_b32_e32 v7, v0
	v_mov_b32_e32 v8, v0
	v_mov_b32_e32 v9, v0
	v_mov_b32_e32 v10, v0
	v_mov_b32_e32 v11, v0
	v_mov_b32_e32 v12, v0
	v_mov_b32_e32 v13, v0
	v_mov_b32_e32 v14, v0
	v_mov_b32_e32 v15, v0
	v_mov_b32_e32 v16, v0
	v_mov_b32_e32 v17, v0
	v_mov_b32_e32 v18, v0
	v_mov_b32_e32 v19, v0
	v_mov_b32_e32 v20, v0
	v_mov_b32_e32 v21, v0
	v_mov_b32_e32 v22, v0
	v_mov_b32_e32 v23, v0
	v_mov_b32_e32 v24, v0
	v_mov_b32_e32 v25, v0
	v_mov_b32_e32 v26, v0
	v_mov_b32_e32 v27, v0
	v_mov_b32_e32 v28, v0
	v_mov_b32_e32 v29, v0
	v_mov_b32_e32 v30, v0
	v_mov_b32_e32 v31, v0
	v_mov_b32_e32 v32, v0
	v_mov_b32_e32 v33, v0
	v_mov_b32_e32 v34, v0
	v_mov_b32_e32 v35, v0
	v_mov_b32_e32 v36, v0
	v_mov_b32_e32 v37, v0
	v_mov_b32_e32 v38, v0
	v_mov_b32_e32 v39, v0
	v_mov_b32_e32 v40, v0
	v_mov_b32_e32 v41, v0
	v_mov_b32_e32 v42, v0
	v_mov_b32_e32 v43, v0
	v_mov_b32_e32 v44, v0
	v_mov_b32_e32 v45, v0
	v_mov_b32_e32 v46, v0
	v_mov_b32_e32 v47, v0
	v_mov_b32_e32 v48, v0
	v_mov_b32_e32 v49, v0
	v_mov_b32_e32 v50, v0
	v_mov_b32_e32 v51, v0
	v_mov_b32_e32 v52, v0
	v_mov_b32_e32 v53, v0
	v_mov_b32_e32 v54, v0
	v_mov_b32_e32 v55, v0
	v_mov_b32_e32 v56, v0
	v_mov_b32_e32 v57, v0
	v_mov_b32_e32 v58, v0
	v_mov_b32_e32 v59, v0
	v_mov_b32_e32 v60, v0
	v_mov_b32_e32 v61, v0
	v_mov_b32_e32 v62, v0
	v_mov_b32_e32 v63, v0
	v_mov_b32_e32 v64, v0
	v_mov_b32_e32 v65, v0
	v_mov_b32_e32 v66, v0
	v_mov_b32_e32 v67, v0
	v_mov_b32_e32 v68, v0
	v_mov_b32_e32 v69, v0
	v_mov_b32_e32 v70, v0
	v_mov_b32_e32 v71, v0
	v_mov_b32_e32 v72, v0
	v_mov_b32_e32 v73, v0
	v_mov_b32_e32 v74, v0
	v_mov_b32_e32 v75, v0
	v_mov_b32_e32 v76, v0
	v_mov_b32_e32 v77, v0
	v_mov_b32_e32 v78, v0
	v_mov_b32_e32 v79, v0
	v_mov_b32_e32 v80, v0
	v_mov_b32_e32 v81, v0
	v_mov_b32_e32 v82, v0
	v_mov_b32_e32 v83, v0
	v_mov_b32_e32 v84, v0
	v_mov_b32_e32 v85, v0
	v_mov_b32_e32 v86, v0
	v_mov_b32_e32 v87, v0
	v_mov_b32_e32 v88, v0
	v_mov_b32_e32 v89, v0
	v_mov_b32_e32 v90, v0
	v_mov_b32_e32 v91, v0
	v_mov_b32_e32 v92, v0
	v_mov_b32_e32 v93, v0
	v_mov_b32_e32 v94, v0
	v_mov_b32_e32 v95, v0
	v_mov_b32_e32 v96, v0
	v_mov_b32_e32 v97, v0
	v_mov_b32_e32 v98, v0
	v_mov_b32_e32 v99, v0
	v_mov_b32_e32 v100, v0
	v_mov_b32_e32 v101, v0
	v_mov_b32_e32 v102, v0
	v_mov_b32_e32 v103, v0
	v_mov_b32_e32 v104, v0
	v_mov_b32_e32 v105, v0
	v_mov_b32_e32 v106, v0
	v_mov_b32_e32 v107, v0
	v_mov_b32_e32 v108, v0
	v_mov_b32_e32 v109, v0
	v_mov_b32_e32 v110, v0
	v_mov_b32_e32 v111, v0
	v_mov_b32_e32 v112, v0
	v_mov_b32_e32 v113, v0
	v_mov_b32_e32 v114, v0
	v_mov_b32_e32 v115, v0
	v_mov_b32_e32 v116, v0
	v_mov_b32_e32 v117, v0
	v_mov_b32_e32 v118, v0
	v_mov_b32_e32 v119, v0
	v_mov_b32_e32 v120, v0
	v_mov_b32_e32 v121, v0
	v_mov_b32_e32 v122, v0
	v_mov_b32_e32 v123, v0
	v_mov_b32_e32 v124, v0
	v_mov_b32_e32 v125, v0
	v_mov_b32_e32 v126, v0
	v_mov_b32_e32 v127, v0
.Lzm_3:
	s_waitcnt vmcnt(8)
	s_waitcnt lgkmcnt(0)
	s_barrier
	s_setprio 1
	s_waitcnt lgkmcnt(0)
	v_mfma_f32_16x16x32_bf16 v[124:127], v[144:147], v[182:185], v[124:127]
	v_mfma_f32_16x16x32_bf16 v[120:123], v[158:161], v[182:185], v[120:123]
	v_mfma_f32_16x16x32_bf16 v[112:115], v[144:147], v[190:193], v[112:115]
	v_mfma_f32_16x16x32_bf16 v[104:107], v[158:161], v[190:193], v[104:107]
	v_mfma_f32_16x16x32_bf16 v[92:95], v[144:147], v[198:201], v[92:95]
	v_mfma_f32_16x16x32_bf16 v[88:91], v[158:161], v[198:201], v[88:91]
	v_mfma_f32_16x16x32_bf16 v[80:83], v[144:147], v[214:217], v[80:83]
	v_mfma_f32_16x16x32_bf16 v[72:75], v[158:161], v[214:217], v[72:75]
	v_mfma_f32_16x16x32_bf16 v[124:127], v[148:151], v[186:189], v[124:127]
	v_mfma_f32_16x16x32_bf16 v[120:123], v[162:165], v[186:189], v[120:123]
	v_mfma_f32_16x16x32_bf16 v[112:115], v[148:151], v[194:197], v[112:115]
	v_mfma_f32_16x16x32_bf16 v[104:107], v[162:165], v[194:197], v[104:107]
	v_mfma_f32_16x16x32_bf16 v[92:95], v[148:151], v[210:213], v[92:95]
	v_mfma_f32_16x16x32_bf16 v[88:91], v[162:165], v[210:213], v[88:91]
	v_mfma_f32_16x16x32_bf16 v[80:83], v[148:151], v[218:221], v[80:83]
	v_mfma_f32_16x16x32_bf16 v[72:75], v[162:165], v[218:221], v[72:75]
	s_setprio 0
	s_setprio 1
	v_mfma_f32_16x16x32_bf16 v[116:119], v[166:169], v[182:185], v[116:119]
	v_mfma_f32_16x16x32_bf16 v[108:111], v[174:177], v[182:185], v[108:111]
	v_mfma_f32_16x16x32_bf16 v[100:103], v[166:169], v[190:193], v[100:103]
	v_mfma_f32_16x16x32_bf16 v[96:99], v[174:177], v[190:193], v[96:99]
	v_mfma_f32_16x16x32_bf16 v[84:87], v[166:169], v[198:201], v[84:87]
	v_mfma_f32_16x16x32_bf16 v[76:79], v[174:177], v[198:201], v[76:79]
	v_mfma_f32_16x16x32_bf16 v[68:71], v[166:169], v[214:217], v[68:71]
	v_mfma_f32_16x16x32_bf16 v[64:67], v[174:177], v[214:217], v[64:67]
	v_mfma_f32_16x16x32_bf16 v[116:119], v[170:173], v[186:189], v[116:119]
	v_mfma_f32_16x16x32_bf16 v[108:111], v[178:181], v[186:189], v[108:111]
	v_mfma_f32_16x16x32_bf16 v[100:103], v[170:173], v[194:197], v[100:103]
	v_mfma_f32_16x16x32_bf16 v[96:99], v[178:181], v[194:197], v[96:99]
	v_mfma_f32_16x16x32_bf16 v[84:87], v[170:173], v[210:213], v[84:87]
	v_mfma_f32_16x16x32_bf16 v[76:79], v[178:181], v[210:213], v[76:79]
	v_mfma_f32_16x16x32_bf16 v[68:71], v[170:173], v[218:221], v[68:71]
	v_mfma_f32_16x16x32_bf16 v[64:67], v[178:181], v[218:221], v[64:67]
	s_setprio 0
	s_barrier
	s_add_i32 s55, s47, s40
	v_lshl_add_u64 v[204:205], s[28:29], 0, v[134:135]
	s_mov_b32 m0, s55
	ds_read_b128 v[182:185], v157 offset:16384
	ds_read_b128 v[186:189], v157 offset:17408
	ds_read_b128 v[190:193], v157 offset:18432
	ds_read_b128 v[194:197], v157 offset:19456
	ds_read_b128 v[198:201], v157 offset:20480
	ds_read_b128 v[210:213], v157 offset:21504
	ds_read_b128 v[214:217], v157 offset:22528
	ds_read_b128 v[218:221], v157 offset:23552
	global_load_lds_dwordx4 v[204:205], off
	s_add_i32 m0, s55, 0x2000
	s_add_u32 s56, s28, 0x4000
	v_lshl_add_u64 v[204:205], s[28:29], 0, v[138:139]
	s_addc_u32 s57, s29, 0
	s_add_i32 s55, s48, s40
	global_load_lds_dwordx4 v[204:205], off
	v_lshl_add_u64 v[204:205], s[56:57], 0, v[134:135]
	s_mov_b32 m0, s55
	v_lshl_add_u64 v[206:207], s[30:31], 0, v[136:137]
	global_load_lds_dwordx4 v[204:205], off
	v_lshl_add_u64 v[204:205], s[56:57], 0, v[138:139]
	s_add_i32 m0, s55, 0x2000
	s_nop 0
	global_load_lds_dwordx4 v[204:205], off
	v_lshl_add_u64 v[204:205], s[30:31], 0, v[132:133]
	s_mov_b32 m0, s23
	s_nop 0
	global_load_lds_dwordx4 v[204:205], off
	s_mov_b32 m0, s25
	s_nop 0
	global_load_lds_dwordx4 v[206:207], off
	s_waitcnt vmcnt(8)
	s_waitcnt lgkmcnt(0)
	s_barrier
	s_setprio 1
	s_waitcnt lgkmcnt(0)
	v_mfma_f32_16x16x32_bf16 v[60:63], v[144:147], v[182:185], v[60:63]
	v_mfma_f32_16x16x32_bf16 v[56:59], v[158:161], v[182:185], v[56:59]
	v_mfma_f32_16x16x32_bf16 v[48:51], v[144:147], v[190:193], v[48:51]
	v_mfma_f32_16x16x32_bf16 v[40:43], v[158:161], v[190:193], v[40:43]
	v_mfma_f32_16x16x32_bf16 v[28:31], v[144:147], v[198:201], v[28:31]
	v_mfma_f32_16x16x32_bf16 v[24:27], v[158:161], v[198:201], v[24:27]
	v_mfma_f32_16x16x32_bf16 v[16:19], v[144:147], v[214:217], v[16:19]
	v_mfma_f32_16x16x32_bf16 v[8:11], v[158:161], v[214:217], v[8:11]
	v_mfma_f32_16x16x32_bf16 v[60:63], v[148:151], v[186:189], v[60:63]
	v_mfma_f32_16x16x32_bf16 v[56:59], v[162:165], v[186:189], v[56:59]
	v_mfma_f32_16x16x32_bf16 v[48:51], v[148:151], v[194:197], v[48:51]
	v_mfma_f32_16x16x32_bf16 v[40:43], v[162:165], v[194:197], v[40:43]
	v_mfma_f32_16x16x32_bf16 v[28:31], v[148:151], v[210:213], v[28:31]
	v_mfma_f32_16x16x32_bf16 v[24:27], v[162:165], v[210:213], v[24:27]
	v_mfma_f32_16x16x32_bf16 v[16:19], v[148:151], v[218:221], v[16:19]
	v_mfma_f32_16x16x32_bf16 v[8:11], v[162:165], v[218:221], v[8:11]
	s_setprio 0
	s_setprio 1
	v_mfma_f32_16x16x32_bf16 v[52:55], v[166:169], v[182:185], v[52:55]
	v_mfma_f32_16x16x32_bf16 v[44:47], v[174:177], v[182:185], v[44:47]
	v_mfma_f32_16x16x32_bf16 v[36:39], v[166:169], v[190:193], v[36:39]
	v_mfma_f32_16x16x32_bf16 v[32:35], v[174:177], v[190:193], v[32:35]
	v_mfma_f32_16x16x32_bf16 v[20:23], v[166:169], v[198:201], v[20:23]
	v_mfma_f32_16x16x32_bf16 v[12:15], v[174:177], v[198:201], v[12:15]
	v_mfma_f32_16x16x32_bf16 v[4:7], v[166:169], v[214:217], v[4:7]
	v_mfma_f32_16x16x32_bf16 v[0:3], v[174:177], v[214:217], v[0:3]
	v_mfma_f32_16x16x32_bf16 v[52:55], v[170:173], v[186:189], v[52:55]
	v_mfma_f32_16x16x32_bf16 v[44:47], v[178:181], v[186:189], v[44:47]
	v_mfma_f32_16x16x32_bf16 v[36:39], v[170:173], v[194:197], v[36:39]
	v_mfma_f32_16x16x32_bf16 v[32:35], v[178:181], v[194:197], v[32:35]
	v_mfma_f32_16x16x32_bf16 v[20:23], v[170:173], v[210:213], v[20:23]
	v_mfma_f32_16x16x32_bf16 v[12:15], v[178:181], v[210:213], v[12:15]
	v_mfma_f32_16x16x32_bf16 v[4:7], v[170:173], v[218:221], v[4:7]
	v_mfma_f32_16x16x32_bf16 v[0:3], v[178:181], v[218:221], v[0:3]
	s_setprio 0
	s_barrier
	s_add_i32 s55, 0, 0x18000
	s_add_i32 s56, 0, 0x1c000
	v_add_u32_e32 v162, s55, v153
	v_add_u32_e32 v178, s56, v153
	ds_read_b128 v[144:147], v162
	ds_read_b128 v[148:151], v162 offset:1024
	ds_read_b128 v[158:161], v162 offset:2048
	ds_read_b128 v[162:165], v162 offset:3072
	ds_read_b128 v[166:169], v178
	ds_read_b128 v[170:173], v178 offset:1024
	ds_read_b128 v[174:177], v178 offset:2048
	ds_read_b128 v[178:181], v178 offset:3072
	s_add_u32 s30, s30, 0x20000
	s_addc_u32 s31, s31, 0
	s_mov_b32 m0, s41
	v_lshl_add_u64 v[222:223], s[30:31], 0, v[132:133]
	ds_read_b128 v[182:185], v157 offset:32768
	ds_read_b128 v[186:189], v157 offset:33792
	ds_read_b128 v[190:193], v157 offset:34816
	ds_read_b128 v[194:197], v157 offset:35840
	ds_read_b128 v[198:201], v157 offset:36864
	ds_read_b128 v[210:213], v157 offset:37888
	ds_read_b128 v[214:217], v157 offset:38912
	ds_read_b128 v[218:221], v157 offset:39936
	global_load_lds_dwordx4 v[222:223], off
	v_lshl_add_u64 v[222:223], s[30:31], 0, v[136:137]
	s_mov_b32 m0, s42
	s_nop 0
	global_load_lds_dwordx4 v[222:223], off
	s_waitcnt vmcnt(8)
	s_waitcnt lgkmcnt(0)
	s_barrier
	s_setprio 1
	s_waitcnt lgkmcnt(0)
	v_mfma_f32_16x16x32_bf16 v[124:127], v[144:147], v[182:185], v[124:127]
	v_mfma_f32_16x16x32_bf16 v[120:123], v[158:161], v[182:185], v[120:123]
	v_mfma_f32_16x16x32_bf16 v[112:115], v[144:147], v[190:193], v[112:115]
	v_mfma_f32_16x16x32_bf16 v[104:107], v[158:161], v[190:193], v[104:107]
	v_mfma_f32_16x16x32_bf16 v[92:95], v[144:147], v[198:201], v[92:95]
	v_mfma_f32_16x16x32_bf16 v[88:91], v[158:161], v[198:201], v[88:91]
	v_mfma_f32_16x16x32_bf16 v[80:83], v[144:147], v[214:217], v[80:83]
	v_mfma_f32_16x16x32_bf16 v[72:75], v[158:161], v[214:217], v[72:75]
	v_mfma_f32_16x16x32_bf16 v[124:127], v[148:151], v[186:189], v[124:127]
	v_mfma_f32_16x16x32_bf16 v[120:123], v[162:165], v[186:189], v[120:123]
	v_mfma_f32_16x16x32_bf16 v[112:115], v[148:151], v[194:197], v[112:115]
	v_mfma_f32_16x16x32_bf16 v[104:107], v[162:165], v[194:197], v[104:107]
	v_mfma_f32_16x16x32_bf16 v[92:95], v[148:151], v[210:213], v[92:95]
	v_mfma_f32_16x16x32_bf16 v[88:91], v[162:165], v[210:213], v[88:91]
	v_mfma_f32_16x16x32_bf16 v[80:83], v[148:151], v[218:221], v[80:83]
	v_mfma_f32_16x16x32_bf16 v[72:75], v[162:165], v[218:221], v[72:75]
	s_setprio 0
	s_setprio 1
	v_mfma_f32_16x16x32_bf16 v[116:119], v[166:169], v[182:185], v[116:119]
	v_mfma_f32_16x16x32_bf16 v[108:111], v[174:177], v[182:185], v[108:111]
	v_mfma_f32_16x16x32_bf16 v[100:103], v[166:169], v[190:193], v[100:103]
	v_mfma_f32_16x16x32_bf16 v[96:99], v[174:177], v[190:193], v[96:99]
	v_mfma_f32_16x16x32_bf16 v[84:87], v[166:169], v[198:201], v[84:87]
	v_mfma_f32_16x16x32_bf16 v[76:79], v[174:177], v[198:201], v[76:79]
	v_mfma_f32_16x16x32_bf16 v[68:71], v[166:169], v[214:217], v[68:71]
	v_mfma_f32_16x16x32_bf16 v[64:67], v[174:177], v[214:217], v[64:67]
	v_mfma_f32_16x16x32_bf16 v[116:119], v[170:173], v[186:189], v[116:119]
	v_mfma_f32_16x16x32_bf16 v[108:111], v[178:181], v[186:189], v[108:111]
	v_mfma_f32_16x16x32_bf16 v[100:103], v[170:173], v[194:197], v[100:103]
	v_mfma_f32_16x16x32_bf16 v[96:99], v[178:181], v[194:197], v[96:99]
	v_mfma_f32_16x16x32_bf16 v[84:87], v[170:173], v[210:213], v[84:87]
	v_mfma_f32_16x16x32_bf16 v[76:79], v[178:181], v[210:213], v[76:79]
	v_mfma_f32_16x16x32_bf16 v[68:71], v[170:173], v[218:221], v[68:71]
	v_mfma_f32_16x16x32_bf16 v[64:67], v[178:181], v[218:221], v[64:67]
	s_setprio 0
	s_barrier
	s_add_u32 s30, s28, 0x8000
	s_addc_u32 s31, s29, 0
	s_add_i32 s55, s55, s40
	v_lshl_add_u64 v[222:223], s[30:31], 0, v[134:135]
	s_mov_b32 m0, s55
	ds_read_b128 v[182:185], v157 offset:49152
	ds_read_b128 v[186:189], v157 offset:50176
	ds_read_b128 v[190:193], v157 offset:51200
	ds_read_b128 v[194:197], v157 offset:52224
	ds_read_b128 v[198:201], v157 offset:53248
	ds_read_b128 v[210:213], v157 offset:54272
	ds_read_b128 v[214:217], v157 offset:55296
	ds_read_b128 v[218:221], v157 offset:56320
	global_load_lds_dwordx4 v[222:223], off
	s_add_i32 m0, s55, 0x2000
	s_add_u32 s28, s28, 0xc000
	v_lshl_add_u64 v[222:223], s[30:31], 0, v[138:139]
	s_addc_u32 s29, s29, 0
	s_add_i32 s30, s56, s40
	global_load_lds_dwordx4 v[222:223], off
	v_lshl_add_u64 v[222:223], s[28:29], 0, v[134:135]
	s_mov_b32 m0, s30
	v_lshl_add_u64 v[204:205], v[204:205], 0, s[8:9]
	global_load_lds_dwordx4 v[222:223], off
	v_lshl_add_u64 v[222:223], s[28:29], 0, v[138:139]
	s_add_i32 m0, s30, 0x2000
	s_nop 0
	global_load_lds_dwordx4 v[222:223], off
	s_mov_b32 m0, s44
	s_nop 0
	global_load_lds_dwordx4 v[204:205], off
	v_lshl_add_u64 v[204:205], v[206:207], 0, s[8:9]
	s_mov_b32 m0, s45
	s_nop 0
	global_load_lds_dwordx4 v[204:205], off
	s_waitcnt vmcnt(8)
	s_waitcnt lgkmcnt(0)
	s_barrier
	s_setprio 1
	s_waitcnt lgkmcnt(0)
	v_mfma_f32_16x16x32_bf16 v[60:63], v[144:147], v[182:185], v[60:63]
	v_mfma_f32_16x16x32_bf16 v[56:59], v[158:161], v[182:185], v[56:59]
	v_mfma_f32_16x16x32_bf16 v[48:51], v[144:147], v[190:193], v[48:51]
	v_mfma_f32_16x16x32_bf16 v[40:43], v[158:161], v[190:193], v[40:43]
	v_mfma_f32_16x16x32_bf16 v[28:31], v[144:147], v[198:201], v[28:31]
	v_mfma_f32_16x16x32_bf16 v[24:27], v[158:161], v[198:201], v[24:27]
	v_mfma_f32_16x16x32_bf16 v[16:19], v[144:147], v[214:217], v[16:19]
	v_mfma_f32_16x16x32_bf16 v[8:11], v[158:161], v[214:217], v[8:11]
	v_mfma_f32_16x16x32_bf16 v[60:63], v[148:151], v[186:189], v[60:63]
	v_mfma_f32_16x16x32_bf16 v[56:59], v[162:165], v[186:189], v[56:59]
	v_mfma_f32_16x16x32_bf16 v[48:51], v[148:151], v[194:197], v[48:51]
	v_mfma_f32_16x16x32_bf16 v[40:43], v[162:165], v[194:197], v[40:43]
	v_mfma_f32_16x16x32_bf16 v[28:31], v[148:151], v[210:213], v[28:31]
	v_mfma_f32_16x16x32_bf16 v[24:27], v[162:165], v[210:213], v[24:27]
	v_mfma_f32_16x16x32_bf16 v[16:19], v[148:151], v[218:221], v[16:19]
	v_mfma_f32_16x16x32_bf16 v[8:11], v[162:165], v[218:221], v[8:11]
	s_setprio 0
	s_setprio 1
	v_mfma_f32_16x16x32_bf16 v[52:55], v[166:169], v[182:185], v[52:55]
	v_mfma_f32_16x16x32_bf16 v[44:47], v[174:177], v[182:185], v[44:47]
	v_mfma_f32_16x16x32_bf16 v[36:39], v[166:169], v[190:193], v[36:39]
	v_mfma_f32_16x16x32_bf16 v[32:35], v[174:177], v[190:193], v[32:35]
	v_mfma_f32_16x16x32_bf16 v[20:23], v[166:169], v[198:201], v[20:23]
	v_mfma_f32_16x16x32_bf16 v[12:15], v[174:177], v[198:201], v[12:15]
	v_mfma_f32_16x16x32_bf16 v[4:7], v[166:169], v[214:217], v[4:7]
	v_mfma_f32_16x16x32_bf16 v[0:3], v[174:177], v[214:217], v[0:3]
	v_mfma_f32_16x16x32_bf16 v[52:55], v[170:173], v[186:189], v[52:55]
	v_mfma_f32_16x16x32_bf16 v[44:47], v[178:181], v[186:189], v[44:47]
	v_mfma_f32_16x16x32_bf16 v[36:39], v[170:173], v[194:197], v[36:39]
	v_mfma_f32_16x16x32_bf16 v[32:35], v[178:181], v[194:197], v[32:35]
	v_mfma_f32_16x16x32_bf16 v[20:23], v[170:173], v[210:213], v[20:23]
	v_mfma_f32_16x16x32_bf16 v[12:15], v[178:181], v[210:213], v[12:15]
	v_mfma_f32_16x16x32_bf16 v[4:7], v[170:173], v[218:221], v[4:7]
	v_mfma_f32_16x16x32_bf16 v[0:3], v[178:181], v[218:221], v[0:3]
	s_setprio 0
	s_barrier
	s_add_i32 s54, s54, 2
	s_add_u32 s52, s52, 0x10000
	s_addc_u32 s53, s53, 0
	s_add_u32 s26, s26, 0x100
	s_addc_u32 s27, s27, 0
	s_cmp_gt_u32 s54, 5
	s_cbranch_scc0 .LBB0_2282
	s_and_b64 vcc, exec, s[10:11]
	s_cbranch_vccz .LBB0_2285
	s_barrier

.LBB0_2358:
	v_add_u32_e32 v168, s77, v182
	v_add_u32_e32 v204, s78, v182
	ds_read_b128 v[156:159], v168
	ds_read_b128 v[160:163], v168 offset:1024
	ds_read_b128 v[164:167], v168 offset:2048
	ds_read_b128 v[168:171], v168 offset:3072
	ds_read_b128 v[172:175], v204
	ds_read_b128 v[176:179], v204 offset:1024
	ds_read_b128 v[212:215], v204 offset:2048
	ds_read_b128 v[216:219], v204 offset:3072
	s_add_u32 s48, s46, 0xfffc0080
	s_addc_u32 s49, s47, -1
	s_cmp_eq_u32 s54, 12
	s_cselect_b32 s51, s35, s49
	s_cselect_b32 s50, s43, s48
	s_cselect_b32 s49, s37, s53
	s_cselect_b32 s48, s45, s52
	v_lshl_add_u64 v[204:205], s[46:47], 0, v[154:155]
	s_add_i32 m0, s65, 0xc000
	ds_read_b128 v[220:223], v199
	ds_read_b128 v[224:227], v199 offset:1024
	ds_read_b128 v[228:231], v199 offset:2048
	ds_read_b128 v[232:235], v199 offset:3072
	ds_read_b128 v[236:239], v199 offset:4096
	ds_read_b128 v[240:243], v199 offset:5120
	ds_read_b128 v[244:247], v199 offset:6144
	ds_read_b128 v[248:251], v199 offset:7168
	global_load_lds_dwordx4 v[204:205], off
	v_lshl_add_u64 v[204:205], s[46:47], 0, v[152:153]
	s_add_i32 m0, s65, 0xe000
	s_nop 0
	global_load_lds_dwordx4 v[204:205], off
	s_cmp_lg_u32 s54, -2
	s_cbranch_scc1 .Lzm_2
	v_mov_b32_e32 v0, 0
	v_mov_b32_e32 v1, v0
	v_mov_b32_e32 v2, v0
	v_mov_b32_e32 v3, v0
	v_mov_b32_e32 v4, v0
	v_mov_b32_e32 v5, v0
	v_mov_b32_e32 v6, v0
	v_mov_b32_e32 v7, v0
	v_mov_b32_e32 v8, v0
	v_mov_b32_e32 v9, v0
	v_mov_b32_e32 v10, v0
	v_mov_b32_e32 v11, v0
	v_mov_b32_e32 v12, v0
	v_mov_b32_e32 v13, v0
	v_mov_b32_e32 v14, v0
	v_mov_b32_e32 v15, v0
	v_mov_b32_e32 v16, v0
	v_mov_b32_e32 v17, v0
	v_mov_b32_e32 v18, v0
	v_mov_b32_e32 v19, v0
	v_mov_b32_e32 v20, v0
	v_mov_b32_e32 v21, v0
	v_mov_b32_e32 v22, v0
	v_mov_b32_e32 v23, v0
	v_mov_b32_e32 v24, v0
	v_mov_b32_e32 v25, v0
	v_mov_b32_e32 v26, v0
	v_mov_b32_e32 v27, v0
	v_mov_b32_e32 v28, v0
	v_mov_b32_e32 v29, v0
	v_mov_b32_e32 v30, v0
	v_mov_b32_e32 v31, v0
	v_mov_b32_e32 v32, v0
	v_mov_b32_e32 v33, v0
	v_mov_b32_e32 v34, v0
	v_mov_b32_e32 v35, v0
	v_mov_b32_e32 v36, v0
	v_mov_b32_e32 v37, v0
	v_mov_b32_e32 v38, v0
	v_mov_b32_e32 v39, v0
	v_mov_b32_e32 v40, v0
	v_mov_b32_e32 v41, v0
	v_mov_b32_e32 v42, v0
	v_mov_b32_e32 v43, v0
	v_mov_b32_e32 v44, v0
	v_mov_b32_e32 v45, v0
	v_mov_b32_e32 v46, v0
	v_mov_b32_e32 v47, v0
	v_mov_b32_e32 v48, v0
	v_mov_b32_e32 v49, v0
	v_mov_b32_e32 v50, v0
	v_mov_b32_e32 v51, v0
	v_mov_b32_e32 v52, v0
	v_mov_b32_e32 v53, v0
	v_mov_b32_e32 v54, v0
	v_mov_b32_e32 v55, v0
	v_mov_b32_e32 v56, v0
	v_mov_b32_e32 v57, v0
	v_mov_b32_e32 v58, v0
	v_mov_b32_e32 v59, v0
	v_mov_b32_e32 v60, v0
	v_mov_b32_e32 v61, v0
	v_mov_b32_e32 v62, v0
	v_mov_b32_e32 v63, v0
	v_mov_b32_e32 v64, v0
	v_mov_b32_e32 v65, v0
	v_mov_b32_e32 v66, v0
	v_mov_b32_e32 v67, v0
	v_mov_b32_e32 v68, v0
	v_mov_b32_e32 v69, v0
	v_mov_b32_e32 v70, v0
	v_mov_b32_e32 v71, v0
	v_mov_b32_e32 v72, v0
	v_mov_b32_e32 v73, v0
	v_mov_b32_e32 v74, v0
	v_mov_b32_e32 v75, v0
	v_mov_b32_e32 v76, v0
	v_mov_b32_e32 v77, v0
	v_mov_b32_e32 v78, v0
	v_mov_b32_e32 v79, v0
	v_mov_b32_e32 v80, v0
	v_mov_b32_e32 v81, v0
	v_mov_b32_e32 v82, v0
	v_mov_b32_e32 v83, v0
	v_mov_b32_e32 v84, v0
	v_mov_b32_e32 v85, v0
	v_mov_b32_e32 v86, v0
	v_mov_b32_e32 v87, v0
	v_mov_b32_e32 v88, v0
	v_mov_b32_e32 v89, v0
	v_mov_b32_e32 v90, v0
	v_mov_b32_e32 v91, v0
	v_mov_b32_e32 v92, v0
	v_mov_b32_e32 v93, v0
	v_mov_b32_e32 v94, v0
	v_mov_b32_e32 v95, v0
	v_mov_b32_e32 v96, v0
	v_mov_b32_e32 v97, v0
	v_mov_b32_e32 v98, v0
	v_mov_b32_e32 v99, v0
	v_mov_b32_e32 v100, v0
	v_mov_b32_e32 v101, v0
	v_mov_b32_e32 v102, v0
	v_mov_b32_e32 v103, v0
	v_mov_b32_e32 v104, v0
	v_mov_b32_e32 v105, v0
	v_mov_b32_e32 v106, v0
	v_mov_b32_e32 v107, v0
	v_mov_b32_e32 v108, v0
	v_mov_b32_e32 v109, v0
	v_mov_b32_e32 v110, v0
	v_mov_b32_e32 v111, v0
	v_mov_b32_e32 v112, v0
	v_mov_b32_e32 v113, v0
	v_mov_b32_e32 v114, v0
	v_mov_b32_e32 v115, v0
	v_mov_b32_e32 v116, v0
	v_mov_b32_e32 v117, v0
	v_mov_b32_e32 v118, v0
	v_mov_b32_e32 v119, v0
	v_mov_b32_e32 v120, v0
	v_mov_b32_e32 v121, v0
	v_mov_b32_e32 v122, v0
	v_mov_b32_e32 v123, v0
	v_mov_b32_e32 v124, v0
	v_mov_b32_e32 v125, v0
	v_mov_b32_e32 v126, v0
	v_mov_b32_e32 v127, v0
.Lzm_2:
	s_waitcnt vmcnt(8)
	s_waitcnt lgkmcnt(0)
	s_barrier
	s_setprio 1
	s_waitcnt lgkmcnt(0)
	v_mfma_f32_16x16x32_bf16 v[124:127], v[156:159], v[220:223], v[124:127]
	v_mfma_f32_16x16x32_bf16 v[120:123], v[164:167], v[220:223], v[120:123]
	v_mfma_f32_16x16x32_bf16 v[116:119], v[156:159], v[228:231], v[116:119]
	v_mfma_f32_16x16x32_bf16 v[112:115], v[164:167], v[228:231], v[112:115]
	v_mfma_f32_16x16x32_bf16 v[92:95], v[156:159], v[236:239], v[92:95]
	v_mfma_f32_16x16x32_bf16 v[88:91], v[164:167], v[236:239], v[88:91]
	v_mfma_f32_16x16x32_bf16 v[84:87], v[156:159], v[244:247], v[84:87]
	v_mfma_f32_16x16x32_bf16 v[80:83], v[164:167], v[244:247], v[80:83]
	v_mfma_f32_16x16x32_bf16 v[124:127], v[160:163], v[224:227], v[124:127]
	v_mfma_f32_16x16x32_bf16 v[120:123], v[168:171], v[224:227], v[120:123]
	v_mfma_f32_16x16x32_bf16 v[116:119], v[160:163], v[232:235], v[116:119]
	v_mfma_f32_16x16x32_bf16 v[112:115], v[168:171], v[232:235], v[112:115]
	v_mfma_f32_16x16x32_bf16 v[92:95], v[160:163], v[240:243], v[92:95]
	v_mfma_f32_16x16x32_bf16 v[88:91], v[168:171], v[240:243], v[88:91]
	v_mfma_f32_16x16x32_bf16 v[84:87], v[160:163], v[248:251], v[84:87]
	v_mfma_f32_16x16x32_bf16 v[80:83], v[168:171], v[248:251], v[80:83]
	s_setprio 0
	s_setprio 1
	v_mfma_f32_16x16x32_bf16 v[108:111], v[172:175], v[220:223], v[108:111]
	v_mfma_f32_16x16x32_bf16 v[104:107], v[212:215], v[220:223], v[104:107]
	v_mfma_f32_16x16x32_bf16 v[100:103], v[172:175], v[228:231], v[100:103]
	v_mfma_f32_16x16x32_bf16 v[96:99], v[212:215], v[228:231], v[96:99]
	v_mfma_f32_16x16x32_bf16 v[76:79], v[172:175], v[236:239], v[76:79]
	v_mfma_f32_16x16x32_bf16 v[72:75], v[212:215], v[236:239], v[72:75]
	v_mfma_f32_16x16x32_bf16 v[68:71], v[172:175], v[244:247], v[68:71]
	v_mfma_f32_16x16x32_bf16 v[64:67], v[212:215], v[244:247], v[64:67]
	v_mfma_f32_16x16x32_bf16 v[108:111], v[176:179], v[224:227], v[108:111]
	v_mfma_f32_16x16x32_bf16 v[104:107], v[216:219], v[224:227], v[104:107]
	v_mfma_f32_16x16x32_bf16 v[100:103], v[176:179], v[232:235], v[100:103]
	v_mfma_f32_16x16x32_bf16 v[96:99], v[216:219], v[232:235], v[96:99]
	v_mfma_f32_16x16x32_bf16 v[76:79], v[176:179], v[240:243], v[76:79]
	v_mfma_f32_16x16x32_bf16 v[72:75], v[216:219], v[240:243], v[72:75]
	v_mfma_f32_16x16x32_bf16 v[68:71], v[176:179], v[248:251], v[68:71]
	v_mfma_f32_16x16x32_bf16 v[64:67], v[216:219], v[248:251], v[64:67]
	s_setprio 0
	s_barrier
	s_add_i32 s55, s77, s64
	v_lshl_add_u64 v[204:205], s[48:49], 0, v[130:131]
	s_mov_b32 m0, s55
	ds_read_b128 v[220:223], v199 offset:16384
	ds_read_b128 v[224:227], v199 offset:17408
	ds_read_b128 v[228:231], v199 offset:18432
	ds_read_b128 v[232:235], v199 offset:19456
	ds_read_b128 v[236:239], v199 offset:20480
	ds_read_b128 v[240:243], v199 offset:21504
	ds_read_b128 v[244:247], v199 offset:22528
	ds_read_b128 v[248:251], v199 offset:23552
	global_load_lds_dwordx4 v[204:205], off
	s_add_i32 m0, s55, 0x2000
	s_add_u32 s56, s48, 0x4000
	v_lshl_add_u64 v[204:205], s[48:49], 0, v[134:135]
	s_addc_u32 s57, s49, 0
	s_add_i32 s55, s78, s64
	global_load_lds_dwordx4 v[204:205], off
	v_lshl_add_u64 v[204:205], s[56:57], 0, v[130:131]
	s_mov_b32 m0, s55
	v_lshl_add_u64 v[206:207], s[50:51], 0, v[132:133]
	global_load_lds_dwordx4 v[204:205], off
	v_lshl_add_u64 v[204:205], s[56:57], 0, v[134:135]
	s_add_i32 m0, s55, 0x2000
	s_nop 0
	global_load_lds_dwordx4 v[204:205], off
	v_lshl_add_u64 v[204:205], s[50:51], 0, v[128:129]
	s_mov_b32 m0, s65
	s_nop 0
	global_load_lds_dwordx4 v[204:205], off
	s_mov_b32 m0, s66
	s_nop 0
	global_load_lds_dwordx4 v[206:207], off
	s_waitcnt vmcnt(8)
	s_waitcnt lgkmcnt(0)
	s_barrier
	s_setprio 1
	s_waitcnt lgkmcnt(0)
	v_mfma_f32_16x16x32_bf16 v[60:63], v[156:159], v[220:223], v[60:63]
	v_mfma_f32_16x16x32_bf16 v[56:59], v[164:167], v[220:223], v[56:59]
	v_mfma_f32_16x16x32_bf16 v[52:55], v[156:159], v[228:231], v[52:55]
	v_mfma_f32_16x16x32_bf16 v[48:51], v[164:167], v[228:231], v[48:51]
	v_mfma_f32_16x16x32_bf16 v[28:31], v[156:159], v[236:239], v[28:31]
	v_mfma_f32_16x16x32_bf16 v[24:27], v[164:167], v[236:239], v[24:27]
	v_mfma_f32_16x16x32_bf16 v[20:23], v[156:159], v[244:247], v[20:23]
	v_mfma_f32_16x16x32_bf16 v[12:15], v[164:167], v[244:247], v[12:15]
	v_mfma_f32_16x16x32_bf16 v[60:63], v[160:163], v[224:227], v[60:63]
	v_mfma_f32_16x16x32_bf16 v[56:59], v[168:171], v[224:227], v[56:59]
	v_mfma_f32_16x16x32_bf16 v[52:55], v[160:163], v[232:235], v[52:55]
	v_mfma_f32_16x16x32_bf16 v[48:51], v[168:171], v[232:235], v[48:51]
	v_mfma_f32_16x16x32_bf16 v[28:31], v[160:163], v[240:243], v[28:31]
	v_mfma_f32_16x16x32_bf16 v[24:27], v[168:171], v[240:243], v[24:27]
	v_mfma_f32_16x16x32_bf16 v[20:23], v[160:163], v[248:251], v[20:23]
	v_mfma_f32_16x16x32_bf16 v[12:15], v[168:171], v[248:251], v[12:15]
	s_setprio 0
	s_setprio 1
	v_mfma_f32_16x16x32_bf16 v[44:47], v[172:175], v[220:223], v[44:47]
	v_mfma_f32_16x16x32_bf16 v[40:43], v[212:215], v[220:223], v[40:43]
	v_mfma_f32_16x16x32_bf16 v[36:39], v[172:175], v[228:231], v[36:39]
	v_mfma_f32_16x16x32_bf16 v[32:35], v[212:215], v[228:231], v[32:35]
	v_mfma_f32_16x16x32_bf16 v[16:19], v[172:175], v[236:239], v[16:19]
	v_mfma_f32_16x16x32_bf16 v[8:11], v[212:215], v[236:239], v[8:11]
	v_mfma_f32_16x16x32_bf16 v[4:7], v[172:175], v[244:247], v[4:7]
	v_mfma_f32_16x16x32_bf16 v[0:3], v[212:215], v[244:247], v[0:3]
	v_mfma_f32_16x16x32_bf16 v[44:47], v[176:179], v[224:227], v[44:47]
	v_mfma_f32_16x16x32_bf16 v[40:43], v[216:219], v[224:227], v[40:43]
	v_mfma_f32_16x16x32_bf16 v[36:39], v[176:179], v[232:235], v[36:39]
	v_mfma_f32_16x16x32_bf16 v[32:35], v[216:219], v[232:235], v[32:35]
	v_mfma_f32_16x16x32_bf16 v[16:19], v[176:179], v[240:243], v[16:19]
	v_mfma_f32_16x16x32_bf16 v[8:11], v[216:219], v[240:243], v[8:11]
	v_mfma_f32_16x16x32_bf16 v[4:7], v[176:179], v[248:251], v[4:7]
	v_mfma_f32_16x16x32_bf16 v[0:3], v[216:219], v[248:251], v[0:3]
	s_setprio 0
	s_barrier
	s_add_i32 s55, 0, 0x18000
	s_add_i32 s56, 0, 0x1c000
	v_add_u32_e32 v168, s55, v182
	v_add_u32_e32 v216, s56, v182
	ds_read_b128 v[156:159], v168
	ds_read_b128 v[160:163], v168 offset:1024
	ds_read_b128 v[164:167], v168 offset:2048
	ds_read_b128 v[168:171], v168 offset:3072
	ds_read_b128 v[172:175], v216
	ds_read_b128 v[176:179], v216 offset:1024
	ds_read_b128 v[212:215], v216 offset:2048
	ds_read_b128 v[216:219], v216 offset:3072
	s_add_u32 s50, s50, 0x40000
	s_addc_u32 s51, s51, 0
	s_mov_b32 m0, s67
	v_lshl_add_u64 v[252:253], s[50:51], 0, v[128:129]
	ds_read_b128 v[220:223], v199 offset:32768
	ds_read_b128 v[224:227], v199 offset:33792
	ds_read_b128 v[228:231], v199 offset:34816
	ds_read_b128 v[232:235], v199 offset:35840
	ds_read_b128 v[236:239], v199 offset:36864
	ds_read_b128 v[240:243], v199 offset:37888
	ds_read_b128 v[244:247], v199 offset:38912
	ds_read_b128 v[248:251], v199 offset:39936
	global_load_lds_dwordx4 v[252:253], off
	v_lshl_add_u64 v[252:253], s[50:51], 0, v[132:133]
	s_mov_b32 m0, s68
	s_nop 0
	global_load_lds_dwordx4 v[252:253], off
	s_waitcnt vmcnt(8)
	s_waitcnt lgkmcnt(0)
	s_barrier
	s_setprio 1
	s_waitcnt lgkmcnt(0)
	v_mfma_f32_16x16x32_bf16 v[124:127], v[156:159], v[220:223], v[124:127]
	v_mfma_f32_16x16x32_bf16 v[120:123], v[164:167], v[220:223], v[120:123]
	v_mfma_f32_16x16x32_bf16 v[116:119], v[156:159], v[228:231], v[116:119]
	v_mfma_f32_16x16x32_bf16 v[112:115], v[164:167], v[228:231], v[112:115]
	v_mfma_f32_16x16x32_bf16 v[92:95], v[156:159], v[236:239], v[92:95]
	v_mfma_f32_16x16x32_bf16 v[88:91], v[164:167], v[236:239], v[88:91]
	v_mfma_f32_16x16x32_bf16 v[84:87], v[156:159], v[244:247], v[84:87]
	v_mfma_f32_16x16x32_bf16 v[80:83], v[164:167], v[244:247], v[80:83]
	v_mfma_f32_16x16x32_bf16 v[124:127], v[160:163], v[224:227], v[124:127]
	v_mfma_f32_16x16x32_bf16 v[120:123], v[168:171], v[224:227], v[120:123]
	v_mfma_f32_16x16x32_bf16 v[116:119], v[160:163], v[232:235], v[116:119]
	v_mfma_f32_16x16x32_bf16 v[112:115], v[168:171], v[232:235], v[112:115]
	v_mfma_f32_16x16x32_bf16 v[92:95], v[160:163], v[240:243], v[92:95]
	v_mfma_f32_16x16x32_bf16 v[88:91], v[168:171], v[240:243], v[88:91]
	v_mfma_f32_16x16x32_bf16 v[84:87], v[160:163], v[248:251], v[84:87]
	v_mfma_f32_16x16x32_bf16 v[80:83], v[168:171], v[248:251], v[80:83]
	s_setprio 0
	s_setprio 1
	v_mfma_f32_16x16x32_bf16 v[108:111], v[172:175], v[220:223], v[108:111]
	v_mfma_f32_16x16x32_bf16 v[104:107], v[212:215], v[220:223], v[104:107]
	v_mfma_f32_16x16x32_bf16 v[100:103], v[172:175], v[228:231], v[100:103]
	v_mfma_f32_16x16x32_bf16 v[96:99], v[212:215], v[228:231], v[96:99]
	v_mfma_f32_16x16x32_bf16 v[76:79], v[172:175], v[236:239], v[76:79]
	v_mfma_f32_16x16x32_bf16 v[72:75], v[212:215], v[236:239], v[72:75]
	v_mfma_f32_16x16x32_bf16 v[68:71], v[172:175], v[244:247], v[68:71]
	v_mfma_f32_16x16x32_bf16 v[64:67], v[212:215], v[244:247], v[64:67]
	v_mfma_f32_16x16x32_bf16 v[108:111], v[176:179], v[224:227], v[108:111]
	v_mfma_f32_16x16x32_bf16 v[104:107], v[216:219], v[224:227], v[104:107]
	v_mfma_f32_16x16x32_bf16 v[100:103], v[176:179], v[232:235], v[100:103]
	v_mfma_f32_16x16x32_bf16 v[96:99], v[216:219], v[232:235], v[96:99]
	v_mfma_f32_16x16x32_bf16 v[76:79], v[176:179], v[240:243], v[76:79]
	v_mfma_f32_16x16x32_bf16 v[72:75], v[216:219], v[240:243], v[72:75]
	v_mfma_f32_16x16x32_bf16 v[68:71], v[176:179], v[248:251], v[68:71]
	v_mfma_f32_16x16x32_bf16 v[64:67], v[216:219], v[248:251], v[64:67]
	s_setprio 0
	s_barrier
	s_add_u32 s50, s48, 0x8000
	s_addc_u32 s51, s49, 0
	s_add_i32 s55, s55, s64
	v_lshl_add_u64 v[252:253], s[50:51], 0, v[130:131]
	s_mov_b32 m0, s55
	ds_read_b128 v[220:223], v199 offset:49152
	ds_read_b128 v[224:227], v199 offset:50176
	ds_read_b128 v[228:231], v199 offset:51200
	ds_read_b128 v[232:235], v199 offset:52224
	ds_read_b128 v[236:239], v199 offset:53248
	ds_read_b128 v[240:243], v199 offset:54272
	ds_read_b128 v[244:247], v199 offset:55296
	ds_read_b128 v[248:251], v199 offset:56320
	global_load_lds_dwordx4 v[252:253], off
	s_add_i32 m0, s55, 0x2000
	s_add_u32 s48, s48, 0xc000
	v_lshl_add_u64 v[252:253], s[50:51], 0, v[134:135]
	s_addc_u32 s49, s49, 0
	s_add_i32 s50, s56, s64
	global_load_lds_dwordx4 v[252:253], off
	v_lshl_add_u64 v[252:253], s[48:49], 0, v[130:131]
	s_mov_b32 m0, s50
	v_lshl_add_u64 v[204:205], v[204:205], 0, s[14:15]
	global_load_lds_dwordx4 v[252:253], off
	v_lshl_add_u64 v[252:253], s[48:49], 0, v[134:135]
	s_add_i32 m0, s50, 0x2000
	s_nop 0
	global_load_lds_dwordx4 v[252:253], off
	s_mov_b32 m0, s74
	s_nop 0
	global_load_lds_dwordx4 v[204:205], off
	v_lshl_add_u64 v[204:205], v[206:207], 0, s[14:15]
	s_mov_b32 m0, s75
	s_nop 0
	global_load_lds_dwordx4 v[204:205], off
	s_waitcnt vmcnt(8)
	s_waitcnt lgkmcnt(0)
	s_barrier
	s_setprio 1
	s_waitcnt lgkmcnt(0)
	v_mfma_f32_16x16x32_bf16 v[60:63], v[156:159], v[220:223], v[60:63]
	v_mfma_f32_16x16x32_bf16 v[56:59], v[164:167], v[220:223], v[56:59]
	v_mfma_f32_16x16x32_bf16 v[52:55], v[156:159], v[228:231], v[52:55]
	v_mfma_f32_16x16x32_bf16 v[48:51], v[164:167], v[228:231], v[48:51]
	v_mfma_f32_16x16x32_bf16 v[28:31], v[156:159], v[236:239], v[28:31]
	v_mfma_f32_16x16x32_bf16 v[24:27], v[164:167], v[236:239], v[24:27]
	v_mfma_f32_16x16x32_bf16 v[20:23], v[156:159], v[244:247], v[20:23]
	v_mfma_f32_16x16x32_bf16 v[12:15], v[164:167], v[244:247], v[12:15]
	v_mfma_f32_16x16x32_bf16 v[60:63], v[160:163], v[224:227], v[60:63]
	v_mfma_f32_16x16x32_bf16 v[56:59], v[168:171], v[224:227], v[56:59]
	v_mfma_f32_16x16x32_bf16 v[52:55], v[160:163], v[232:235], v[52:55]
	v_mfma_f32_16x16x32_bf16 v[48:51], v[168:171], v[232:235], v[48:51]
	v_mfma_f32_16x16x32_bf16 v[28:31], v[160:163], v[240:243], v[28:31]
	v_mfma_f32_16x16x32_bf16 v[24:27], v[168:171], v[240:243], v[24:27]
	v_mfma_f32_16x16x32_bf16 v[20:23], v[160:163], v[248:251], v[20:23]
	v_mfma_f32_16x16x32_bf16 v[12:15], v[168:171], v[248:251], v[12:15]
	s_setprio 0
	s_setprio 1
	v_mfma_f32_16x16x32_bf16 v[44:47], v[172:175], v[220:223], v[44:47]
	v_mfma_f32_16x16x32_bf16 v[40:43], v[212:215], v[220:223], v[40:43]
	v_mfma_f32_16x16x32_bf16 v[36:39], v[172:175], v[228:231], v[36:39]
	v_mfma_f32_16x16x32_bf16 v[32:35], v[212:215], v[228:231], v[32:35]
	v_mfma_f32_16x16x32_bf16 v[16:19], v[172:175], v[236:239], v[16:19]
	v_mfma_f32_16x16x32_bf16 v[8:11], v[212:215], v[236:239], v[8:11]
	v_mfma_f32_16x16x32_bf16 v[4:7], v[172:175], v[244:247], v[4:7]
	v_mfma_f32_16x16x32_bf16 v[0:3], v[212:215], v[244:247], v[0:3]
	v_mfma_f32_16x16x32_bf16 v[44:47], v[176:179], v[224:227], v[44:47]
	v_mfma_f32_16x16x32_bf16 v[40:43], v[216:219], v[224:227], v[40:43]
	v_mfma_f32_16x16x32_bf16 v[36:39], v[176:179], v[232:235], v[36:39]
	v_mfma_f32_16x16x32_bf16 v[32:35], v[216:219], v[232:235], v[32:35]
	v_mfma_f32_16x16x32_bf16 v[16:19], v[176:179], v[240:243], v[16:19]
	v_mfma_f32_16x16x32_bf16 v[8:11], v[216:219], v[240:243], v[8:11]
	v_mfma_f32_16x16x32_bf16 v[4:7], v[176:179], v[248:251], v[4:7]
	v_mfma_f32_16x16x32_bf16 v[0:3], v[216:219], v[248:251], v[0:3]
	s_setprio 0
	s_barrier
	s_add_i32 s54, s54, 2
	s_add_u32 s52, s52, 0x10000
	s_addc_u32 s53, s53, 0
	s_add_u32 s46, s46, 0x100
	s_addc_u32 s47, s47, 0
	s_cmp_gt_u32 s54, 13
	s_cbranch_scc0 .LBB0_2358
	s_and_b64 vcc, exec, s[16:17]
	s_cbranch_vccz .LBB0_2361
	s_barrier

.LBB0_2518:
	s_add_u32 s62, s30, 0x10000
	s_addc_u32 s63, s31, 0
	s_add_u32 s30, s34, 0xc000
	s_addc_u32 s31, s35, 0
	s_mov_b32 s64, -2
.LBB0_2519:
	ds_read_b128 v[144:147], v178
	ds_read_b128 v[148:151], v178 offset:1024
	ds_read_b128 v[152:155], v178 offset:2048
	ds_read_b128 v[156:159], v178 offset:3072
	ds_read_b128 v[160:163], v179
	ds_read_b128 v[164:167], v179 offset:1024
	ds_read_b128 v[182:185], v179 offset:2048
	ds_read_b128 v[186:189], v179 offset:3072
	s_add_u32 s34, s30, 0x4000
	s_addc_u32 s35, s31, 0
	s_cmp_eq_u32 s64, 40
	s_cselect_b32 s38, s4, s34
	s_cselect_b32 s39, s5, s35
	s_cselect_b32 s36, s28, s62
	s_cselect_b32 s37, s29, s63
	s_add_u32 s34, s38, 0x8000
	s_addc_u32 s35, s39, 0
	v_lshl_add_u64 v[222:223], s[30:31], 0, v[138:139]
	s_add_i32 m0, s42, 0xc000
	ds_read_b128 v[190:193], v180
	ds_read_b128 v[194:197], v180 offset:1024
	ds_read_b128 v[198:201], v180 offset:2048
	ds_read_b128 v[202:205], v180 offset:3072
	ds_read_b128 v[206:209], v180 offset:4096
	ds_read_b128 v[210:213], v180 offset:5120
	ds_read_b128 v[214:217], v180 offset:6144
	ds_read_b128 v[218:221], v180 offset:7168
	global_load_lds_dwordx4 v[222:223], off
	v_lshl_add_u64 v[222:223], s[30:31], 0, v[136:137]
	s_add_i32 m0, s42, 0xe000
	s_nop 0
	global_load_lds_dwordx4 v[222:223], off
	s_cmp_lg_u32 s64, -2
	s_cbranch_scc1 .Lzm_0
	v_mov_b32_e32 v0, 0
	v_mov_b32_e32 v1, v0
	v_mov_b32_e32 v2, v0
	v_mov_b32_e32 v3, v0
	v_mov_b32_e32 v4, v0
	v_mov_b32_e32 v5, v0
	v_mov_b32_e32 v6, v0
	v_mov_b32_e32 v7, v0
	v_mov_b32_e32 v8, v0
	v_mov_b32_e32 v9, v0
	v_mov_b32_e32 v10, v0
	v_mov_b32_e32 v11, v0
	v_mov_b32_e32 v12, v0
	v_mov_b32_e32 v13, v0
	v_mov_b32_e32 v14, v0
	v_mov_b32_e32 v15, v0
	v_mov_b32_e32 v16, v0
	v_mov_b32_e32 v17, v0
	v_mov_b32_e32 v18, v0
	v_mov_b32_e32 v19, v0
	v_mov_b32_e32 v20, v0
	v_mov_b32_e32 v21, v0
	v_mov_b32_e32 v22, v0
	v_mov_b32_e32 v23, v0
	v_mov_b32_e32 v24, v0
	v_mov_b32_e32 v25, v0
	v_mov_b32_e32 v26, v0
	v_mov_b32_e32 v27, v0
	v_mov_b32_e32 v28, v0
	v_mov_b32_e32 v29, v0
	v_mov_b32_e32 v30, v0
	v_mov_b32_e32 v31, v0
	v_mov_b32_e32 v32, v0
	v_mov_b32_e32 v33, v0
	v_mov_b32_e32 v34, v0
	v_mov_b32_e32 v35, v0
	v_mov_b32_e32 v36, v0
	v_mov_b32_e32 v37, v0
	v_mov_b32_e32 v38, v0
	v_mov_b32_e32 v39, v0
	v_mov_b32_e32 v40, v0
	v_mov_b32_e32 v41, v0
	v_mov_b32_e32 v42, v0
	v_mov_b32_e32 v43, v0
	v_mov_b32_e32 v44, v0
	v_mov_b32_e32 v45, v0
	v_mov_b32_e32 v46, v0
	v_mov_b32_e32 v47, v0
	v_mov_b32_e32 v48, v0
	v_mov_b32_e32 v49, v0
	v_mov_b32_e32 v50, v0
	v_mov_b32_e32 v51, v0
	v_mov_b32_e32 v52, v0
	v_mov_b32_e32 v53, v0
	v_mov_b32_e32 v54, v0
	v_mov_b32_e32 v55, v0
	v_mov_b32_e32 v56, v0
	v_mov_b32_e32 v57, v0
	v_mov_b32_e32 v58, v0
	v_mov_b32_e32 v59, v0
	v_mov_b32_e32 v60, v0
	v_mov_b32_e32 v61, v0
	v_mov_b32_e32 v62, v0
	v_mov_b32_e32 v63, v0
	v_mov_b32_e32 v64, v0
	v_mov_b32_e32 v65, v0
	v_mov_b32_e32 v66, v0
	v_mov_b32_e32 v67, v0
	v_mov_b32_e32 v68, v0
	v_mov_b32_e32 v69, v0
	v_mov_b32_e32 v70, v0
	v_mov_b32_e32 v71, v0
	v_mov_b32_e32 v72, v0
	v_mov_b32_e32 v73, v0
	v_mov_b32_e32 v74, v0
	v_mov_b32_e32 v75, v0
	v_mov_b32_e32 v76, v0
	v_mov_b32_e32 v77, v0
	v_mov_b32_e32 v78, v0
	v_mov_b32_e32 v79, v0
	v_mov_b32_e32 v80, v0
	v_mov_b32_e32 v81, v0
	v_mov_b32_e32 v82, v0
	v_mov_b32_e32 v83, v0
	v_mov_b32_e32 v84, v0
	v_mov_b32_e32 v85, v0
	v_mov_b32_e32 v86, v0
	v_mov_b32_e32 v87, v0
	v_mov_b32_e32 v88, v0
	v_mov_b32_e32 v89, v0
	v_mov_b32_e32 v90, v0
	v_mov_b32_e32 v91, v0
	v_mov_b32_e32 v92, v0
	v_mov_b32_e32 v93, v0
	v_mov_b32_e32 v94, v0
	v_mov_b32_e32 v95, v0
	v_mov_b32_e32 v96, v0
	v_mov_b32_e32 v97, v0
	v_mov_b32_e32 v98, v0
	v_mov_b32_e32 v99, v0
	v_mov_b32_e32 v100, v0
	v_mov_b32_e32 v101, v0
	v_mov_b32_e32 v102, v0
	v_mov_b32_e32 v103, v0
	v_mov_b32_e32 v104, v0
	v_mov_b32_e32 v105, v0
	v_mov_b32_e32 v106, v0
	v_mov_b32_e32 v107, v0
	v_mov_b32_e32 v108, v0
	v_mov_b32_e32 v109, v0
	v_mov_b32_e32 v110, v0
	v_mov_b32_e32 v111, v0
	v_mov_b32_e32 v112, v0
	v_mov_b32_e32 v113, v0
	v_mov_b32_e32 v114, v0
	v_mov_b32_e32 v115, v0
	v_mov_b32_e32 v116, v0
	v_mov_b32_e32 v117, v0
	v_mov_b32_e32 v118, v0
	v_mov_b32_e32 v119, v0
	v_mov_b32_e32 v120, v0
	v_mov_b32_e32 v121, v0
	v_mov_b32_e32 v122, v0
	v_mov_b32_e32 v123, v0
	v_mov_b32_e32 v124, v0
	v_mov_b32_e32 v125, v0
	v_mov_b32_e32 v126, v0
	v_mov_b32_e32 v127, v0
.Lzm_0:
	s_waitcnt vmcnt(8)
	s_waitcnt lgkmcnt(0)
	s_barrier
	s_setprio 1
	s_waitcnt lgkmcnt(0)
	v_mfma_f32_16x16x32_bf16 v[124:127], v[144:147], v[190:193], v[124:127]
	v_mfma_f32_16x16x32_bf16 v[120:123], v[152:155], v[190:193], v[120:123]
	v_mfma_f32_16x16x32_bf16 v[116:119], v[144:147], v[198:201], v[116:119]
	v_mfma_f32_16x16x32_bf16 v[112:115], v[152:155], v[198:201], v[112:115]
	v_mfma_f32_16x16x32_bf16 v[92:95], v[144:147], v[206:209], v[92:95]
	v_mfma_f32_16x16x32_bf16 v[88:91], v[152:155], v[206:209], v[88:91]
	v_mfma_f32_16x16x32_bf16 v[84:87], v[144:147], v[214:217], v[84:87]
	v_mfma_f32_16x16x32_bf16 v[80:83], v[152:155], v[214:217], v[80:83]
	v_mfma_f32_16x16x32_bf16 v[124:127], v[148:151], v[194:197], v[124:127]
	v_mfma_f32_16x16x32_bf16 v[120:123], v[156:159], v[194:197], v[120:123]
	v_mfma_f32_16x16x32_bf16 v[116:119], v[148:151], v[202:205], v[116:119]
	v_mfma_f32_16x16x32_bf16 v[112:115], v[156:159], v[202:205], v[112:115]
	v_mfma_f32_16x16x32_bf16 v[92:95], v[148:151], v[210:213], v[92:95]
	v_mfma_f32_16x16x32_bf16 v[88:91], v[156:159], v[210:213], v[88:91]
	v_mfma_f32_16x16x32_bf16 v[84:87], v[148:151], v[218:221], v[84:87]
	v_mfma_f32_16x16x32_bf16 v[80:83], v[156:159], v[218:221], v[80:83]
	s_setprio 0
	s_setprio 1
	v_mfma_f32_16x16x32_bf16 v[108:111], v[160:163], v[190:193], v[108:111]
	v_mfma_f32_16x16x32_bf16 v[104:107], v[182:185], v[190:193], v[104:107]
	v_mfma_f32_16x16x32_bf16 v[100:103], v[160:163], v[198:201], v[100:103]
	v_mfma_f32_16x16x32_bf16 v[96:99], v[182:185], v[198:201], v[96:99]
	v_mfma_f32_16x16x32_bf16 v[76:79], v[160:163], v[206:209], v[76:79]
	v_mfma_f32_16x16x32_bf16 v[72:75], v[182:185], v[206:209], v[72:75]
	v_mfma_f32_16x16x32_bf16 v[68:71], v[160:163], v[214:217], v[68:71]
	v_mfma_f32_16x16x32_bf16 v[64:67], v[182:185], v[214:217], v[64:67]
	v_mfma_f32_16x16x32_bf16 v[108:111], v[164:167], v[194:197], v[108:111]
	v_mfma_f32_16x16x32_bf16 v[104:107], v[186:189], v[194:197], v[104:107]
	v_mfma_f32_16x16x32_bf16 v[100:103], v[164:167], v[202:205], v[100:103]
	v_mfma_f32_16x16x32_bf16 v[96:99], v[186:189], v[202:205], v[96:99]
	v_mfma_f32_16x16x32_bf16 v[76:79], v[164:167], v[210:213], v[76:79]
	v_mfma_f32_16x16x32_bf16 v[72:75], v[186:189], v[210:213], v[72:75]
	v_mfma_f32_16x16x32_bf16 v[68:71], v[164:167], v[218:221], v[68:71]
	v_mfma_f32_16x16x32_bf16 v[64:67], v[186:189], v[218:221], v[64:67]
	s_setprio 0
	s_barrier
	s_add_i32 s65, s55, s41
	v_lshl_add_u64 v[222:223], s[36:37], 0, v[128:129]
	s_mov_b32 m0, s65
	ds_read_b128 v[190:193], v180 offset:16384
	ds_read_b128 v[194:197], v180 offset:17408
	ds_read_b128 v[198:201], v180 offset:18432
	ds_read_b128 v[202:205], v180 offset:19456
	ds_read_b128 v[206:209], v180 offset:20480
	ds_read_b128 v[210:213], v180 offset:21504
	ds_read_b128 v[214:217], v180 offset:22528
	ds_read_b128 v[218:221], v180 offset:23552
	global_load_lds_dwordx4 v[222:223], off
	s_add_i32 m0, s65, 0x2000
	s_add_u32 s66, s36, 0x4000
	v_lshl_add_u64 v[222:223], s[36:37], 0, v[130:131]
	s_addc_u32 s67, s37, 0
	s_add_i32 s65, s56, s41
	global_load_lds_dwordx4 v[222:223], off
	v_lshl_add_u64 v[222:223], s[66:67], 0, v[128:129]
	s_mov_b32 m0, s65
	s_nop 0
	global_load_lds_dwordx4 v[222:223], off
	v_lshl_add_u64 v[222:223], s[66:67], 0, v[130:131]
	s_add_i32 m0, s65, 0x2000
	s_nop 0
	global_load_lds_dwordx4 v[222:223], off
	v_lshl_add_u64 v[222:223], s[38:39], 0, v[128:129]
	s_mov_b32 m0, s42
	s_nop 0
	global_load_lds_dwordx4 v[222:223], off
	v_lshl_add_u64 v[222:223], s[38:39], 0, v[130:131]
	s_mov_b32 m0, s43
	s_nop 0
	global_load_lds_dwordx4 v[222:223], off
	s_waitcnt vmcnt(8)
	s_waitcnt lgkmcnt(0)
	s_barrier
	s_setprio 1
	s_waitcnt lgkmcnt(0)
	v_mfma_f32_16x16x32_bf16 v[60:63], v[144:147], v[190:193], v[60:63]
	v_mfma_f32_16x16x32_bf16 v[56:59], v[152:155], v[190:193], v[56:59]
	v_mfma_f32_16x16x32_bf16 v[52:55], v[144:147], v[198:201], v[52:55]
	v_mfma_f32_16x16x32_bf16 v[48:51], v[152:155], v[198:201], v[48:51]
	v_mfma_f32_16x16x32_bf16 v[28:31], v[144:147], v[206:209], v[28:31]
	v_mfma_f32_16x16x32_bf16 v[24:27], v[152:155], v[206:209], v[24:27]
	v_mfma_f32_16x16x32_bf16 v[20:23], v[144:147], v[214:217], v[20:23]
	v_mfma_f32_16x16x32_bf16 v[12:15], v[152:155], v[214:217], v[12:15]
	v_mfma_f32_16x16x32_bf16 v[60:63], v[148:151], v[194:197], v[60:63]
	v_mfma_f32_16x16x32_bf16 v[56:59], v[156:159], v[194:197], v[56:59]
	v_mfma_f32_16x16x32_bf16 v[52:55], v[148:151], v[202:205], v[52:55]
	v_mfma_f32_16x16x32_bf16 v[48:51], v[156:159], v[202:205], v[48:51]
	v_mfma_f32_16x16x32_bf16 v[28:31], v[148:151], v[210:213], v[28:31]
	v_mfma_f32_16x16x32_bf16 v[24:27], v[156:159], v[210:213], v[24:27]
	v_mfma_f32_16x16x32_bf16 v[20:23], v[148:151], v[218:221], v[20:23]
	v_mfma_f32_16x16x32_bf16 v[12:15], v[156:159], v[218:221], v[12:15]
	s_setprio 0
	s_setprio 1
	v_mfma_f32_16x16x32_bf16 v[44:47], v[160:163], v[190:193], v[44:47]
	v_mfma_f32_16x16x32_bf16 v[40:43], v[182:185], v[190:193], v[40:43]
	v_mfma_f32_16x16x32_bf16 v[36:39], v[160:163], v[198:201], v[36:39]
	v_mfma_f32_16x16x32_bf16 v[32:35], v[182:185], v[198:201], v[32:35]
	v_mfma_f32_16x16x32_bf16 v[16:19], v[160:163], v[206:209], v[16:19]
	v_mfma_f32_16x16x32_bf16 v[8:11], v[182:185], v[206:209], v[8:11]
	v_mfma_f32_16x16x32_bf16 v[4:7], v[160:163], v[214:217], v[4:7]
	v_mfma_f32_16x16x32_bf16 v[0:3], v[182:185], v[214:217], v[0:3]
	v_mfma_f32_16x16x32_bf16 v[44:47], v[164:167], v[194:197], v[44:47]
	v_mfma_f32_16x16x32_bf16 v[40:43], v[186:189], v[194:197], v[40:43]
	v_mfma_f32_16x16x32_bf16 v[36:39], v[164:167], v[202:205], v[36:39]
	v_mfma_f32_16x16x32_bf16 v[32:35], v[186:189], v[202:205], v[32:35]
	v_mfma_f32_16x16x32_bf16 v[16:19], v[164:167], v[210:213], v[16:19]
	v_mfma_f32_16x16x32_bf16 v[8:11], v[186:189], v[210:213], v[8:11]
	v_mfma_f32_16x16x32_bf16 v[4:7], v[164:167], v[218:221], v[4:7]
	v_mfma_f32_16x16x32_bf16 v[0:3], v[186:189], v[218:221], v[0:3]
	s_setprio 0
	s_barrier
	s_add_i32 s65, 0, 0x18000
	s_add_i32 s66, 0, 0x1c000
	v_add_u32_e32 v156, s65, v170
	v_add_u32_e32 v186, s66, v170
	ds_read_b128 v[144:147], v156
	ds_read_b128 v[148:151], v156 offset:1024
	ds_read_b128 v[152:155], v156 offset:2048
	ds_read_b128 v[156:159], v156 offset:3072
	ds_read_b128 v[160:163], v186
	ds_read_b128 v[164:167], v186 offset:1024
	ds_read_b128 v[182:185], v186 offset:2048
	ds_read_b128 v[186:189], v186 offset:3072
	s_add_u32 s38, s38, 0x4000
	s_addc_u32 s39, s39, 0
	s_mov_b32 m0, s44
	v_lshl_add_u64 v[222:223], s[38:39], 0, v[128:129]
	ds_read_b128 v[190:193], v180 offset:32768
	ds_read_b128 v[194:197], v180 offset:33792
	ds_read_b128 v[198:201], v180 offset:34816
	ds_read_b128 v[202:205], v180 offset:35840
	ds_read_b128 v[206:209], v180 offset:36864
	ds_read_b128 v[210:213], v180 offset:37888
	ds_read_b128 v[214:217], v180 offset:38912
	ds_read_b128 v[218:221], v180 offset:39936
	global_load_lds_dwordx4 v[222:223], off
	v_lshl_add_u64 v[222:223], s[38:39], 0, v[130:131]
	s_mov_b32 m0, s45
	s_nop 0
	global_load_lds_dwordx4 v[222:223], off
	s_waitcnt vmcnt(8)
	s_waitcnt lgkmcnt(0)
	s_barrier
	s_setprio 1
	s_waitcnt lgkmcnt(0)
	v_mfma_f32_16x16x32_bf16 v[124:127], v[144:147], v[190:193], v[124:127]
	v_mfma_f32_16x16x32_bf16 v[120:123], v[152:155], v[190:193], v[120:123]
	v_mfma_f32_16x16x32_bf16 v[116:119], v[144:147], v[198:201], v[116:119]
	v_mfma_f32_16x16x32_bf16 v[112:115], v[152:155], v[198:201], v[112:115]
	v_mfma_f32_16x16x32_bf16 v[92:95], v[144:147], v[206:209], v[92:95]
	v_mfma_f32_16x16x32_bf16 v[88:91], v[152:155], v[206:209], v[88:91]
	v_mfma_f32_16x16x32_bf16 v[84:87], v[144:147], v[214:217], v[84:87]
	v_mfma_f32_16x16x32_bf16 v[80:83], v[152:155], v[214:217], v[80:83]
	v_mfma_f32_16x16x32_bf16 v[124:127], v[148:151], v[194:197], v[124:127]
	v_mfma_f32_16x16x32_bf16 v[120:123], v[156:159], v[194:197], v[120:123]
	v_mfma_f32_16x16x32_bf16 v[116:119], v[148:151], v[202:205], v[116:119]
	v_mfma_f32_16x16x32_bf16 v[112:115], v[156:159], v[202:205], v[112:115]
	v_mfma_f32_16x16x32_bf16 v[92:95], v[148:151], v[210:213], v[92:95]
	v_mfma_f32_16x16x32_bf16 v[88:91], v[156:159], v[210:213], v[88:91]
	v_mfma_f32_16x16x32_bf16 v[84:87], v[148:151], v[218:221], v[84:87]
	v_mfma_f32_16x16x32_bf16 v[80:83], v[156:159], v[218:221], v[80:83]
	s_setprio 0
	s_setprio 1
	v_mfma_f32_16x16x32_bf16 v[108:111], v[160:163], v[190:193], v[108:111]
	v_mfma_f32_16x16x32_bf16 v[104:107], v[182:185], v[190:193], v[104:107]
	v_mfma_f32_16x16x32_bf16 v[100:103], v[160:163], v[198:201], v[100:103]
	v_mfma_f32_16x16x32_bf16 v[96:99], v[182:185], v[198:201], v[96:99]
	v_mfma_f32_16x16x32_bf16 v[76:79], v[160:163], v[206:209], v[76:79]
	v_mfma_f32_16x16x32_bf16 v[72:75], v[182:185], v[206:209], v[72:75]
	v_mfma_f32_16x16x32_bf16 v[68:71], v[160:163], v[214:217], v[68:71]
	v_mfma_f32_16x16x32_bf16 v[64:67], v[182:185], v[214:217], v[64:67]
	v_mfma_f32_16x16x32_bf16 v[108:111], v[164:167], v[194:197], v[108:111]
	v_mfma_f32_16x16x32_bf16 v[104:107], v[186:189], v[194:197], v[104:107]
	v_mfma_f32_16x16x32_bf16 v[100:103], v[164:167], v[202:205], v[100:103]
	v_mfma_f32_16x16x32_bf16 v[96:99], v[186:189], v[202:205], v[96:99]
	v_mfma_f32_16x16x32_bf16 v[76:79], v[164:167], v[210:213], v[76:79]
	v_mfma_f32_16x16x32_bf16 v[72:75], v[186:189], v[210:213], v[72:75]
	v_mfma_f32_16x16x32_bf16 v[68:71], v[164:167], v[218:221], v[68:71]
	v_mfma_f32_16x16x32_bf16 v[64:67], v[186:189], v[218:221], v[64:67]
	s_setprio 0
	s_barrier
	s_add_u32 s38, s36, 0x8000
	s_addc_u32 s39, s37, 0
	s_add_i32 s65, s65, s41
	v_lshl_add_u64 v[222:223], s[38:39], 0, v[128:129]
	s_mov_b32 m0, s65
	ds_read_b128 v[190:193], v180 offset:49152
	ds_read_b128 v[194:197], v180 offset:50176
	ds_read_b128 v[198:201], v180 offset:51200
	ds_read_b128 v[202:205], v180 offset:52224
	ds_read_b128 v[206:209], v180 offset:53248
	ds_read_b128 v[210:213], v180 offset:54272
	ds_read_b128 v[214:217], v180 offset:55296
	ds_read_b128 v[218:221], v180 offset:56320
	global_load_lds_dwordx4 v[222:223], off
	s_add_i32 m0, s65, 0x2000
	s_add_u32 s36, s36, 0xc000
	v_lshl_add_u64 v[222:223], s[38:39], 0, v[130:131]
	s_addc_u32 s37, s37, 0
	s_add_i32 s38, s66, s41
	global_load_lds_dwordx4 v[222:223], off
	v_lshl_add_u64 v[222:223], s[36:37], 0, v[128:129]
	s_mov_b32 m0, s38
	s_nop 0
	global_load_lds_dwordx4 v[222:223], off
	v_lshl_add_u64 v[222:223], s[36:37], 0, v[130:131]
	s_add_i32 m0, s38, 0x2000
	s_nop 0
	global_load_lds_dwordx4 v[222:223], off
	v_lshl_add_u64 v[222:223], s[34:35], 0, v[128:129]
	s_mov_b32 m0, s51
	s_nop 0
	global_load_lds_dwordx4 v[222:223], off
	v_lshl_add_u64 v[222:223], s[34:35], 0, v[130:131]
	s_mov_b32 m0, s52
	s_nop 0
	global_load_lds_dwordx4 v[222:223], off
	s_waitcnt vmcnt(8)
	s_waitcnt lgkmcnt(0)
	s_barrier
	s_setprio 1
	s_waitcnt lgkmcnt(0)
	v_mfma_f32_16x16x32_bf16 v[60:63], v[144:147], v[190:193], v[60:63]
	v_mfma_f32_16x16x32_bf16 v[56:59], v[152:155], v[190:193], v[56:59]
	v_mfma_f32_16x16x32_bf16 v[52:55], v[144:147], v[198:201], v[52:55]
	v_mfma_f32_16x16x32_bf16 v[48:51], v[152:155], v[198:201], v[48:51]
	v_mfma_f32_16x16x32_bf16 v[28:31], v[144:147], v[206:209], v[28:31]
	v_mfma_f32_16x16x32_bf16 v[24:27], v[152:155], v[206:209], v[24:27]
	v_mfma_f32_16x16x32_bf16 v[20:23], v[144:147], v[214:217], v[20:23]
	v_mfma_f32_16x16x32_bf16 v[12:15], v[152:155], v[214:217], v[12:15]
	v_mfma_f32_16x16x32_bf16 v[60:63], v[148:151], v[194:197], v[60:63]
	v_mfma_f32_16x16x32_bf16 v[56:59], v[156:159], v[194:197], v[56:59]
	v_mfma_f32_16x16x32_bf16 v[52:55], v[148:151], v[202:205], v[52:55]
	v_mfma_f32_16x16x32_bf16 v[48:51], v[156:159], v[202:205], v[48:51]
	v_mfma_f32_16x16x32_bf16 v[28:31], v[148:151], v[210:213], v[28:31]
	v_mfma_f32_16x16x32_bf16 v[24:27], v[156:159], v[210:213], v[24:27]
	v_mfma_f32_16x16x32_bf16 v[20:23], v[148:151], v[218:221], v[20:23]
	v_mfma_f32_16x16x32_bf16 v[12:15], v[156:159], v[218:221], v[12:15]
	s_setprio 0
	s_setprio 1
	v_mfma_f32_16x16x32_bf16 v[44:47], v[160:163], v[190:193], v[44:47]
	v_mfma_f32_16x16x32_bf16 v[40:43], v[182:185], v[190:193], v[40:43]
	v_mfma_f32_16x16x32_bf16 v[36:39], v[160:163], v[198:201], v[36:39]
	v_mfma_f32_16x16x32_bf16 v[32:35], v[182:185], v[198:201], v[32:35]
	v_mfma_f32_16x16x32_bf16 v[16:19], v[160:163], v[206:209], v[16:19]
	v_mfma_f32_16x16x32_bf16 v[8:11], v[182:185], v[206:209], v[8:11]
	v_mfma_f32_16x16x32_bf16 v[4:7], v[160:163], v[214:217], v[4:7]
	v_mfma_f32_16x16x32_bf16 v[0:3], v[182:185], v[214:217], v[0:3]
	v_mfma_f32_16x16x32_bf16 v[44:47], v[164:167], v[194:197], v[44:47]
	v_mfma_f32_16x16x32_bf16 v[40:43], v[186:189], v[194:197], v[40:43]
	v_mfma_f32_16x16x32_bf16 v[36:39], v[164:167], v[202:205], v[36:39]
	v_mfma_f32_16x16x32_bf16 v[32:35], v[186:189], v[202:205], v[32:35]
	v_mfma_f32_16x16x32_bf16 v[16:19], v[164:167], v[210:213], v[16:19]
	v_mfma_f32_16x16x32_bf16 v[8:11], v[186:189], v[210:213], v[8:11]
	v_mfma_f32_16x16x32_bf16 v[4:7], v[164:167], v[218:221], v[4:7]
	v_mfma_f32_16x16x32_bf16 v[0:3], v[186:189], v[218:221], v[0:3]
	s_setprio 0
	s_barrier
	s_add_i32 s64, s64, 2
	s_add_u32 s62, s62, 0x10000
	s_addc_u32 s63, s63, 0
	s_add_u32 s30, s30, 0x10000
	s_addc_u32 s31, s31, 0
	s_cmp_gt_u32 s64, 41
	s_cbranch_scc0 .LBB0_2519
	s_and_b64 vcc, exec, s[14:15]
	s_cbranch_vccz .LBB0_2522
	s_barrier
